# GEMM LDS-DMA issue positions spread every 3 MFMAs (1,4,7,10,13,15) instead of every 2
# speedup vs baseline: 1.0098x; 1.0010x over previous
.LBB0_94:
	s_ashr_i32 s0, s2, 31
	s_lshr_b32 s0, s0, 29
	s_add_i32 s0, s2, s0
	v_mov_b32_e32 v78, v133
	s_and_b32 s1, s0, 0x1fffff8
	s_lshl_b32 s0, s0, 5
	s_and_b32 s22, s0, 0xffffff00
	v_ashrrev_i32_e32 v6, 6, v78
	v_bfe_u32 v7, v78, 3, 3
	v_lshl_or_b32 v8, v6, 5, v7
	v_add_u32_e32 v0, s22, v8
	s_waitcnt lgkmcnt(0)
	v_ashrrev_i32_e32 v1, 31, v0
	v_lshlrev_b64 v[2:3], 11, v[0:1]
	v_bfe_u32 v1, v78, 4, 2
	v_readlane_b32 s20, v214, 4
	v_xor_b32_e32 v1, v1, v78
	v_readlane_b32 s21, v214, 5
	v_lshlrev_b32_e32 v1, 4, v1
	v_and_b32_e32 v64, 0x70, v1
	v_lshl_add_u64 v[2:3], s[20:21], 0, v[2:3]
	v_or_b32_e32 v1, 8, v8
	v_lshl_add_u64 v[66:67], v[2:3], 0, v[64:65]
	v_add_u32_e32 v2, s22, v1
	v_lshrrev_b32_e32 v1, 1, v1
	v_xor_b32_e32 v1, v1, v78
	v_ashrrev_i32_e32 v3, 31, v2
	v_lshlrev_b32_e32 v1, 4, v1
	v_or_b32_e32 v0, 16, v0
	v_lshlrev_b64 v[2:3], 11, v[2:3]
	v_and_b32_e32 v4, 0x70, v1
	v_ashrrev_i32_e32 v1, 31, v0
	v_lshl_add_u64 v[2:3], s[20:21], 0, v[2:3]
	v_mov_b32_e32 v5, v65
	v_lshlrev_b64 v[0:1], 11, v[0:1]
	v_lshl_add_u64 v[68:69], v[2:3], 0, v[4:5]
	v_lshl_add_u64 v[0:1], s[20:21], 0, v[0:1]
	v_or_b32_e32 v2, 24, v8
	v_lshl_add_u64 v[70:71], v[0:1], 0, v[64:65]
	v_add_u32_e32 v0, s22, v2
	v_lshrrev_b32_e32 v2, 1, v2
	v_ashrrev_i32_e32 v1, 31, v0
	v_xor_b32_e32 v2, v2, v78
	v_lshlrev_b64 v[0:1], 11, v[0:1]
	v_lshlrev_b32_e32 v2, 4, v2
	s_sub_i32 s1, s2, s1
	v_lshl_add_u64 v[0:1], s[20:21], 0, v[0:1]
	v_and_b32_e32 v2, 0x70, v2
	v_mov_b32_e32 v3, v65
	s_lshl_b32 s0, s1, 7
	v_lshl_add_u64 v[72:73], v[0:1], 0, v[2:3]
	v_lshl_or_b32 v2, v6, 4, v7
	v_add_u32_e32 v0, s0, v2
	v_lshlrev_b32_e32 v3, 12, v6
	v_ashrrev_i32_e32 v1, 31, v0
	v_add_u32_e32 v126, 0, v3
	v_lshlrev_b64 v[0:1], 11, v[0:1]
	s_waitcnt vmcnt(0)
	v_readfirstlane_b32 s38, v126
	v_add_u32_e32 v127, 0x400, v126
	v_lshl_add_u64 v[0:1], s[40:41], 0, v[0:1]
	v_or_b32_e32 v2, 8, v2
	s_waitcnt lgkmcnt(0)
	s_barrier
	s_mov_b32 m0, s38
	v_readfirstlane_b32 s39, v127
	v_add_u32_e32 v128, 0x800, v126
	v_lshlrev_b32_e32 v5, 11, v6
	v_and_b32_e32 v80, 1, v6
	v_lshl_add_u64 v[74:75], v[0:1], 0, v[64:65]
	v_add_u32_e32 v0, s0, v2
	v_lshrrev_b32_e32 v2, 1, v2
	global_load_lds_dwordx4 v[66:67], off
	s_mov_b32 m0, s39
	v_readfirstlane_b32 s48, v128
	v_add_u32_e32 v129, 0xc00, v126
	v_add_u32_e32 v6, 0, v5
	v_ashrrev_i32_e32 v1, 31, v0
	v_xor_b32_e32 v2, v2, v78
	global_load_lds_dwordx4 v[68:69], off
	s_mov_b32 m0, s48
	v_readfirstlane_b32 s49, v129
	v_add_u32_e32 v131, 0x8000, v6
	v_lshlrev_b64 v[0:1], 11, v[0:1]
	v_lshlrev_b32_e32 v2, 4, v2
	global_load_lds_dwordx4 v[70:71], off
	s_mov_b32 m0, s49
	v_readfirstlane_b32 s53, v131
	v_add_u32_e32 v130, 0x8400, v6
	v_lshl_add_u64 v[0:1], s[40:41], 0, v[0:1]
	v_and_b32_e32 v64, 0x70, v2
	global_load_lds_dwordx4 v[72:73], off
	s_mov_b32 m0, s53
	v_readfirstlane_b32 s54, v130
	v_add_u32_e32 v120, 0xc000, v126
	v_lshl_add_u64 v[76:77], v[0:1], 0, v[64:65]
	global_load_lds_dwordx4 v[74:75], off
	s_mov_b32 m0, s54
	s_mov_b64 s[20:21], 0x80
	v_readfirstlane_b32 s29, v120
	v_add_u32_e32 v121, 0xc400, v126
	global_load_lds_dwordx4 v[76:77], off
	v_lshl_add_u64 v[0:1], v[66:67], 0, s[20:21]
	s_mov_b32 m0, s29
	v_readfirstlane_b32 s33, v121
	v_add_u32_e32 v122, 0xc800, v126
	global_load_lds_dwordx4 v[0:1], off
	v_lshl_add_u64 v[0:1], v[68:69], 0, s[20:21]
	s_mov_b32 m0, s33
	v_readfirstlane_b32 s34, v122
	v_add_u32_e32 v123, 0xcc00, v126
	global_load_lds_dwordx4 v[0:1], off
	v_lshl_add_u64 v[0:1], v[70:71], 0, s[20:21]
	s_mov_b32 m0, s34
	v_readfirstlane_b32 s35, v123
	v_add_u32_e32 v124, s85, v5
	global_load_lds_dwordx4 v[0:1], off
	v_lshl_add_u64 v[0:1], v[72:73], 0, s[20:21]
	s_mov_b32 m0, s35
	v_readfirstlane_b32 s36, v124
	v_add_u32_e32 v125, 0x14400, v6
	global_load_lds_dwordx4 v[0:1], off
	v_lshl_add_u64 v[0:1], v[74:75], 0, s[20:21]
	s_mov_b32 m0, s36
	v_readfirstlane_b32 s37, v125
	global_load_lds_dwordx4 v[0:1], off
	v_lshl_add_u64 v[0:1], v[76:77], 0, s[20:21]
	s_mov_b32 m0, s37
	v_lshrrev_b32_e32 v2, 1, v78
	v_bfe_u32 v64, v78, 5, 1
	global_load_lds_dwordx4 v[0:1], off
	v_add_u32_e32 v114, s3, v3
	v_bitop3_b32 v0, v2, v64, 7 bitop3:0x6c
	s_waitcnt vmcnt(6)
	s_mov_b64 s[30:31], 0x100
	v_readfirstlane_b32 s1, v114
	v_add_u32_e32 v115, 0x400, v114
	v_lshlrev_b32_e32 v132, 4, v0
	s_waitcnt lgkmcnt(0)
	s_barrier
	v_lshl_add_u64 v[0:1], v[66:67], 0, s[30:31]
	s_mov_b32 m0, s1
	v_readfirstlane_b32 s20, v115
	v_add_u32_e32 v116, 0x800, v114
	global_load_lds_dwordx4 v[0:1], off
	v_lshl_add_u64 v[0:1], v[68:69], 0, s[30:31]
	s_mov_b32 m0, s20
	v_readfirstlane_b32 s21, v116
	v_add_u32_e32 v117, 0xc00, v114
	v_readlane_b32 s24, v212, 31
	v_and_b32_e32 v79, 31, v78
	global_load_lds_dwordx4 v[0:1], off
	v_lshl_add_u64 v[0:1], v[70:71], 0, s[30:31]
	s_mov_b32 m0, s21
	v_readfirstlane_b32 s23, v117
	v_add_u32_e32 v118, s24, v5
	v_add_u32_e32 v2, s3, v5
	v_lshlrev_b32_e32 v4, 7, v79
	global_load_lds_dwordx4 v[0:1], off
	v_lshl_add_u64 v[0:1], v[72:73], 0, s[30:31]
	s_mov_b32 m0, s23
	v_readfirstlane_b32 s24, v118
	v_add_u32_e32 v119, 0x8400, v2
	v_lshl_or_b32 v102, v80, 13, v4
	global_load_lds_dwordx4 v[0:1], off
	v_lshl_add_u64 v[0:1], v[74:75], 0, s[30:31]
	s_mov_b32 m0, s24
	v_readfirstlane_b32 s28, v119
	global_load_lds_dwordx4 v[0:1], off
	v_lshl_add_u64 v[0:1], v[76:77], 0, s[30:31]
	s_mov_b32 m0, s28
	v_add_u32_e32 v100, 0, v102
	global_load_lds_dwordx4 v[0:1], off
	v_add_u32_e32 v83, v100, v132
	v_ashrrev_i32_e32 v81, 7, v78
	ds_read_b128 a[0:3], v83 offset:32768
	ds_read_b128 a[4:7], v83 offset:36864
	v_lshl_or_b32 v134, v81, 13, v4
	v_add_u32_e32 v101, 0, v134
	v_add_u32_e32 v82, v101, v132
	ds_read_b128 a[8:11], v82
	ds_read_b128 a[12:15], v82 offset:4096
	v_lshrrev_b32_e32 v182, 6, v133
	s_nop 0
	v_readfirstlane_b32 s32, v182
	s_waitcnt lgkmcnt(1)
	v_mfma_f32_32x32x16_bf16 v[48:63], a[0:3], a[8:11], 0
	v_bfe_u32 v103, v78, 1, 3
	s_mov_b64 s[30:31], 0x180
	s_nop 0
	v_or_b32_e32 v143, 0x8000, v102
	v_or_b32_e32 v144, 0x9000, v102
	v_add_u32_e32 v145, s3, v134
	v_lshl_or_b32 v81, v81, 6, v79
	s_waitcnt vmcnt(12)
	v_mfma_f32_32x32x16_bf16 v[32:47], a[4:7], a[8:11], 0
	v_mul_lo_u32 v81, v81, s26
	s_mov_b64 s[80:81], 0x200
	s_waitcnt lgkmcnt(0)
	v_mfma_f32_32x32x16_bf16 v[16:31], a[0:3], a[12:15], 0
	v_bitop3_b32 v0, v64, v103, 2 bitop3:0x36
	v_lshlrev_b32_e32 v138, 4, v0
	v_add_u32_e32 v84, v101, v138
	ds_read_b128 a[28:31], v84 offset:4096
	s_nop 0
	s_nop 0
	ds_read_b128 a[24:27], v84
	s_nop 0
	v_add_u32_e32 v85, v100, v138
	ds_read_b128 a[20:23], v85 offset:36864
	s_nop 0
	s_nop 0
	ds_read_b128 a[16:19], v85 offset:32768
	s_nop 0
	s_nop 0
	s_nop 0
	s_nop 0
	s_nop 0
	s_nop 0
	v_mfma_f32_32x32x16_bf16 v[0:15], a[4:7], a[12:15], 0
	s_nop 0
	s_waitcnt lgkmcnt(0)
	v_mfma_f32_32x32x16_bf16 v[48:63], a[16:19], a[24:27], v[48:63]
	v_mfma_f32_32x32x16_bf16 v[32:47], a[20:23], a[24:27], v[32:47]
	v_mfma_f32_32x32x16_bf16 v[16:31], a[16:19], a[28:31], v[16:31]
	v_bitop3_b32 v86, v64, v103, 4 bitop3:0x36
	v_lshlrev_b32_e32 v139, 4, v86
	v_add_u32_e32 v86, v101, v139
	ds_read_b128 a[12:15], v86 offset:4096
	s_nop 0
	s_nop 0
	ds_read_b128 a[8:11], v86
	s_nop 0
	v_add_u32_e32 v87, v100, v139
	ds_read_b128 a[4:7], v87 offset:36864
	s_nop 0
	s_nop 0
	ds_read_b128 a[0:3], v87 offset:32768
	s_nop 0
	s_nop 0
	s_nop 0
	v_mfma_f32_32x32x16_bf16 v[0:15], a[20:23], a[28:31], v[0:15]
	s_nop 0
	s_nop 0
	s_nop 0
	s_nop 0
	s_waitcnt lgkmcnt(0)
	v_mfma_f32_32x32x16_bf16 v[48:63], a[0:3], a[8:11], v[48:63]
	v_mfma_f32_32x32x16_bf16 v[32:47], a[4:7], a[8:11], v[32:47]
	v_mfma_f32_32x32x16_bf16 v[16:31], a[0:3], a[12:15], v[16:31]
	v_bitop3_b32 v88, v64, v103, 6 bitop3:0x36
	v_lshlrev_b32_e32 v142, 4, v88
	v_add_u32_e32 v88, v101, v142
	ds_read_b128 a[28:31], v88 offset:4096
	s_nop 0
	s_nop 0
	ds_read_b128 a[24:27], v88
	s_nop 0
	v_add_u32_e32 v89, v100, v142
	ds_read_b128 a[20:23], v89 offset:36864
	s_nop 0
	s_nop 0
	ds_read_b128 a[16:19], v89 offset:32768
	s_nop 0
	s_nop 0
	s_nop 0
	v_lshlrev_b32_e32 v64, 4, v64
	v_lshl_or_b32 v64, v80, 8, v64
	v_add3_u32 v64, 0, v81, v64
	v_mfma_f32_32x32x16_bf16 v[0:15], a[4:7], a[12:15], v[0:15]
	s_nop 0
	s_nop 0
	s_nop 0
	s_nop 0
	s_waitcnt lgkmcnt(0)
	v_mfma_f32_32x32x16_bf16 v[48:63], a[16:19], a[24:27], v[48:63]
	v_mfma_f32_32x32x16_bf16 v[32:47], a[20:23], a[24:27], v[32:47]
	s_waitcnt vmcnt(6)
	s_waitcnt lgkmcnt(0)
	s_barrier
	ds_read_b128 a[12:15], v82 offset:53248
	ds_read_b128 a[8:11], v82 offset:49152
	v_mfma_f32_32x32x16_bf16 v[16:31], a[16:19], a[28:31], v[16:31]
	v_lshl_add_u64 v[158:159], v[66:67], 0, s[30:31]
	s_nop 0
	v_lshl_add_u64 v[160:161], v[68:69], 0, s[30:31]
	s_nop 0
	s_nop 0
	s_nop 0
	v_lshl_add_u64 v[162:163], v[70:71], 0, s[30:31]
	s_nop 0
	v_mfma_f32_32x32x16_bf16 v[0:15], a[20:23], a[28:31], v[0:15]
	s_and_b32 m0, s32, 7
	s_lshl_b32 m0, m0, 12
	s_add_i32 m0, m0, 0x0
	s_nop 0
	global_load_lds_dwordx4 v[158:159], off
	s_nop 0
	v_lshl_add_u64 v[164:165], v[72:73], 0, s[30:31]
	s_nop 0
	s_nop 0
	s_nop 0
	v_lshl_add_u64 v[166:167], v[74:75], 0, s[30:31]
	s_nop 0
	s_nop 0
	s_nop 0
	v_lshl_add_u64 v[168:169], v[76:77], 0, s[30:31]
	s_nop 0
	s_add_i32 s30, 0, 0xc000
	v_add_u32_e32 v90, s30, v132
	v_add_u32_e32 v92, v90, v143
	v_add_u32_e32 v90, v90, v144
	ds_read_b128 a[4:7], v90
	ds_read_b128 a[0:3], v92
	s_nop 0
	s_nop 0
	s_nop 0
	s_nop 0
	s_nop 0
	s_nop 0
	s_nop 0
	s_nop 0
	v_add_u32_e32 v91, s30, v138
	v_add_u32_e32 v93, v91, v143
	ds_read_b128 a[16:19], v93
	v_add_u32_e32 v91, v91, v144
	ds_read_b128 a[20:23], v91
	ds_read_b128 a[24:27], v84 offset:49152
	ds_read_b128 a[28:31], v84 offset:53248
	s_waitcnt lgkmcnt(4)
	v_mfma_f32_32x32x16_bf16 v[48:63], a[0:3], a[8:11], v[48:63]
	s_nop 0
	s_nop 0
	s_nop 0
	s_nop 0
	v_mfma_f32_32x32x16_bf16 v[32:47], a[4:7], a[8:11], v[32:47]
	v_mfma_f32_32x32x16_bf16 v[16:31], a[0:3], a[12:15], v[16:31]
	s_and_b32 m0, s32, 7
	s_lshl_b32 m0, m0, 12
	s_add_i32 m0, m0, 0x400
	s_nop 0
	global_load_lds_dwordx4 v[160:161], off
	v_mfma_f32_32x32x16_bf16 v[0:15], a[4:7], a[12:15], v[0:15]
	s_nop 0
	s_nop 0
	s_nop 0
	s_nop 0
	v_add_u32_e32 v94, s30, v139
	v_add_u32_e32 v95, v94, v143
	ds_read_b128 a[0:3], v95
	v_add_u32_e32 v94, v94, v144
	ds_read_b128 a[4:7], v94
	ds_read_b128 a[8:11], v86 offset:49152
	ds_read_b128 a[12:15], v86 offset:53248
	s_waitcnt lgkmcnt(5)
	v_mfma_f32_32x32x16_bf16 v[48:63], a[16:19], a[24:27], v[48:63]
	v_mfma_f32_32x32x16_bf16 v[32:47], a[20:23], a[24:27], v[32:47]
	s_and_b32 m0, s32, 7
	s_lshl_b32 m0, m0, 12
	s_add_i32 m0, m0, 0x800
	s_nop 0
	global_load_lds_dwordx4 v[162:163], off
	s_waitcnt lgkmcnt(4)
	v_mfma_f32_32x32x16_bf16 v[16:31], a[16:19], a[28:31], v[16:31]
	s_nop 0
	s_nop 0
	s_nop 0
	v_mfma_f32_32x32x16_bf16 v[0:15], a[20:23], a[28:31], v[0:15]
	s_nop 0
	s_nop 0
	s_nop 0
	s_nop 0
	v_add_u32_e32 v96, s30, v142
	v_add_u32_e32 v97, v96, v143
	ds_read_b128 a[16:19], v97
	v_add_u32_e32 v96, v96, v144
	ds_read_b128 a[20:23], v96
	ds_read_b128 a[24:27], v88 offset:49152
	ds_read_b128 a[28:31], v88 offset:53248
	s_waitcnt lgkmcnt(5)
	v_mfma_f32_32x32x16_bf16 v[48:63], a[0:3], a[8:11], v[48:63]
	s_and_b32 m0, s32, 7
	s_lshl_b32 m0, m0, 12
	s_add_i32 m0, m0, 0xc00
	s_nop 0
	global_load_lds_dwordx4 v[164:165], off
	v_mfma_f32_32x32x16_bf16 v[32:47], a[4:7], a[8:11], v[32:47]
	s_waitcnt lgkmcnt(4)
	v_mfma_f32_32x32x16_bf16 v[16:31], a[0:3], a[12:15], v[16:31]
	s_nop 0
	s_nop 0
	s_nop 0
	s_mov_b64 s[30:31], 0x200
	v_mfma_f32_32x32x16_bf16 v[0:15], a[4:7], a[12:15], v[0:15]
	s_and_b32 m0, s32, 7
	s_lshl_b32 m0, m0, 11
	s_add_i32 m0, m0, 0x8000
	s_nop 0
	global_load_lds_dwordx4 v[166:167], off
	s_nop 0
	s_nop 0
	s_nop 0
	s_nop 0
	s_waitcnt lgkmcnt(1)
	v_mfma_f32_32x32x16_bf16 v[48:63], a[16:19], a[24:27], v[48:63]
	v_mfma_f32_32x32x16_bf16 v[32:47], a[20:23], a[24:27], v[32:47]
	s_and_b32 m0, s32, 7
	s_lshl_b32 m0, m0, 11
	s_add_i32 m0, m0, 0x8400
	s_nop 0
	global_load_lds_dwordx4 v[168:169], off
	s_waitcnt vmcnt(6)
	s_waitcnt lgkmcnt(0)
	s_barrier
	v_add_u32_e32 v100, v145, v132
	ds_read_b128 a[8:11], v100
	v_add_u32_e32 v101, s3, v132
	v_add_u32_e32 v99, v101, v144
	ds_read_b128 a[4:7], v99
	s_nop 0
	v_add_u32_e32 v98, v101, v143
	v_or_b32_e32 v132, 0x1000, v134
	v_add_u32_e32 v101, v101, v132
	ds_read_b128 a[12:15], v101
	ds_read_b128 a[0:3], v98
	v_mfma_f32_32x32x16_bf16 v[16:31], a[16:19], a[28:31], v[16:31]
	v_lshl_add_u64 v[170:171], v[66:67], 0, s[30:31]
	s_nop 0
	v_lshl_add_u64 v[172:173], v[68:69], 0, s[30:31]
	s_nop 0
	s_nop 0
	s_nop 0
	v_lshl_add_u64 v[174:175], v[70:71], 0, s[30:31]
	s_nop 0
	v_mfma_f32_32x32x16_bf16 v[0:15], a[20:23], a[28:31], v[0:15]
	s_and_b32 m0, s32, 7
	s_lshl_b32 m0, m0, 12
	s_add_i32 m0, m0, 0xc000
	s_nop 0
	global_load_lds_dwordx4 v[170:171], off
	s_nop 0
	v_lshl_add_u64 v[176:177], v[72:73], 0, s[30:31]
	s_nop 0
	s_nop 0
	s_nop 0
	v_lshl_add_u64 v[178:179], v[74:75], 0, s[30:31]
	s_nop 0
	s_nop 0
	s_nop 0
	v_lshl_add_u64 v[180:181], v[76:77], 0, s[30:31]
	s_nop 0
	s_mov_b64 s[30:31], 0x280
	s_nop 0
	s_nop 0
	s_nop 0
	s_nop 0
	s_nop 0
	s_nop 0
	s_nop 0
	s_nop 0
	v_add_u32_e32 v105, s3, v138
	v_add_u32_e32 v102, v105, v143
	ds_read_b128 a[16:19], v102
	v_add_u32_e32 v103, v105, v144
	ds_read_b128 a[20:23], v103
	v_add_u32_e32 v104, v145, v138
	ds_read_b128 a[24:27], v104
	v_add_u32_e32 v105, v105, v132
	ds_read_b128 a[28:31], v105
	s_waitcnt lgkmcnt(4)
	v_mfma_f32_32x32x16_bf16 v[48:63], a[0:3], a[8:11], v[48:63]
	s_nop 0
	v_mfma_f32_32x32x16_bf16 v[32:47], a[4:7], a[8:11], v[32:47]
	s_nop 0
	s_nop 0
	s_nop 0
	s_nop 0
	s_nop 0
	v_mfma_f32_32x32x16_bf16 v[16:31], a[0:3], a[12:15], v[16:31]
	s_and_b32 m0, s32, 7
	s_lshl_b32 m0, m0, 12
	s_add_i32 m0, m0, 0xc400
	s_nop 0
	global_load_lds_dwordx4 v[172:173], off
	s_nop 0
	v_mfma_f32_32x32x16_bf16 v[0:15], a[4:7], a[12:15], v[0:15]
	s_nop 0
	s_nop 0
	s_nop 0
	v_add_u32_e32 v109, s3, v139
	v_add_u32_e32 v106, v109, v143
	ds_read_b128 a[0:3], v106
	v_add_u32_e32 v107, v109, v144
	ds_read_b128 a[4:7], v107
	v_add_u32_e32 v108, v145, v139
	ds_read_b128 a[8:11], v108
	v_add_u32_e32 v109, v109, v132
	ds_read_b128 a[12:15], v109
	s_waitcnt lgkmcnt(5)
	v_mfma_f32_32x32x16_bf16 v[48:63], a[16:19], a[24:27], v[48:63]
	v_mfma_f32_32x32x16_bf16 v[32:47], a[20:23], a[24:27], v[32:47]
	s_and_b32 m0, s32, 7
	s_lshl_b32 m0, m0, 12
	s_add_i32 m0, m0, 0xc800
	s_nop 0
	global_load_lds_dwordx4 v[174:175], off
	s_waitcnt lgkmcnt(4)
	v_mfma_f32_32x32x16_bf16 v[16:31], a[16:19], a[28:31], v[16:31]
	s_nop 0
	s_nop 0
	s_nop 0
	s_nop 0
	s_nop 0
	s_nop 0
	v_mfma_f32_32x32x16_bf16 v[0:15], a[20:23], a[28:31], v[0:15]
	s_nop 0
	s_nop 0
	s_nop 0
	v_add_u32_e32 v113, s3, v142
	v_add_u32_e32 v110, v113, v143
	ds_read_b128 a[16:19], v110
	v_add_u32_e32 v111, v113, v144
	ds_read_b128 a[20:23], v111
	v_add_u32_e32 v112, v145, v142
	ds_read_b128 a[24:27], v112
	v_add_u32_e32 v113, v113, v132
	ds_read_b128 a[28:31], v113
	s_waitcnt lgkmcnt(5)
	v_mfma_f32_32x32x16_bf16 v[48:63], a[0:3], a[8:11], v[48:63]
	s_and_b32 m0, s32, 7
	s_lshl_b32 m0, m0, 12
	s_add_i32 m0, m0, 0xcc00
	s_nop 0
	global_load_lds_dwordx4 v[176:177], off
	v_mfma_f32_32x32x16_bf16 v[32:47], a[4:7], a[8:11], v[32:47]
	s_waitcnt lgkmcnt(4)
	v_mfma_f32_32x32x16_bf16 v[16:31], a[0:3], a[12:15], v[16:31]
	s_nop 0
	s_nop 0
	s_nop 0
	s_nop 0
	s_nop 0
	s_nop 0
	v_mfma_f32_32x32x16_bf16 v[0:15], a[4:7], a[12:15], v[0:15]
	s_and_b32 m0, s32, 7
	s_lshl_b32 m0, m0, 11
	s_add_i32 m0, m0, 0x14000
	s_nop 0
	global_load_lds_dwordx4 v[178:179], off
	s_nop 0
	s_nop 0
	s_nop 0
	s_waitcnt lgkmcnt(1)
	v_mfma_f32_32x32x16_bf16 v[48:63], a[16:19], a[24:27], v[48:63]
	v_mfma_f32_32x32x16_bf16 v[32:47], a[20:23], a[24:27], v[32:47]
	s_and_b32 m0, s32, 7
	s_lshl_b32 m0, m0, 11
	s_add_i32 m0, m0, 0x14400
	s_nop 0
	global_load_lds_dwordx4 v[180:181], off
	s_waitcnt vmcnt(6)
	s_waitcnt lgkmcnt(0)
	s_barrier
	ds_read_b128 a[12:15], v82 offset:4096
	ds_read_b128 a[8:11], v82
	ds_read_b128 a[4:7], v83 offset:36864
	ds_read_b128 a[0:3], v83 offset:32768
	v_mfma_f32_32x32x16_bf16 v[16:31], a[16:19], a[28:31], v[16:31]
	v_lshl_add_u64 v[158:159], v[66:67], 0, s[30:31]
	s_nop 0
	v_lshl_add_u64 v[160:161], v[68:69], 0, s[30:31]
	s_nop 0
	s_nop 0
	s_nop 0
	v_lshl_add_u64 v[162:163], v[70:71], 0, s[30:31]
	s_nop 0
	v_mfma_f32_32x32x16_bf16 v[0:15], a[20:23], a[28:31], v[0:15]
	s_and_b32 m0, s32, 7
	s_lshl_b32 m0, m0, 12
	s_add_i32 m0, m0, 0x18000
	s_nop 0
	global_load_lds_dwordx4 v[158:159], off
	s_nop 0
	v_lshl_add_u64 v[164:165], v[72:73], 0, s[30:31]
	s_nop 0
	s_nop 0
	s_nop 0
	v_lshl_add_u64 v[166:167], v[74:75], 0, s[30:31]
	s_nop 0
	s_nop 0
	s_nop 0
	v_lshl_add_u64 v[168:169], v[76:77], 0, s[30:31]
	s_nop 0
	s_mov_b64 s[30:31], 0x300
	s_nop 0
	s_nop 0
	s_nop 0
	s_nop 0
	s_nop 0
	ds_read_b128 a[16:19], v85 offset:32768
	ds_read_b128 a[20:23], v85 offset:36864
	ds_read_b128 a[24:27], v84
	ds_read_b128 a[28:31], v84 offset:4096
	s_waitcnt lgkmcnt(4)
	v_mfma_f32_32x32x16_bf16 v[48:63], a[0:3], a[8:11], v[48:63]
	s_nop 0
	v_readfirstlane_b32 s38, v114
	v_mfma_f32_32x32x16_bf16 v[32:47], a[4:7], a[8:11], v[32:47]
	v_mfma_f32_32x32x16_bf16 v[16:31], a[0:3], a[12:15], v[16:31]
	s_and_b32 m0, s32, 7
	s_lshl_b32 m0, m0, 12
	s_add_i32 m0, m0, 0x18400
	s_nop 0
	global_load_lds_dwordx4 v[160:161], off
	v_mfma_f32_32x32x16_bf16 v[0:15], a[4:7], a[12:15], v[0:15]
	s_nop 0
	s_nop 0
	s_nop 0
	s_nop 0
	ds_read_b128 a[0:3], v87 offset:32768
	ds_read_b128 a[4:7], v87 offset:36864
	ds_read_b128 a[8:11], v86
	ds_read_b128 a[12:15], v86 offset:4096
	s_waitcnt lgkmcnt(5)
	v_mfma_f32_32x32x16_bf16 v[48:63], a[16:19], a[24:27], v[48:63]
	v_mfma_f32_32x32x16_bf16 v[32:47], a[20:23], a[24:27], v[32:47]
	s_and_b32 m0, s32, 7
	s_lshl_b32 m0, m0, 12
	s_add_i32 m0, m0, 0x18800
	s_nop 0
	global_load_lds_dwordx4 v[162:163], off
	s_waitcnt lgkmcnt(4)
	v_mfma_f32_32x32x16_bf16 v[16:31], a[16:19], a[28:31], v[16:31]
	v_mfma_f32_32x32x16_bf16 v[0:15], a[20:23], a[28:31], v[0:15]
	s_nop 0
	s_nop 0
	s_nop 0
	s_nop 0
	ds_read_b128 a[16:19], v89 offset:32768
	ds_read_b128 a[20:23], v89 offset:36864
	ds_read_b128 a[24:27], v88
	ds_read_b128 a[28:31], v88 offset:4096
	s_waitcnt lgkmcnt(5)
	v_mfma_f32_32x32x16_bf16 v[48:63], a[0:3], a[8:11], v[48:63]
	s_and_b32 m0, s32, 7
	s_lshl_b32 m0, m0, 12
	s_add_i32 m0, m0, 0x18c00
	s_nop 0
	global_load_lds_dwordx4 v[164:165], off
	v_mfma_f32_32x32x16_bf16 v[32:47], a[4:7], a[8:11], v[32:47]
	s_waitcnt lgkmcnt(4)
	v_mfma_f32_32x32x16_bf16 v[16:31], a[0:3], a[12:15], v[16:31]
	v_mfma_f32_32x32x16_bf16 v[0:15], a[4:7], a[12:15], v[0:15]
	s_and_b32 m0, s32, 7
	s_lshl_b32 m0, m0, 11
	s_add_i32 m0, m0, 0x20000
	s_nop 0
	global_load_lds_dwordx4 v[166:167], off
	s_nop 0
	s_nop 0
	s_nop 0
	s_nop 0
	s_waitcnt lgkmcnt(1)
	v_mfma_f32_32x32x16_bf16 v[48:63], a[16:19], a[24:27], v[48:63]
	v_mfma_f32_32x32x16_bf16 v[32:47], a[20:23], a[24:27], v[32:47]
	s_and_b32 m0, s32, 7
	s_lshl_b32 m0, m0, 11
	s_add_i32 m0, m0, 0x20400
	s_nop 0
	global_load_lds_dwordx4 v[168:169], off
	s_waitcnt vmcnt(6)
	s_waitcnt lgkmcnt(0)
	s_barrier
	ds_read_b128 a[12:15], v82 offset:53248
	ds_read_b128 a[8:11], v82 offset:49152
	ds_read_b128 a[4:7], v90
	ds_read_b128 a[0:3], v92
	v_mfma_f32_32x32x16_bf16 v[16:31], a[16:19], a[28:31], v[16:31]
	v_lshl_add_u64 v[170:171], v[66:67], 0, s[30:31]
	s_nop 0
	v_lshl_add_u64 v[172:173], v[68:69], 0, s[30:31]
	s_nop 0
	v_readfirstlane_b32 s39, v115
	s_nop 0
	v_lshl_add_u64 v[174:175], v[70:71], 0, s[30:31]
	s_nop 0
	v_mfma_f32_32x32x16_bf16 v[0:15], a[20:23], a[28:31], v[0:15]
	s_and_b32 m0, s32, 7
	s_lshl_b32 m0, m0, 12
	s_add_i32 m0, m0, 0x0
	s_nop 0
	global_load_lds_dwordx4 v[170:171], off
	s_nop 0
	v_lshl_add_u64 v[176:177], v[72:73], 0, s[30:31]
	s_nop 0
	v_readfirstlane_b32 s48, v116
	s_nop 0
	v_lshl_add_u64 v[178:179], v[74:75], 0, s[30:31]
	s_nop 0
	v_readfirstlane_b32 s49, v117
	s_nop 0
	v_lshl_add_u64 v[180:181], v[76:77], 0, s[30:31]
	s_nop 0
	s_mov_b64 s[30:31], 0x380
	s_nop 0
	s_nop 0
	s_nop 0
	s_nop 0
	s_nop 0
	ds_read_b128 a[16:19], v93
	ds_read_b128 a[20:23], v91
	ds_read_b128 a[24:27], v84 offset:49152
	ds_read_b128 a[28:31], v84 offset:53248
	s_waitcnt lgkmcnt(4)
	v_mfma_f32_32x32x16_bf16 v[48:63], a[0:3], a[8:11], v[48:63]
	s_nop 0
	v_readfirstlane_b32 s53, v118
	v_readfirstlane_b32 s54, v119
	v_mfma_f32_32x32x16_bf16 v[32:47], a[4:7], a[8:11], v[32:47]
	v_mfma_f32_32x32x16_bf16 v[16:31], a[0:3], a[12:15], v[16:31]
	s_and_b32 m0, s32, 7
	s_lshl_b32 m0, m0, 12
	s_add_i32 m0, m0, 0x400
	s_nop 0
	global_load_lds_dwordx4 v[172:173], off
	v_mfma_f32_32x32x16_bf16 v[0:15], a[4:7], a[12:15], v[0:15]
	s_nop 0
	s_nop 0
	s_nop 0
	s_nop 0
	ds_read_b128 a[0:3], v95
	ds_read_b128 a[4:7], v94
	ds_read_b128 a[8:11], v86 offset:49152
	ds_read_b128 a[12:15], v86 offset:53248
	s_waitcnt lgkmcnt(5)
	v_mfma_f32_32x32x16_bf16 v[48:63], a[16:19], a[24:27], v[48:63]
	v_mfma_f32_32x32x16_bf16 v[32:47], a[20:23], a[24:27], v[32:47]
	s_and_b32 m0, s32, 7
	s_lshl_b32 m0, m0, 12
	s_add_i32 m0, m0, 0x800
	s_nop 0
	global_load_lds_dwordx4 v[174:175], off
	s_waitcnt lgkmcnt(4)
	v_mfma_f32_32x32x16_bf16 v[16:31], a[16:19], a[28:31], v[16:31]
	v_mfma_f32_32x32x16_bf16 v[0:15], a[20:23], a[28:31], v[0:15]
	s_nop 0
	s_nop 0
	s_nop 0
	s_nop 0
	ds_read_b128 a[16:19], v97
	ds_read_b128 a[20:23], v96
	ds_read_b128 a[24:27], v88 offset:49152
	ds_read_b128 a[28:31], v88 offset:53248
	s_waitcnt lgkmcnt(5)
	v_mfma_f32_32x32x16_bf16 v[48:63], a[0:3], a[8:11], v[48:63]
	s_and_b32 m0, s32, 7
	s_lshl_b32 m0, m0, 12
	s_add_i32 m0, m0, 0xc00
	s_nop 0
	global_load_lds_dwordx4 v[176:177], off
	v_mfma_f32_32x32x16_bf16 v[32:47], a[4:7], a[8:11], v[32:47]
	s_waitcnt lgkmcnt(4)
	v_mfma_f32_32x32x16_bf16 v[16:31], a[0:3], a[12:15], v[16:31]
	v_mfma_f32_32x32x16_bf16 v[0:15], a[4:7], a[12:15], v[0:15]
	s_and_b32 m0, s32, 7
	s_lshl_b32 m0, m0, 11
	s_add_i32 m0, m0, 0x8000
	s_nop 0
	global_load_lds_dwordx4 v[178:179], off
	s_nop 0
	s_nop 0
	s_nop 0
	s_nop 0
	s_waitcnt lgkmcnt(1)
	v_mfma_f32_32x32x16_bf16 v[48:63], a[16:19], a[24:27], v[48:63]
	v_mfma_f32_32x32x16_bf16 v[32:47], a[20:23], a[24:27], v[32:47]
	s_and_b32 m0, s32, 7
	s_lshl_b32 m0, m0, 11
	s_add_i32 m0, m0, 0x8400
	s_nop 0
	global_load_lds_dwordx4 v[180:181], off
	s_waitcnt vmcnt(6)
	s_waitcnt lgkmcnt(0)
	s_barrier
	ds_read_b128 a[12:15], v101
	ds_read_b128 a[8:11], v100
	ds_read_b128 a[4:7], v99
	ds_read_b128 a[0:3], v98
	v_mfma_f32_32x32x16_bf16 v[16:31], a[16:19], a[28:31], v[16:31]
	v_lshl_add_u64 v[158:159], v[66:67], 0, s[30:31]
	s_nop 0
	v_lshl_add_u64 v[160:161], v[68:69], 0, s[30:31]
	s_nop 0
	v_readfirstlane_b32 s33, v121
	s_nop 0
	v_lshl_add_u64 v[162:163], v[70:71], 0, s[30:31]
	s_nop 0
	v_mfma_f32_32x32x16_bf16 v[0:15], a[20:23], a[28:31], v[0:15]
	s_and_b32 m0, s32, 7
	s_lshl_b32 m0, m0, 12
	s_add_i32 m0, m0, 0xc000
	s_nop 0
	global_load_lds_dwordx4 v[158:159], off
	s_nop 0
	v_lshl_add_u64 v[164:165], v[72:73], 0, s[30:31]
	s_nop 0
	v_readfirstlane_b32 s34, v122
	s_nop 0
	v_lshl_add_u64 v[166:167], v[74:75], 0, s[30:31]
	s_nop 0
	v_readfirstlane_b32 s35, v123
	s_nop 0
	v_lshl_add_u64 v[168:169], v[76:77], 0, s[30:31]
	s_nop 0
	s_mov_b64 s[30:31], 0x400
	s_nop 0
	s_nop 0
	s_nop 0
	s_nop 0
	s_nop 0
	ds_read_b128 a[16:19], v102
	ds_read_b128 a[20:23], v103
	ds_read_b128 a[24:27], v104
	ds_read_b128 a[28:31], v105
	s_waitcnt lgkmcnt(4)
	v_mfma_f32_32x32x16_bf16 v[48:63], a[0:3], a[8:11], v[48:63]
	s_nop 0
	v_readfirstlane_b32 s1, v126
	v_readfirstlane_b32 s36, v124
	v_readfirstlane_b32 s37, v125
	v_mfma_f32_32x32x16_bf16 v[32:47], a[4:7], a[8:11], v[32:47]
	v_mfma_f32_32x32x16_bf16 v[16:31], a[0:3], a[12:15], v[16:31]
	s_and_b32 m0, s32, 7
	s_lshl_b32 m0, m0, 12
	s_add_i32 m0, m0, 0xc400
	s_nop 0
	global_load_lds_dwordx4 v[160:161], off
	v_mfma_f32_32x32x16_bf16 v[0:15], a[4:7], a[12:15], v[0:15]
	s_nop 0
	s_nop 0
	s_nop 0
	s_nop 0
	ds_read_b128 a[0:3], v106
	ds_read_b128 a[4:7], v107
	ds_read_b128 a[8:11], v108
	ds_read_b128 a[12:15], v109
	s_waitcnt lgkmcnt(5)
	v_mfma_f32_32x32x16_bf16 v[48:63], a[16:19], a[24:27], v[48:63]
	v_mfma_f32_32x32x16_bf16 v[32:47], a[20:23], a[24:27], v[32:47]
	s_and_b32 m0, s32, 7
	s_lshl_b32 m0, m0, 12
	s_add_i32 m0, m0, 0xc800
	s_nop 0
	global_load_lds_dwordx4 v[162:163], off
	s_waitcnt lgkmcnt(4)
	v_mfma_f32_32x32x16_bf16 v[16:31], a[16:19], a[28:31], v[16:31]
	v_mfma_f32_32x32x16_bf16 v[0:15], a[20:23], a[28:31], v[0:15]
	s_nop 0
	s_nop 0
	s_nop 0
	s_nop 0
	ds_read_b128 a[16:19], v110
	ds_read_b128 a[20:23], v111
	ds_read_b128 a[24:27], v112
	ds_read_b128 a[28:31], v113
	s_waitcnt lgkmcnt(5)
	v_mfma_f32_32x32x16_bf16 v[48:63], a[0:3], a[8:11], v[48:63]
	s_and_b32 m0, s32, 7
	s_lshl_b32 m0, m0, 12
	s_add_i32 m0, m0, 0xcc00
	s_nop 0
	global_load_lds_dwordx4 v[164:165], off
	v_mfma_f32_32x32x16_bf16 v[32:47], a[4:7], a[8:11], v[32:47]
	s_waitcnt lgkmcnt(4)
	v_mfma_f32_32x32x16_bf16 v[16:31], a[0:3], a[12:15], v[16:31]
	v_mfma_f32_32x32x16_bf16 v[0:15], a[4:7], a[12:15], v[0:15]
	s_and_b32 m0, s32, 7
	s_lshl_b32 m0, m0, 11
	s_add_i32 m0, m0, 0x14000
	s_nop 0
	global_load_lds_dwordx4 v[166:167], off
	s_nop 0
	s_nop 0
	s_nop 0
	s_nop 0
	s_waitcnt lgkmcnt(1)
	v_mfma_f32_32x32x16_bf16 v[48:63], a[16:19], a[24:27], v[48:63]
	v_mfma_f32_32x32x16_bf16 v[32:47], a[20:23], a[24:27], v[32:47]
	s_and_b32 m0, s32, 7
	s_lshl_b32 m0, m0, 11
	s_add_i32 m0, m0, 0x14400
	s_nop 0
	global_load_lds_dwordx4 v[168:169], off
	s_waitcnt vmcnt(6)
	s_waitcnt lgkmcnt(0)
	s_barrier
	ds_read_b128 a[12:15], v82 offset:4096
	ds_read_b128 a[8:11], v82
	ds_read_b128 a[4:7], v83 offset:36864
	ds_read_b128 a[0:3], v83 offset:32768
	v_mfma_f32_32x32x16_bf16 v[16:31], a[16:19], a[28:31], v[16:31]
	v_lshl_add_u64 v[170:171], v[66:67], 0, s[30:31]
	s_nop 0
	v_lshl_add_u64 v[172:173], v[68:69], 0, s[30:31]
	s_nop 0
	v_readfirstlane_b32 s20, v127
	s_nop 0
	v_lshl_add_u64 v[174:175], v[70:71], 0, s[30:31]
	s_nop 0
	v_mfma_f32_32x32x16_bf16 v[0:15], a[20:23], a[28:31], v[0:15]
	s_and_b32 m0, s32, 7
	s_lshl_b32 m0, m0, 12
	s_add_i32 m0, m0, 0x18000
	s_nop 0
	global_load_lds_dwordx4 v[170:171], off
	s_nop 0
	v_lshl_add_u64 v[176:177], v[72:73], 0, s[30:31]
	s_nop 0
	v_readfirstlane_b32 s21, v128
	s_nop 0
	v_lshl_add_u64 v[178:179], v[74:75], 0, s[30:31]
	s_nop 0
	v_readfirstlane_b32 s23, v129
	s_nop 0
	v_lshl_add_u64 v[180:181], v[76:77], 0, s[30:31]
	s_nop 0
	s_mov_b64 s[28:29], 0x480
	s_nop 0
	s_nop 0
	s_nop 0
	s_nop 0
	s_nop 0
	ds_read_b128 a[16:19], v85 offset:32768
	ds_read_b128 a[20:23], v85 offset:36864
	ds_read_b128 a[24:27], v84
	ds_read_b128 a[28:31], v84 offset:4096
	s_waitcnt lgkmcnt(4)
	v_mfma_f32_32x32x16_bf16 v[48:63], a[0:3], a[8:11], v[48:63]
	s_nop 0
	v_lshl_add_u64 v[162:163], v[70:71], 0, s[28:29]
	v_readfirstlane_b32 s24, v131
	s_mov_b64 s[30:31], 0x500
	v_mfma_f32_32x32x16_bf16 v[32:47], a[4:7], a[8:11], v[32:47]
	v_mfma_f32_32x32x16_bf16 v[16:31], a[0:3], a[12:15], v[16:31]
	s_and_b32 m0, s32, 7
	s_lshl_b32 m0, m0, 12
	s_add_i32 m0, m0, 0x18400
	s_nop 0
	global_load_lds_dwordx4 v[172:173], off
	v_mfma_f32_32x32x16_bf16 v[0:15], a[4:7], a[12:15], v[0:15]
	s_nop 0
	s_nop 0
	s_nop 0
	s_nop 0
	ds_read_b128 a[0:3], v87 offset:32768
	ds_read_b128 a[4:7], v87 offset:36864
	ds_read_b128 a[8:11], v86
	ds_read_b128 a[12:15], v86 offset:4096
	s_waitcnt lgkmcnt(5)
	v_mfma_f32_32x32x16_bf16 v[48:63], a[16:19], a[24:27], v[48:63]
	v_mfma_f32_32x32x16_bf16 v[32:47], a[20:23], a[24:27], v[32:47]
	s_and_b32 m0, s32, 7
	s_lshl_b32 m0, m0, 12
	s_add_i32 m0, m0, 0x18800
	s_nop 0
	global_load_lds_dwordx4 v[174:175], off
	s_waitcnt lgkmcnt(4)
	v_mfma_f32_32x32x16_bf16 v[16:31], a[16:19], a[28:31], v[16:31]
	v_mfma_f32_32x32x16_bf16 v[0:15], a[20:23], a[28:31], v[0:15]
	s_nop 0
	s_nop 0
	s_nop 0
	s_nop 0
	ds_read_b128 a[16:19], v89 offset:32768
	ds_read_b128 a[20:23], v89 offset:36864
	ds_read_b128 a[24:27], v88
	ds_read_b128 a[28:31], v88 offset:4096
	s_waitcnt lgkmcnt(5)
	v_mfma_f32_32x32x16_bf16 v[48:63], a[0:3], a[8:11], v[48:63]
	s_and_b32 m0, s32, 7
	s_lshl_b32 m0, m0, 12
	s_add_i32 m0, m0, 0x18c00
	s_nop 0
	global_load_lds_dwordx4 v[176:177], off
	v_mfma_f32_32x32x16_bf16 v[32:47], a[4:7], a[8:11], v[32:47]
	s_waitcnt lgkmcnt(4)
	v_mfma_f32_32x32x16_bf16 v[16:31], a[0:3], a[12:15], v[16:31]
	v_mfma_f32_32x32x16_bf16 v[0:15], a[4:7], a[12:15], v[0:15]
	s_and_b32 m0, s32, 7
	s_lshl_b32 m0, m0, 11
	s_add_i32 m0, m0, 0x20000
	s_nop 0
	global_load_lds_dwordx4 v[178:179], off
	s_nop 0
	s_nop 0
	s_nop 0
	s_nop 0
	s_waitcnt lgkmcnt(1)
	v_mfma_f32_32x32x16_bf16 v[48:63], a[16:19], a[24:27], v[48:63]
	v_mfma_f32_32x32x16_bf16 v[32:47], a[20:23], a[24:27], v[32:47]
	s_and_b32 m0, s32, 7
	s_lshl_b32 m0, m0, 11
	s_add_i32 m0, m0, 0x20400
	s_nop 0
	global_load_lds_dwordx4 v[180:181], off
	s_waitcnt vmcnt(6)
	s_waitcnt lgkmcnt(0)
	s_barrier
	ds_read_b128 a[12:15], v82 offset:53248
	ds_read_b128 a[8:11], v82 offset:49152
	ds_read_b128 a[4:7], v90
	ds_read_b128 a[0:3], v92
	v_mfma_f32_32x32x16_bf16 v[16:31], a[16:19], a[28:31], v[16:31]
	v_lshl_add_u64 v[158:159], v[66:67], 0, s[28:29]
	s_nop 0
	v_lshl_add_u64 v[160:161], v[68:69], 0, s[28:29]
	s_nop 0
	s_nop 0
	s_nop 0
	s_nop 0
	v_mfma_f32_32x32x16_bf16 v[0:15], a[20:23], a[28:31], v[0:15]
	s_and_b32 m0, s32, 7
	s_lshl_b32 m0, m0, 12
	s_add_i32 m0, m0, 0x0
	s_nop 0
	global_load_lds_dwordx4 v[158:159], off
	s_nop 0
	v_lshl_add_u64 v[164:165], v[72:73], 0, s[28:29]
	s_nop 0
	s_nop 0
	s_nop 0
	v_lshl_add_u64 v[166:167], v[74:75], 0, s[28:29]
	s_nop 0
	s_nop 0
	s_nop 0
	v_lshl_add_u64 v[168:169], v[76:77], 0, s[28:29]
	v_readfirstlane_b32 s28, v130
	s_nop 0
	v_readfirstlane_b32 s29, v120
	s_nop 0
	s_nop 0
	s_nop 0
	s_nop 0
	s_nop 0
	ds_read_b128 a[16:19], v93
	ds_read_b128 a[20:23], v91
	ds_read_b128 a[24:27], v84 offset:49152
	ds_read_b128 a[28:31], v84 offset:53248
	s_waitcnt lgkmcnt(4)
	v_mfma_f32_32x32x16_bf16 v[48:63], a[0:3], a[8:11], v[48:63]
	s_nop 0
	v_lshl_add_u64 v[174:175], v[70:71], 0, s[30:31]
	v_mfma_f32_32x32x16_bf16 v[32:47], a[4:7], a[8:11], v[32:47]
	v_mfma_f32_32x32x16_bf16 v[16:31], a[0:3], a[12:15], v[16:31]
	s_and_b32 m0, s32, 7
	s_lshl_b32 m0, m0, 12
	s_add_i32 m0, m0, 0x400
	s_nop 0
	global_load_lds_dwordx4 v[160:161], off
	v_mfma_f32_32x32x16_bf16 v[0:15], a[4:7], a[12:15], v[0:15]
	s_nop 0
	s_nop 0
	s_nop 0
	s_nop 0
	ds_read_b128 a[0:3], v95
	ds_read_b128 a[4:7], v94
	ds_read_b128 a[8:11], v86 offset:49152
	ds_read_b128 a[12:15], v86 offset:53248
	s_waitcnt lgkmcnt(5)
	v_mfma_f32_32x32x16_bf16 v[48:63], a[16:19], a[24:27], v[48:63]
	v_mfma_f32_32x32x16_bf16 v[32:47], a[20:23], a[24:27], v[32:47]
	s_and_b32 m0, s32, 7
	s_lshl_b32 m0, m0, 12
	s_add_i32 m0, m0, 0x800
	s_nop 0
	global_load_lds_dwordx4 v[162:163], off
	s_waitcnt lgkmcnt(4)
	v_mfma_f32_32x32x16_bf16 v[16:31], a[16:19], a[28:31], v[16:31]
	v_mfma_f32_32x32x16_bf16 v[0:15], a[20:23], a[28:31], v[0:15]
	s_nop 0
	s_nop 0
	s_nop 0
	s_nop 0
	ds_read_b128 a[16:19], v97
	ds_read_b128 a[20:23], v96
	ds_read_b128 a[24:27], v88 offset:49152
	ds_read_b128 a[28:31], v88 offset:53248
	s_waitcnt lgkmcnt(5)
	v_mfma_f32_32x32x16_bf16 v[48:63], a[0:3], a[8:11], v[48:63]
	s_and_b32 m0, s32, 7
	s_lshl_b32 m0, m0, 12
	s_add_i32 m0, m0, 0xc00
	s_nop 0
	global_load_lds_dwordx4 v[164:165], off
	v_mfma_f32_32x32x16_bf16 v[32:47], a[4:7], a[8:11], v[32:47]
	s_waitcnt lgkmcnt(4)
	v_mfma_f32_32x32x16_bf16 v[16:31], a[0:3], a[12:15], v[16:31]
	v_mfma_f32_32x32x16_bf16 v[0:15], a[4:7], a[12:15], v[0:15]
	s_and_b32 m0, s32, 7
	s_lshl_b32 m0, m0, 11
	s_add_i32 m0, m0, 0x8000
	s_nop 0
	global_load_lds_dwordx4 v[166:167], off
	s_nop 0
	s_nop 0
	s_nop 0
	s_nop 0
	s_waitcnt lgkmcnt(1)
	v_mfma_f32_32x32x16_bf16 v[48:63], a[16:19], a[24:27], v[48:63]
	v_mfma_f32_32x32x16_bf16 v[32:47], a[20:23], a[24:27], v[32:47]
	s_and_b32 m0, s32, 7
	s_lshl_b32 m0, m0, 11
	s_add_i32 m0, m0, 0x8400
	s_nop 0
	global_load_lds_dwordx4 v[168:169], off
	s_waitcnt vmcnt(6)
	s_waitcnt lgkmcnt(0)
	s_barrier
	ds_read_b128 a[12:15], v101
	ds_read_b128 a[8:11], v100
	ds_read_b128 a[4:7], v99
	ds_read_b128 a[0:3], v98
	v_mfma_f32_32x32x16_bf16 v[16:31], a[16:19], a[28:31], v[16:31]
	v_lshl_add_u64 v[170:171], v[66:67], 0, s[30:31]
	s_nop 0
	v_lshl_add_u64 v[172:173], v[68:69], 0, s[30:31]
	s_nop 0
	s_nop 0
	s_nop 0
	s_nop 0
	v_mfma_f32_32x32x16_bf16 v[0:15], a[20:23], a[28:31], v[0:15]
	s_and_b32 m0, s32, 7
	s_lshl_b32 m0, m0, 12
	s_add_i32 m0, m0, 0xc000
	s_nop 0
	global_load_lds_dwordx4 v[170:171], off
	s_nop 0
	v_lshl_add_u64 v[176:177], v[72:73], 0, s[30:31]
	s_nop 0
	s_nop 0
	s_nop 0
	v_lshl_add_u64 v[178:179], v[74:75], 0, s[30:31]
	s_nop 0
	s_nop 0
	s_nop 0
	v_lshl_add_u64 v[180:181], v[76:77], 0, s[30:31]
	s_nop 0
	s_mov_b64 s[30:31], 0x580
	s_nop 0
	s_nop 0
	s_nop 0
	s_nop 0
	s_nop 0
	ds_read_b128 a[16:19], v102
	ds_read_b128 a[20:23], v103
	ds_read_b128 a[24:27], v104
	ds_read_b128 a[28:31], v105
	s_waitcnt lgkmcnt(4)
	v_mfma_f32_32x32x16_bf16 v[48:63], a[0:3], a[8:11], v[48:63]
	s_nop 0
	v_lshl_add_u64 v[162:163], v[70:71], 0, s[30:31]
	v_mfma_f32_32x32x16_bf16 v[32:47], a[4:7], a[8:11], v[32:47]
	v_mfma_f32_32x32x16_bf16 v[16:31], a[0:3], a[12:15], v[16:31]
	s_and_b32 m0, s32, 7
	s_lshl_b32 m0, m0, 12
	s_add_i32 m0, m0, 0xc400
	s_nop 0
	global_load_lds_dwordx4 v[172:173], off
	v_mfma_f32_32x32x16_bf16 v[0:15], a[4:7], a[12:15], v[0:15]
	s_nop 0
	s_nop 0
	s_nop 0
	s_nop 0
	ds_read_b128 a[0:3], v106
	ds_read_b128 a[4:7], v107
	ds_read_b128 a[8:11], v108
	ds_read_b128 a[12:15], v109
	s_waitcnt lgkmcnt(5)
	v_mfma_f32_32x32x16_bf16 v[48:63], a[16:19], a[24:27], v[48:63]
	v_mfma_f32_32x32x16_bf16 v[32:47], a[20:23], a[24:27], v[32:47]
	s_and_b32 m0, s32, 7
	s_lshl_b32 m0, m0, 12
	s_add_i32 m0, m0, 0xc800
	s_nop 0
	global_load_lds_dwordx4 v[174:175], off
	s_waitcnt lgkmcnt(4)
	v_mfma_f32_32x32x16_bf16 v[16:31], a[16:19], a[28:31], v[16:31]
	v_mfma_f32_32x32x16_bf16 v[0:15], a[20:23], a[28:31], v[0:15]
	s_nop 0
	s_nop 0
	s_nop 0
	s_nop 0
	ds_read_b128 a[16:19], v110
	ds_read_b128 a[20:23], v111
	ds_read_b128 a[24:27], v112
	ds_read_b128 a[28:31], v113
	s_waitcnt lgkmcnt(5)
	v_mfma_f32_32x32x16_bf16 v[48:63], a[0:3], a[8:11], v[48:63]
	s_and_b32 m0, s32, 7
	s_lshl_b32 m0, m0, 12
	s_add_i32 m0, m0, 0xcc00
	s_nop 0
	global_load_lds_dwordx4 v[176:177], off
	v_mfma_f32_32x32x16_bf16 v[32:47], a[4:7], a[8:11], v[32:47]
	s_waitcnt lgkmcnt(4)
	v_mfma_f32_32x32x16_bf16 v[16:31], a[0:3], a[12:15], v[16:31]
	v_mfma_f32_32x32x16_bf16 v[0:15], a[4:7], a[12:15], v[0:15]
	s_and_b32 m0, s32, 7
	s_lshl_b32 m0, m0, 11
	s_add_i32 m0, m0, 0x14000
	s_nop 0
	global_load_lds_dwordx4 v[178:179], off
	s_nop 0
	s_nop 0
	s_nop 0
	s_nop 0
	s_waitcnt lgkmcnt(1)
	v_mfma_f32_32x32x16_bf16 v[48:63], a[16:19], a[24:27], v[48:63]
	v_mfma_f32_32x32x16_bf16 v[32:47], a[20:23], a[24:27], v[32:47]
	s_and_b32 m0, s32, 7
	s_lshl_b32 m0, m0, 11
	s_add_i32 m0, m0, 0x14400
	s_nop 0
	global_load_lds_dwordx4 v[180:181], off
	s_waitcnt vmcnt(6)
	s_waitcnt lgkmcnt(0)
	s_barrier
	ds_read_b128 a[12:15], v82 offset:4096
	ds_read_b128 a[8:11], v82
	ds_read_b128 a[4:7], v83 offset:36864
	ds_read_b128 a[0:3], v83 offset:32768
	v_mfma_f32_32x32x16_bf16 v[16:31], a[16:19], a[28:31], v[16:31]
	v_lshl_add_u64 v[158:159], v[66:67], 0, s[30:31]
	s_nop 0
	v_lshl_add_u64 v[160:161], v[68:69], 0, s[30:31]
	s_nop 0
	s_nop 0
	s_nop 0
	s_nop 0
	v_mfma_f32_32x32x16_bf16 v[0:15], a[20:23], a[28:31], v[0:15]
	s_and_b32 m0, s32, 7
	s_lshl_b32 m0, m0, 12
	s_add_i32 m0, m0, 0x18000
	s_nop 0
	global_load_lds_dwordx4 v[158:159], off
	s_nop 0
	v_lshl_add_u64 v[164:165], v[72:73], 0, s[30:31]
	s_nop 0
	s_nop 0
	s_nop 0
	v_lshl_add_u64 v[166:167], v[74:75], 0, s[30:31]
	s_nop 0
	s_nop 0
	s_nop 0
	v_lshl_add_u64 v[168:169], v[76:77], 0, s[30:31]
	s_nop 0
	s_mov_b64 s[30:31], 0x600
	s_nop 0
	s_nop 0
	s_nop 0
	s_nop 0
	s_nop 0
	ds_read_b128 a[16:19], v85 offset:32768
	ds_read_b128 a[20:23], v85 offset:36864
	ds_read_b128 a[24:27], v84
	ds_read_b128 a[28:31], v84 offset:4096
	s_waitcnt lgkmcnt(4)
	v_mfma_f32_32x32x16_bf16 v[48:63], a[0:3], a[8:11], v[48:63]
	s_nop 0
	v_mfma_f32_32x32x16_bf16 v[32:47], a[4:7], a[8:11], v[32:47]
	v_mfma_f32_32x32x16_bf16 v[16:31], a[0:3], a[12:15], v[16:31]
	s_and_b32 m0, s32, 7
	s_lshl_b32 m0, m0, 12
	s_add_i32 m0, m0, 0x18400
	s_nop 0
	global_load_lds_dwordx4 v[160:161], off
	v_mfma_f32_32x32x16_bf16 v[0:15], a[4:7], a[12:15], v[0:15]
	s_nop 0
	s_nop 0
	s_nop 0
	s_nop 0
	ds_read_b128 a[0:3], v87 offset:32768
	ds_read_b128 a[4:7], v87 offset:36864
	ds_read_b128 a[8:11], v86
	ds_read_b128 a[12:15], v86 offset:4096
	s_waitcnt lgkmcnt(5)
	v_mfma_f32_32x32x16_bf16 v[48:63], a[16:19], a[24:27], v[48:63]
	v_mfma_f32_32x32x16_bf16 v[32:47], a[20:23], a[24:27], v[32:47]
	s_and_b32 m0, s32, 7
	s_lshl_b32 m0, m0, 12
	s_add_i32 m0, m0, 0x18800
	s_nop 0
	global_load_lds_dwordx4 v[162:163], off
	s_waitcnt lgkmcnt(4)
	v_mfma_f32_32x32x16_bf16 v[16:31], a[16:19], a[28:31], v[16:31]
	v_mfma_f32_32x32x16_bf16 v[0:15], a[20:23], a[28:31], v[0:15]
	s_nop 0
	s_nop 0
	s_nop 0
	s_nop 0
	ds_read_b128 a[16:19], v89 offset:32768
	ds_read_b128 a[20:23], v89 offset:36864
	ds_read_b128 a[24:27], v88
	ds_read_b128 a[28:31], v88 offset:4096
	s_waitcnt lgkmcnt(5)
	v_mfma_f32_32x32x16_bf16 v[48:63], a[0:3], a[8:11], v[48:63]
	s_and_b32 m0, s32, 7
	s_lshl_b32 m0, m0, 12
	s_add_i32 m0, m0, 0x18c00
	s_nop 0
	global_load_lds_dwordx4 v[164:165], off
	v_mfma_f32_32x32x16_bf16 v[32:47], a[4:7], a[8:11], v[32:47]
	s_waitcnt lgkmcnt(4)
	v_mfma_f32_32x32x16_bf16 v[16:31], a[0:3], a[12:15], v[16:31]
	v_mfma_f32_32x32x16_bf16 v[0:15], a[4:7], a[12:15], v[0:15]
	s_and_b32 m0, s32, 7
	s_lshl_b32 m0, m0, 11
	s_add_i32 m0, m0, 0x20000
	s_nop 0
	global_load_lds_dwordx4 v[166:167], off
	s_nop 0
	s_nop 0
	s_nop 0
	s_nop 0
	s_waitcnt lgkmcnt(1)
	v_mfma_f32_32x32x16_bf16 v[48:63], a[16:19], a[24:27], v[48:63]
	v_mfma_f32_32x32x16_bf16 v[32:47], a[20:23], a[24:27], v[32:47]
	s_and_b32 m0, s32, 7
	s_lshl_b32 m0, m0, 11
	s_add_i32 m0, m0, 0x20400
	s_nop 0
	global_load_lds_dwordx4 v[168:169], off
	s_waitcnt vmcnt(6)
	s_waitcnt lgkmcnt(0)
	s_barrier
	ds_read_b128 a[12:15], v82 offset:53248
	ds_read_b128 a[8:11], v82 offset:49152
	ds_read_b128 a[4:7], v90
	ds_read_b128 a[0:3], v92
	v_mfma_f32_32x32x16_bf16 v[16:31], a[16:19], a[28:31], v[16:31]
	v_lshl_add_u64 v[170:171], v[66:67], 0, s[30:31]
	s_nop 0
	v_lshl_add_u64 v[172:173], v[68:69], 0, s[30:31]
	s_nop 0
	s_nop 0
	s_nop 0
	v_lshl_add_u64 v[174:175], v[70:71], 0, s[30:31]
	s_nop 0
	v_mfma_f32_32x32x16_bf16 v[0:15], a[20:23], a[28:31], v[0:15]
	s_and_b32 m0, s32, 7
	s_lshl_b32 m0, m0, 12
	s_add_i32 m0, m0, 0x0
	s_nop 0
	global_load_lds_dwordx4 v[170:171], off
	s_nop 0
	v_lshl_add_u64 v[176:177], v[72:73], 0, s[30:31]
	s_nop 0
	s_nop 0
	s_nop 0
	v_lshl_add_u64 v[178:179], v[74:75], 0, s[30:31]
	s_nop 0
	s_nop 0
	s_nop 0
	v_lshl_add_u64 v[180:181], v[76:77], 0, s[30:31]
	s_nop 0
	s_mov_b64 s[30:31], 0x680
	s_nop 0
	s_nop 0
	s_nop 0
	s_nop 0
	s_nop 0
	ds_read_b128 a[16:19], v93
	ds_read_b128 a[20:23], v91
	ds_read_b128 a[24:27], v84 offset:49152
	ds_read_b128 a[28:31], v84 offset:53248
	s_waitcnt lgkmcnt(4)
	v_mfma_f32_32x32x16_bf16 v[48:63], a[0:3], a[8:11], v[48:63]
	s_nop 0
	v_mfma_f32_32x32x16_bf16 v[32:47], a[4:7], a[8:11], v[32:47]
	v_mfma_f32_32x32x16_bf16 v[16:31], a[0:3], a[12:15], v[16:31]
	s_and_b32 m0, s32, 7
	s_lshl_b32 m0, m0, 12
	s_add_i32 m0, m0, 0x400
	s_nop 0
	global_load_lds_dwordx4 v[172:173], off
	v_mfma_f32_32x32x16_bf16 v[0:15], a[4:7], a[12:15], v[0:15]
	s_nop 0
	s_nop 0
	s_nop 0
	s_nop 0
	ds_read_b128 a[0:3], v95
	ds_read_b128 a[4:7], v94
	ds_read_b128 a[8:11], v86 offset:49152
	ds_read_b128 a[12:15], v86 offset:53248
	s_waitcnt lgkmcnt(5)
	v_mfma_f32_32x32x16_bf16 v[48:63], a[16:19], a[24:27], v[48:63]
	v_mfma_f32_32x32x16_bf16 v[32:47], a[20:23], a[24:27], v[32:47]
	s_and_b32 m0, s32, 7
	s_lshl_b32 m0, m0, 12
	s_add_i32 m0, m0, 0x800
	s_nop 0
	global_load_lds_dwordx4 v[174:175], off
	s_waitcnt lgkmcnt(4)
	v_mfma_f32_32x32x16_bf16 v[16:31], a[16:19], a[28:31], v[16:31]
	v_mfma_f32_32x32x16_bf16 v[0:15], a[20:23], a[28:31], v[0:15]
	s_nop 0
	s_nop 0
	s_nop 0
	s_nop 0
	ds_read_b128 a[16:19], v97
	ds_read_b128 a[20:23], v96
	ds_read_b128 a[24:27], v88 offset:49152
	ds_read_b128 a[28:31], v88 offset:53248
	s_waitcnt lgkmcnt(5)
	v_mfma_f32_32x32x16_bf16 v[48:63], a[0:3], a[8:11], v[48:63]
	s_and_b32 m0, s32, 7
	s_lshl_b32 m0, m0, 12
	s_add_i32 m0, m0, 0xc00
	s_nop 0
	global_load_lds_dwordx4 v[176:177], off
	v_mfma_f32_32x32x16_bf16 v[32:47], a[4:7], a[8:11], v[32:47]
	s_waitcnt lgkmcnt(4)
	v_mfma_f32_32x32x16_bf16 v[16:31], a[0:3], a[12:15], v[16:31]
	v_mfma_f32_32x32x16_bf16 v[0:15], a[4:7], a[12:15], v[0:15]
	s_and_b32 m0, s32, 7
	s_lshl_b32 m0, m0, 11
	s_add_i32 m0, m0, 0x8000
	s_nop 0
	global_load_lds_dwordx4 v[178:179], off
	s_nop 0
	s_nop 0
	s_nop 0
	s_nop 0
	s_waitcnt lgkmcnt(1)
	v_mfma_f32_32x32x16_bf16 v[48:63], a[16:19], a[24:27], v[48:63]
	v_mfma_f32_32x32x16_bf16 v[32:47], a[20:23], a[24:27], v[32:47]
	s_and_b32 m0, s32, 7
	s_lshl_b32 m0, m0, 11
	s_add_i32 m0, m0, 0x8400
	s_nop 0
	global_load_lds_dwordx4 v[180:181], off
	s_waitcnt vmcnt(6)
	s_waitcnt lgkmcnt(0)
	s_barrier
	ds_read_b128 a[12:15], v101
	ds_read_b128 a[8:11], v100
	ds_read_b128 a[4:7], v99
	ds_read_b128 a[0:3], v98
	v_mfma_f32_32x32x16_bf16 v[16:31], a[16:19], a[28:31], v[16:31]
	v_lshl_add_u64 v[158:159], v[66:67], 0, s[30:31]
	s_nop 0
	v_lshl_add_u64 v[160:161], v[68:69], 0, s[30:31]
	s_nop 0
	s_nop 0
	s_nop 0
	v_lshl_add_u64 v[162:163], v[70:71], 0, s[30:31]
	s_nop 0
	v_mfma_f32_32x32x16_bf16 v[0:15], a[20:23], a[28:31], v[0:15]
	s_and_b32 m0, s32, 7
	s_lshl_b32 m0, m0, 12
	s_add_i32 m0, m0, 0xc000
	s_nop 0
	global_load_lds_dwordx4 v[158:159], off
	s_nop 0
	v_lshl_add_u64 v[164:165], v[72:73], 0, s[30:31]
	s_nop 0
	s_nop 0
	s_nop 0
	v_lshl_add_u64 v[166:167], v[74:75], 0, s[30:31]
	s_nop 0
	s_nop 0
	s_nop 0
	v_lshl_add_u64 v[168:169], v[76:77], 0, s[30:31]
	s_nop 0
	s_mov_b64 s[30:31], 0x700
	s_nop 0
	s_nop 0
	s_nop 0
	s_nop 0
	s_nop 0
	ds_read_b128 a[16:19], v102
	ds_read_b128 a[20:23], v103
	ds_read_b128 a[24:27], v104
	ds_read_b128 a[28:31], v105
	s_waitcnt lgkmcnt(4)
	v_mfma_f32_32x32x16_bf16 v[48:63], a[0:3], a[8:11], v[48:63]
	s_nop 0
	v_mfma_f32_32x32x16_bf16 v[32:47], a[4:7], a[8:11], v[32:47]
	v_mfma_f32_32x32x16_bf16 v[16:31], a[0:3], a[12:15], v[16:31]
	s_and_b32 m0, s32, 7
	s_lshl_b32 m0, m0, 12
	s_add_i32 m0, m0, 0xc400
	s_nop 0
	global_load_lds_dwordx4 v[160:161], off
	v_mfma_f32_32x32x16_bf16 v[0:15], a[4:7], a[12:15], v[0:15]
	s_nop 0
	s_nop 0
	s_nop 0
	s_nop 0
	ds_read_b128 a[0:3], v106
	ds_read_b128 a[4:7], v107
	ds_read_b128 a[8:11], v108
	ds_read_b128 a[12:15], v109
	s_waitcnt lgkmcnt(5)
	v_mfma_f32_32x32x16_bf16 v[48:63], a[16:19], a[24:27], v[48:63]
	v_mfma_f32_32x32x16_bf16 v[32:47], a[20:23], a[24:27], v[32:47]
	s_and_b32 m0, s32, 7
	s_lshl_b32 m0, m0, 12
	s_add_i32 m0, m0, 0xc800
	s_nop 0
	global_load_lds_dwordx4 v[162:163], off
	s_waitcnt lgkmcnt(4)
	v_mfma_f32_32x32x16_bf16 v[16:31], a[16:19], a[28:31], v[16:31]
	v_mfma_f32_32x32x16_bf16 v[0:15], a[20:23], a[28:31], v[0:15]
	s_nop 0
	s_nop 0
	s_nop 0
	s_nop 0
	ds_read_b128 a[16:19], v110
	ds_read_b128 a[20:23], v111
	ds_read_b128 a[24:27], v112
	ds_read_b128 a[28:31], v113
	s_waitcnt lgkmcnt(5)
	v_mfma_f32_32x32x16_bf16 v[48:63], a[0:3], a[8:11], v[48:63]
	s_and_b32 m0, s32, 7
	s_lshl_b32 m0, m0, 12
	s_add_i32 m0, m0, 0xcc00
	s_nop 0
	global_load_lds_dwordx4 v[164:165], off
	v_mfma_f32_32x32x16_bf16 v[32:47], a[4:7], a[8:11], v[32:47]
	s_waitcnt lgkmcnt(4)
	v_mfma_f32_32x32x16_bf16 v[16:31], a[0:3], a[12:15], v[16:31]
	v_mfma_f32_32x32x16_bf16 v[0:15], a[4:7], a[12:15], v[0:15]
	s_and_b32 m0, s32, 7
	s_lshl_b32 m0, m0, 11
	s_add_i32 m0, m0, 0x14000
	s_nop 0
	global_load_lds_dwordx4 v[166:167], off
	s_nop 0
	s_nop 0
	s_nop 0
	s_nop 0
	s_waitcnt lgkmcnt(1)
	v_mfma_f32_32x32x16_bf16 v[48:63], a[16:19], a[24:27], v[48:63]
	v_mfma_f32_32x32x16_bf16 v[32:47], a[20:23], a[24:27], v[32:47]
	s_and_b32 m0, s32, 7
	s_lshl_b32 m0, m0, 11
	s_add_i32 m0, m0, 0x14400
	s_nop 0
	global_load_lds_dwordx4 v[168:169], off
	s_waitcnt vmcnt(6)
	s_waitcnt lgkmcnt(0)
	s_barrier
	ds_read_b128 a[12:15], v82 offset:4096
	ds_read_b128 a[8:11], v82
	ds_read_b128 a[4:7], v83 offset:36864
	ds_read_b128 a[0:3], v83 offset:32768
	v_mfma_f32_32x32x16_bf16 v[16:31], a[16:19], a[28:31], v[16:31]
	v_lshl_add_u64 v[170:171], v[66:67], 0, s[30:31]
	s_nop 0
	v_lshl_add_u64 v[172:173], v[68:69], 0, s[30:31]
	s_nop 0
	s_nop 0
	s_nop 0
	v_lshl_add_u64 v[174:175], v[70:71], 0, s[30:31]
	s_nop 0
	v_mfma_f32_32x32x16_bf16 v[0:15], a[20:23], a[28:31], v[0:15]
	s_and_b32 m0, s32, 7
	s_lshl_b32 m0, m0, 12
	s_add_i32 m0, m0, 0x18000
	s_nop 0
	global_load_lds_dwordx4 v[170:171], off
	s_nop 0
	v_lshl_add_u64 v[176:177], v[72:73], 0, s[30:31]
	s_nop 0
	s_nop 0
	s_nop 0
	v_lshl_add_u64 v[178:179], v[74:75], 0, s[30:31]
	s_nop 0
	s_nop 0
	s_nop 0
	v_lshl_add_u64 v[180:181], v[76:77], 0, s[30:31]
	s_nop 0
	s_mov_b64 s[30:31], 0x780
	s_nop 0
	s_nop 0
	s_nop 0
	s_nop 0
	s_nop 0
	ds_read_b128 a[16:19], v85 offset:32768
	ds_read_b128 a[20:23], v85 offset:36864
	ds_read_b128 a[24:27], v84
	ds_read_b128 a[28:31], v84 offset:4096
	s_waitcnt lgkmcnt(4)
	v_mfma_f32_32x32x16_bf16 v[48:63], a[0:3], a[8:11], v[48:63]
	v_lshl_add_u64 v[158:159], v[66:67], 0, s[30:31]
	s_nop 0
	v_mfma_f32_32x32x16_bf16 v[32:47], a[4:7], a[8:11], v[32:47]
	v_mfma_f32_32x32x16_bf16 v[16:31], a[0:3], a[12:15], v[16:31]
	s_and_b32 m0, s32, 7
	s_lshl_b32 m0, m0, 12
	s_add_i32 m0, m0, 0x18400
	s_nop 0
	global_load_lds_dwordx4 v[172:173], off
	v_mfma_f32_32x32x16_bf16 v[0:15], a[4:7], a[12:15], v[0:15]
	s_nop 0
	s_nop 0
	s_nop 0
	s_nop 0
	ds_read_b128 a[0:3], v87 offset:32768
	ds_read_b128 a[4:7], v87 offset:36864
	ds_read_b128 a[8:11], v86
	ds_read_b128 a[12:15], v86 offset:4096
	s_waitcnt lgkmcnt(5)
	v_mfma_f32_32x32x16_bf16 v[48:63], a[16:19], a[24:27], v[48:63]
	v_mfma_f32_32x32x16_bf16 v[32:47], a[20:23], a[24:27], v[32:47]
	s_and_b32 m0, s32, 7
	s_lshl_b32 m0, m0, 12
	s_add_i32 m0, m0, 0x18800
	s_nop 0
	global_load_lds_dwordx4 v[174:175], off
	s_waitcnt lgkmcnt(4)
	v_mfma_f32_32x32x16_bf16 v[16:31], a[16:19], a[28:31], v[16:31]
	v_mfma_f32_32x32x16_bf16 v[0:15], a[20:23], a[28:31], v[0:15]
	s_nop 0
	s_nop 0
	s_nop 0
	s_nop 0
	ds_read_b128 a[16:19], v89 offset:32768
	ds_read_b128 a[20:23], v89 offset:36864
	ds_read_b128 a[24:27], v88
	ds_read_b128 a[28:31], v88 offset:4096
	s_waitcnt lgkmcnt(5)
	v_mfma_f32_32x32x16_bf16 v[48:63], a[0:3], a[8:11], v[48:63]
	s_and_b32 m0, s32, 7
	s_lshl_b32 m0, m0, 12
	s_add_i32 m0, m0, 0x18c00
	s_nop 0
	global_load_lds_dwordx4 v[176:177], off
	v_mfma_f32_32x32x16_bf16 v[32:47], a[4:7], a[8:11], v[32:47]
	s_waitcnt lgkmcnt(4)
	v_mfma_f32_32x32x16_bf16 v[16:31], a[0:3], a[12:15], v[16:31]
	v_mfma_f32_32x32x16_bf16 v[0:15], a[4:7], a[12:15], v[0:15]
	s_and_b32 m0, s32, 7
	s_lshl_b32 m0, m0, 11
	s_add_i32 m0, m0, 0x20000
	s_nop 0
	global_load_lds_dwordx4 v[178:179], off
	s_nop 0
	s_nop 0
	s_nop 0
	s_nop 0
	s_waitcnt lgkmcnt(1)
	v_mfma_f32_32x32x16_bf16 v[48:63], a[16:19], a[24:27], v[48:63]
	v_mfma_f32_32x32x16_bf16 v[32:47], a[20:23], a[24:27], v[32:47]
	s_and_b32 m0, s32, 7
	s_lshl_b32 m0, m0, 11
	s_add_i32 m0, m0, 0x20400
	s_nop 0
	global_load_lds_dwordx4 v[180:181], off
	s_waitcnt vmcnt(6)
	s_waitcnt lgkmcnt(0)
	s_barrier
	ds_read_b128 a[12:15], v82 offset:53248
	ds_read_b128 a[8:11], v82 offset:49152
	ds_read_b128 a[4:7], v90
	ds_read_b128 a[0:3], v92
	s_nop 0
	v_lshl_add_u64 v[160:161], v[68:69], 0, s[30:31]
	s_nop 0
	v_mfma_f32_32x32x16_bf16 v[16:31], a[16:19], a[28:31], v[16:31]
	s_nop 0
	v_lshl_add_u64 v[162:163], v[70:71], 0, s[30:31]
	s_nop 0
	v_readlane_b32 s20, v215, 52
	s_nop 0
	v_lshl_add_u64 v[164:165], v[72:73], 0, s[30:31]
	s_nop 0
	v_mfma_f32_32x32x16_bf16 v[0:15], a[20:23], a[28:31], v[0:15]
	s_and_b32 m0, s32, 7
	s_lshl_b32 m0, m0, 12
	s_add_i32 m0, m0, 0x0
	s_nop 0
	global_load_lds_dwordx4 v[158:159], off
	s_nop 0
	v_lshl_add_u64 v[166:167], v[74:75], 0, s[30:31]
	s_nop 0
	v_readlane_b32 s21, v215, 53
	s_nop 0
	v_lshl_add_u64 v[168:169], v[76:77], 0, s[30:31]
	s_nop 0
	s_mov_b32 s23, 0
	s_nop 0
	s_nop 0
	s_nop 0
	s_nop 0
	s_nop 0
	ds_read_b128 a[16:19], v93
	ds_read_b128 a[20:23], v91
	ds_read_b128 a[24:27], v84 offset:49152
	ds_read_b128 a[28:31], v84 offset:53248
	s_waitcnt lgkmcnt(4)
	v_mfma_f32_32x32x16_bf16 v[48:63], a[0:3], a[8:11], v[48:63]
	v_mfma_f32_32x32x16_bf16 v[32:47], a[4:7], a[8:11], v[32:47]
	v_mfma_f32_32x32x16_bf16 v[16:31], a[0:3], a[12:15], v[16:31]
	s_and_b32 m0, s32, 7
	s_lshl_b32 m0, m0, 12
	s_add_i32 m0, m0, 0x400
	s_nop 0
	global_load_lds_dwordx4 v[160:161], off
	v_mfma_f32_32x32x16_bf16 v[0:15], a[4:7], a[12:15], v[0:15]
	s_nop 0
	s_nop 0
	s_nop 0
	s_nop 0
	ds_read_b128 a[0:3], v95
	ds_read_b128 a[4:7], v94
	ds_read_b128 a[8:11], v86 offset:49152
	ds_read_b128 a[12:15], v86 offset:53248
	s_waitcnt lgkmcnt(5)
	v_mfma_f32_32x32x16_bf16 v[48:63], a[16:19], a[24:27], v[48:63]
	v_mfma_f32_32x32x16_bf16 v[32:47], a[20:23], a[24:27], v[32:47]
	s_and_b32 m0, s32, 7
	s_lshl_b32 m0, m0, 12
	s_add_i32 m0, m0, 0x800
	s_nop 0
	global_load_lds_dwordx4 v[162:163], off
	s_waitcnt lgkmcnt(4)
	v_mfma_f32_32x32x16_bf16 v[16:31], a[16:19], a[28:31], v[16:31]
	v_mfma_f32_32x32x16_bf16 v[0:15], a[20:23], a[28:31], v[0:15]
	s_nop 0
	s_nop 0
	s_nop 0
	s_nop 0
	ds_read_b128 a[16:19], v97
	ds_read_b128 a[20:23], v96
	ds_read_b128 a[24:27], v88 offset:49152
	ds_read_b128 a[28:31], v88 offset:53248
	s_waitcnt lgkmcnt(5)
	v_mfma_f32_32x32x16_bf16 v[48:63], a[0:3], a[8:11], v[48:63]
	s_and_b32 m0, s32, 7
	s_lshl_b32 m0, m0, 12
	s_add_i32 m0, m0, 0xc00
	s_nop 0
	global_load_lds_dwordx4 v[164:165], off
	v_mfma_f32_32x32x16_bf16 v[32:47], a[4:7], a[8:11], v[32:47]
	s_waitcnt lgkmcnt(4)
	v_mfma_f32_32x32x16_bf16 v[16:31], a[0:3], a[12:15], v[16:31]
	v_mfma_f32_32x32x16_bf16 v[0:15], a[4:7], a[12:15], v[0:15]
	s_and_b32 m0, s32, 7
	s_lshl_b32 m0, m0, 11
	s_add_i32 m0, m0, 0x8000
	s_nop 0
	global_load_lds_dwordx4 v[166:167], off
	s_nop 0
	s_nop 0
	s_nop 0
	s_nop 0
	s_waitcnt lgkmcnt(1)
	v_mfma_f32_32x32x16_bf16 v[48:63], a[16:19], a[24:27], v[48:63]
	v_mfma_f32_32x32x16_bf16 v[32:47], a[20:23], a[24:27], v[32:47]
	s_and_b32 m0, s32, 7
	s_lshl_b32 m0, m0, 11
	s_add_i32 m0, m0, 0x8400
	s_nop 0
	global_load_lds_dwordx4 v[168:169], off
	s_waitcnt vmcnt(6)
	s_waitcnt lgkmcnt(0)
	s_barrier
	ds_read_b128 a[12:15], v101
	ds_read_b128 a[8:11], v100
	ds_read_b128 a[4:7], v99
	ds_read_b128 a[0:3], v98
	v_mfma_f32_32x32x16_bf16 v[16:31], a[16:19], a[28:31], v[16:31]
	v_mfma_f32_32x32x16_bf16 v[0:15], a[20:23], a[28:31], v[0:15]
	s_nop 0
	s_nop 0
	s_nop 0
	s_nop 0
	ds_read_b128 a[16:19], v102
	ds_read_b128 a[20:23], v103
	ds_read_b128 a[24:27], v104
	ds_read_b128 a[28:31], v105
	s_waitcnt lgkmcnt(4)
	v_mfma_f32_32x32x16_bf16 v[48:63], a[0:3], a[8:11], v[48:63]
	v_mfma_f32_32x32x16_bf16 v[32:47], a[4:7], a[8:11], v[32:47]
	v_mfma_f32_32x32x16_bf16 v[16:31], a[0:3], a[12:15], v[16:31]
	v_mfma_f32_32x32x16_bf16 v[0:15], a[4:7], a[12:15], v[0:15]
	s_nop 0
	s_nop 0
	s_nop 0
	s_nop 0
	ds_read_b128 a[0:3], v106
	ds_read_b128 a[4:7], v107
	ds_read_b128 a[8:11], v108
	ds_read_b128 a[12:15], v109
	s_waitcnt lgkmcnt(5)
	v_mfma_f32_32x32x16_bf16 v[48:63], a[16:19], a[24:27], v[48:63]
	v_mfma_f32_32x32x16_bf16 v[32:47], a[20:23], a[24:27], v[32:47]
	s_waitcnt lgkmcnt(4)
	v_mfma_f32_32x32x16_bf16 v[16:31], a[16:19], a[28:31], v[16:31]
	v_mfma_f32_32x32x16_bf16 v[0:15], a[20:23], a[28:31], v[0:15]
	s_nop 0
	s_nop 0
	s_nop 0
	s_nop 0
	ds_read_b128 a[16:19], v110
	ds_read_b128 a[20:23], v111
	ds_read_b128 a[24:27], v112
	ds_read_b128 a[28:31], v113
	s_waitcnt lgkmcnt(5)
	v_mfma_f32_32x32x16_bf16 v[48:63], a[0:3], a[8:11], v[48:63]
	v_mfma_f32_32x32x16_bf16 v[32:47], a[4:7], a[8:11], v[32:47]
	s_waitcnt lgkmcnt(4)
	v_mfma_f32_32x32x16_bf16 v[16:31], a[0:3], a[12:15], v[16:31]
	v_mfma_f32_32x32x16_bf16 v[0:15], a[4:7], a[12:15], v[0:15]
	s_nop 0
	s_nop 0
	s_nop 0
	s_nop 0
	s_waitcnt lgkmcnt(1)
	v_mfma_f32_32x32x16_bf16 v[48:63], a[16:19], a[24:27], v[48:63]
	v_mfma_f32_32x32x16_bf16 v[32:47], a[20:23], a[24:27], v[32:47]
	s_waitcnt vmcnt(0)
	s_waitcnt lgkmcnt(0)
	s_barrier
	ds_read_b128 a[12:15], v82 offset:4096
	ds_read_b128 a[8:11], v82
	ds_read_b128 a[4:7], v83 offset:36864
	ds_read_b128 a[0:3], v83 offset:32768
	v_mfma_f32_32x32x16_bf16 v[16:31], a[16:19], a[28:31], v[16:31]
	v_mfma_f32_32x32x16_bf16 v[0:15], a[20:23], a[28:31], v[0:15]
	s_nop 0
	s_nop 0
	s_nop 0
	s_nop 0
	ds_read_b128 a[16:19], v85 offset:32768
	ds_read_b128 a[20:23], v85 offset:36864
	ds_read_b128 a[24:27], v84
	ds_read_b128 a[28:31], v84 offset:4096
	s_waitcnt lgkmcnt(4)
	v_mfma_f32_32x32x16_bf16 v[48:63], a[0:3], a[8:11], v[48:63]
	v_mfma_f32_32x32x16_bf16 v[32:47], a[4:7], a[8:11], v[32:47]
	v_mfma_f32_32x32x16_bf16 v[16:31], a[0:3], a[12:15], v[16:31]
	v_mfma_f32_32x32x16_bf16 v[0:15], a[4:7], a[12:15], v[0:15]
	s_nop 0
	s_nop 0
	s_nop 0
	s_nop 0
	ds_read_b128 a[0:3], v87 offset:32768
	ds_read_b128 a[4:7], v87 offset:36864
	ds_read_b128 a[8:11], v86
	ds_read_b128 a[12:15], v86 offset:4096
	s_waitcnt lgkmcnt(5)
	v_mfma_f32_32x32x16_bf16 v[48:63], a[16:19], a[24:27], v[48:63]
	v_mfma_f32_32x32x16_bf16 v[32:47], a[20:23], a[24:27], v[32:47]
	s_waitcnt lgkmcnt(4)
	v_mfma_f32_32x32x16_bf16 v[16:31], a[16:19], a[28:31], v[16:31]
	v_mfma_f32_32x32x16_bf16 v[0:15], a[20:23], a[28:31], v[0:15]
	s_nop 0
	s_nop 0
	s_nop 0
	s_waitcnt lgkmcnt(1)
	v_mfma_f32_32x32x16_bf16 v[48:63], a[0:3], a[8:11], v[48:63]
	v_mfma_f32_32x32x16_bf16 v[32:47], a[4:7], a[8:11], v[32:47]
	s_nop 0
	s_waitcnt lgkmcnt(0)
	v_mfma_f32_32x32x16_bf16 v[0:15], a[4:7], a[12:15], v[0:15]
	v_mfma_f32_32x32x16_bf16 v[16:31], a[0:3], a[12:15], v[16:31]
	ds_read_b128 v[66:69], v89 offset:32768
	ds_read_b128 v[70:73], v88
	ds_read_b128 v[74:77], v89 offset:36864
	ds_read_b128 v[82:85], v88 offset:4096
	s_waitcnt lgkmcnt(0)
	s_barrier
	s_waitcnt lgkmcnt(0)
	v_mfma_f32_32x32x16_bf16 v[48:63], v[66:69], v[70:73], v[48:63]
	v_mfma_f32_32x32x16_bf16 v[32:47], v[74:77], v[70:73], v[32:47]
	s_nop 10
	ds_write_b128 v64, v[48:51]
	ds_write_b128 v64, v[52:55] offset:32
	ds_write_b128 v64, v[56:59] offset:64
	ds_write_b128 v64, v[60:63] offset:96
	ds_write_b128 v64, v[32:35] offset:128
	v_mfma_f32_32x32x16_bf16 v[0:15], v[74:77], v[82:85], v[0:15]
	v_mfma_f32_32x32x16_bf16 v[16:31], v[66:69], v[82:85], v[16:31]
	ds_write_b128 v64, v[36:39] offset:160
	ds_write_b128 v64, v[40:43] offset:192
	ds_write_b128 v64, v[44:47] offset:224
	s_nop 8
	ds_write_b128 v64, v[16:19] offset:16896
	ds_write_b128 v64, v[20:23] offset:16928
	ds_write_b128 v64, v[24:27] offset:16960
	ds_write_b128 v64, v[28:31] offset:16992
	ds_write_b128 v64, v[0:3] offset:17024
	ds_write_b128 v64, v[4:7] offset:17056
	ds_write_b128 v64, v[8:11] offset:17088
	ds_write_b128 v64, v[12:15] offset:17120
	s_waitcnt lgkmcnt(0)
	s_barrier
	v_lshl_or_b32 v0, v79, 2, s0
	v_ashrrev_i32_e32 v1, 31, v0
	v_lshl_add_u32 v4, v79, 4, 0
	v_cmp_eq_u32_e64 s[0:1], 0, v79
	v_lshl_add_u64 v[6:7], v[0:1], 2, s[92:93]
	v_lshl_add_u64 v[8:9], v[0:1], 1, s[20:21]
	s_branch .LBB0_96

.LBB0_159:
	v_mov_b32_e32 v78, v133
	s_lshl_b32 s22, s2, 8
	v_ashrrev_i32_e32 v6, 6, v78
	v_bfe_u32 v7, v78, 3, 3
	v_lshl_or_b32 v8, v6, 5, v7
	v_add_u32_e32 v0, s22, v8
	s_waitcnt lgkmcnt(0)
	v_ashrrev_i32_e32 v1, 31, v0
	v_lshlrev_b64 v[2:3], 11, v[0:1]
	v_bfe_u32 v1, v78, 4, 2
	v_readlane_b32 s0, v214, 4
	v_xor_b32_e32 v1, v1, v78
	v_readlane_b32 s1, v214, 5
	v_lshlrev_b32_e32 v1, 4, v1
	v_and_b32_e32 v64, 0x70, v1
	v_lshl_add_u64 v[2:3], s[0:1], 0, v[2:3]
	v_or_b32_e32 v1, 8, v8
	v_lshl_add_u64 v[66:67], v[2:3], 0, v[64:65]
	v_add_u32_e32 v2, s22, v1
	v_lshrrev_b32_e32 v1, 1, v1
	v_xor_b32_e32 v1, v1, v78
	v_ashrrev_i32_e32 v3, 31, v2
	v_lshlrev_b32_e32 v1, 4, v1
	v_or_b32_e32 v0, 16, v0
	v_lshlrev_b64 v[2:3], 11, v[2:3]
	v_and_b32_e32 v4, 0x70, v1
	v_ashrrev_i32_e32 v1, 31, v0
	v_lshl_add_u64 v[2:3], s[0:1], 0, v[2:3]
	v_mov_b32_e32 v5, v65
	v_lshlrev_b64 v[0:1], 11, v[0:1]
	v_lshl_add_u64 v[68:69], v[2:3], 0, v[4:5]
	v_lshl_add_u64 v[0:1], s[0:1], 0, v[0:1]
	v_or_b32_e32 v2, 24, v8
	v_lshl_add_u64 v[70:71], v[0:1], 0, v[64:65]
	v_add_u32_e32 v0, s22, v2
	v_lshrrev_b32_e32 v2, 1, v2
	v_ashrrev_i32_e32 v1, 31, v0
	v_xor_b32_e32 v2, v2, v78
	v_lshlrev_b64 v[0:1], 11, v[0:1]
	v_lshlrev_b32_e32 v2, 4, v2
	v_lshl_add_u64 v[0:1], s[0:1], 0, v[0:1]
	v_and_b32_e32 v2, 0x70, v2
	v_mov_b32_e32 v3, v65
	v_lshl_add_u64 v[72:73], v[0:1], 0, v[2:3]
	v_lshl_or_b32 v2, v6, 4, v7
	v_readlane_b32 s31, v214, 58
	v_lshlrev_b32_e32 v3, 12, v6
	v_add_u32_e32 v126, 0, v3
	v_add_u32_e32 v0, s31, v2
	v_ashrrev_i32_e32 v1, 31, v0
	v_lshlrev_b64 v[0:1], 11, v[0:1]
	s_waitcnt vmcnt(0)
	v_readfirstlane_b32 s37, v126
	v_add_u32_e32 v127, 0x400, v126
	v_lshl_add_u64 v[0:1], s[40:41], 0, v[0:1]
	v_or_b32_e32 v2, 8, v2
	s_waitcnt lgkmcnt(0)
	s_barrier
	s_mov_b32 m0, s37
	v_readfirstlane_b32 s38, v127
	v_add_u32_e32 v128, 0x800, v126
	v_lshlrev_b32_e32 v5, 11, v6
	v_and_b32_e32 v80, 1, v6
	v_lshl_add_u64 v[74:75], v[0:1], 0, v[64:65]
	v_add_u32_e32 v0, s31, v2
	v_lshrrev_b32_e32 v2, 1, v2
	global_load_lds_dwordx4 v[66:67], off
	s_mov_b32 m0, s38
	v_readfirstlane_b32 s39, v128
	v_add_u32_e32 v129, 0xc00, v126
	v_add_u32_e32 v6, 0, v5
	v_ashrrev_i32_e32 v1, 31, v0
	v_xor_b32_e32 v2, v2, v78
	global_load_lds_dwordx4 v[68:69], off
	s_mov_b32 m0, s39
	v_readfirstlane_b32 s48, v129
	v_add_u32_e32 v131, 0x8000, v6
	v_lshlrev_b64 v[0:1], 11, v[0:1]
	v_lshlrev_b32_e32 v2, 4, v2
	global_load_lds_dwordx4 v[70:71], off
	s_mov_b32 m0, s48
	v_readfirstlane_b32 s49, v131
	v_add_u32_e32 v130, 0x8400, v6
	v_lshl_add_u64 v[0:1], s[40:41], 0, v[0:1]
	v_and_b32_e32 v64, 0x70, v2
	global_load_lds_dwordx4 v[72:73], off
	s_mov_b32 m0, s49
	v_readfirstlane_b32 s53, v130
	v_add_u32_e32 v120, 0xc000, v126
	v_lshl_add_u64 v[76:77], v[0:1], 0, v[64:65]
	global_load_lds_dwordx4 v[74:75], off
	s_mov_b32 m0, s53
	s_mov_b64 s[0:1], 0x80
	v_readfirstlane_b32 s28, v120
	v_add_u32_e32 v121, 0xc400, v126
	global_load_lds_dwordx4 v[76:77], off
	v_lshl_add_u64 v[0:1], v[66:67], 0, s[0:1]
	s_mov_b32 m0, s28
	v_readfirstlane_b32 s29, v121
	v_add_u32_e32 v122, 0xc800, v126
	global_load_lds_dwordx4 v[0:1], off
	v_lshl_add_u64 v[0:1], v[68:69], 0, s[0:1]
	s_mov_b32 m0, s29
	v_readfirstlane_b32 s33, v122
	v_add_u32_e32 v123, 0xcc00, v126
	global_load_lds_dwordx4 v[0:1], off
	v_lshl_add_u64 v[0:1], v[70:71], 0, s[0:1]
	s_mov_b32 m0, s33
	v_readfirstlane_b32 s34, v123
	v_add_u32_e32 v124, s85, v5
	global_load_lds_dwordx4 v[0:1], off
	v_lshl_add_u64 v[0:1], v[72:73], 0, s[0:1]
	s_mov_b32 m0, s34
	v_readfirstlane_b32 s35, v124
	v_add_u32_e32 v125, 0x14400, v6
	global_load_lds_dwordx4 v[0:1], off
	v_lshl_add_u64 v[0:1], v[74:75], 0, s[0:1]
	s_mov_b32 m0, s35
	v_readfirstlane_b32 s36, v125
	global_load_lds_dwordx4 v[0:1], off
	v_lshl_add_u64 v[0:1], v[76:77], 0, s[0:1]
	s_mov_b32 m0, s36
	v_lshrrev_b32_e32 v2, 1, v78
	v_bfe_u32 v64, v78, 5, 1
	global_load_lds_dwordx4 v[0:1], off
	v_add_u32_e32 v114, s3, v3
	v_bitop3_b32 v0, v2, v64, 7 bitop3:0x6c
	s_waitcnt vmcnt(6)
	s_mov_b64 s[46:47], 0x100
	v_readfirstlane_b32 s0, v114
	v_add_u32_e32 v115, 0x400, v114
	v_lshlrev_b32_e32 v132, 4, v0
	s_waitcnt lgkmcnt(0)
	s_barrier
	v_lshl_add_u64 v[0:1], v[66:67], 0, s[46:47]
	s_mov_b32 m0, s0
	v_readfirstlane_b32 s1, v115
	v_add_u32_e32 v116, 0x800, v114
	global_load_lds_dwordx4 v[0:1], off
	v_lshl_add_u64 v[0:1], v[68:69], 0, s[46:47]
	s_mov_b32 m0, s1
	v_readfirstlane_b32 s20, v116
	v_add_u32_e32 v117, 0xc00, v114
	v_readlane_b32 s23, v212, 31
	v_and_b32_e32 v79, 31, v78
	global_load_lds_dwordx4 v[0:1], off
	v_lshl_add_u64 v[0:1], v[70:71], 0, s[46:47]
	s_mov_b32 m0, s20
	v_readfirstlane_b32 s21, v117
	v_add_u32_e32 v118, s23, v5
	v_add_u32_e32 v2, s3, v5
	v_lshlrev_b32_e32 v4, 7, v79
	global_load_lds_dwordx4 v[0:1], off
	v_lshl_add_u64 v[0:1], v[72:73], 0, s[46:47]
	s_mov_b32 m0, s21
	v_readfirstlane_b32 s23, v118
	v_add_u32_e32 v119, 0x8400, v2
	v_lshl_or_b32 v102, v80, 13, v4
	global_load_lds_dwordx4 v[0:1], off
	v_lshl_add_u64 v[0:1], v[74:75], 0, s[46:47]
	s_mov_b32 m0, s23
	v_readfirstlane_b32 s24, v119
	global_load_lds_dwordx4 v[0:1], off
	v_lshl_add_u64 v[0:1], v[76:77], 0, s[46:47]
	s_mov_b32 m0, s24
	v_add_u32_e32 v100, 0, v102
	global_load_lds_dwordx4 v[0:1], off
	v_add_u32_e32 v83, v100, v132
	v_ashrrev_i32_e32 v81, 7, v78
	ds_read_b128 a[0:3], v83 offset:32768
	ds_read_b128 a[4:7], v83 offset:36864
	v_lshl_or_b32 v134, v81, 13, v4
	v_add_u32_e32 v101, 0, v134
	v_add_u32_e32 v82, v101, v132
	ds_read_b128 a[8:11], v82
	ds_read_b128 a[12:15], v82 offset:4096
	v_lshrrev_b32_e32 v182, 6, v133
	s_nop 0
	v_readfirstlane_b32 s32, v182
	s_waitcnt lgkmcnt(1)
	v_mfma_f32_32x32x16_bf16 v[48:63], a[0:3], a[8:11], 0
	v_bfe_u32 v103, v78, 1, 3
	s_mov_b64 s[46:47], 0x180
	s_nop 0
	s_add_i32 s30, 0, 0xc000
	v_or_b32_e32 v143, 0x8000, v102
	v_or_b32_e32 v144, 0x9000, v102
	v_add_u32_e32 v145, s3, v134
	s_waitcnt vmcnt(12)
	v_mfma_f32_32x32x16_bf16 v[32:47], a[4:7], a[8:11], 0
	v_lshl_or_b32 v81, v81, 6, v79
	v_mul_lo_u32 v81, v81, s26
	s_mov_b64 s[80:81], 0x200
	s_waitcnt lgkmcnt(0)
	v_mfma_f32_32x32x16_bf16 v[16:31], a[0:3], a[12:15], 0
	v_bitop3_b32 v0, v64, v103, 2 bitop3:0x36
	v_lshlrev_b32_e32 v138, 4, v0
	v_add_u32_e32 v84, v101, v138
	ds_read_b128 a[28:31], v84 offset:4096
	s_nop 0
	s_nop 0
	ds_read_b128 a[24:27], v84
	s_nop 0
	v_add_u32_e32 v85, v100, v138
	ds_read_b128 a[20:23], v85 offset:36864
	s_nop 0
	s_nop 0
	ds_read_b128 a[16:19], v85 offset:32768
	s_nop 0
	s_nop 0
	s_nop 0
	s_nop 0
	s_nop 0
	s_nop 0
	v_mfma_f32_32x32x16_bf16 v[0:15], a[4:7], a[12:15], 0
	s_nop 0
	s_waitcnt lgkmcnt(0)
	v_mfma_f32_32x32x16_bf16 v[48:63], a[16:19], a[24:27], v[48:63]
	v_mfma_f32_32x32x16_bf16 v[32:47], a[20:23], a[24:27], v[32:47]
	v_mfma_f32_32x32x16_bf16 v[16:31], a[16:19], a[28:31], v[16:31]
	v_bitop3_b32 v86, v64, v103, 4 bitop3:0x36
	v_lshlrev_b32_e32 v139, 4, v86
	v_add_u32_e32 v86, v101, v139
	ds_read_b128 a[12:15], v86 offset:4096
	s_nop 0
	s_nop 0
	ds_read_b128 a[8:11], v86
	s_nop 0
	v_add_u32_e32 v87, v100, v139
	ds_read_b128 a[4:7], v87 offset:36864
	s_nop 0
	s_nop 0
	ds_read_b128 a[0:3], v87 offset:32768
	s_nop 0
	s_nop 0
	s_nop 0
	v_mfma_f32_32x32x16_bf16 v[0:15], a[20:23], a[28:31], v[0:15]
	s_nop 0
	s_nop 0
	s_nop 0
	s_nop 0
	s_waitcnt lgkmcnt(0)
	v_mfma_f32_32x32x16_bf16 v[48:63], a[0:3], a[8:11], v[48:63]
	v_mfma_f32_32x32x16_bf16 v[32:47], a[4:7], a[8:11], v[32:47]
	v_mfma_f32_32x32x16_bf16 v[16:31], a[0:3], a[12:15], v[16:31]
	v_bitop3_b32 v88, v64, v103, 6 bitop3:0x36
	v_lshlrev_b32_e32 v142, 4, v88
	v_add_u32_e32 v88, v101, v142
	ds_read_b128 a[28:31], v88 offset:4096
	s_nop 0
	s_nop 0
	ds_read_b128 a[24:27], v88
	s_nop 0
	v_add_u32_e32 v89, v100, v142
	ds_read_b128 a[20:23], v89 offset:36864
	s_nop 0
	s_nop 0
	ds_read_b128 a[16:19], v89 offset:32768
	s_nop 0
	s_nop 0
	s_nop 0
	v_lshlrev_b32_e32 v64, 4, v64
	v_lshl_or_b32 v64, v80, 8, v64
	v_add3_u32 v64, 0, v81, v64
	v_mfma_f32_32x32x16_bf16 v[0:15], a[4:7], a[12:15], v[0:15]
	s_nop 0
	s_nop 0
	s_nop 0
	s_nop 0
	s_waitcnt lgkmcnt(0)
	v_mfma_f32_32x32x16_bf16 v[48:63], a[16:19], a[24:27], v[48:63]
	v_mfma_f32_32x32x16_bf16 v[32:47], a[20:23], a[24:27], v[32:47]
	s_waitcnt vmcnt(6)
	s_waitcnt lgkmcnt(0)
	s_barrier
	ds_read_b128 a[12:15], v82 offset:53248
	ds_read_b128 a[8:11], v82 offset:49152
	v_add_u32_e32 v90, s30, v132
	v_add_u32_e32 v92, v90, v143
	v_add_u32_e32 v90, v90, v144
	ds_read_b128 a[4:7], v90
	ds_read_b128 a[0:3], v92
	v_mfma_f32_32x32x16_bf16 v[16:31], a[16:19], a[28:31], v[16:31]
	v_lshl_add_u64 v[158:159], v[66:67], 0, s[46:47]
	s_nop 0
	v_lshl_add_u64 v[160:161], v[68:69], 0, s[46:47]
	s_nop 0
	s_nop 0
	s_nop 0
	v_lshl_add_u64 v[162:163], v[70:71], 0, s[46:47]
	s_nop 0
	v_mfma_f32_32x32x16_bf16 v[0:15], a[20:23], a[28:31], v[0:15]
	s_and_b32 m0, s32, 7
	s_lshl_b32 m0, m0, 12
	s_add_i32 m0, m0, 0x0
	s_nop 0
	global_load_lds_dwordx4 v[158:159], off
	s_nop 0
	v_lshl_add_u64 v[164:165], v[72:73], 0, s[46:47]
	s_nop 0
	s_nop 0
	s_nop 0
	v_lshl_add_u64 v[166:167], v[74:75], 0, s[46:47]
	s_nop 0
	s_nop 0
	s_nop 0
	v_lshl_add_u64 v[168:169], v[76:77], 0, s[46:47]
	s_nop 0
	s_mov_b64 s[46:47], 0x200
	s_nop 0
	s_nop 0
	s_nop 0
	s_nop 0
	s_nop 0
	s_nop 0
	s_nop 0
	s_nop 0
	v_add_u32_e32 v91, s30, v138
	v_add_u32_e32 v93, v91, v143
	ds_read_b128 a[16:19], v93
	v_add_u32_e32 v91, v91, v144
	ds_read_b128 a[20:23], v91
	ds_read_b128 a[24:27], v84 offset:49152
	ds_read_b128 a[28:31], v84 offset:53248
	s_waitcnt lgkmcnt(4)
	v_mfma_f32_32x32x16_bf16 v[48:63], a[0:3], a[8:11], v[48:63]
	s_nop 0
	s_nop 0
	s_nop 0
	s_nop 0
	v_mfma_f32_32x32x16_bf16 v[32:47], a[4:7], a[8:11], v[32:47]
	v_mfma_f32_32x32x16_bf16 v[16:31], a[0:3], a[12:15], v[16:31]
	s_and_b32 m0, s32, 7
	s_lshl_b32 m0, m0, 12
	s_add_i32 m0, m0, 0x400
	s_nop 0
	global_load_lds_dwordx4 v[160:161], off
	v_mfma_f32_32x32x16_bf16 v[0:15], a[4:7], a[12:15], v[0:15]
	s_nop 0
	s_nop 0
	s_nop 0
	s_nop 0
	v_add_u32_e32 v94, s30, v139
	v_add_u32_e32 v95, v94, v143
	ds_read_b128 a[0:3], v95
	v_add_u32_e32 v94, v94, v144
	ds_read_b128 a[4:7], v94
	ds_read_b128 a[8:11], v86 offset:49152
	ds_read_b128 a[12:15], v86 offset:53248
	s_waitcnt lgkmcnt(5)
	v_mfma_f32_32x32x16_bf16 v[48:63], a[16:19], a[24:27], v[48:63]
	v_mfma_f32_32x32x16_bf16 v[32:47], a[20:23], a[24:27], v[32:47]
	s_and_b32 m0, s32, 7
	s_lshl_b32 m0, m0, 12
	s_add_i32 m0, m0, 0x800
	s_nop 0
	global_load_lds_dwordx4 v[162:163], off
	s_waitcnt lgkmcnt(4)
	v_mfma_f32_32x32x16_bf16 v[16:31], a[16:19], a[28:31], v[16:31]
	s_nop 0
	s_nop 0
	s_nop 0
	v_mfma_f32_32x32x16_bf16 v[0:15], a[20:23], a[28:31], v[0:15]
	s_nop 0
	s_nop 0
	s_nop 0
	s_nop 0
	v_add_u32_e32 v96, s30, v142
	v_add_u32_e32 v97, v96, v143
	ds_read_b128 a[16:19], v97
	v_add_u32_e32 v96, v96, v144
	ds_read_b128 a[20:23], v96
	ds_read_b128 a[24:27], v88 offset:49152
	ds_read_b128 a[28:31], v88 offset:53248
	s_waitcnt lgkmcnt(5)
	v_mfma_f32_32x32x16_bf16 v[48:63], a[0:3], a[8:11], v[48:63]
	s_and_b32 m0, s32, 7
	s_lshl_b32 m0, m0, 12
	s_add_i32 m0, m0, 0xc00
	s_nop 0
	global_load_lds_dwordx4 v[164:165], off
	v_mfma_f32_32x32x16_bf16 v[32:47], a[4:7], a[8:11], v[32:47]
	s_waitcnt lgkmcnt(4)
	v_mfma_f32_32x32x16_bf16 v[16:31], a[0:3], a[12:15], v[16:31]
	s_nop 0
	s_nop 0
	s_nop 0
	v_mfma_f32_32x32x16_bf16 v[0:15], a[4:7], a[12:15], v[0:15]
	s_and_b32 m0, s32, 7
	s_lshl_b32 m0, m0, 11
	s_add_i32 m0, m0, 0x8000
	s_nop 0
	global_load_lds_dwordx4 v[166:167], off
	s_nop 0
	s_nop 0
	s_nop 0
	s_nop 0
	s_waitcnt lgkmcnt(1)
	v_mfma_f32_32x32x16_bf16 v[48:63], a[16:19], a[24:27], v[48:63]
	v_mfma_f32_32x32x16_bf16 v[32:47], a[20:23], a[24:27], v[32:47]
	s_and_b32 m0, s32, 7
	s_lshl_b32 m0, m0, 11
	s_add_i32 m0, m0, 0x8400
	s_nop 0
	global_load_lds_dwordx4 v[168:169], off
	s_waitcnt vmcnt(6)
	s_waitcnt lgkmcnt(0)
	s_barrier
	v_add_u32_e32 v100, v145, v132
	ds_read_b128 a[8:11], v100
	v_add_u32_e32 v101, s3, v132
	v_add_u32_e32 v99, v101, v144
	ds_read_b128 a[4:7], v99
	s_nop 0
	v_add_u32_e32 v98, v101, v143
	v_or_b32_e32 v132, 0x1000, v134
	v_add_u32_e32 v101, v101, v132
	ds_read_b128 a[12:15], v101
	ds_read_b128 a[0:3], v98
	v_mfma_f32_32x32x16_bf16 v[16:31], a[16:19], a[28:31], v[16:31]
	v_lshl_add_u64 v[170:171], v[66:67], 0, s[46:47]
	s_nop 0
	v_lshl_add_u64 v[172:173], v[68:69], 0, s[46:47]
	s_nop 0
	s_nop 0
	s_nop 0
	v_lshl_add_u64 v[174:175], v[70:71], 0, s[46:47]
	s_nop 0
	v_mfma_f32_32x32x16_bf16 v[0:15], a[20:23], a[28:31], v[0:15]
	s_and_b32 m0, s32, 7
	s_lshl_b32 m0, m0, 12
	s_add_i32 m0, m0, 0xc000
	s_nop 0
	global_load_lds_dwordx4 v[170:171], off
	s_nop 0
	v_lshl_add_u64 v[176:177], v[72:73], 0, s[46:47]
	s_nop 0
	s_nop 0
	s_nop 0
	v_lshl_add_u64 v[178:179], v[74:75], 0, s[46:47]
	s_nop 0
	s_nop 0
	s_nop 0
	v_lshl_add_u64 v[180:181], v[76:77], 0, s[46:47]
	s_nop 0
	s_mov_b64 s[46:47], 0x280
	s_nop 0
	s_nop 0
	s_nop 0
	s_nop 0
	s_nop 0
	s_nop 0
	s_nop 0
	s_nop 0
	v_add_u32_e32 v105, s3, v138
	v_add_u32_e32 v102, v105, v143
	ds_read_b128 a[16:19], v102
	v_add_u32_e32 v103, v105, v144
	ds_read_b128 a[20:23], v103
	v_add_u32_e32 v104, v145, v138
	ds_read_b128 a[24:27], v104
	v_add_u32_e32 v105, v105, v132
	ds_read_b128 a[28:31], v105
	s_waitcnt lgkmcnt(4)
	v_mfma_f32_32x32x16_bf16 v[48:63], a[0:3], a[8:11], v[48:63]
	s_nop 0
	v_mfma_f32_32x32x16_bf16 v[32:47], a[4:7], a[8:11], v[32:47]
	s_nop 0
	s_nop 0
	s_nop 0
	s_nop 0
	s_nop 0
	v_mfma_f32_32x32x16_bf16 v[16:31], a[0:3], a[12:15], v[16:31]
	s_and_b32 m0, s32, 7
	s_lshl_b32 m0, m0, 12
	s_add_i32 m0, m0, 0xc400
	s_nop 0
	global_load_lds_dwordx4 v[172:173], off
	s_nop 0
	v_mfma_f32_32x32x16_bf16 v[0:15], a[4:7], a[12:15], v[0:15]
	s_nop 0
	s_nop 0
	s_nop 0
	v_add_u32_e32 v109, s3, v139
	v_add_u32_e32 v106, v109, v143
	ds_read_b128 a[0:3], v106
	v_add_u32_e32 v107, v109, v144
	ds_read_b128 a[4:7], v107
	v_add_u32_e32 v108, v145, v139
	ds_read_b128 a[8:11], v108
	v_add_u32_e32 v109, v109, v132
	ds_read_b128 a[12:15], v109
	s_waitcnt lgkmcnt(5)
	v_mfma_f32_32x32x16_bf16 v[48:63], a[16:19], a[24:27], v[48:63]
	v_mfma_f32_32x32x16_bf16 v[32:47], a[20:23], a[24:27], v[32:47]
	s_and_b32 m0, s32, 7
	s_lshl_b32 m0, m0, 12
	s_add_i32 m0, m0, 0xc800
	s_nop 0
	global_load_lds_dwordx4 v[174:175], off
	s_waitcnt lgkmcnt(4)
	v_mfma_f32_32x32x16_bf16 v[16:31], a[16:19], a[28:31], v[16:31]
	s_nop 0
	s_nop 0
	s_nop 0
	s_nop 0
	s_nop 0
	s_nop 0
	v_mfma_f32_32x32x16_bf16 v[0:15], a[20:23], a[28:31], v[0:15]
	s_nop 0
	s_nop 0
	s_nop 0
	v_add_u32_e32 v113, s3, v142
	v_add_u32_e32 v110, v113, v143
	ds_read_b128 a[16:19], v110
	v_add_u32_e32 v111, v113, v144
	ds_read_b128 a[20:23], v111
	v_add_u32_e32 v112, v145, v142
	ds_read_b128 a[24:27], v112
	v_add_u32_e32 v113, v113, v132
	ds_read_b128 a[28:31], v113
	s_waitcnt lgkmcnt(5)
	v_mfma_f32_32x32x16_bf16 v[48:63], a[0:3], a[8:11], v[48:63]
	s_and_b32 m0, s32, 7
	s_lshl_b32 m0, m0, 12
	s_add_i32 m0, m0, 0xcc00
	s_nop 0
	global_load_lds_dwordx4 v[176:177], off
	v_mfma_f32_32x32x16_bf16 v[32:47], a[4:7], a[8:11], v[32:47]
	s_waitcnt lgkmcnt(4)
	v_mfma_f32_32x32x16_bf16 v[16:31], a[0:3], a[12:15], v[16:31]
	s_nop 0
	s_nop 0
	s_nop 0
	s_nop 0
	s_nop 0
	s_nop 0
	v_mfma_f32_32x32x16_bf16 v[0:15], a[4:7], a[12:15], v[0:15]
	s_and_b32 m0, s32, 7
	s_lshl_b32 m0, m0, 11
	s_add_i32 m0, m0, 0x14000
	s_nop 0
	global_load_lds_dwordx4 v[178:179], off
	s_nop 0
	s_nop 0
	s_nop 0
	s_waitcnt lgkmcnt(1)
	v_mfma_f32_32x32x16_bf16 v[48:63], a[16:19], a[24:27], v[48:63]
	v_mfma_f32_32x32x16_bf16 v[32:47], a[20:23], a[24:27], v[32:47]
	s_and_b32 m0, s32, 7
	s_lshl_b32 m0, m0, 11
	s_add_i32 m0, m0, 0x14400
	s_nop 0
	global_load_lds_dwordx4 v[180:181], off
	s_waitcnt vmcnt(6)
	s_waitcnt lgkmcnt(0)
	s_barrier
	ds_read_b128 a[12:15], v82 offset:4096
	ds_read_b128 a[8:11], v82
	ds_read_b128 a[4:7], v83 offset:36864
	ds_read_b128 a[0:3], v83 offset:32768
	v_mfma_f32_32x32x16_bf16 v[16:31], a[16:19], a[28:31], v[16:31]
	v_lshl_add_u64 v[158:159], v[66:67], 0, s[46:47]
	s_nop 0
	v_lshl_add_u64 v[160:161], v[68:69], 0, s[46:47]
	s_nop 0
	s_nop 0
	s_nop 0
	v_lshl_add_u64 v[162:163], v[70:71], 0, s[46:47]
	s_nop 0
	v_mfma_f32_32x32x16_bf16 v[0:15], a[20:23], a[28:31], v[0:15]
	s_and_b32 m0, s32, 7
	s_lshl_b32 m0, m0, 12
	s_add_i32 m0, m0, 0x18000
	s_nop 0
	global_load_lds_dwordx4 v[158:159], off
	s_nop 0
	v_lshl_add_u64 v[164:165], v[72:73], 0, s[46:47]
	s_nop 0
	s_nop 0
	s_nop 0
	v_lshl_add_u64 v[166:167], v[74:75], 0, s[46:47]
	s_nop 0
	s_nop 0
	s_nop 0
	v_lshl_add_u64 v[168:169], v[76:77], 0, s[46:47]
	s_nop 0
	s_mov_b64 s[46:47], 0x300
	s_nop 0
	s_nop 0
	s_nop 0
	s_nop 0
	s_nop 0
	ds_read_b128 a[16:19], v85 offset:32768
	ds_read_b128 a[20:23], v85 offset:36864
	ds_read_b128 a[24:27], v84
	ds_read_b128 a[28:31], v84 offset:4096
	s_waitcnt lgkmcnt(4)
	v_mfma_f32_32x32x16_bf16 v[48:63], a[0:3], a[8:11], v[48:63]
	s_nop 0
	v_mfma_f32_32x32x16_bf16 v[32:47], a[4:7], a[8:11], v[32:47]
	v_mfma_f32_32x32x16_bf16 v[16:31], a[0:3], a[12:15], v[16:31]
	s_and_b32 m0, s32, 7
	s_lshl_b32 m0, m0, 12
	s_add_i32 m0, m0, 0x18400
	s_nop 0
	global_load_lds_dwordx4 v[160:161], off
	v_mfma_f32_32x32x16_bf16 v[0:15], a[4:7], a[12:15], v[0:15]
	s_nop 0
	s_nop 0
	s_nop 0
	s_nop 0
	ds_read_b128 a[0:3], v87 offset:32768
	ds_read_b128 a[4:7], v87 offset:36864
	ds_read_b128 a[8:11], v86
	ds_read_b128 a[12:15], v86 offset:4096
	s_waitcnt lgkmcnt(5)
	v_mfma_f32_32x32x16_bf16 v[48:63], a[16:19], a[24:27], v[48:63]
	v_mfma_f32_32x32x16_bf16 v[32:47], a[20:23], a[24:27], v[32:47]
	s_and_b32 m0, s32, 7
	s_lshl_b32 m0, m0, 12
	s_add_i32 m0, m0, 0x18800
	s_nop 0
	global_load_lds_dwordx4 v[162:163], off
	s_waitcnt lgkmcnt(4)
	v_mfma_f32_32x32x16_bf16 v[16:31], a[16:19], a[28:31], v[16:31]
	v_mfma_f32_32x32x16_bf16 v[0:15], a[20:23], a[28:31], v[0:15]
	s_nop 0
	s_nop 0
	s_nop 0
	s_nop 0
	ds_read_b128 a[16:19], v89 offset:32768
	ds_read_b128 a[20:23], v89 offset:36864
	ds_read_b128 a[24:27], v88
	ds_read_b128 a[28:31], v88 offset:4096
	s_waitcnt lgkmcnt(5)
	v_mfma_f32_32x32x16_bf16 v[48:63], a[0:3], a[8:11], v[48:63]
	s_and_b32 m0, s32, 7
	s_lshl_b32 m0, m0, 12
	s_add_i32 m0, m0, 0x18c00
	s_nop 0
	global_load_lds_dwordx4 v[164:165], off
	v_mfma_f32_32x32x16_bf16 v[32:47], a[4:7], a[8:11], v[32:47]
	s_waitcnt lgkmcnt(4)
	v_mfma_f32_32x32x16_bf16 v[16:31], a[0:3], a[12:15], v[16:31]
	v_mfma_f32_32x32x16_bf16 v[0:15], a[4:7], a[12:15], v[0:15]
	s_and_b32 m0, s32, 7
	s_lshl_b32 m0, m0, 11
	s_add_i32 m0, m0, 0x20000
	s_nop 0
	global_load_lds_dwordx4 v[166:167], off
	s_nop 0
	s_nop 0
	s_nop 0
	s_nop 0
	s_waitcnt lgkmcnt(1)
	v_mfma_f32_32x32x16_bf16 v[48:63], a[16:19], a[24:27], v[48:63]
	v_mfma_f32_32x32x16_bf16 v[32:47], a[20:23], a[24:27], v[32:47]
	s_and_b32 m0, s32, 7
	s_lshl_b32 m0, m0, 11
	s_add_i32 m0, m0, 0x20400
	s_nop 0
	global_load_lds_dwordx4 v[168:169], off
	s_waitcnt vmcnt(6)
	s_waitcnt lgkmcnt(0)
	s_barrier
	ds_read_b128 a[12:15], v82 offset:53248
	ds_read_b128 a[8:11], v82 offset:49152
	ds_read_b128 a[4:7], v90
	ds_read_b128 a[0:3], v92
	v_mfma_f32_32x32x16_bf16 v[16:31], a[16:19], a[28:31], v[16:31]
	v_lshl_add_u64 v[170:171], v[66:67], 0, s[46:47]
	s_nop 0
	v_lshl_add_u64 v[172:173], v[68:69], 0, s[46:47]
	s_nop 0
	s_nop 0
	s_nop 0
	v_lshl_add_u64 v[174:175], v[70:71], 0, s[46:47]
	s_nop 0
	v_mfma_f32_32x32x16_bf16 v[0:15], a[20:23], a[28:31], v[0:15]
	s_and_b32 m0, s32, 7
	s_lshl_b32 m0, m0, 12
	s_add_i32 m0, m0, 0x0
	s_nop 0
	global_load_lds_dwordx4 v[170:171], off
	s_nop 0
	v_lshl_add_u64 v[176:177], v[72:73], 0, s[46:47]
	s_nop 0
	s_mov_b64 s[38:39], 0x380
	s_nop 0
	v_lshl_add_u64 v[178:179], v[74:75], 0, s[46:47]
	s_nop 0
	v_readfirstlane_b32 s48, v117
	s_nop 0
	v_lshl_add_u64 v[180:181], v[76:77], 0, s[46:47]
	s_nop 0
	s_mov_b64 s[46:47], 0x580
	s_nop 0
	s_nop 0
	s_nop 0
	s_nop 0
	s_nop 0
	ds_read_b128 a[16:19], v93
	ds_read_b128 a[20:23], v91
	ds_read_b128 a[24:27], v84 offset:49152
	ds_read_b128 a[28:31], v84 offset:53248
	s_waitcnt lgkmcnt(4)
	v_mfma_f32_32x32x16_bf16 v[48:63], a[0:3], a[8:11], v[48:63]
	s_nop 0
	v_readfirstlane_b32 s49, v118
	v_readfirstlane_b32 s53, v119
	v_mfma_f32_32x32x16_bf16 v[32:47], a[4:7], a[8:11], v[32:47]
	v_mfma_f32_32x32x16_bf16 v[16:31], a[0:3], a[12:15], v[16:31]
	s_and_b32 m0, s32, 7
	s_lshl_b32 m0, m0, 12
	s_add_i32 m0, m0, 0x400
	s_nop 0
	global_load_lds_dwordx4 v[172:173], off
	v_mfma_f32_32x32x16_bf16 v[0:15], a[4:7], a[12:15], v[0:15]
	s_nop 0
	s_nop 0
	s_nop 0
	s_nop 0
	ds_read_b128 a[0:3], v95
	ds_read_b128 a[4:7], v94
	ds_read_b128 a[8:11], v86 offset:49152
	ds_read_b128 a[12:15], v86 offset:53248
	s_waitcnt lgkmcnt(5)
	v_mfma_f32_32x32x16_bf16 v[48:63], a[16:19], a[24:27], v[48:63]
	v_mfma_f32_32x32x16_bf16 v[32:47], a[20:23], a[24:27], v[32:47]
	s_and_b32 m0, s32, 7
	s_lshl_b32 m0, m0, 12
	s_add_i32 m0, m0, 0x800
	s_nop 0
	global_load_lds_dwordx4 v[174:175], off
	s_waitcnt lgkmcnt(4)
	v_mfma_f32_32x32x16_bf16 v[16:31], a[16:19], a[28:31], v[16:31]
	v_mfma_f32_32x32x16_bf16 v[0:15], a[20:23], a[28:31], v[0:15]
	s_nop 0
	s_nop 0
	s_nop 0
	s_nop 0
	ds_read_b128 a[16:19], v97
	ds_read_b128 a[20:23], v96
	ds_read_b128 a[24:27], v88 offset:49152
	ds_read_b128 a[28:31], v88 offset:53248
	s_waitcnt lgkmcnt(5)
	v_mfma_f32_32x32x16_bf16 v[48:63], a[0:3], a[8:11], v[48:63]
	s_and_b32 m0, s32, 7
	s_lshl_b32 m0, m0, 12
	s_add_i32 m0, m0, 0xc00
	s_nop 0
	global_load_lds_dwordx4 v[176:177], off
	v_mfma_f32_32x32x16_bf16 v[32:47], a[4:7], a[8:11], v[32:47]
	s_waitcnt lgkmcnt(4)
	v_mfma_f32_32x32x16_bf16 v[16:31], a[0:3], a[12:15], v[16:31]
	v_mfma_f32_32x32x16_bf16 v[0:15], a[4:7], a[12:15], v[0:15]
	s_and_b32 m0, s32, 7
	s_lshl_b32 m0, m0, 11
	s_add_i32 m0, m0, 0x8000
	s_nop 0
	global_load_lds_dwordx4 v[178:179], off
	s_nop 0
	s_nop 0
	s_nop 0
	s_nop 0
	s_waitcnt lgkmcnt(1)
	v_mfma_f32_32x32x16_bf16 v[48:63], a[16:19], a[24:27], v[48:63]
	v_mfma_f32_32x32x16_bf16 v[32:47], a[20:23], a[24:27], v[32:47]
	s_and_b32 m0, s32, 7
	s_lshl_b32 m0, m0, 11
	s_add_i32 m0, m0, 0x8400
	s_nop 0
	global_load_lds_dwordx4 v[180:181], off
	s_waitcnt vmcnt(6)
	s_waitcnt lgkmcnt(0)
	s_barrier
	ds_read_b128 a[12:15], v101
	ds_read_b128 a[8:11], v100
	ds_read_b128 a[4:7], v99
	ds_read_b128 a[0:3], v98
	v_mfma_f32_32x32x16_bf16 v[16:31], a[16:19], a[28:31], v[16:31]
	v_lshl_add_u64 v[158:159], v[66:67], 0, s[38:39]
	s_nop 0
	v_lshl_add_u64 v[160:161], v[68:69], 0, s[38:39]
	s_nop 0
	s_mov_b64 s[28:29], 0x400
	s_nop 0
	v_lshl_add_u64 v[162:163], v[70:71], 0, s[38:39]
	s_nop 0
	v_mfma_f32_32x32x16_bf16 v[0:15], a[20:23], a[28:31], v[0:15]
	s_and_b32 m0, s32, 7
	s_lshl_b32 m0, m0, 12
	s_add_i32 m0, m0, 0xc000
	s_nop 0
	global_load_lds_dwordx4 v[158:159], off
	s_nop 0
	v_lshl_add_u64 v[164:165], v[72:73], 0, s[38:39]
	s_nop 0
	v_readfirstlane_b32 s33, v122
	s_nop 0
	v_lshl_add_u64 v[166:167], v[74:75], 0, s[38:39]
	s_nop 0
	v_readfirstlane_b32 s34, v123
	s_nop 0
	v_lshl_add_u64 v[168:169], v[76:77], 0, s[38:39]
	s_nop 0
	s_mov_b64 s[36:37], 0x500
	s_nop 0
	s_nop 0
	s_nop 0
	s_nop 0
	s_nop 0
	ds_read_b128 a[16:19], v102
	ds_read_b128 a[20:23], v103
	ds_read_b128 a[24:27], v104
	ds_read_b128 a[28:31], v105
	s_waitcnt lgkmcnt(4)
	v_mfma_f32_32x32x16_bf16 v[48:63], a[0:3], a[8:11], v[48:63]
	s_nop 0
	v_readfirstlane_b32 s0, v126
	v_readfirstlane_b32 s35, v124
	v_readfirstlane_b32 s38, v115
	v_readfirstlane_b32 s39, v116
	v_mfma_f32_32x32x16_bf16 v[32:47], a[4:7], a[8:11], v[32:47]
	v_mfma_f32_32x32x16_bf16 v[16:31], a[0:3], a[12:15], v[16:31]
	s_and_b32 m0, s32, 7
	s_lshl_b32 m0, m0, 12
	s_add_i32 m0, m0, 0xc400
	s_nop 0
	global_load_lds_dwordx4 v[160:161], off
	v_mfma_f32_32x32x16_bf16 v[0:15], a[4:7], a[12:15], v[0:15]
	s_nop 0
	s_nop 0
	s_nop 0
	s_nop 0
	ds_read_b128 a[0:3], v106
	ds_read_b128 a[4:7], v107
	ds_read_b128 a[8:11], v108
	ds_read_b128 a[12:15], v109
	s_waitcnt lgkmcnt(5)
	v_mfma_f32_32x32x16_bf16 v[48:63], a[16:19], a[24:27], v[48:63]
	v_mfma_f32_32x32x16_bf16 v[32:47], a[20:23], a[24:27], v[32:47]
	s_and_b32 m0, s32, 7
	s_lshl_b32 m0, m0, 12
	s_add_i32 m0, m0, 0xc800
	s_nop 0
	global_load_lds_dwordx4 v[162:163], off
	s_waitcnt lgkmcnt(4)
	v_mfma_f32_32x32x16_bf16 v[16:31], a[16:19], a[28:31], v[16:31]
	v_mfma_f32_32x32x16_bf16 v[0:15], a[20:23], a[28:31], v[0:15]
	s_nop 0
	s_nop 0
	s_nop 0
	s_nop 0
	ds_read_b128 a[16:19], v110
	ds_read_b128 a[20:23], v111
	ds_read_b128 a[24:27], v112
	ds_read_b128 a[28:31], v113
	s_waitcnt lgkmcnt(5)
	v_mfma_f32_32x32x16_bf16 v[48:63], a[0:3], a[8:11], v[48:63]
	s_and_b32 m0, s32, 7
	s_lshl_b32 m0, m0, 12
	s_add_i32 m0, m0, 0xcc00
	s_nop 0
	global_load_lds_dwordx4 v[164:165], off
	v_mfma_f32_32x32x16_bf16 v[32:47], a[4:7], a[8:11], v[32:47]
	s_waitcnt lgkmcnt(4)
	v_mfma_f32_32x32x16_bf16 v[16:31], a[0:3], a[12:15], v[16:31]
	v_mfma_f32_32x32x16_bf16 v[0:15], a[4:7], a[12:15], v[0:15]
	s_and_b32 m0, s32, 7
	s_lshl_b32 m0, m0, 11
	s_add_i32 m0, m0, 0x14000
	s_nop 0
	global_load_lds_dwordx4 v[166:167], off
	s_nop 0
	s_nop 0
	s_nop 0
	s_nop 0
	s_waitcnt lgkmcnt(1)
	v_mfma_f32_32x32x16_bf16 v[48:63], a[16:19], a[24:27], v[48:63]
	v_mfma_f32_32x32x16_bf16 v[32:47], a[20:23], a[24:27], v[32:47]
	s_and_b32 m0, s32, 7
	s_lshl_b32 m0, m0, 11
	s_add_i32 m0, m0, 0x14400
	s_nop 0
	global_load_lds_dwordx4 v[168:169], off
	s_waitcnt vmcnt(6)
	s_waitcnt lgkmcnt(0)
	s_barrier
	ds_read_b128 a[12:15], v82 offset:4096
	ds_read_b128 a[8:11], v82
	ds_read_b128 a[4:7], v83 offset:36864
	ds_read_b128 a[0:3], v83 offset:32768
	v_mfma_f32_32x32x16_bf16 v[16:31], a[16:19], a[28:31], v[16:31]
	v_lshl_add_u64 v[170:171], v[66:67], 0, s[28:29]
	s_nop 0
	v_lshl_add_u64 v[172:173], v[68:69], 0, s[28:29]
	s_nop 0
	v_readfirstlane_b32 s1, v127
	s_nop 0
	v_lshl_add_u64 v[174:175], v[70:71], 0, s[28:29]
	s_nop 0
	v_mfma_f32_32x32x16_bf16 v[0:15], a[20:23], a[28:31], v[0:15]
	s_and_b32 m0, s32, 7
	s_lshl_b32 m0, m0, 12
	s_add_i32 m0, m0, 0x18000
	s_nop 0
	global_load_lds_dwordx4 v[170:171], off
	s_nop 0
	v_lshl_add_u64 v[176:177], v[72:73], 0, s[28:29]
	s_nop 0
	v_readfirstlane_b32 s20, v128
	s_nop 0
	v_lshl_add_u64 v[178:179], v[74:75], 0, s[28:29]
	s_nop 0
	v_readfirstlane_b32 s21, v129
	s_nop 0
	v_lshl_add_u64 v[180:181], v[76:77], 0, s[28:29]
	s_nop 0
	s_mov_b64 s[28:29], 0x480
	s_nop 0
	s_nop 0
	s_nop 0
	s_nop 0
	s_nop 0
	ds_read_b128 a[16:19], v85 offset:32768
	ds_read_b128 a[20:23], v85 offset:36864
	ds_read_b128 a[24:27], v84
	ds_read_b128 a[28:31], v84 offset:4096
	s_waitcnt lgkmcnt(4)
	v_mfma_f32_32x32x16_bf16 v[48:63], a[0:3], a[8:11], v[48:63]
	s_nop 0
	v_lshl_add_u64 v[162:163], v[70:71], 0, s[28:29]
	v_readfirstlane_b32 s23, v131
	v_readfirstlane_b32 s24, v130
	v_mfma_f32_32x32x16_bf16 v[32:47], a[4:7], a[8:11], v[32:47]
	v_mfma_f32_32x32x16_bf16 v[16:31], a[0:3], a[12:15], v[16:31]
	s_and_b32 m0, s32, 7
	s_lshl_b32 m0, m0, 12
	s_add_i32 m0, m0, 0x18400
	s_nop 0
	global_load_lds_dwordx4 v[172:173], off
	v_mfma_f32_32x32x16_bf16 v[0:15], a[4:7], a[12:15], v[0:15]
	s_nop 0
	s_nop 0
	s_nop 0
	s_nop 0
	ds_read_b128 a[0:3], v87 offset:32768
	ds_read_b128 a[4:7], v87 offset:36864
	ds_read_b128 a[8:11], v86
	ds_read_b128 a[12:15], v86 offset:4096
	s_waitcnt lgkmcnt(5)
	v_mfma_f32_32x32x16_bf16 v[48:63], a[16:19], a[24:27], v[48:63]
	v_mfma_f32_32x32x16_bf16 v[32:47], a[20:23], a[24:27], v[32:47]
	s_and_b32 m0, s32, 7
	s_lshl_b32 m0, m0, 12
	s_add_i32 m0, m0, 0x18800
	s_nop 0
	global_load_lds_dwordx4 v[174:175], off
	s_waitcnt lgkmcnt(4)
	v_mfma_f32_32x32x16_bf16 v[16:31], a[16:19], a[28:31], v[16:31]
	v_mfma_f32_32x32x16_bf16 v[0:15], a[20:23], a[28:31], v[0:15]
	s_nop 0
	s_nop 0
	s_nop 0
	s_nop 0
	ds_read_b128 a[16:19], v89 offset:32768
	ds_read_b128 a[20:23], v89 offset:36864
	ds_read_b128 a[24:27], v88
	ds_read_b128 a[28:31], v88 offset:4096
	s_waitcnt lgkmcnt(5)
	v_mfma_f32_32x32x16_bf16 v[48:63], a[0:3], a[8:11], v[48:63]
	s_and_b32 m0, s32, 7
	s_lshl_b32 m0, m0, 12
	s_add_i32 m0, m0, 0x18c00
	s_nop 0
	global_load_lds_dwordx4 v[176:177], off
	v_mfma_f32_32x32x16_bf16 v[32:47], a[4:7], a[8:11], v[32:47]
	s_waitcnt lgkmcnt(4)
	v_mfma_f32_32x32x16_bf16 v[16:31], a[0:3], a[12:15], v[16:31]
	v_mfma_f32_32x32x16_bf16 v[0:15], a[4:7], a[12:15], v[0:15]
	s_and_b32 m0, s32, 7
	s_lshl_b32 m0, m0, 11
	s_add_i32 m0, m0, 0x20000
	s_nop 0
	global_load_lds_dwordx4 v[178:179], off
	s_nop 0
	s_nop 0
	s_nop 0
	s_nop 0
	s_waitcnt lgkmcnt(1)
	v_mfma_f32_32x32x16_bf16 v[48:63], a[16:19], a[24:27], v[48:63]
	v_mfma_f32_32x32x16_bf16 v[32:47], a[20:23], a[24:27], v[32:47]
	s_and_b32 m0, s32, 7
	s_lshl_b32 m0, m0, 11
	s_add_i32 m0, m0, 0x20400
	s_nop 0
	global_load_lds_dwordx4 v[180:181], off
	s_waitcnt vmcnt(6)
	s_waitcnt lgkmcnt(0)
	s_barrier
	ds_read_b128 a[12:15], v82 offset:53248
	ds_read_b128 a[8:11], v82 offset:49152
	ds_read_b128 a[4:7], v90
	ds_read_b128 a[0:3], v92
	v_mfma_f32_32x32x16_bf16 v[16:31], a[16:19], a[28:31], v[16:31]
	v_lshl_add_u64 v[158:159], v[66:67], 0, s[28:29]
	s_nop 0
	v_lshl_add_u64 v[160:161], v[68:69], 0, s[28:29]
	s_nop 0
	s_nop 0
	s_nop 0
	s_nop 0
	v_mfma_f32_32x32x16_bf16 v[0:15], a[20:23], a[28:31], v[0:15]
	s_and_b32 m0, s32, 7
	s_lshl_b32 m0, m0, 12
	s_add_i32 m0, m0, 0x0
	s_nop 0
	global_load_lds_dwordx4 v[158:159], off
	s_nop 0
	v_lshl_add_u64 v[164:165], v[72:73], 0, s[28:29]
	s_nop 0
	s_nop 0
	s_nop 0
	v_lshl_add_u64 v[166:167], v[74:75], 0, s[28:29]
	s_nop 0
	s_nop 0
	s_nop 0
	v_lshl_add_u64 v[168:169], v[76:77], 0, s[28:29]
	s_nop 0
	v_readfirstlane_b32 s28, v120
	s_nop 0
	s_nop 0
	s_nop 0
	s_nop 0
	s_nop 0
	ds_read_b128 a[16:19], v93
	ds_read_b128 a[20:23], v91
	ds_read_b128 a[24:27], v84 offset:49152
	ds_read_b128 a[28:31], v84 offset:53248
	s_waitcnt lgkmcnt(4)
	v_mfma_f32_32x32x16_bf16 v[48:63], a[0:3], a[8:11], v[48:63]
	s_nop 0
	v_readfirstlane_b32 s29, v121
	v_lshl_add_u64 v[174:175], v[70:71], 0, s[36:37]
	v_mfma_f32_32x32x16_bf16 v[32:47], a[4:7], a[8:11], v[32:47]
	v_mfma_f32_32x32x16_bf16 v[16:31], a[0:3], a[12:15], v[16:31]
	s_and_b32 m0, s32, 7
	s_lshl_b32 m0, m0, 12
	s_add_i32 m0, m0, 0x400
	s_nop 0
	global_load_lds_dwordx4 v[160:161], off
	v_mfma_f32_32x32x16_bf16 v[0:15], a[4:7], a[12:15], v[0:15]
	s_nop 0
	s_nop 0
	s_nop 0
	s_nop 0
	ds_read_b128 a[0:3], v95
	ds_read_b128 a[4:7], v94
	ds_read_b128 a[8:11], v86 offset:49152
	ds_read_b128 a[12:15], v86 offset:53248
	s_waitcnt lgkmcnt(5)
	v_mfma_f32_32x32x16_bf16 v[48:63], a[16:19], a[24:27], v[48:63]
	v_mfma_f32_32x32x16_bf16 v[32:47], a[20:23], a[24:27], v[32:47]
	s_and_b32 m0, s32, 7
	s_lshl_b32 m0, m0, 12
	s_add_i32 m0, m0, 0x800
	s_nop 0
	global_load_lds_dwordx4 v[162:163], off
	s_waitcnt lgkmcnt(4)
	v_mfma_f32_32x32x16_bf16 v[16:31], a[16:19], a[28:31], v[16:31]
	v_mfma_f32_32x32x16_bf16 v[0:15], a[20:23], a[28:31], v[0:15]
	s_nop 0
	s_nop 0
	s_nop 0
	s_nop 0
	ds_read_b128 a[16:19], v97
	ds_read_b128 a[20:23], v96
	ds_read_b128 a[24:27], v88 offset:49152
	ds_read_b128 a[28:31], v88 offset:53248
	s_waitcnt lgkmcnt(5)
	v_mfma_f32_32x32x16_bf16 v[48:63], a[0:3], a[8:11], v[48:63]
	s_and_b32 m0, s32, 7
	s_lshl_b32 m0, m0, 12
	s_add_i32 m0, m0, 0xc00
	s_nop 0
	global_load_lds_dwordx4 v[164:165], off
	v_mfma_f32_32x32x16_bf16 v[32:47], a[4:7], a[8:11], v[32:47]
	s_waitcnt lgkmcnt(4)
	v_mfma_f32_32x32x16_bf16 v[16:31], a[0:3], a[12:15], v[16:31]
	v_mfma_f32_32x32x16_bf16 v[0:15], a[4:7], a[12:15], v[0:15]
	s_and_b32 m0, s32, 7
	s_lshl_b32 m0, m0, 11
	s_add_i32 m0, m0, 0x8000
	s_nop 0
	global_load_lds_dwordx4 v[166:167], off
	s_nop 0
	s_nop 0
	s_nop 0
	s_nop 0
	s_waitcnt lgkmcnt(1)
	v_mfma_f32_32x32x16_bf16 v[48:63], a[16:19], a[24:27], v[48:63]
	v_mfma_f32_32x32x16_bf16 v[32:47], a[20:23], a[24:27], v[32:47]
	s_and_b32 m0, s32, 7
	s_lshl_b32 m0, m0, 11
	s_add_i32 m0, m0, 0x8400
	s_nop 0
	global_load_lds_dwordx4 v[168:169], off
	s_waitcnt vmcnt(6)
	s_waitcnt lgkmcnt(0)
	s_barrier
	ds_read_b128 a[12:15], v101
	ds_read_b128 a[8:11], v100
	ds_read_b128 a[4:7], v99
	ds_read_b128 a[0:3], v98
	v_mfma_f32_32x32x16_bf16 v[16:31], a[16:19], a[28:31], v[16:31]
	v_lshl_add_u64 v[170:171], v[66:67], 0, s[36:37]
	s_nop 0
	v_lshl_add_u64 v[172:173], v[68:69], 0, s[36:37]
	s_nop 0
	s_nop 0
	s_nop 0
	s_nop 0
	v_mfma_f32_32x32x16_bf16 v[0:15], a[20:23], a[28:31], v[0:15]
	s_and_b32 m0, s32, 7
	s_lshl_b32 m0, m0, 12
	s_add_i32 m0, m0, 0xc000
	s_nop 0
	global_load_lds_dwordx4 v[170:171], off
	s_nop 0
	v_lshl_add_u64 v[176:177], v[72:73], 0, s[36:37]
	s_nop 0
	s_nop 0
	s_nop 0
	v_lshl_add_u64 v[178:179], v[74:75], 0, s[36:37]
	s_nop 0
	s_nop 0
	s_nop 0
	v_lshl_add_u64 v[180:181], v[76:77], 0, s[36:37]
	v_readfirstlane_b32 s36, v125
	s_nop 0
	v_readfirstlane_b32 s37, v114
	s_nop 0
	s_nop 0
	s_nop 0
	s_nop 0
	s_nop 0
	ds_read_b128 a[16:19], v102
	ds_read_b128 a[20:23], v103
	ds_read_b128 a[24:27], v104
	ds_read_b128 a[28:31], v105
	s_waitcnt lgkmcnt(4)
	v_mfma_f32_32x32x16_bf16 v[48:63], a[0:3], a[8:11], v[48:63]
	s_nop 0
	v_lshl_add_u64 v[162:163], v[70:71], 0, s[46:47]
	v_mfma_f32_32x32x16_bf16 v[32:47], a[4:7], a[8:11], v[32:47]
	v_mfma_f32_32x32x16_bf16 v[16:31], a[0:3], a[12:15], v[16:31]
	s_and_b32 m0, s32, 7
	s_lshl_b32 m0, m0, 12
	s_add_i32 m0, m0, 0xc400
	s_nop 0
	global_load_lds_dwordx4 v[172:173], off
	v_mfma_f32_32x32x16_bf16 v[0:15], a[4:7], a[12:15], v[0:15]
	s_nop 0
	s_nop 0
	s_nop 0
	s_nop 0
	ds_read_b128 a[0:3], v106
	ds_read_b128 a[4:7], v107
	ds_read_b128 a[8:11], v108
	ds_read_b128 a[12:15], v109
	s_waitcnt lgkmcnt(5)
	v_mfma_f32_32x32x16_bf16 v[48:63], a[16:19], a[24:27], v[48:63]
	v_mfma_f32_32x32x16_bf16 v[32:47], a[20:23], a[24:27], v[32:47]
	s_and_b32 m0, s32, 7
	s_lshl_b32 m0, m0, 12
	s_add_i32 m0, m0, 0xc800
	s_nop 0
	global_load_lds_dwordx4 v[174:175], off
	s_waitcnt lgkmcnt(4)
	v_mfma_f32_32x32x16_bf16 v[16:31], a[16:19], a[28:31], v[16:31]
	v_mfma_f32_32x32x16_bf16 v[0:15], a[20:23], a[28:31], v[0:15]
	s_nop 0
	s_nop 0
	s_nop 0
	s_nop 0
	ds_read_b128 a[16:19], v110
	ds_read_b128 a[20:23], v111
	ds_read_b128 a[24:27], v112
	ds_read_b128 a[28:31], v113
	s_waitcnt lgkmcnt(5)
	v_mfma_f32_32x32x16_bf16 v[48:63], a[0:3], a[8:11], v[48:63]
	s_and_b32 m0, s32, 7
	s_lshl_b32 m0, m0, 12
	s_add_i32 m0, m0, 0xcc00
	s_nop 0
	global_load_lds_dwordx4 v[176:177], off
	v_mfma_f32_32x32x16_bf16 v[32:47], a[4:7], a[8:11], v[32:47]
	s_waitcnt lgkmcnt(4)
	v_mfma_f32_32x32x16_bf16 v[16:31], a[0:3], a[12:15], v[16:31]
	v_mfma_f32_32x32x16_bf16 v[0:15], a[4:7], a[12:15], v[0:15]
	s_and_b32 m0, s32, 7
	s_lshl_b32 m0, m0, 11
	s_add_i32 m0, m0, 0x14000
	s_nop 0
	global_load_lds_dwordx4 v[178:179], off
	s_nop 0
	s_nop 0
	s_nop 0
	s_nop 0
	s_waitcnt lgkmcnt(1)
	v_mfma_f32_32x32x16_bf16 v[48:63], a[16:19], a[24:27], v[48:63]
	v_mfma_f32_32x32x16_bf16 v[32:47], a[20:23], a[24:27], v[32:47]
	s_and_b32 m0, s32, 7
	s_lshl_b32 m0, m0, 11
	s_add_i32 m0, m0, 0x14400
	s_nop 0
	global_load_lds_dwordx4 v[180:181], off
	s_waitcnt vmcnt(6)
	s_waitcnt lgkmcnt(0)
	s_barrier
	ds_read_b128 a[12:15], v82 offset:4096
	ds_read_b128 a[8:11], v82
	ds_read_b128 a[4:7], v83 offset:36864
	ds_read_b128 a[0:3], v83 offset:32768
	v_mfma_f32_32x32x16_bf16 v[16:31], a[16:19], a[28:31], v[16:31]
	v_lshl_add_u64 v[158:159], v[66:67], 0, s[46:47]
	s_nop 0
	v_lshl_add_u64 v[160:161], v[68:69], 0, s[46:47]
	s_nop 0
	s_nop 0
	s_nop 0
	s_nop 0
	v_mfma_f32_32x32x16_bf16 v[0:15], a[20:23], a[28:31], v[0:15]
	s_and_b32 m0, s32, 7
	s_lshl_b32 m0, m0, 12
	s_add_i32 m0, m0, 0x18000
	s_nop 0
	global_load_lds_dwordx4 v[158:159], off
	s_nop 0
	v_lshl_add_u64 v[164:165], v[72:73], 0, s[46:47]
	s_nop 0
	s_nop 0
	s_nop 0
	v_lshl_add_u64 v[166:167], v[74:75], 0, s[46:47]
	s_nop 0
	s_nop 0
	s_nop 0
	v_lshl_add_u64 v[168:169], v[76:77], 0, s[46:47]
	s_nop 0
	s_mov_b64 s[46:47], 0x600
	s_nop 0
	s_nop 0
	s_nop 0
	s_nop 0
	s_nop 0
	ds_read_b128 a[16:19], v85 offset:32768
	ds_read_b128 a[20:23], v85 offset:36864
	ds_read_b128 a[24:27], v84
	ds_read_b128 a[28:31], v84 offset:4096
	s_waitcnt lgkmcnt(4)
	v_mfma_f32_32x32x16_bf16 v[48:63], a[0:3], a[8:11], v[48:63]
	s_nop 0
	v_mfma_f32_32x32x16_bf16 v[32:47], a[4:7], a[8:11], v[32:47]
	v_mfma_f32_32x32x16_bf16 v[16:31], a[0:3], a[12:15], v[16:31]
	s_and_b32 m0, s32, 7
	s_lshl_b32 m0, m0, 12
	s_add_i32 m0, m0, 0x18400
	s_nop 0
	global_load_lds_dwordx4 v[160:161], off
	v_mfma_f32_32x32x16_bf16 v[0:15], a[4:7], a[12:15], v[0:15]
	s_nop 0
	s_nop 0
	s_nop 0
	s_nop 0
	ds_read_b128 a[0:3], v87 offset:32768
	ds_read_b128 a[4:7], v87 offset:36864
	ds_read_b128 a[8:11], v86
	ds_read_b128 a[12:15], v86 offset:4096
	s_waitcnt lgkmcnt(5)
	v_mfma_f32_32x32x16_bf16 v[48:63], a[16:19], a[24:27], v[48:63]
	v_mfma_f32_32x32x16_bf16 v[32:47], a[20:23], a[24:27], v[32:47]
	s_and_b32 m0, s32, 7
	s_lshl_b32 m0, m0, 12
	s_add_i32 m0, m0, 0x18800
	s_nop 0
	global_load_lds_dwordx4 v[162:163], off
	s_waitcnt lgkmcnt(4)
	v_mfma_f32_32x32x16_bf16 v[16:31], a[16:19], a[28:31], v[16:31]
	v_mfma_f32_32x32x16_bf16 v[0:15], a[20:23], a[28:31], v[0:15]
	s_nop 0
	s_nop 0
	s_nop 0
	s_nop 0
	ds_read_b128 a[16:19], v89 offset:32768
	ds_read_b128 a[20:23], v89 offset:36864
	ds_read_b128 a[24:27], v88
	ds_read_b128 a[28:31], v88 offset:4096
	s_waitcnt lgkmcnt(5)
	v_mfma_f32_32x32x16_bf16 v[48:63], a[0:3], a[8:11], v[48:63]
	s_and_b32 m0, s32, 7
	s_lshl_b32 m0, m0, 12
	s_add_i32 m0, m0, 0x18c00
	s_nop 0
	global_load_lds_dwordx4 v[164:165], off
	v_mfma_f32_32x32x16_bf16 v[32:47], a[4:7], a[8:11], v[32:47]
	s_waitcnt lgkmcnt(4)
	v_mfma_f32_32x32x16_bf16 v[16:31], a[0:3], a[12:15], v[16:31]
	v_mfma_f32_32x32x16_bf16 v[0:15], a[4:7], a[12:15], v[0:15]
	s_and_b32 m0, s32, 7
	s_lshl_b32 m0, m0, 11
	s_add_i32 m0, m0, 0x20000
	s_nop 0
	global_load_lds_dwordx4 v[166:167], off
	s_nop 0
	s_nop 0
	s_nop 0
	s_nop 0
	s_waitcnt lgkmcnt(1)
	v_mfma_f32_32x32x16_bf16 v[48:63], a[16:19], a[24:27], v[48:63]
	v_mfma_f32_32x32x16_bf16 v[32:47], a[20:23], a[24:27], v[32:47]
	s_and_b32 m0, s32, 7
	s_lshl_b32 m0, m0, 11
	s_add_i32 m0, m0, 0x20400
	s_nop 0
	global_load_lds_dwordx4 v[168:169], off
	s_waitcnt vmcnt(6)
	s_waitcnt lgkmcnt(0)
	s_barrier
	ds_read_b128 a[12:15], v82 offset:53248
	ds_read_b128 a[8:11], v82 offset:49152
	ds_read_b128 a[4:7], v90
	ds_read_b128 a[0:3], v92
	v_mfma_f32_32x32x16_bf16 v[16:31], a[16:19], a[28:31], v[16:31]
	v_lshl_add_u64 v[170:171], v[66:67], 0, s[46:47]
	s_nop 0
	v_lshl_add_u64 v[172:173], v[68:69], 0, s[46:47]
	s_nop 0
	s_nop 0
	s_nop 0
	v_lshl_add_u64 v[174:175], v[70:71], 0, s[46:47]
	s_nop 0
	v_mfma_f32_32x32x16_bf16 v[0:15], a[20:23], a[28:31], v[0:15]
	s_and_b32 m0, s32, 7
	s_lshl_b32 m0, m0, 12
	s_add_i32 m0, m0, 0x0
	s_nop 0
	global_load_lds_dwordx4 v[170:171], off
	s_nop 0
	v_lshl_add_u64 v[176:177], v[72:73], 0, s[46:47]
	s_nop 0
	s_nop 0
	s_nop 0
	v_lshl_add_u64 v[178:179], v[74:75], 0, s[46:47]
	s_nop 0
	s_nop 0
	s_nop 0
	v_lshl_add_u64 v[180:181], v[76:77], 0, s[46:47]
	s_nop 0
	s_mov_b64 s[46:47], 0x680
	s_nop 0
	s_nop 0
	s_nop 0
	s_nop 0
	s_nop 0
	ds_read_b128 a[16:19], v93
	ds_read_b128 a[20:23], v91
	ds_read_b128 a[24:27], v84 offset:49152
	ds_read_b128 a[28:31], v84 offset:53248
	s_waitcnt lgkmcnt(4)
	v_mfma_f32_32x32x16_bf16 v[48:63], a[0:3], a[8:11], v[48:63]
	s_nop 0
	v_mfma_f32_32x32x16_bf16 v[32:47], a[4:7], a[8:11], v[32:47]
	v_mfma_f32_32x32x16_bf16 v[16:31], a[0:3], a[12:15], v[16:31]
	s_and_b32 m0, s32, 7
	s_lshl_b32 m0, m0, 12
	s_add_i32 m0, m0, 0x400
	s_nop 0
	global_load_lds_dwordx4 v[172:173], off
	v_mfma_f32_32x32x16_bf16 v[0:15], a[4:7], a[12:15], v[0:15]
	s_nop 0
	s_nop 0
	s_nop 0
	s_nop 0
	ds_read_b128 a[0:3], v95
	ds_read_b128 a[4:7], v94
	ds_read_b128 a[8:11], v86 offset:49152
	ds_read_b128 a[12:15], v86 offset:53248
	s_waitcnt lgkmcnt(5)
	v_mfma_f32_32x32x16_bf16 v[48:63], a[16:19], a[24:27], v[48:63]
	v_mfma_f32_32x32x16_bf16 v[32:47], a[20:23], a[24:27], v[32:47]
	s_and_b32 m0, s32, 7
	s_lshl_b32 m0, m0, 12
	s_add_i32 m0, m0, 0x800
	s_nop 0
	global_load_lds_dwordx4 v[174:175], off
	s_waitcnt lgkmcnt(4)
	v_mfma_f32_32x32x16_bf16 v[16:31], a[16:19], a[28:31], v[16:31]
	v_mfma_f32_32x32x16_bf16 v[0:15], a[20:23], a[28:31], v[0:15]
	s_nop 0
	s_nop 0
	s_nop 0
	s_nop 0
	ds_read_b128 a[16:19], v97
	ds_read_b128 a[20:23], v96
	ds_read_b128 a[24:27], v88 offset:49152
	ds_read_b128 a[28:31], v88 offset:53248
	s_waitcnt lgkmcnt(5)
	v_mfma_f32_32x32x16_bf16 v[48:63], a[0:3], a[8:11], v[48:63]
	s_and_b32 m0, s32, 7
	s_lshl_b32 m0, m0, 12
	s_add_i32 m0, m0, 0xc00
	s_nop 0
	global_load_lds_dwordx4 v[176:177], off
	v_mfma_f32_32x32x16_bf16 v[32:47], a[4:7], a[8:11], v[32:47]
	s_waitcnt lgkmcnt(4)
	v_mfma_f32_32x32x16_bf16 v[16:31], a[0:3], a[12:15], v[16:31]
	v_mfma_f32_32x32x16_bf16 v[0:15], a[4:7], a[12:15], v[0:15]
	s_and_b32 m0, s32, 7
	s_lshl_b32 m0, m0, 11
	s_add_i32 m0, m0, 0x8000
	s_nop 0
	global_load_lds_dwordx4 v[178:179], off
	s_nop 0
	s_nop 0
	s_nop 0
	s_nop 0
	s_waitcnt lgkmcnt(1)
	v_mfma_f32_32x32x16_bf16 v[48:63], a[16:19], a[24:27], v[48:63]
	v_mfma_f32_32x32x16_bf16 v[32:47], a[20:23], a[24:27], v[32:47]
	s_and_b32 m0, s32, 7
	s_lshl_b32 m0, m0, 11
	s_add_i32 m0, m0, 0x8400
	s_nop 0
	global_load_lds_dwordx4 v[180:181], off
	s_waitcnt vmcnt(6)
	s_waitcnt lgkmcnt(0)
	s_barrier
	ds_read_b128 a[12:15], v101
	ds_read_b128 a[8:11], v100
	ds_read_b128 a[4:7], v99
	ds_read_b128 a[0:3], v98
	v_mfma_f32_32x32x16_bf16 v[16:31], a[16:19], a[28:31], v[16:31]
	v_lshl_add_u64 v[158:159], v[66:67], 0, s[46:47]
	s_nop 0
	v_lshl_add_u64 v[160:161], v[68:69], 0, s[46:47]
	s_nop 0
	s_mov_b64 s[28:29], 0x700
	s_nop 0
	v_lshl_add_u64 v[162:163], v[70:71], 0, s[46:47]
	s_nop 0
	v_mfma_f32_32x32x16_bf16 v[0:15], a[20:23], a[28:31], v[0:15]
	s_and_b32 m0, s32, 7
	s_lshl_b32 m0, m0, 12
	s_add_i32 m0, m0, 0xc000
	s_nop 0
	global_load_lds_dwordx4 v[158:159], off
	s_nop 0
	v_lshl_add_u64 v[164:165], v[72:73], 0, s[46:47]
	s_nop 0
	s_nop 0
	s_nop 0
	v_lshl_add_u64 v[166:167], v[74:75], 0, s[46:47]
	s_nop 0
	s_nop 0
	s_nop 0
	v_lshl_add_u64 v[168:169], v[76:77], 0, s[46:47]
	s_nop 0
	s_nop 0
	s_nop 0
	s_nop 0
	s_nop 0
	s_nop 0
	s_nop 0
	ds_read_b128 a[16:19], v102
	ds_read_b128 a[20:23], v103
	ds_read_b128 a[24:27], v104
	ds_read_b128 a[28:31], v105
	s_waitcnt lgkmcnt(4)
	v_mfma_f32_32x32x16_bf16 v[48:63], a[0:3], a[8:11], v[48:63]
	s_nop 0
	v_mfma_f32_32x32x16_bf16 v[32:47], a[4:7], a[8:11], v[32:47]
	v_mfma_f32_32x32x16_bf16 v[16:31], a[0:3], a[12:15], v[16:31]
	s_and_b32 m0, s32, 7
	s_lshl_b32 m0, m0, 12
	s_add_i32 m0, m0, 0xc400
	s_nop 0
	global_load_lds_dwordx4 v[160:161], off
	v_mfma_f32_32x32x16_bf16 v[0:15], a[4:7], a[12:15], v[0:15]
	s_nop 0
	s_nop 0
	s_nop 0
	s_nop 0
	ds_read_b128 a[0:3], v106
	ds_read_b128 a[4:7], v107
	ds_read_b128 a[8:11], v108
	ds_read_b128 a[12:15], v109
	s_waitcnt lgkmcnt(5)
	v_mfma_f32_32x32x16_bf16 v[48:63], a[16:19], a[24:27], v[48:63]
	v_mfma_f32_32x32x16_bf16 v[32:47], a[20:23], a[24:27], v[32:47]
	s_and_b32 m0, s32, 7
	s_lshl_b32 m0, m0, 12
	s_add_i32 m0, m0, 0xc800
	s_nop 0
	global_load_lds_dwordx4 v[162:163], off
	s_waitcnt lgkmcnt(4)
	v_mfma_f32_32x32x16_bf16 v[16:31], a[16:19], a[28:31], v[16:31]
	v_mfma_f32_32x32x16_bf16 v[0:15], a[20:23], a[28:31], v[0:15]
	s_nop 0
	s_nop 0
	s_nop 0
	s_nop 0
	ds_read_b128 a[16:19], v110
	ds_read_b128 a[20:23], v111
	ds_read_b128 a[24:27], v112
	ds_read_b128 a[28:31], v113
	s_waitcnt lgkmcnt(5)
	v_mfma_f32_32x32x16_bf16 v[48:63], a[0:3], a[8:11], v[48:63]
	s_and_b32 m0, s32, 7
	s_lshl_b32 m0, m0, 12
	s_add_i32 m0, m0, 0xcc00
	s_nop 0
	global_load_lds_dwordx4 v[164:165], off
	v_mfma_f32_32x32x16_bf16 v[32:47], a[4:7], a[8:11], v[32:47]
	s_waitcnt lgkmcnt(4)
	v_mfma_f32_32x32x16_bf16 v[16:31], a[0:3], a[12:15], v[16:31]
	v_mfma_f32_32x32x16_bf16 v[0:15], a[4:7], a[12:15], v[0:15]
	s_and_b32 m0, s32, 7
	s_lshl_b32 m0, m0, 11
	s_add_i32 m0, m0, 0x14000
	s_nop 0
	global_load_lds_dwordx4 v[166:167], off
	s_nop 0
	s_nop 0
	s_nop 0
	s_nop 0
	s_waitcnt lgkmcnt(1)
	v_mfma_f32_32x32x16_bf16 v[48:63], a[16:19], a[24:27], v[48:63]
	v_mfma_f32_32x32x16_bf16 v[32:47], a[20:23], a[24:27], v[32:47]
	s_and_b32 m0, s32, 7
	s_lshl_b32 m0, m0, 11
	s_add_i32 m0, m0, 0x14400
	s_nop 0
	global_load_lds_dwordx4 v[168:169], off
	s_waitcnt vmcnt(6)
	s_waitcnt lgkmcnt(0)
	s_barrier
	ds_read_b128 a[12:15], v82 offset:4096
	ds_read_b128 a[8:11], v82
	ds_read_b128 a[4:7], v83 offset:36864
	ds_read_b128 a[0:3], v83 offset:32768
	v_mfma_f32_32x32x16_bf16 v[16:31], a[16:19], a[28:31], v[16:31]
	v_lshl_add_u64 v[170:171], v[66:67], 0, s[28:29]
	s_nop 0
	v_lshl_add_u64 v[172:173], v[68:69], 0, s[28:29]
	s_nop 0
	s_nop 0
	s_nop 0
	v_lshl_add_u64 v[174:175], v[70:71], 0, s[28:29]
	s_nop 0
	v_mfma_f32_32x32x16_bf16 v[0:15], a[20:23], a[28:31], v[0:15]
	s_and_b32 m0, s32, 7
	s_lshl_b32 m0, m0, 12
	s_add_i32 m0, m0, 0x18000
	s_nop 0
	global_load_lds_dwordx4 v[170:171], off
	s_nop 0
	v_lshl_add_u64 v[176:177], v[72:73], 0, s[28:29]
	s_nop 0
	s_nop 0
	s_nop 0
	v_lshl_add_u64 v[178:179], v[74:75], 0, s[28:29]
	s_nop 0
	s_nop 0
	s_nop 0
	v_lshl_add_u64 v[180:181], v[76:77], 0, s[28:29]
	s_nop 0
	s_mov_b64 s[28:29], 0x780
	s_nop 0
	s_nop 0
	s_nop 0
	s_nop 0
	s_nop 0
	ds_read_b128 a[16:19], v85 offset:32768
	ds_read_b128 a[20:23], v85 offset:36864
	ds_read_b128 a[24:27], v84
	ds_read_b128 a[28:31], v84 offset:4096
	s_waitcnt lgkmcnt(4)
	v_mfma_f32_32x32x16_bf16 v[48:63], a[0:3], a[8:11], v[48:63]
	v_lshl_add_u64 v[158:159], v[66:67], 0, s[28:29]
	s_nop 0
	v_mfma_f32_32x32x16_bf16 v[32:47], a[4:7], a[8:11], v[32:47]
	v_mfma_f32_32x32x16_bf16 v[16:31], a[0:3], a[12:15], v[16:31]
	s_and_b32 m0, s32, 7
	s_lshl_b32 m0, m0, 12
	s_add_i32 m0, m0, 0x18400
	s_nop 0
	global_load_lds_dwordx4 v[172:173], off
	v_mfma_f32_32x32x16_bf16 v[0:15], a[4:7], a[12:15], v[0:15]
	s_nop 0
	s_nop 0
	s_nop 0
	s_nop 0
	ds_read_b128 a[0:3], v87 offset:32768
	ds_read_b128 a[4:7], v87 offset:36864
	ds_read_b128 a[8:11], v86
	ds_read_b128 a[12:15], v86 offset:4096
	s_waitcnt lgkmcnt(5)
	v_mfma_f32_32x32x16_bf16 v[48:63], a[16:19], a[24:27], v[48:63]
	v_mfma_f32_32x32x16_bf16 v[32:47], a[20:23], a[24:27], v[32:47]
	s_and_b32 m0, s32, 7
	s_lshl_b32 m0, m0, 12
	s_add_i32 m0, m0, 0x18800
	s_nop 0
	global_load_lds_dwordx4 v[174:175], off
	s_waitcnt lgkmcnt(4)
	v_mfma_f32_32x32x16_bf16 v[16:31], a[16:19], a[28:31], v[16:31]
	v_mfma_f32_32x32x16_bf16 v[0:15], a[20:23], a[28:31], v[0:15]
	s_nop 0
	s_nop 0
	s_nop 0
	s_nop 0
	ds_read_b128 a[16:19], v89 offset:32768
	ds_read_b128 a[20:23], v89 offset:36864
	ds_read_b128 a[24:27], v88
	ds_read_b128 a[28:31], v88 offset:4096
	s_waitcnt lgkmcnt(5)
	v_mfma_f32_32x32x16_bf16 v[48:63], a[0:3], a[8:11], v[48:63]
	s_and_b32 m0, s32, 7
	s_lshl_b32 m0, m0, 12
	s_add_i32 m0, m0, 0x18c00
	s_nop 0
	global_load_lds_dwordx4 v[176:177], off
	v_mfma_f32_32x32x16_bf16 v[32:47], a[4:7], a[8:11], v[32:47]
	s_waitcnt lgkmcnt(4)
	v_mfma_f32_32x32x16_bf16 v[16:31], a[0:3], a[12:15], v[16:31]
	v_mfma_f32_32x32x16_bf16 v[0:15], a[4:7], a[12:15], v[0:15]
	s_and_b32 m0, s32, 7
	s_lshl_b32 m0, m0, 11
	s_add_i32 m0, m0, 0x20000
	s_nop 0
	global_load_lds_dwordx4 v[178:179], off
	s_nop 0
	s_nop 0
	s_nop 0
	s_nop 0
	s_waitcnt lgkmcnt(1)
	v_mfma_f32_32x32x16_bf16 v[48:63], a[16:19], a[24:27], v[48:63]
	v_mfma_f32_32x32x16_bf16 v[32:47], a[20:23], a[24:27], v[32:47]
	s_and_b32 m0, s32, 7
	s_lshl_b32 m0, m0, 11
	s_add_i32 m0, m0, 0x20400
	s_nop 0
	global_load_lds_dwordx4 v[180:181], off
	s_waitcnt vmcnt(6)
	s_waitcnt lgkmcnt(0)
	s_barrier
	ds_read_b128 a[12:15], v82 offset:53248
	ds_read_b128 a[8:11], v82 offset:49152
	ds_read_b128 a[4:7], v90
	ds_read_b128 a[0:3], v92
	s_nop 0
	v_lshl_add_u64 v[160:161], v[68:69], 0, s[28:29]
	s_nop 0
	v_mfma_f32_32x32x16_bf16 v[16:31], a[16:19], a[28:31], v[16:31]
	s_nop 0
	v_lshl_add_u64 v[162:163], v[70:71], 0, s[28:29]
	s_nop 0
	v_cmp_eq_u32_e64 s[0:1], 0, v79
	s_nop 0
	v_lshl_add_u64 v[164:165], v[72:73], 0, s[28:29]
	s_nop 0
	v_mfma_f32_32x32x16_bf16 v[0:15], a[20:23], a[28:31], v[0:15]
	s_and_b32 m0, s32, 7
	s_lshl_b32 m0, m0, 12
	s_add_i32 m0, m0, 0x0
	s_nop 0
	global_load_lds_dwordx4 v[158:159], off
	s_nop 0
	v_lshl_add_u64 v[166:167], v[74:75], 0, s[28:29]
	s_nop 0
	v_readlane_b32 s20, v215, 52
	s_nop 0
	v_lshl_add_u64 v[168:169], v[76:77], 0, s[28:29]
	s_nop 0
	v_readlane_b32 s21, v215, 53
	s_nop 0
	s_nop 0
	s_nop 0
	s_nop 0
	s_nop 0
	ds_read_b128 a[16:19], v93
	ds_read_b128 a[20:23], v91
	ds_read_b128 a[24:27], v84 offset:49152
	ds_read_b128 a[28:31], v84 offset:53248
	s_waitcnt lgkmcnt(4)
	v_mfma_f32_32x32x16_bf16 v[48:63], a[0:3], a[8:11], v[48:63]
	s_mov_b32 s23, 0
	v_mfma_f32_32x32x16_bf16 v[32:47], a[4:7], a[8:11], v[32:47]
	v_mfma_f32_32x32x16_bf16 v[16:31], a[0:3], a[12:15], v[16:31]
	s_and_b32 m0, s32, 7
	s_lshl_b32 m0, m0, 12
	s_add_i32 m0, m0, 0x400
	s_nop 0
	global_load_lds_dwordx4 v[160:161], off
	v_mfma_f32_32x32x16_bf16 v[0:15], a[4:7], a[12:15], v[0:15]
	s_nop 0
	s_nop 0
	s_nop 0
	s_nop 0
	ds_read_b128 a[0:3], v95
	ds_read_b128 a[4:7], v94
	ds_read_b128 a[8:11], v86 offset:49152
	ds_read_b128 a[12:15], v86 offset:53248
	s_waitcnt lgkmcnt(5)
	v_mfma_f32_32x32x16_bf16 v[48:63], a[16:19], a[24:27], v[48:63]
	v_mfma_f32_32x32x16_bf16 v[32:47], a[20:23], a[24:27], v[32:47]
	s_and_b32 m0, s32, 7
	s_lshl_b32 m0, m0, 12
	s_add_i32 m0, m0, 0x800
	s_nop 0
	global_load_lds_dwordx4 v[162:163], off
	s_waitcnt lgkmcnt(4)
	v_mfma_f32_32x32x16_bf16 v[16:31], a[16:19], a[28:31], v[16:31]
	v_mfma_f32_32x32x16_bf16 v[0:15], a[20:23], a[28:31], v[0:15]
	s_nop 0
	s_nop 0
	s_nop 0
	s_nop 0
	ds_read_b128 a[16:19], v97
	ds_read_b128 a[20:23], v96
	ds_read_b128 a[24:27], v88 offset:49152
	ds_read_b128 a[28:31], v88 offset:53248
	s_waitcnt lgkmcnt(5)
	v_mfma_f32_32x32x16_bf16 v[48:63], a[0:3], a[8:11], v[48:63]
	s_and_b32 m0, s32, 7
	s_lshl_b32 m0, m0, 12
	s_add_i32 m0, m0, 0xc00
	s_nop 0
	global_load_lds_dwordx4 v[164:165], off
	v_mfma_f32_32x32x16_bf16 v[32:47], a[4:7], a[8:11], v[32:47]
	s_waitcnt lgkmcnt(4)
	v_mfma_f32_32x32x16_bf16 v[16:31], a[0:3], a[12:15], v[16:31]
	v_mfma_f32_32x32x16_bf16 v[0:15], a[4:7], a[12:15], v[0:15]
	s_and_b32 m0, s32, 7
	s_lshl_b32 m0, m0, 11
	s_add_i32 m0, m0, 0x8000
	s_nop 0
	global_load_lds_dwordx4 v[166:167], off
	s_nop 0
	s_nop 0
	s_nop 0
	s_nop 0
	s_waitcnt lgkmcnt(1)
	v_mfma_f32_32x32x16_bf16 v[48:63], a[16:19], a[24:27], v[48:63]
	v_mfma_f32_32x32x16_bf16 v[32:47], a[20:23], a[24:27], v[32:47]
	s_and_b32 m0, s32, 7
	s_lshl_b32 m0, m0, 11
	s_add_i32 m0, m0, 0x8400
	s_nop 0
	global_load_lds_dwordx4 v[168:169], off
	s_waitcnt vmcnt(6)
	s_waitcnt lgkmcnt(0)
	s_barrier
	ds_read_b128 a[12:15], v101
	ds_read_b128 a[8:11], v100
	ds_read_b128 a[4:7], v99
	ds_read_b128 a[0:3], v98
	v_mfma_f32_32x32x16_bf16 v[16:31], a[16:19], a[28:31], v[16:31]
	v_mfma_f32_32x32x16_bf16 v[0:15], a[20:23], a[28:31], v[0:15]
	s_nop 0
	s_nop 0
	s_nop 0
	s_nop 0
	ds_read_b128 a[16:19], v102
	ds_read_b128 a[20:23], v103
	ds_read_b128 a[24:27], v104
	ds_read_b128 a[28:31], v105
	s_waitcnt lgkmcnt(4)
	v_mfma_f32_32x32x16_bf16 v[48:63], a[0:3], a[8:11], v[48:63]
	v_mfma_f32_32x32x16_bf16 v[32:47], a[4:7], a[8:11], v[32:47]
	v_mfma_f32_32x32x16_bf16 v[16:31], a[0:3], a[12:15], v[16:31]
	v_mfma_f32_32x32x16_bf16 v[0:15], a[4:7], a[12:15], v[0:15]
	s_nop 0
	s_nop 0
	s_nop 0
	s_nop 0
	ds_read_b128 a[0:3], v106
	ds_read_b128 a[4:7], v107
	ds_read_b128 a[8:11], v108
	ds_read_b128 a[12:15], v109
	s_waitcnt lgkmcnt(5)
	v_mfma_f32_32x32x16_bf16 v[48:63], a[16:19], a[24:27], v[48:63]
	v_mfma_f32_32x32x16_bf16 v[32:47], a[20:23], a[24:27], v[32:47]
	s_waitcnt lgkmcnt(4)
	v_mfma_f32_32x32x16_bf16 v[16:31], a[16:19], a[28:31], v[16:31]
	v_mfma_f32_32x32x16_bf16 v[0:15], a[20:23], a[28:31], v[0:15]
	s_nop 0
	s_nop 0
	s_nop 0
	s_nop 0
	ds_read_b128 a[16:19], v110
	ds_read_b128 a[20:23], v111
	ds_read_b128 a[24:27], v112
	ds_read_b128 a[28:31], v113
	s_waitcnt lgkmcnt(5)
	v_mfma_f32_32x32x16_bf16 v[48:63], a[0:3], a[8:11], v[48:63]
	v_mfma_f32_32x32x16_bf16 v[32:47], a[4:7], a[8:11], v[32:47]
	s_waitcnt lgkmcnt(4)
	v_mfma_f32_32x32x16_bf16 v[16:31], a[0:3], a[12:15], v[16:31]
	v_mfma_f32_32x32x16_bf16 v[0:15], a[4:7], a[12:15], v[0:15]
	s_nop 0
	s_nop 0
	s_nop 0
	s_nop 0
	s_waitcnt lgkmcnt(1)
	v_mfma_f32_32x32x16_bf16 v[48:63], a[16:19], a[24:27], v[48:63]
	v_mfma_f32_32x32x16_bf16 v[32:47], a[20:23], a[24:27], v[32:47]
	s_waitcnt vmcnt(0)
	s_waitcnt lgkmcnt(0)
	s_barrier
	ds_read_b128 a[12:15], v82 offset:4096
	ds_read_b128 a[8:11], v82
	ds_read_b128 a[4:7], v83 offset:36864
	ds_read_b128 a[0:3], v83 offset:32768
	v_mfma_f32_32x32x16_bf16 v[16:31], a[16:19], a[28:31], v[16:31]
	v_mfma_f32_32x32x16_bf16 v[0:15], a[20:23], a[28:31], v[0:15]
	s_nop 0
	s_nop 0
	s_nop 0
	s_nop 0
	ds_read_b128 a[16:19], v85 offset:32768
	ds_read_b128 a[20:23], v85 offset:36864
	ds_read_b128 a[24:27], v84
	ds_read_b128 a[28:31], v84 offset:4096
	s_waitcnt lgkmcnt(4)
	v_mfma_f32_32x32x16_bf16 v[48:63], a[0:3], a[8:11], v[48:63]
	v_mfma_f32_32x32x16_bf16 v[32:47], a[4:7], a[8:11], v[32:47]
	v_mfma_f32_32x32x16_bf16 v[16:31], a[0:3], a[12:15], v[16:31]
	v_mfma_f32_32x32x16_bf16 v[0:15], a[4:7], a[12:15], v[0:15]
	s_nop 0
	s_nop 0
	s_nop 0
	s_nop 0
	ds_read_b128 a[0:3], v87 offset:32768
	ds_read_b128 a[4:7], v87 offset:36864
	ds_read_b128 a[8:11], v86
	ds_read_b128 a[12:15], v86 offset:4096
	s_waitcnt lgkmcnt(5)
	v_mfma_f32_32x32x16_bf16 v[48:63], a[16:19], a[24:27], v[48:63]
	v_mfma_f32_32x32x16_bf16 v[32:47], a[20:23], a[24:27], v[32:47]
	s_waitcnt lgkmcnt(4)
	v_mfma_f32_32x32x16_bf16 v[16:31], a[16:19], a[28:31], v[16:31]
	v_mfma_f32_32x32x16_bf16 v[0:15], a[20:23], a[28:31], v[0:15]
	s_nop 0
	s_nop 0
	s_nop 0
	s_waitcnt lgkmcnt(1)
	v_mfma_f32_32x32x16_bf16 v[48:63], a[0:3], a[8:11], v[48:63]
	v_mfma_f32_32x32x16_bf16 v[32:47], a[4:7], a[8:11], v[32:47]
	s_nop 0
	s_waitcnt lgkmcnt(0)
	v_mfma_f32_32x32x16_bf16 v[0:15], a[4:7], a[12:15], v[0:15]
	v_mfma_f32_32x32x16_bf16 v[16:31], a[0:3], a[12:15], v[16:31]
	ds_read_b128 v[66:69], v89 offset:32768
	ds_read_b128 v[70:73], v88
	ds_read_b128 v[74:77], v89 offset:36864
	ds_read_b128 v[82:85], v88 offset:4096
	s_waitcnt lgkmcnt(0)
	s_barrier
	s_waitcnt lgkmcnt(0)
	v_mfma_f32_32x32x16_bf16 v[48:63], v[66:69], v[70:73], v[48:63]
	v_mfma_f32_32x32x16_bf16 v[32:47], v[74:77], v[70:73], v[32:47]
	s_nop 10
	ds_write_b128 v64, v[48:51]
	ds_write_b128 v64, v[52:55] offset:32
	ds_write_b128 v64, v[56:59] offset:64
	ds_write_b128 v64, v[60:63] offset:96
	ds_write_b128 v64, v[32:35] offset:128
	v_mfma_f32_32x32x16_bf16 v[0:15], v[74:77], v[82:85], v[0:15]
	v_mfma_f32_32x32x16_bf16 v[16:31], v[66:69], v[82:85], v[16:31]
	ds_write_b128 v64, v[36:39] offset:160
	ds_write_b128 v64, v[40:43] offset:192
	ds_write_b128 v64, v[44:47] offset:224
	s_nop 8
	ds_write_b128 v64, v[16:19] offset:16896
	ds_write_b128 v64, v[20:23] offset:16928
	ds_write_b128 v64, v[24:27] offset:16960
	ds_write_b128 v64, v[28:31] offset:16992
	ds_write_b128 v64, v[0:3] offset:17024
	ds_write_b128 v64, v[4:7] offset:17056
	ds_write_b128 v64, v[8:11] offset:17088
	ds_write_b128 v64, v[12:15] offset:17120
	s_waitcnt lgkmcnt(0)
	s_barrier
	v_lshl_or_b32 v0, v79, 2, s31
	v_ashrrev_i32_e32 v1, 31, v0
	v_lshl_add_u32 v4, v79, 4, 0
	v_lshl_add_u64 v[6:7], v[0:1], 2, s[92:93]
	v_lshl_add_u64 v[8:9], v[0:1], 1, s[20:21]
	s_branch .LBB0_161

.LBB0_585:
	s_and_b64 vcc, exec, s[0:1]
	s_cbranch_vccz .LBB0_518
	s_mul_hi_i32 s0, s33, 0x51eb851f
	s_lshr_b32 s1, s0, 31
	s_ashr_i32 s0, s0, 3
	v_mov_b32_e32 v78, v133
	s_add_i32 s21, s0, s1
	s_lshl_b32 s20, s21, 8
	v_ashrrev_i32_e32 v6, 6, v78
	v_bfe_u32 v7, v78, 3, 3
	v_lshl_or_b32 v8, v6, 5, v7
	v_add_u32_e32 v0, s20, v8
	s_waitcnt lgkmcnt(0)
	v_ashrrev_i32_e32 v1, 31, v0
	v_lshlrev_b64 v[2:3], 11, v[0:1]
	v_bfe_u32 v1, v78, 4, 2
	v_readlane_b32 s0, v215, 52
	v_xor_b32_e32 v1, v1, v78
	v_readlane_b32 s1, v215, 53
	v_lshlrev_b32_e32 v1, 4, v1
	v_and_b32_e32 v64, 0x70, v1
	v_lshl_add_u64 v[2:3], s[0:1], 0, v[2:3]
	v_or_b32_e32 v1, 8, v8
	v_lshl_add_u64 v[66:67], v[2:3], 0, v[64:65]
	v_add_u32_e32 v2, s20, v1
	v_lshrrev_b32_e32 v1, 1, v1
	v_xor_b32_e32 v1, v1, v78
	v_ashrrev_i32_e32 v3, 31, v2
	v_lshlrev_b32_e32 v1, 4, v1
	v_or_b32_e32 v0, 16, v0
	v_lshlrev_b64 v[2:3], 11, v[2:3]
	v_and_b32_e32 v4, 0x70, v1
	v_ashrrev_i32_e32 v1, 31, v0
	v_lshl_add_u64 v[2:3], s[0:1], 0, v[2:3]
	v_mov_b32_e32 v5, v65
	v_lshlrev_b64 v[0:1], 11, v[0:1]
	v_lshl_add_u64 v[68:69], v[2:3], 0, v[4:5]
	v_lshl_add_u64 v[0:1], s[0:1], 0, v[0:1]
	v_or_b32_e32 v2, 24, v8
	v_lshl_add_u64 v[70:71], v[0:1], 0, v[64:65]
	v_add_u32_e32 v0, s20, v2
	v_lshrrev_b32_e32 v2, 1, v2
	v_ashrrev_i32_e32 v1, 31, v0
	v_xor_b32_e32 v2, v2, v78
	v_lshlrev_b64 v[0:1], 11, v[0:1]
	v_lshlrev_b32_e32 v2, 4, v2
	v_lshl_add_u64 v[0:1], s[0:1], 0, v[0:1]
	v_and_b32_e32 v2, 0x70, v2
	v_mov_b32_e32 v3, v65
	v_lshl_or_b32 v4, v6, 4, v7
	s_mulk_i32 s21, 0xc80
	v_lshl_add_u64 v[72:73], v[0:1], 0, v[2:3]
	v_subrev_u32_e32 v0, s21, v4
	v_add_u32_e32 v0, s23, v0
	v_ashrrev_i32_e32 v1, 31, v0
	v_lshlrev_b64 v[2:3], 11, v[0:1]
	v_lshl_add_u64 v[2:3], s[96:97], 0, v[2:3]
	v_lshl_add_u64 v[74:75], v[2:3], 0, v[64:65]
	v_lshlrev_b32_e32 v3, 12, v6
	v_add_u32_e32 v126, 0, v3
	s_waitcnt vmcnt(0)
	v_add_u32_e32 v127, 0x400, v126
	v_readfirstlane_b32 s41, v126
	v_or_b32_e32 v2, 8, v4
	s_waitcnt lgkmcnt(0)
	s_barrier
	s_mov_b32 m0, s41
	v_readfirstlane_b32 s42, v127
	v_add_u32_e32 v128, 0x800, v126
	v_lshlrev_b32_e32 v5, 11, v6
	v_and_b32_e32 v79, 1, v6
	v_add_u32_e32 v0, 8, v0
	v_lshrrev_b32_e32 v2, 1, v2
	global_load_lds_dwordx4 v[66:67], off
	s_mov_b32 m0, s42
	v_readfirstlane_b32 s43, v128
	v_add_u32_e32 v129, 0xc00, v126
	v_add_u32_e32 v6, 0, v5
	v_ashrrev_i32_e32 v1, 31, v0
	v_xor_b32_e32 v2, v2, v78
	global_load_lds_dwordx4 v[68:69], off
	s_mov_b32 m0, s43
	v_readfirstlane_b32 s44, v129
	v_add_u32_e32 v131, 0x8000, v6
	v_lshlrev_b64 v[0:1], 11, v[0:1]
	v_lshlrev_b32_e32 v2, 4, v2
	global_load_lds_dwordx4 v[70:71], off
	s_mov_b32 m0, s44
	v_readfirstlane_b32 s45, v131
	v_add_u32_e32 v130, 0x8400, v6
	v_lshl_add_u64 v[0:1], s[96:97], 0, v[0:1]
	v_and_b32_e32 v64, 0x70, v2
	global_load_lds_dwordx4 v[72:73], off
	s_mov_b32 m0, s45
	v_readfirstlane_b32 s46, v130
	v_add_u32_e32 v120, 0xc000, v126
	v_lshl_add_u64 v[76:77], v[0:1], 0, v[64:65]
	global_load_lds_dwordx4 v[74:75], off
	s_mov_b32 m0, s46
	s_mov_b64 s[0:1], 0x80
	v_readfirstlane_b32 s35, v120
	v_add_u32_e32 v121, 0xc400, v126
	global_load_lds_dwordx4 v[76:77], off
	v_lshl_add_u64 v[0:1], v[66:67], 0, s[0:1]
	s_mov_b32 m0, s35
	v_readfirstlane_b32 s36, v121
	v_add_u32_e32 v122, 0xc800, v126
	global_load_lds_dwordx4 v[0:1], off
	v_lshl_add_u64 v[0:1], v[68:69], 0, s[0:1]
	s_mov_b32 m0, s36
	v_readfirstlane_b32 s37, v122
	v_add_u32_e32 v123, 0xcc00, v126
	global_load_lds_dwordx4 v[0:1], off
	v_lshl_add_u64 v[0:1], v[70:71], 0, s[0:1]
	s_mov_b32 m0, s37
	v_readfirstlane_b32 s38, v123
	v_add_u32_e32 v124, s85, v5
	global_load_lds_dwordx4 v[0:1], off
	v_lshl_add_u64 v[0:1], v[72:73], 0, s[0:1]
	s_mov_b32 m0, s38
	v_readfirstlane_b32 s39, v124
	v_add_u32_e32 v125, 0x14400, v6
	global_load_lds_dwordx4 v[0:1], off
	v_lshl_add_u64 v[0:1], v[74:75], 0, s[0:1]
	s_mov_b32 m0, s39
	v_readfirstlane_b32 s40, v125
	global_load_lds_dwordx4 v[0:1], off
	v_lshl_add_u64 v[0:1], v[76:77], 0, s[0:1]
	s_mov_b32 m0, s40
	v_lshrrev_b32_e32 v2, 1, v78
	v_bfe_u32 v64, v78, 5, 1
	global_load_lds_dwordx4 v[0:1], off
	v_add_u32_e32 v114, s3, v3
	v_bitop3_b32 v0, v2, v64, 7 bitop3:0x6c
	s_waitcnt vmcnt(6)
	s_mov_b64 s[30:31], 0x100
	v_readfirstlane_b32 s0, v114
	v_add_u32_e32 v115, 0x400, v114
	v_lshlrev_b32_e32 v132, 4, v0
	s_waitcnt lgkmcnt(0)
	s_barrier
	v_lshl_add_u64 v[0:1], v[66:67], 0, s[30:31]
	s_mov_b32 m0, s0
	v_readfirstlane_b32 s1, v115
	v_add_u32_e32 v116, 0x800, v114
	global_load_lds_dwordx4 v[0:1], off
	v_lshl_add_u64 v[0:1], v[68:69], 0, s[30:31]
	s_mov_b32 m0, s1
	v_readfirstlane_b32 s24, v116
	v_add_u32_e32 v117, 0xc00, v114
	v_readlane_b32 s29, v212, 31
	v_and_b32_e32 v81, 31, v78
	global_load_lds_dwordx4 v[0:1], off
	v_lshl_add_u64 v[0:1], v[70:71], 0, s[30:31]
	s_mov_b32 m0, s24
	v_readfirstlane_b32 s28, v117
	v_add_u32_e32 v118, s29, v5
	v_add_u32_e32 v2, s3, v5
	v_lshlrev_b32_e32 v4, 7, v81
	global_load_lds_dwordx4 v[0:1], off
	v_lshl_add_u64 v[0:1], v[72:73], 0, s[30:31]
	s_mov_b32 m0, s28
	v_readfirstlane_b32 s29, v118
	v_add_u32_e32 v119, 0x8400, v2
	v_lshl_or_b32 v102, v79, 13, v4
	global_load_lds_dwordx4 v[0:1], off
	v_lshl_add_u64 v[0:1], v[74:75], 0, s[30:31]
	s_mov_b32 m0, s29
	v_readfirstlane_b32 s34, v119
	global_load_lds_dwordx4 v[0:1], off
	v_lshl_add_u64 v[0:1], v[76:77], 0, s[30:31]
	s_mov_b32 m0, s34
	v_add_u32_e32 v100, 0, v102
	global_load_lds_dwordx4 v[0:1], off
	v_add_u32_e32 v83, v100, v132
	v_ashrrev_i32_e32 v80, 7, v78
	ds_read_b128 a[0:3], v83 offset:32768
	ds_read_b128 a[4:7], v83 offset:36864
	v_lshl_or_b32 v134, v80, 13, v4
	v_add_u32_e32 v101, 0, v134
	v_add_u32_e32 v82, v101, v132
	ds_read_b128 a[8:11], v82
	ds_read_b128 a[12:15], v82 offset:4096
	v_lshrrev_b32_e32 v182, 6, v133
	s_nop 0
	v_readfirstlane_b32 s32, v182
	s_waitcnt lgkmcnt(1)
	v_mfma_f32_32x32x16_bf16 v[48:63], a[0:3], a[8:11], 0
	v_bfe_u32 v103, v78, 1, 3
	s_mov_b64 s[30:31], 0x180
	s_nop 0
	v_or_b32_e32 v143, 0x8000, v102
	v_or_b32_e32 v144, 0x9000, v102
	v_add_u32_e32 v145, s3, v134
	s_mov_b64 s[80:81], 0x200
	s_waitcnt vmcnt(12)
	v_mfma_f32_32x32x16_bf16 v[32:47], a[4:7], a[8:11], 0
	s_waitcnt lgkmcnt(0)
	v_mfma_f32_32x32x16_bf16 v[16:31], a[0:3], a[12:15], 0
	v_bitop3_b32 v0, v64, v103, 2 bitop3:0x36
	v_lshlrev_b32_e32 v138, 4, v0
	v_add_u32_e32 v84, v101, v138
	ds_read_b128 a[28:31], v84 offset:4096
	s_nop 0
	s_nop 0
	ds_read_b128 a[24:27], v84
	s_nop 0
	v_add_u32_e32 v85, v100, v138
	ds_read_b128 a[20:23], v85 offset:36864
	s_nop 0
	s_nop 0
	ds_read_b128 a[16:19], v85 offset:32768
	s_nop 0
	s_nop 0
	s_nop 0
	s_nop 0
	s_nop 0
	s_nop 0
	v_mfma_f32_32x32x16_bf16 v[0:15], a[4:7], a[12:15], 0
	s_nop 0
	s_waitcnt lgkmcnt(0)
	v_mfma_f32_32x32x16_bf16 v[48:63], a[16:19], a[24:27], v[48:63]
	v_mfma_f32_32x32x16_bf16 v[32:47], a[20:23], a[24:27], v[32:47]
	v_mfma_f32_32x32x16_bf16 v[16:31], a[16:19], a[28:31], v[16:31]
	v_bitop3_b32 v86, v64, v103, 4 bitop3:0x36
	v_lshlrev_b32_e32 v139, 4, v86
	v_add_u32_e32 v86, v101, v139
	ds_read_b128 a[12:15], v86 offset:4096
	s_nop 0
	s_nop 0
	ds_read_b128 a[8:11], v86
	s_nop 0
	v_add_u32_e32 v87, v100, v139
	ds_read_b128 a[4:7], v87 offset:36864
	s_nop 0
	s_nop 0
	ds_read_b128 a[0:3], v87 offset:32768
	s_nop 0
	s_nop 0
	s_nop 0
	v_mfma_f32_32x32x16_bf16 v[0:15], a[20:23], a[28:31], v[0:15]
	s_nop 0
	s_nop 0
	s_nop 0
	s_waitcnt lgkmcnt(0)
	v_mfma_f32_32x32x16_bf16 v[48:63], a[0:3], a[8:11], v[48:63]
	v_mfma_f32_32x32x16_bf16 v[32:47], a[4:7], a[8:11], v[32:47]
	s_nop 0
	v_mfma_f32_32x32x16_bf16 v[16:31], a[0:3], a[12:15], v[16:31]
	v_bitop3_b32 v88, v64, v103, 6 bitop3:0x36
	v_lshlrev_b32_e32 v142, 4, v88
	v_add_u32_e32 v88, v101, v142
	ds_read_b128 a[28:31], v88 offset:4096
	s_nop 0
	s_nop 0
	ds_read_b128 a[24:27], v88
	s_nop 0
	v_add_u32_e32 v89, v100, v142
	ds_read_b128 a[20:23], v89 offset:36864
	s_nop 0
	s_nop 0
	ds_read_b128 a[16:19], v89 offset:32768
	s_nop 0
	s_nop 0
	s_nop 0
	v_mfma_f32_32x32x16_bf16 v[0:15], a[4:7], a[12:15], v[0:15]
	s_nop 0
	s_nop 0
	s_nop 0
	s_waitcnt lgkmcnt(0)
	v_mfma_f32_32x32x16_bf16 v[48:63], a[16:19], a[24:27], v[48:63]
	v_mfma_f32_32x32x16_bf16 v[32:47], a[20:23], a[24:27], v[32:47]
	s_nop 0
	s_waitcnt vmcnt(6)
	s_waitcnt lgkmcnt(0)
	s_barrier
	ds_read_b128 a[12:15], v82 offset:53248
	ds_read_b128 a[8:11], v82 offset:49152
	v_mfma_f32_32x32x16_bf16 v[16:31], a[16:19], a[28:31], v[16:31]
	v_lshl_add_u64 v[158:159], v[66:67], 0, s[30:31]
	s_nop 0
	v_lshl_add_u64 v[160:161], v[68:69], 0, s[30:31]
	s_nop 0
	s_nop 0
	s_nop 0
	v_lshl_add_u64 v[162:163], v[70:71], 0, s[30:31]
	s_nop 0
	v_mfma_f32_32x32x16_bf16 v[0:15], a[20:23], a[28:31], v[0:15]
	s_and_b32 m0, s32, 7
	s_lshl_b32 m0, m0, 12
	s_add_i32 m0, m0, 0x0
	s_nop 0
	global_load_lds_dwordx4 v[158:159], off
	s_nop 0
	v_lshl_add_u64 v[164:165], v[72:73], 0, s[30:31]
	s_nop 0
	s_nop 0
	s_nop 0
	v_lshl_add_u64 v[166:167], v[74:75], 0, s[30:31]
	s_nop 0
	s_nop 0
	s_nop 0
	v_lshl_add_u64 v[168:169], v[76:77], 0, s[30:31]
	s_nop 0
	s_add_i32 s30, 0, 0xc000
	v_add_u32_e32 v90, s30, v132
	v_add_u32_e32 v92, v90, v143
	v_add_u32_e32 v90, v90, v144
	ds_read_b128 a[4:7], v90
	ds_read_b128 a[0:3], v92
	s_nop 0
	s_nop 0
	s_nop 0
	s_nop 0
	s_nop 0
	s_nop 0
	s_nop 0
	s_nop 0
	v_add_u32_e32 v91, s30, v138
	v_add_u32_e32 v93, v91, v143
	ds_read_b128 a[16:19], v93
	v_add_u32_e32 v91, v91, v144
	ds_read_b128 a[20:23], v91
	ds_read_b128 a[24:27], v84 offset:49152
	ds_read_b128 a[28:31], v84 offset:53248
	s_waitcnt lgkmcnt(4)
	v_mfma_f32_32x32x16_bf16 v[48:63], a[0:3], a[8:11], v[48:63]
	s_nop 0
	s_nop 0
	s_nop 0
	s_nop 0
	v_mfma_f32_32x32x16_bf16 v[32:47], a[4:7], a[8:11], v[32:47]
	v_mfma_f32_32x32x16_bf16 v[16:31], a[0:3], a[12:15], v[16:31]
	s_and_b32 m0, s32, 7
	s_lshl_b32 m0, m0, 12
	s_add_i32 m0, m0, 0x400
	s_nop 0
	global_load_lds_dwordx4 v[160:161], off
	v_mfma_f32_32x32x16_bf16 v[0:15], a[4:7], a[12:15], v[0:15]
	s_nop 0
	s_nop 0
	s_nop 0
	s_nop 0
	v_add_u32_e32 v94, s30, v139
	v_add_u32_e32 v95, v94, v143
	ds_read_b128 a[0:3], v95
	v_add_u32_e32 v94, v94, v144
	ds_read_b128 a[4:7], v94
	ds_read_b128 a[8:11], v86 offset:49152
	ds_read_b128 a[12:15], v86 offset:53248
	s_waitcnt lgkmcnt(5)
	v_mfma_f32_32x32x16_bf16 v[48:63], a[16:19], a[24:27], v[48:63]
	v_mfma_f32_32x32x16_bf16 v[32:47], a[20:23], a[24:27], v[32:47]
	s_and_b32 m0, s32, 7
	s_lshl_b32 m0, m0, 12
	s_add_i32 m0, m0, 0x800
	s_nop 0
	global_load_lds_dwordx4 v[162:163], off
	s_waitcnt lgkmcnt(4)
	v_mfma_f32_32x32x16_bf16 v[16:31], a[16:19], a[28:31], v[16:31]
	s_nop 0
	s_nop 0
	s_nop 0
	v_mfma_f32_32x32x16_bf16 v[0:15], a[20:23], a[28:31], v[0:15]
	s_nop 0
	s_nop 0
	s_nop 0
	s_nop 0
	v_add_u32_e32 v96, s30, v142
	v_add_u32_e32 v97, v96, v143
	ds_read_b128 a[16:19], v97
	v_add_u32_e32 v96, v96, v144
	ds_read_b128 a[20:23], v96
	ds_read_b128 a[24:27], v88 offset:49152
	ds_read_b128 a[28:31], v88 offset:53248
	s_waitcnt lgkmcnt(5)
	v_mfma_f32_32x32x16_bf16 v[48:63], a[0:3], a[8:11], v[48:63]
	s_and_b32 m0, s32, 7
	s_lshl_b32 m0, m0, 12
	s_add_i32 m0, m0, 0xc00
	s_nop 0
	global_load_lds_dwordx4 v[164:165], off
	v_mfma_f32_32x32x16_bf16 v[32:47], a[4:7], a[8:11], v[32:47]
	s_waitcnt lgkmcnt(4)
	v_mfma_f32_32x32x16_bf16 v[16:31], a[0:3], a[12:15], v[16:31]
	s_nop 0
	s_nop 0
	s_nop 0
	s_mov_b64 s[30:31], 0x200
	v_mfma_f32_32x32x16_bf16 v[0:15], a[4:7], a[12:15], v[0:15]
	s_and_b32 m0, s32, 7
	s_lshl_b32 m0, m0, 11
	s_add_i32 m0, m0, 0x8000
	s_nop 0
	global_load_lds_dwordx4 v[166:167], off
	s_nop 0
	s_nop 0
	s_nop 0
	s_nop 0
	s_waitcnt lgkmcnt(1)
	v_mfma_f32_32x32x16_bf16 v[48:63], a[16:19], a[24:27], v[48:63]
	v_mfma_f32_32x32x16_bf16 v[32:47], a[20:23], a[24:27], v[32:47]
	s_and_b32 m0, s32, 7
	s_lshl_b32 m0, m0, 11
	s_add_i32 m0, m0, 0x8400
	s_nop 0
	global_load_lds_dwordx4 v[168:169], off
	s_waitcnt vmcnt(6)
	s_waitcnt lgkmcnt(0)
	s_barrier
	v_add_u32_e32 v100, v145, v132
	ds_read_b128 a[8:11], v100
	v_add_u32_e32 v101, s3, v132
	v_add_u32_e32 v99, v101, v144
	ds_read_b128 a[4:7], v99
	s_nop 0
	v_add_u32_e32 v98, v101, v143
	v_or_b32_e32 v132, 0x1000, v134
	v_add_u32_e32 v101, v101, v132
	ds_read_b128 a[12:15], v101
	ds_read_b128 a[0:3], v98
	v_mfma_f32_32x32x16_bf16 v[16:31], a[16:19], a[28:31], v[16:31]
	v_lshl_add_u64 v[170:171], v[66:67], 0, s[30:31]
	s_nop 0
	v_lshl_add_u64 v[172:173], v[68:69], 0, s[30:31]
	s_nop 0
	s_nop 0
	s_nop 0
	v_lshl_add_u64 v[174:175], v[70:71], 0, s[30:31]
	s_nop 0
	v_mfma_f32_32x32x16_bf16 v[0:15], a[20:23], a[28:31], v[0:15]
	s_and_b32 m0, s32, 7
	s_lshl_b32 m0, m0, 12
	s_add_i32 m0, m0, 0xc000
	s_nop 0
	global_load_lds_dwordx4 v[170:171], off
	s_nop 0
	v_lshl_add_u64 v[176:177], v[72:73], 0, s[30:31]
	s_nop 0
	s_nop 0
	s_nop 0
	v_lshl_add_u64 v[178:179], v[74:75], 0, s[30:31]
	s_nop 0
	s_nop 0
	s_nop 0
	v_lshl_add_u64 v[180:181], v[76:77], 0, s[30:31]
	s_nop 0
	s_mov_b64 s[30:31], 0x280
	s_nop 0
	s_nop 0
	s_nop 0
	s_nop 0
	s_nop 0
	s_nop 0
	s_nop 0
	s_nop 0
	v_add_u32_e32 v105, s3, v138
	v_add_u32_e32 v102, v105, v143
	ds_read_b128 a[16:19], v102
	v_add_u32_e32 v103, v105, v144
	ds_read_b128 a[20:23], v103
	v_add_u32_e32 v104, v145, v138
	ds_read_b128 a[24:27], v104
	v_add_u32_e32 v105, v105, v132
	ds_read_b128 a[28:31], v105
	s_waitcnt lgkmcnt(4)
	v_mfma_f32_32x32x16_bf16 v[48:63], a[0:3], a[8:11], v[48:63]
	s_nop 0
	v_mfma_f32_32x32x16_bf16 v[32:47], a[4:7], a[8:11], v[32:47]
	s_nop 0
	s_nop 0
	s_nop 0
	s_nop 0
	s_nop 0
	v_mfma_f32_32x32x16_bf16 v[16:31], a[0:3], a[12:15], v[16:31]
	s_and_b32 m0, s32, 7
	s_lshl_b32 m0, m0, 12
	s_add_i32 m0, m0, 0xc400
	s_nop 0
	global_load_lds_dwordx4 v[172:173], off
	s_nop 0
	v_mfma_f32_32x32x16_bf16 v[0:15], a[4:7], a[12:15], v[0:15]
	s_nop 0
	s_nop 0
	s_nop 0
	v_add_u32_e32 v109, s3, v139
	v_add_u32_e32 v106, v109, v143
	ds_read_b128 a[0:3], v106
	v_add_u32_e32 v107, v109, v144
	ds_read_b128 a[4:7], v107
	v_add_u32_e32 v108, v145, v139
	ds_read_b128 a[8:11], v108
	v_add_u32_e32 v109, v109, v132
	ds_read_b128 a[12:15], v109
	s_waitcnt lgkmcnt(5)
	v_mfma_f32_32x32x16_bf16 v[48:63], a[16:19], a[24:27], v[48:63]
	v_mfma_f32_32x32x16_bf16 v[32:47], a[20:23], a[24:27], v[32:47]
	s_and_b32 m0, s32, 7
	s_lshl_b32 m0, m0, 12
	s_add_i32 m0, m0, 0xc800
	s_nop 0
	global_load_lds_dwordx4 v[174:175], off
	s_waitcnt lgkmcnt(4)
	v_mfma_f32_32x32x16_bf16 v[16:31], a[16:19], a[28:31], v[16:31]
	s_nop 0
	s_nop 0
	s_nop 0
	s_nop 0
	s_nop 0
	s_nop 0
	v_mfma_f32_32x32x16_bf16 v[0:15], a[20:23], a[28:31], v[0:15]
	s_nop 0
	s_nop 0
	s_nop 0
	v_add_u32_e32 v113, s3, v142
	v_add_u32_e32 v110, v113, v143
	ds_read_b128 a[16:19], v110
	v_add_u32_e32 v111, v113, v144
	ds_read_b128 a[20:23], v111
	v_add_u32_e32 v112, v145, v142
	ds_read_b128 a[24:27], v112
	v_add_u32_e32 v113, v113, v132
	ds_read_b128 a[28:31], v113
	s_waitcnt lgkmcnt(5)
	v_mfma_f32_32x32x16_bf16 v[48:63], a[0:3], a[8:11], v[48:63]
	s_and_b32 m0, s32, 7
	s_lshl_b32 m0, m0, 12
	s_add_i32 m0, m0, 0xcc00
	s_nop 0
	global_load_lds_dwordx4 v[176:177], off
	v_mfma_f32_32x32x16_bf16 v[32:47], a[4:7], a[8:11], v[32:47]
	s_waitcnt lgkmcnt(4)
	v_mfma_f32_32x32x16_bf16 v[16:31], a[0:3], a[12:15], v[16:31]
	s_nop 0
	s_nop 0
	s_nop 0
	s_nop 0
	s_nop 0
	s_nop 0
	v_mfma_f32_32x32x16_bf16 v[0:15], a[4:7], a[12:15], v[0:15]
	s_and_b32 m0, s32, 7
	s_lshl_b32 m0, m0, 11
	s_add_i32 m0, m0, 0x14000
	s_nop 0
	global_load_lds_dwordx4 v[178:179], off
	s_nop 0
	s_nop 0
	s_nop 0
	s_waitcnt lgkmcnt(1)
	v_mfma_f32_32x32x16_bf16 v[48:63], a[16:19], a[24:27], v[48:63]
	v_mfma_f32_32x32x16_bf16 v[32:47], a[20:23], a[24:27], v[32:47]
	s_and_b32 m0, s32, 7
	s_lshl_b32 m0, m0, 11
	s_add_i32 m0, m0, 0x14400
	s_nop 0
	global_load_lds_dwordx4 v[180:181], off
	s_waitcnt vmcnt(6)
	s_waitcnt lgkmcnt(0)
	s_barrier
	ds_read_b128 a[12:15], v82 offset:4096
	ds_read_b128 a[8:11], v82
	ds_read_b128 a[4:7], v83 offset:36864
	ds_read_b128 a[0:3], v83 offset:32768
	v_mfma_f32_32x32x16_bf16 v[16:31], a[16:19], a[28:31], v[16:31]
	v_lshl_add_u64 v[158:159], v[66:67], 0, s[30:31]
	s_nop 0
	v_lshl_add_u64 v[160:161], v[68:69], 0, s[30:31]
	s_nop 0
	s_nop 0
	s_nop 0
	v_lshl_add_u64 v[162:163], v[70:71], 0, s[30:31]
	s_nop 0
	v_mfma_f32_32x32x16_bf16 v[0:15], a[20:23], a[28:31], v[0:15]
	s_and_b32 m0, s32, 7
	s_lshl_b32 m0, m0, 12
	s_add_i32 m0, m0, 0x18000
	s_nop 0
	global_load_lds_dwordx4 v[158:159], off
	s_nop 0
	v_lshl_add_u64 v[164:165], v[72:73], 0, s[30:31]
	s_nop 0
	s_nop 0
	s_nop 0
	v_lshl_add_u64 v[166:167], v[74:75], 0, s[30:31]
	s_nop 0
	s_nop 0
	s_nop 0
	v_lshl_add_u64 v[168:169], v[76:77], 0, s[30:31]
	s_nop 0
	s_mov_b64 s[30:31], 0x300
	s_nop 0
	s_nop 0
	s_nop 0
	s_nop 0
	s_nop 0
	ds_read_b128 a[16:19], v85 offset:32768
	ds_read_b128 a[20:23], v85 offset:36864
	ds_read_b128 a[24:27], v84
	ds_read_b128 a[28:31], v84 offset:4096
	s_waitcnt lgkmcnt(4)
	v_mfma_f32_32x32x16_bf16 v[48:63], a[0:3], a[8:11], v[48:63]
	s_nop 0
	v_readfirstlane_b32 s41, v114
	v_mfma_f32_32x32x16_bf16 v[32:47], a[4:7], a[8:11], v[32:47]
	v_mfma_f32_32x32x16_bf16 v[16:31], a[0:3], a[12:15], v[16:31]
	s_and_b32 m0, s32, 7
	s_lshl_b32 m0, m0, 12
	s_add_i32 m0, m0, 0x18400
	s_nop 0
	global_load_lds_dwordx4 v[160:161], off
	v_mfma_f32_32x32x16_bf16 v[0:15], a[4:7], a[12:15], v[0:15]
	s_nop 0
	s_nop 0
	s_nop 0
	s_nop 0
	ds_read_b128 a[0:3], v87 offset:32768
	ds_read_b128 a[4:7], v87 offset:36864
	ds_read_b128 a[8:11], v86
	ds_read_b128 a[12:15], v86 offset:4096
	s_waitcnt lgkmcnt(5)
	v_mfma_f32_32x32x16_bf16 v[48:63], a[16:19], a[24:27], v[48:63]
	v_mfma_f32_32x32x16_bf16 v[32:47], a[20:23], a[24:27], v[32:47]
	s_and_b32 m0, s32, 7
	s_lshl_b32 m0, m0, 12
	s_add_i32 m0, m0, 0x18800
	s_nop 0
	global_load_lds_dwordx4 v[162:163], off
	s_waitcnt lgkmcnt(4)
	v_mfma_f32_32x32x16_bf16 v[16:31], a[16:19], a[28:31], v[16:31]
	v_mfma_f32_32x32x16_bf16 v[0:15], a[20:23], a[28:31], v[0:15]
	s_nop 0
	s_nop 0
	s_nop 0
	s_nop 0
	ds_read_b128 a[16:19], v89 offset:32768
	ds_read_b128 a[20:23], v89 offset:36864
	ds_read_b128 a[24:27], v88
	ds_read_b128 a[28:31], v88 offset:4096
	s_waitcnt lgkmcnt(5)
	v_mfma_f32_32x32x16_bf16 v[48:63], a[0:3], a[8:11], v[48:63]
	s_and_b32 m0, s32, 7
	s_lshl_b32 m0, m0, 12
	s_add_i32 m0, m0, 0x18c00
	s_nop 0
	global_load_lds_dwordx4 v[164:165], off
	v_mfma_f32_32x32x16_bf16 v[32:47], a[4:7], a[8:11], v[32:47]
	s_waitcnt lgkmcnt(4)
	v_mfma_f32_32x32x16_bf16 v[16:31], a[0:3], a[12:15], v[16:31]
	v_mfma_f32_32x32x16_bf16 v[0:15], a[4:7], a[12:15], v[0:15]
	s_and_b32 m0, s32, 7
	s_lshl_b32 m0, m0, 11
	s_add_i32 m0, m0, 0x20000
	s_nop 0
	global_load_lds_dwordx4 v[166:167], off
	s_nop 0
	s_nop 0
	s_nop 0
	s_nop 0
	s_waitcnt lgkmcnt(1)
	v_mfma_f32_32x32x16_bf16 v[48:63], a[16:19], a[24:27], v[48:63]
	v_mfma_f32_32x32x16_bf16 v[32:47], a[20:23], a[24:27], v[32:47]
	s_and_b32 m0, s32, 7
	s_lshl_b32 m0, m0, 11
	s_add_i32 m0, m0, 0x20400
	s_nop 0
	global_load_lds_dwordx4 v[168:169], off
	s_waitcnt vmcnt(6)
	s_waitcnt lgkmcnt(0)
	s_barrier
	ds_read_b128 a[12:15], v82 offset:53248
	ds_read_b128 a[8:11], v82 offset:49152
	ds_read_b128 a[4:7], v90
	ds_read_b128 a[0:3], v92
	v_mfma_f32_32x32x16_bf16 v[16:31], a[16:19], a[28:31], v[16:31]
	v_lshl_add_u64 v[170:171], v[66:67], 0, s[30:31]
	s_nop 0
	v_lshl_add_u64 v[172:173], v[68:69], 0, s[30:31]
	s_nop 0
	v_readfirstlane_b32 s42, v115
	s_nop 0
	v_lshl_add_u64 v[174:175], v[70:71], 0, s[30:31]
	s_nop 0
	v_mfma_f32_32x32x16_bf16 v[0:15], a[20:23], a[28:31], v[0:15]
	s_and_b32 m0, s32, 7
	s_lshl_b32 m0, m0, 12
	s_add_i32 m0, m0, 0x0
	s_nop 0
	global_load_lds_dwordx4 v[170:171], off
	s_nop 0
	v_lshl_add_u64 v[176:177], v[72:73], 0, s[30:31]
	s_nop 0
	v_readfirstlane_b32 s43, v116
	s_nop 0
	v_lshl_add_u64 v[178:179], v[74:75], 0, s[30:31]
	s_nop 0
	v_readfirstlane_b32 s44, v117
	s_nop 0
	v_lshl_add_u64 v[180:181], v[76:77], 0, s[30:31]
	s_nop 0
	s_mov_b64 s[30:31], 0x380
	s_nop 0
	s_nop 0
	s_nop 0
	s_nop 0
	s_nop 0
	ds_read_b128 a[16:19], v93
	ds_read_b128 a[20:23], v91
	ds_read_b128 a[24:27], v84 offset:49152
	ds_read_b128 a[28:31], v84 offset:53248
	s_waitcnt lgkmcnt(4)
	v_mfma_f32_32x32x16_bf16 v[48:63], a[0:3], a[8:11], v[48:63]
	s_nop 0
	v_readfirstlane_b32 s35, v120
	v_readfirstlane_b32 s45, v118
	v_readfirstlane_b32 s46, v119
	v_mfma_f32_32x32x16_bf16 v[32:47], a[4:7], a[8:11], v[32:47]
	v_mfma_f32_32x32x16_bf16 v[16:31], a[0:3], a[12:15], v[16:31]
	s_and_b32 m0, s32, 7
	s_lshl_b32 m0, m0, 12
	s_add_i32 m0, m0, 0x400
	s_nop 0
	global_load_lds_dwordx4 v[172:173], off
	v_mfma_f32_32x32x16_bf16 v[0:15], a[4:7], a[12:15], v[0:15]
	s_nop 0
	s_nop 0
	s_nop 0
	s_nop 0
	ds_read_b128 a[0:3], v95
	ds_read_b128 a[4:7], v94
	ds_read_b128 a[8:11], v86 offset:49152
	ds_read_b128 a[12:15], v86 offset:53248
	s_waitcnt lgkmcnt(5)
	v_mfma_f32_32x32x16_bf16 v[48:63], a[16:19], a[24:27], v[48:63]
	v_mfma_f32_32x32x16_bf16 v[32:47], a[20:23], a[24:27], v[32:47]
	s_and_b32 m0, s32, 7
	s_lshl_b32 m0, m0, 12
	s_add_i32 m0, m0, 0x800
	s_nop 0
	global_load_lds_dwordx4 v[174:175], off
	s_waitcnt lgkmcnt(4)
	v_mfma_f32_32x32x16_bf16 v[16:31], a[16:19], a[28:31], v[16:31]
	v_mfma_f32_32x32x16_bf16 v[0:15], a[20:23], a[28:31], v[0:15]
	s_nop 0
	s_nop 0
	s_nop 0
	s_nop 0
	ds_read_b128 a[16:19], v97
	ds_read_b128 a[20:23], v96
	ds_read_b128 a[24:27], v88 offset:49152
	ds_read_b128 a[28:31], v88 offset:53248
	s_waitcnt lgkmcnt(5)
	v_mfma_f32_32x32x16_bf16 v[48:63], a[0:3], a[8:11], v[48:63]
	s_and_b32 m0, s32, 7
	s_lshl_b32 m0, m0, 12
	s_add_i32 m0, m0, 0xc00
	s_nop 0
	global_load_lds_dwordx4 v[176:177], off
	v_mfma_f32_32x32x16_bf16 v[32:47], a[4:7], a[8:11], v[32:47]
	s_waitcnt lgkmcnt(4)
	v_mfma_f32_32x32x16_bf16 v[16:31], a[0:3], a[12:15], v[16:31]
	v_mfma_f32_32x32x16_bf16 v[0:15], a[4:7], a[12:15], v[0:15]
	s_and_b32 m0, s32, 7
	s_lshl_b32 m0, m0, 11
	s_add_i32 m0, m0, 0x8000
	s_nop 0
	global_load_lds_dwordx4 v[178:179], off
	s_nop 0
	s_nop 0
	s_nop 0
	s_nop 0
	s_waitcnt lgkmcnt(1)
	v_mfma_f32_32x32x16_bf16 v[48:63], a[16:19], a[24:27], v[48:63]
	v_mfma_f32_32x32x16_bf16 v[32:47], a[20:23], a[24:27], v[32:47]
	s_and_b32 m0, s32, 7
	s_lshl_b32 m0, m0, 11
	s_add_i32 m0, m0, 0x8400
	s_nop 0
	global_load_lds_dwordx4 v[180:181], off
	s_waitcnt vmcnt(6)
	s_waitcnt lgkmcnt(0)
	s_barrier
	ds_read_b128 a[12:15], v101
	ds_read_b128 a[8:11], v100
	ds_read_b128 a[4:7], v99
	ds_read_b128 a[0:3], v98
	v_mfma_f32_32x32x16_bf16 v[16:31], a[16:19], a[28:31], v[16:31]
	v_lshl_add_u64 v[158:159], v[66:67], 0, s[30:31]
	s_nop 0
	v_lshl_add_u64 v[160:161], v[68:69], 0, s[30:31]
	s_nop 0
	v_readfirstlane_b32 s36, v121
	s_nop 0
	v_lshl_add_u64 v[162:163], v[70:71], 0, s[30:31]
	s_nop 0
	v_mfma_f32_32x32x16_bf16 v[0:15], a[20:23], a[28:31], v[0:15]
	s_and_b32 m0, s32, 7
	s_lshl_b32 m0, m0, 12
	s_add_i32 m0, m0, 0xc000
	s_nop 0
	global_load_lds_dwordx4 v[158:159], off
	s_nop 0
	v_lshl_add_u64 v[164:165], v[72:73], 0, s[30:31]
	s_nop 0
	v_readfirstlane_b32 s37, v122
	s_nop 0
	v_lshl_add_u64 v[166:167], v[74:75], 0, s[30:31]
	s_nop 0
	v_readfirstlane_b32 s38, v123
	s_nop 0
	v_lshl_add_u64 v[168:169], v[76:77], 0, s[30:31]
	s_nop 0
	s_mov_b64 s[30:31], 0x400
	s_nop 0
	s_nop 0
	s_nop 0
	s_nop 0
	s_nop 0
	ds_read_b128 a[16:19], v102
	ds_read_b128 a[20:23], v103
	ds_read_b128 a[24:27], v104
	ds_read_b128 a[28:31], v105
	s_waitcnt lgkmcnt(4)
	v_mfma_f32_32x32x16_bf16 v[48:63], a[0:3], a[8:11], v[48:63]
	s_nop 0
	v_readfirstlane_b32 s0, v126
	v_readfirstlane_b32 s39, v124
	v_readfirstlane_b32 s40, v125
	v_mfma_f32_32x32x16_bf16 v[32:47], a[4:7], a[8:11], v[32:47]
	v_mfma_f32_32x32x16_bf16 v[16:31], a[0:3], a[12:15], v[16:31]
	s_and_b32 m0, s32, 7
	s_lshl_b32 m0, m0, 12
	s_add_i32 m0, m0, 0xc400
	s_nop 0
	global_load_lds_dwordx4 v[160:161], off
	v_mfma_f32_32x32x16_bf16 v[0:15], a[4:7], a[12:15], v[0:15]
	s_nop 0
	s_nop 0
	s_nop 0
	s_nop 0
	ds_read_b128 a[0:3], v106
	ds_read_b128 a[4:7], v107
	ds_read_b128 a[8:11], v108
	ds_read_b128 a[12:15], v109
	s_waitcnt lgkmcnt(5)
	v_mfma_f32_32x32x16_bf16 v[48:63], a[16:19], a[24:27], v[48:63]
	v_mfma_f32_32x32x16_bf16 v[32:47], a[20:23], a[24:27], v[32:47]
	s_and_b32 m0, s32, 7
	s_lshl_b32 m0, m0, 12
	s_add_i32 m0, m0, 0xc800
	s_nop 0
	global_load_lds_dwordx4 v[162:163], off
	s_waitcnt lgkmcnt(4)
	v_mfma_f32_32x32x16_bf16 v[16:31], a[16:19], a[28:31], v[16:31]
	v_mfma_f32_32x32x16_bf16 v[0:15], a[20:23], a[28:31], v[0:15]
	s_nop 0
	s_nop 0
	s_nop 0
	s_nop 0
	ds_read_b128 a[16:19], v110
	ds_read_b128 a[20:23], v111
	ds_read_b128 a[24:27], v112
	ds_read_b128 a[28:31], v113
	s_waitcnt lgkmcnt(5)
	v_mfma_f32_32x32x16_bf16 v[48:63], a[0:3], a[8:11], v[48:63]
	s_and_b32 m0, s32, 7
	s_lshl_b32 m0, m0, 12
	s_add_i32 m0, m0, 0xcc00
	s_nop 0
	global_load_lds_dwordx4 v[164:165], off
	v_mfma_f32_32x32x16_bf16 v[32:47], a[4:7], a[8:11], v[32:47]
	s_waitcnt lgkmcnt(4)
	v_mfma_f32_32x32x16_bf16 v[16:31], a[0:3], a[12:15], v[16:31]
	v_mfma_f32_32x32x16_bf16 v[0:15], a[4:7], a[12:15], v[0:15]
	s_and_b32 m0, s32, 7
	s_lshl_b32 m0, m0, 11
	s_add_i32 m0, m0, 0x14000
	s_nop 0
	global_load_lds_dwordx4 v[166:167], off
	s_nop 0
	s_nop 0
	s_nop 0
	s_nop 0
	s_waitcnt lgkmcnt(1)
	v_mfma_f32_32x32x16_bf16 v[48:63], a[16:19], a[24:27], v[48:63]
	v_mfma_f32_32x32x16_bf16 v[32:47], a[20:23], a[24:27], v[32:47]
	s_and_b32 m0, s32, 7
	s_lshl_b32 m0, m0, 11
	s_add_i32 m0, m0, 0x14400
	s_nop 0
	global_load_lds_dwordx4 v[168:169], off
	s_waitcnt vmcnt(6)
	s_waitcnt lgkmcnt(0)
	s_barrier
	ds_read_b128 a[12:15], v82 offset:4096
	ds_read_b128 a[8:11], v82
	ds_read_b128 a[4:7], v83 offset:36864
	ds_read_b128 a[0:3], v83 offset:32768
	v_mfma_f32_32x32x16_bf16 v[16:31], a[16:19], a[28:31], v[16:31]
	v_lshl_add_u64 v[170:171], v[66:67], 0, s[30:31]
	s_nop 0
	v_lshl_add_u64 v[172:173], v[68:69], 0, s[30:31]
	s_nop 0
	v_readfirstlane_b32 s1, v127
	s_nop 0
	v_lshl_add_u64 v[174:175], v[70:71], 0, s[30:31]
	s_nop 0
	v_mfma_f32_32x32x16_bf16 v[0:15], a[20:23], a[28:31], v[0:15]
	s_and_b32 m0, s32, 7
	s_lshl_b32 m0, m0, 12
	s_add_i32 m0, m0, 0x18000
	s_nop 0
	global_load_lds_dwordx4 v[170:171], off
	s_nop 0
	v_lshl_add_u64 v[176:177], v[72:73], 0, s[30:31]
	s_nop 0
	v_readfirstlane_b32 s24, v128
	s_nop 0
	v_lshl_add_u64 v[178:179], v[74:75], 0, s[30:31]
	s_nop 0
	v_readfirstlane_b32 s28, v129
	s_nop 0
	v_lshl_add_u64 v[180:181], v[76:77], 0, s[30:31]
	s_nop 0
	s_mov_b64 s[30:31], 0x480
	s_nop 0
	s_nop 0
	s_nop 0
	s_nop 0
	s_nop 0
	ds_read_b128 a[16:19], v85 offset:32768
	ds_read_b128 a[20:23], v85 offset:36864
	ds_read_b128 a[24:27], v84
	ds_read_b128 a[28:31], v84 offset:4096
	s_waitcnt lgkmcnt(4)
	v_mfma_f32_32x32x16_bf16 v[48:63], a[0:3], a[8:11], v[48:63]
	s_nop 0
	v_lshl_add_u64 v[162:163], v[70:71], 0, s[30:31]
	v_readfirstlane_b32 s29, v131
	v_readfirstlane_b32 s34, v130
	v_mfma_f32_32x32x16_bf16 v[32:47], a[4:7], a[8:11], v[32:47]
	v_mfma_f32_32x32x16_bf16 v[16:31], a[0:3], a[12:15], v[16:31]
	s_and_b32 m0, s32, 7
	s_lshl_b32 m0, m0, 12
	s_add_i32 m0, m0, 0x18400
	s_nop 0
	global_load_lds_dwordx4 v[172:173], off
	v_mfma_f32_32x32x16_bf16 v[0:15], a[4:7], a[12:15], v[0:15]
	s_nop 0
	s_nop 0
	s_nop 0
	s_nop 0
	ds_read_b128 a[0:3], v87 offset:32768
	ds_read_b128 a[4:7], v87 offset:36864
	ds_read_b128 a[8:11], v86
	ds_read_b128 a[12:15], v86 offset:4096
	s_waitcnt lgkmcnt(5)
	v_mfma_f32_32x32x16_bf16 v[48:63], a[16:19], a[24:27], v[48:63]
	v_mfma_f32_32x32x16_bf16 v[32:47], a[20:23], a[24:27], v[32:47]
	s_and_b32 m0, s32, 7
	s_lshl_b32 m0, m0, 12
	s_add_i32 m0, m0, 0x18800
	s_nop 0
	global_load_lds_dwordx4 v[174:175], off
	s_waitcnt lgkmcnt(4)
	v_mfma_f32_32x32x16_bf16 v[16:31], a[16:19], a[28:31], v[16:31]
	v_mfma_f32_32x32x16_bf16 v[0:15], a[20:23], a[28:31], v[0:15]
	s_nop 0
	s_nop 0
	s_nop 0
	s_nop 0
	ds_read_b128 a[16:19], v89 offset:32768
	ds_read_b128 a[20:23], v89 offset:36864
	ds_read_b128 a[24:27], v88
	ds_read_b128 a[28:31], v88 offset:4096
	s_waitcnt lgkmcnt(5)
	v_mfma_f32_32x32x16_bf16 v[48:63], a[0:3], a[8:11], v[48:63]
	s_and_b32 m0, s32, 7
	s_lshl_b32 m0, m0, 12
	s_add_i32 m0, m0, 0x18c00
	s_nop 0
	global_load_lds_dwordx4 v[176:177], off
	v_mfma_f32_32x32x16_bf16 v[32:47], a[4:7], a[8:11], v[32:47]
	s_waitcnt lgkmcnt(4)
	v_mfma_f32_32x32x16_bf16 v[16:31], a[0:3], a[12:15], v[16:31]
	v_mfma_f32_32x32x16_bf16 v[0:15], a[4:7], a[12:15], v[0:15]
	s_and_b32 m0, s32, 7
	s_lshl_b32 m0, m0, 11
	s_add_i32 m0, m0, 0x20000
	s_nop 0
	global_load_lds_dwordx4 v[178:179], off
	s_nop 0
	s_nop 0
	s_nop 0
	s_nop 0
	s_waitcnt lgkmcnt(1)
	v_mfma_f32_32x32x16_bf16 v[48:63], a[16:19], a[24:27], v[48:63]
	v_mfma_f32_32x32x16_bf16 v[32:47], a[20:23], a[24:27], v[32:47]
	s_and_b32 m0, s32, 7
	s_lshl_b32 m0, m0, 11
	s_add_i32 m0, m0, 0x20400
	s_nop 0
	global_load_lds_dwordx4 v[180:181], off
	s_waitcnt vmcnt(6)
	s_waitcnt lgkmcnt(0)
	s_barrier
	ds_read_b128 a[12:15], v82 offset:53248
	ds_read_b128 a[8:11], v82 offset:49152
	ds_read_b128 a[4:7], v90
	ds_read_b128 a[0:3], v92
	v_mfma_f32_32x32x16_bf16 v[16:31], a[16:19], a[28:31], v[16:31]
	v_lshl_add_u64 v[158:159], v[66:67], 0, s[30:31]
	s_nop 0
	v_lshl_add_u64 v[160:161], v[68:69], 0, s[30:31]
	s_nop 0
	s_nop 0
	s_nop 0
	s_nop 0
	v_mfma_f32_32x32x16_bf16 v[0:15], a[20:23], a[28:31], v[0:15]
	s_and_b32 m0, s32, 7
	s_lshl_b32 m0, m0, 12
	s_add_i32 m0, m0, 0x0
	s_nop 0
	global_load_lds_dwordx4 v[158:159], off
	s_nop 0
	v_lshl_add_u64 v[164:165], v[72:73], 0, s[30:31]
	s_nop 0
	s_nop 0
	s_nop 0
	v_lshl_add_u64 v[166:167], v[74:75], 0, s[30:31]
	s_nop 0
	s_nop 0
	s_nop 0
	v_lshl_add_u64 v[168:169], v[76:77], 0, s[30:31]
	s_nop 0
	s_mov_b64 s[30:31], 0x500
	s_nop 0
	s_nop 0
	s_nop 0
	s_nop 0
	s_nop 0
	ds_read_b128 a[16:19], v93
	ds_read_b128 a[20:23], v91
	ds_read_b128 a[24:27], v84 offset:49152
	ds_read_b128 a[28:31], v84 offset:53248
	s_waitcnt lgkmcnt(4)
	v_mfma_f32_32x32x16_bf16 v[48:63], a[0:3], a[8:11], v[48:63]
	s_nop 0
	v_lshl_add_u64 v[174:175], v[70:71], 0, s[30:31]
	v_mfma_f32_32x32x16_bf16 v[32:47], a[4:7], a[8:11], v[32:47]
	v_mfma_f32_32x32x16_bf16 v[16:31], a[0:3], a[12:15], v[16:31]
	s_and_b32 m0, s32, 7
	s_lshl_b32 m0, m0, 12
	s_add_i32 m0, m0, 0x400
	s_nop 0
	global_load_lds_dwordx4 v[160:161], off
	v_mfma_f32_32x32x16_bf16 v[0:15], a[4:7], a[12:15], v[0:15]
	s_nop 0
	s_nop 0
	s_nop 0
	s_nop 0
	ds_read_b128 a[0:3], v95
	ds_read_b128 a[4:7], v94
	ds_read_b128 a[8:11], v86 offset:49152
	ds_read_b128 a[12:15], v86 offset:53248
	s_waitcnt lgkmcnt(5)
	v_mfma_f32_32x32x16_bf16 v[48:63], a[16:19], a[24:27], v[48:63]
	v_mfma_f32_32x32x16_bf16 v[32:47], a[20:23], a[24:27], v[32:47]
	s_and_b32 m0, s32, 7
	s_lshl_b32 m0, m0, 12
	s_add_i32 m0, m0, 0x800
	s_nop 0
	global_load_lds_dwordx4 v[162:163], off
	s_waitcnt lgkmcnt(4)
	v_mfma_f32_32x32x16_bf16 v[16:31], a[16:19], a[28:31], v[16:31]
	v_mfma_f32_32x32x16_bf16 v[0:15], a[20:23], a[28:31], v[0:15]
	s_nop 0
	s_nop 0
	s_nop 0
	s_nop 0
	ds_read_b128 a[16:19], v97
	ds_read_b128 a[20:23], v96
	ds_read_b128 a[24:27], v88 offset:49152
	ds_read_b128 a[28:31], v88 offset:53248
	s_waitcnt lgkmcnt(5)
	v_mfma_f32_32x32x16_bf16 v[48:63], a[0:3], a[8:11], v[48:63]
	s_and_b32 m0, s32, 7
	s_lshl_b32 m0, m0, 12
	s_add_i32 m0, m0, 0xc00
	s_nop 0
	global_load_lds_dwordx4 v[164:165], off
	v_mfma_f32_32x32x16_bf16 v[32:47], a[4:7], a[8:11], v[32:47]
	s_waitcnt lgkmcnt(4)
	v_mfma_f32_32x32x16_bf16 v[16:31], a[0:3], a[12:15], v[16:31]
	v_mfma_f32_32x32x16_bf16 v[0:15], a[4:7], a[12:15], v[0:15]
	s_and_b32 m0, s32, 7
	s_lshl_b32 m0, m0, 11
	s_add_i32 m0, m0, 0x8000
	s_nop 0
	global_load_lds_dwordx4 v[166:167], off
	s_nop 0
	s_nop 0
	s_nop 0
	s_nop 0
	s_waitcnt lgkmcnt(1)
	v_mfma_f32_32x32x16_bf16 v[48:63], a[16:19], a[24:27], v[48:63]
	v_mfma_f32_32x32x16_bf16 v[32:47], a[20:23], a[24:27], v[32:47]
	s_and_b32 m0, s32, 7
	s_lshl_b32 m0, m0, 11
	s_add_i32 m0, m0, 0x8400
	s_nop 0
	global_load_lds_dwordx4 v[168:169], off
	s_waitcnt vmcnt(6)
	s_waitcnt lgkmcnt(0)
	s_barrier
	ds_read_b128 a[12:15], v101
	ds_read_b128 a[8:11], v100
	ds_read_b128 a[4:7], v99
	ds_read_b128 a[0:3], v98
	v_mfma_f32_32x32x16_bf16 v[16:31], a[16:19], a[28:31], v[16:31]
	v_lshl_add_u64 v[170:171], v[66:67], 0, s[30:31]
	s_nop 0
	v_lshl_add_u64 v[172:173], v[68:69], 0, s[30:31]
	s_nop 0
	s_nop 0
	s_nop 0
	s_nop 0
	v_mfma_f32_32x32x16_bf16 v[0:15], a[20:23], a[28:31], v[0:15]
	s_and_b32 m0, s32, 7
	s_lshl_b32 m0, m0, 12
	s_add_i32 m0, m0, 0xc000
	s_nop 0
	global_load_lds_dwordx4 v[170:171], off
	s_nop 0
	v_lshl_add_u64 v[176:177], v[72:73], 0, s[30:31]
	s_nop 0
	s_nop 0
	s_nop 0
	v_lshl_add_u64 v[178:179], v[74:75], 0, s[30:31]
	s_nop 0
	s_nop 0
	s_nop 0
	v_lshl_add_u64 v[180:181], v[76:77], 0, s[30:31]
	s_nop 0
	s_mov_b64 s[30:31], 0x580
	s_nop 0
	s_nop 0
	s_nop 0
	s_nop 0
	s_nop 0
	ds_read_b128 a[16:19], v102
	ds_read_b128 a[20:23], v103
	ds_read_b128 a[24:27], v104
	ds_read_b128 a[28:31], v105
	s_waitcnt lgkmcnt(4)
	v_mfma_f32_32x32x16_bf16 v[48:63], a[0:3], a[8:11], v[48:63]
	s_nop 0
	v_lshl_add_u64 v[162:163], v[70:71], 0, s[30:31]
	v_mfma_f32_32x32x16_bf16 v[32:47], a[4:7], a[8:11], v[32:47]
	v_mfma_f32_32x32x16_bf16 v[16:31], a[0:3], a[12:15], v[16:31]
	s_and_b32 m0, s32, 7
	s_lshl_b32 m0, m0, 12
	s_add_i32 m0, m0, 0xc400
	s_nop 0
	global_load_lds_dwordx4 v[172:173], off
	v_mfma_f32_32x32x16_bf16 v[0:15], a[4:7], a[12:15], v[0:15]
	s_nop 0
	s_nop 0
	s_nop 0
	s_nop 0
	ds_read_b128 a[0:3], v106
	ds_read_b128 a[4:7], v107
	ds_read_b128 a[8:11], v108
	ds_read_b128 a[12:15], v109
	s_waitcnt lgkmcnt(5)
	v_mfma_f32_32x32x16_bf16 v[48:63], a[16:19], a[24:27], v[48:63]
	v_mfma_f32_32x32x16_bf16 v[32:47], a[20:23], a[24:27], v[32:47]
	s_and_b32 m0, s32, 7
	s_lshl_b32 m0, m0, 12
	s_add_i32 m0, m0, 0xc800
	s_nop 0
	global_load_lds_dwordx4 v[174:175], off
	s_waitcnt lgkmcnt(4)
	v_mfma_f32_32x32x16_bf16 v[16:31], a[16:19], a[28:31], v[16:31]
	v_mfma_f32_32x32x16_bf16 v[0:15], a[20:23], a[28:31], v[0:15]
	s_nop 0
	s_nop 0
	s_nop 0
	s_nop 0
	ds_read_b128 a[16:19], v110
	ds_read_b128 a[20:23], v111
	ds_read_b128 a[24:27], v112
	ds_read_b128 a[28:31], v113
	s_waitcnt lgkmcnt(5)
	v_mfma_f32_32x32x16_bf16 v[48:63], a[0:3], a[8:11], v[48:63]
	s_and_b32 m0, s32, 7
	s_lshl_b32 m0, m0, 12
	s_add_i32 m0, m0, 0xcc00
	s_nop 0
	global_load_lds_dwordx4 v[176:177], off
	v_mfma_f32_32x32x16_bf16 v[32:47], a[4:7], a[8:11], v[32:47]
	s_waitcnt lgkmcnt(4)
	v_mfma_f32_32x32x16_bf16 v[16:31], a[0:3], a[12:15], v[16:31]
	v_mfma_f32_32x32x16_bf16 v[0:15], a[4:7], a[12:15], v[0:15]
	s_and_b32 m0, s32, 7
	s_lshl_b32 m0, m0, 11
	s_add_i32 m0, m0, 0x14000
	s_nop 0
	global_load_lds_dwordx4 v[178:179], off
	s_nop 0
	s_nop 0
	s_nop 0
	s_nop 0
	s_waitcnt lgkmcnt(1)
	v_mfma_f32_32x32x16_bf16 v[48:63], a[16:19], a[24:27], v[48:63]
	v_mfma_f32_32x32x16_bf16 v[32:47], a[20:23], a[24:27], v[32:47]
	s_and_b32 m0, s32, 7
	s_lshl_b32 m0, m0, 11
	s_add_i32 m0, m0, 0x14400
	s_nop 0
	global_load_lds_dwordx4 v[180:181], off
	s_waitcnt vmcnt(6)
	s_waitcnt lgkmcnt(0)
	s_barrier
	ds_read_b128 a[12:15], v82 offset:4096
	ds_read_b128 a[8:11], v82
	ds_read_b128 a[4:7], v83 offset:36864
	ds_read_b128 a[0:3], v83 offset:32768
	v_mfma_f32_32x32x16_bf16 v[16:31], a[16:19], a[28:31], v[16:31]
	v_lshl_add_u64 v[158:159], v[66:67], 0, s[30:31]
	s_nop 0
	v_lshl_add_u64 v[160:161], v[68:69], 0, s[30:31]
	s_nop 0
	s_nop 0
	s_nop 0
	s_nop 0
	v_mfma_f32_32x32x16_bf16 v[0:15], a[20:23], a[28:31], v[0:15]
	s_and_b32 m0, s32, 7
	s_lshl_b32 m0, m0, 12
	s_add_i32 m0, m0, 0x18000
	s_nop 0
	global_load_lds_dwordx4 v[158:159], off
	s_nop 0
	v_lshl_add_u64 v[164:165], v[72:73], 0, s[30:31]
	s_nop 0
	s_nop 0
	s_nop 0
	v_lshl_add_u64 v[166:167], v[74:75], 0, s[30:31]
	s_nop 0
	s_nop 0
	s_nop 0
	v_lshl_add_u64 v[168:169], v[76:77], 0, s[30:31]
	s_nop 0
	s_mov_b64 s[30:31], 0x600
	s_nop 0
	s_nop 0
	s_nop 0
	s_nop 0
	s_nop 0
	ds_read_b128 a[16:19], v85 offset:32768
	ds_read_b128 a[20:23], v85 offset:36864
	ds_read_b128 a[24:27], v84
	ds_read_b128 a[28:31], v84 offset:4096
	s_waitcnt lgkmcnt(4)
	v_mfma_f32_32x32x16_bf16 v[48:63], a[0:3], a[8:11], v[48:63]
	s_nop 0
	v_mfma_f32_32x32x16_bf16 v[32:47], a[4:7], a[8:11], v[32:47]
	v_mfma_f32_32x32x16_bf16 v[16:31], a[0:3], a[12:15], v[16:31]
	s_and_b32 m0, s32, 7
	s_lshl_b32 m0, m0, 12
	s_add_i32 m0, m0, 0x18400
	s_nop 0
	global_load_lds_dwordx4 v[160:161], off
	v_mfma_f32_32x32x16_bf16 v[0:15], a[4:7], a[12:15], v[0:15]
	s_nop 0
	s_nop 0
	s_nop 0
	s_nop 0
	ds_read_b128 a[0:3], v87 offset:32768
	ds_read_b128 a[4:7], v87 offset:36864
	ds_read_b128 a[8:11], v86
	ds_read_b128 a[12:15], v86 offset:4096
	s_waitcnt lgkmcnt(5)
	v_mfma_f32_32x32x16_bf16 v[48:63], a[16:19], a[24:27], v[48:63]
	v_mfma_f32_32x32x16_bf16 v[32:47], a[20:23], a[24:27], v[32:47]
	s_and_b32 m0, s32, 7
	s_lshl_b32 m0, m0, 12
	s_add_i32 m0, m0, 0x18800
	s_nop 0
	global_load_lds_dwordx4 v[162:163], off
	s_waitcnt lgkmcnt(4)
	v_mfma_f32_32x32x16_bf16 v[16:31], a[16:19], a[28:31], v[16:31]
	v_mfma_f32_32x32x16_bf16 v[0:15], a[20:23], a[28:31], v[0:15]
	s_nop 0
	s_nop 0
	s_nop 0
	s_nop 0
	ds_read_b128 a[16:19], v89 offset:32768
	ds_read_b128 a[20:23], v89 offset:36864
	ds_read_b128 a[24:27], v88
	ds_read_b128 a[28:31], v88 offset:4096
	s_waitcnt lgkmcnt(5)
	v_mfma_f32_32x32x16_bf16 v[48:63], a[0:3], a[8:11], v[48:63]
	s_and_b32 m0, s32, 7
	s_lshl_b32 m0, m0, 12
	s_add_i32 m0, m0, 0x18c00
	s_nop 0
	global_load_lds_dwordx4 v[164:165], off
	v_mfma_f32_32x32x16_bf16 v[32:47], a[4:7], a[8:11], v[32:47]
	s_waitcnt lgkmcnt(4)
	v_mfma_f32_32x32x16_bf16 v[16:31], a[0:3], a[12:15], v[16:31]
	v_mfma_f32_32x32x16_bf16 v[0:15], a[4:7], a[12:15], v[0:15]
	s_and_b32 m0, s32, 7
	s_lshl_b32 m0, m0, 11
	s_add_i32 m0, m0, 0x20000
	s_nop 0
	global_load_lds_dwordx4 v[166:167], off
	s_nop 0
	s_nop 0
	s_nop 0
	s_nop 0
	s_waitcnt lgkmcnt(1)
	v_mfma_f32_32x32x16_bf16 v[48:63], a[16:19], a[24:27], v[48:63]
	v_mfma_f32_32x32x16_bf16 v[32:47], a[20:23], a[24:27], v[32:47]
	s_and_b32 m0, s32, 7
	s_lshl_b32 m0, m0, 11
	s_add_i32 m0, m0, 0x20400
	s_nop 0
	global_load_lds_dwordx4 v[168:169], off
	s_waitcnt vmcnt(6)
	s_waitcnt lgkmcnt(0)
	s_barrier
	ds_read_b128 a[12:15], v82 offset:53248
	ds_read_b128 a[8:11], v82 offset:49152
	ds_read_b128 a[4:7], v90
	ds_read_b128 a[0:3], v92
	v_mfma_f32_32x32x16_bf16 v[16:31], a[16:19], a[28:31], v[16:31]
	v_lshl_add_u64 v[170:171], v[66:67], 0, s[30:31]
	s_nop 0
	v_lshl_add_u64 v[172:173], v[68:69], 0, s[30:31]
	s_nop 0
	s_nop 0
	s_nop 0
	v_lshl_add_u64 v[174:175], v[70:71], 0, s[30:31]
	s_nop 0
	v_mfma_f32_32x32x16_bf16 v[0:15], a[20:23], a[28:31], v[0:15]
	s_and_b32 m0, s32, 7
	s_lshl_b32 m0, m0, 12
	s_add_i32 m0, m0, 0x0
	s_nop 0
	global_load_lds_dwordx4 v[170:171], off
	s_nop 0
	v_lshl_add_u64 v[176:177], v[72:73], 0, s[30:31]
	s_nop 0
	s_nop 0
	s_nop 0
	v_lshl_add_u64 v[178:179], v[74:75], 0, s[30:31]
	s_nop 0
	s_nop 0
	s_nop 0
	v_lshl_add_u64 v[180:181], v[76:77], 0, s[30:31]
	s_nop 0
	s_mov_b64 s[30:31], 0x680
	s_nop 0
	s_nop 0
	s_nop 0
	s_nop 0
	s_nop 0
	ds_read_b128 a[16:19], v93
	ds_read_b128 a[20:23], v91
	ds_read_b128 a[24:27], v84 offset:49152
	ds_read_b128 a[28:31], v84 offset:53248
	s_waitcnt lgkmcnt(4)
	v_mfma_f32_32x32x16_bf16 v[48:63], a[0:3], a[8:11], v[48:63]
	s_nop 0
	v_mfma_f32_32x32x16_bf16 v[32:47], a[4:7], a[8:11], v[32:47]
	v_mfma_f32_32x32x16_bf16 v[16:31], a[0:3], a[12:15], v[16:31]
	s_and_b32 m0, s32, 7
	s_lshl_b32 m0, m0, 12
	s_add_i32 m0, m0, 0x400
	s_nop 0
	global_load_lds_dwordx4 v[172:173], off
	v_mfma_f32_32x32x16_bf16 v[0:15], a[4:7], a[12:15], v[0:15]
	s_nop 0
	s_nop 0
	s_nop 0
	s_nop 0
	ds_read_b128 a[0:3], v95
	ds_read_b128 a[4:7], v94
	ds_read_b128 a[8:11], v86 offset:49152
	ds_read_b128 a[12:15], v86 offset:53248
	s_waitcnt lgkmcnt(5)
	v_mfma_f32_32x32x16_bf16 v[48:63], a[16:19], a[24:27], v[48:63]
	v_mfma_f32_32x32x16_bf16 v[32:47], a[20:23], a[24:27], v[32:47]
	s_and_b32 m0, s32, 7
	s_lshl_b32 m0, m0, 12
	s_add_i32 m0, m0, 0x800
	s_nop 0
	global_load_lds_dwordx4 v[174:175], off
	s_waitcnt lgkmcnt(4)
	v_mfma_f32_32x32x16_bf16 v[16:31], a[16:19], a[28:31], v[16:31]
	v_mfma_f32_32x32x16_bf16 v[0:15], a[20:23], a[28:31], v[0:15]
	s_nop 0
	s_nop 0
	s_nop 0
	s_nop 0
	ds_read_b128 a[16:19], v97
	ds_read_b128 a[20:23], v96
	ds_read_b128 a[24:27], v88 offset:49152
	ds_read_b128 a[28:31], v88 offset:53248
	s_waitcnt lgkmcnt(5)
	v_mfma_f32_32x32x16_bf16 v[48:63], a[0:3], a[8:11], v[48:63]
	s_and_b32 m0, s32, 7
	s_lshl_b32 m0, m0, 12
	s_add_i32 m0, m0, 0xc00
	s_nop 0
	global_load_lds_dwordx4 v[176:177], off
	v_mfma_f32_32x32x16_bf16 v[32:47], a[4:7], a[8:11], v[32:47]
	s_waitcnt lgkmcnt(4)
	v_mfma_f32_32x32x16_bf16 v[16:31], a[0:3], a[12:15], v[16:31]
	v_mfma_f32_32x32x16_bf16 v[0:15], a[4:7], a[12:15], v[0:15]
	s_and_b32 m0, s32, 7
	s_lshl_b32 m0, m0, 11
	s_add_i32 m0, m0, 0x8000
	s_nop 0
	global_load_lds_dwordx4 v[178:179], off
	s_nop 0
	s_nop 0
	s_nop 0
	s_nop 0
	s_waitcnt lgkmcnt(1)
	v_mfma_f32_32x32x16_bf16 v[48:63], a[16:19], a[24:27], v[48:63]
	v_mfma_f32_32x32x16_bf16 v[32:47], a[20:23], a[24:27], v[32:47]
	s_and_b32 m0, s32, 7
	s_lshl_b32 m0, m0, 11
	s_add_i32 m0, m0, 0x8400
	s_nop 0
	global_load_lds_dwordx4 v[180:181], off
	s_waitcnt vmcnt(6)
	s_waitcnt lgkmcnt(0)
	s_barrier
	ds_read_b128 a[12:15], v101
	ds_read_b128 a[8:11], v100
	ds_read_b128 a[4:7], v99
	ds_read_b128 a[0:3], v98
	v_mfma_f32_32x32x16_bf16 v[16:31], a[16:19], a[28:31], v[16:31]
	v_lshl_add_u64 v[158:159], v[66:67], 0, s[30:31]
	s_nop 0
	v_lshl_add_u64 v[160:161], v[68:69], 0, s[30:31]
	s_nop 0
	s_nop 0
	s_nop 0
	v_lshl_add_u64 v[162:163], v[70:71], 0, s[30:31]
	s_nop 0
	v_mfma_f32_32x32x16_bf16 v[0:15], a[20:23], a[28:31], v[0:15]
	s_and_b32 m0, s32, 7
	s_lshl_b32 m0, m0, 12
	s_add_i32 m0, m0, 0xc000
	s_nop 0
	global_load_lds_dwordx4 v[158:159], off
	s_nop 0
	v_lshl_add_u64 v[164:165], v[72:73], 0, s[30:31]
	s_nop 0
	s_nop 0
	s_nop 0
	v_lshl_add_u64 v[166:167], v[74:75], 0, s[30:31]
	s_nop 0
	s_nop 0
	s_nop 0
	v_lshl_add_u64 v[168:169], v[76:77], 0, s[30:31]
	s_nop 0
	s_mov_b64 s[30:31], 0x700
	s_nop 0
	s_nop 0
	s_nop 0
	s_nop 0
	s_nop 0
	ds_read_b128 a[16:19], v102
	ds_read_b128 a[20:23], v103
	ds_read_b128 a[24:27], v104
	ds_read_b128 a[28:31], v105
	s_waitcnt lgkmcnt(4)
	v_mfma_f32_32x32x16_bf16 v[48:63], a[0:3], a[8:11], v[48:63]
	s_nop 0
	v_mfma_f32_32x32x16_bf16 v[32:47], a[4:7], a[8:11], v[32:47]
	v_mfma_f32_32x32x16_bf16 v[16:31], a[0:3], a[12:15], v[16:31]
	s_and_b32 m0, s32, 7
	s_lshl_b32 m0, m0, 12
	s_add_i32 m0, m0, 0xc400
	s_nop 0
	global_load_lds_dwordx4 v[160:161], off
	v_mfma_f32_32x32x16_bf16 v[0:15], a[4:7], a[12:15], v[0:15]
	s_nop 0
	s_nop 0
	s_nop 0
	s_nop 0
	ds_read_b128 a[0:3], v106
	ds_read_b128 a[4:7], v107
	ds_read_b128 a[8:11], v108
	ds_read_b128 a[12:15], v109
	s_waitcnt lgkmcnt(5)
	v_mfma_f32_32x32x16_bf16 v[48:63], a[16:19], a[24:27], v[48:63]
	v_mfma_f32_32x32x16_bf16 v[32:47], a[20:23], a[24:27], v[32:47]
	s_and_b32 m0, s32, 7
	s_lshl_b32 m0, m0, 12
	s_add_i32 m0, m0, 0xc800
	s_nop 0
	global_load_lds_dwordx4 v[162:163], off
	s_waitcnt lgkmcnt(4)
	v_mfma_f32_32x32x16_bf16 v[16:31], a[16:19], a[28:31], v[16:31]
	v_mfma_f32_32x32x16_bf16 v[0:15], a[20:23], a[28:31], v[0:15]
	s_nop 0
	s_nop 0
	s_nop 0
	s_nop 0
	ds_read_b128 a[16:19], v110
	ds_read_b128 a[20:23], v111
	ds_read_b128 a[24:27], v112
	ds_read_b128 a[28:31], v113
	s_waitcnt lgkmcnt(5)
	v_mfma_f32_32x32x16_bf16 v[48:63], a[0:3], a[8:11], v[48:63]
	s_and_b32 m0, s32, 7
	s_lshl_b32 m0, m0, 12
	s_add_i32 m0, m0, 0xcc00
	s_nop 0
	global_load_lds_dwordx4 v[164:165], off
	v_mfma_f32_32x32x16_bf16 v[32:47], a[4:7], a[8:11], v[32:47]
	s_waitcnt lgkmcnt(4)
	v_mfma_f32_32x32x16_bf16 v[16:31], a[0:3], a[12:15], v[16:31]
	v_mfma_f32_32x32x16_bf16 v[0:15], a[4:7], a[12:15], v[0:15]
	s_and_b32 m0, s32, 7
	s_lshl_b32 m0, m0, 11
	s_add_i32 m0, m0, 0x14000
	s_nop 0
	global_load_lds_dwordx4 v[166:167], off
	s_nop 0
	s_nop 0
	s_nop 0
	s_nop 0
	s_waitcnt lgkmcnt(1)
	v_mfma_f32_32x32x16_bf16 v[48:63], a[16:19], a[24:27], v[48:63]
	v_mfma_f32_32x32x16_bf16 v[32:47], a[20:23], a[24:27], v[32:47]
	s_and_b32 m0, s32, 7
	s_lshl_b32 m0, m0, 11
	s_add_i32 m0, m0, 0x14400
	s_nop 0
	global_load_lds_dwordx4 v[168:169], off
	s_waitcnt vmcnt(6)
	s_waitcnt lgkmcnt(0)
	s_barrier
	ds_read_b128 a[12:15], v82 offset:4096
	ds_read_b128 a[8:11], v82
	ds_read_b128 a[4:7], v83 offset:36864
	ds_read_b128 a[0:3], v83 offset:32768
	v_mfma_f32_32x32x16_bf16 v[16:31], a[16:19], a[28:31], v[16:31]
	v_lshl_add_u64 v[170:171], v[66:67], 0, s[30:31]
	s_nop 0
	v_lshl_add_u64 v[172:173], v[68:69], 0, s[30:31]
	s_nop 0
	s_nop 0
	s_nop 0
	v_lshl_add_u64 v[174:175], v[70:71], 0, s[30:31]
	s_nop 0
	v_mfma_f32_32x32x16_bf16 v[0:15], a[20:23], a[28:31], v[0:15]
	s_and_b32 m0, s32, 7
	s_lshl_b32 m0, m0, 12
	s_add_i32 m0, m0, 0x18000
	s_nop 0
	global_load_lds_dwordx4 v[170:171], off
	s_nop 0
	v_lshl_add_u64 v[176:177], v[72:73], 0, s[30:31]
	s_nop 0
	s_nop 0
	s_nop 0
	v_lshl_add_u64 v[178:179], v[74:75], 0, s[30:31]
	s_nop 0
	s_nop 0
	s_nop 0
	v_lshl_add_u64 v[180:181], v[76:77], 0, s[30:31]
	s_nop 0
	s_mov_b64 s[30:31], 0x780
	s_nop 0
	s_nop 0
	s_nop 0
	s_nop 0
	s_nop 0
	ds_read_b128 a[16:19], v85 offset:32768
	ds_read_b128 a[20:23], v85 offset:36864
	ds_read_b128 a[24:27], v84
	ds_read_b128 a[28:31], v84 offset:4096
	s_waitcnt lgkmcnt(4)
	v_mfma_f32_32x32x16_bf16 v[48:63], a[0:3], a[8:11], v[48:63]
	v_lshl_add_u64 v[158:159], v[66:67], 0, s[30:31]
	s_nop 0
	v_mfma_f32_32x32x16_bf16 v[32:47], a[4:7], a[8:11], v[32:47]
	v_mfma_f32_32x32x16_bf16 v[16:31], a[0:3], a[12:15], v[16:31]
	s_and_b32 m0, s32, 7
	s_lshl_b32 m0, m0, 12
	s_add_i32 m0, m0, 0x18400
	s_nop 0
	global_load_lds_dwordx4 v[172:173], off
	v_mfma_f32_32x32x16_bf16 v[0:15], a[4:7], a[12:15], v[0:15]
	s_nop 0
	s_nop 0
	s_nop 0
	s_nop 0
	ds_read_b128 a[0:3], v87 offset:32768
	ds_read_b128 a[4:7], v87 offset:36864
	ds_read_b128 a[8:11], v86
	ds_read_b128 a[12:15], v86 offset:4096
	s_waitcnt lgkmcnt(5)
	v_mfma_f32_32x32x16_bf16 v[48:63], a[16:19], a[24:27], v[48:63]
	v_mfma_f32_32x32x16_bf16 v[32:47], a[20:23], a[24:27], v[32:47]
	s_and_b32 m0, s32, 7
	s_lshl_b32 m0, m0, 12
	s_add_i32 m0, m0, 0x18800
	s_nop 0
	global_load_lds_dwordx4 v[174:175], off
	s_waitcnt lgkmcnt(4)
	v_mfma_f32_32x32x16_bf16 v[16:31], a[16:19], a[28:31], v[16:31]
	v_mfma_f32_32x32x16_bf16 v[0:15], a[20:23], a[28:31], v[0:15]
	s_nop 0
	s_nop 0
	s_nop 0
	s_nop 0
	ds_read_b128 a[16:19], v89 offset:32768
	ds_read_b128 a[20:23], v89 offset:36864
	ds_read_b128 a[24:27], v88
	ds_read_b128 a[28:31], v88 offset:4096
	s_waitcnt lgkmcnt(5)
	v_mfma_f32_32x32x16_bf16 v[48:63], a[0:3], a[8:11], v[48:63]
	s_and_b32 m0, s32, 7
	s_lshl_b32 m0, m0, 12
	s_add_i32 m0, m0, 0x18c00
	s_nop 0
	global_load_lds_dwordx4 v[176:177], off
	v_mfma_f32_32x32x16_bf16 v[32:47], a[4:7], a[8:11], v[32:47]
	s_waitcnt lgkmcnt(4)
	v_mfma_f32_32x32x16_bf16 v[16:31], a[0:3], a[12:15], v[16:31]
	v_mfma_f32_32x32x16_bf16 v[0:15], a[4:7], a[12:15], v[0:15]
	s_and_b32 m0, s32, 7
	s_lshl_b32 m0, m0, 11
	s_add_i32 m0, m0, 0x20000
	s_nop 0
	global_load_lds_dwordx4 v[178:179], off
	s_nop 0
	s_nop 0
	s_nop 0
	s_nop 0
	s_waitcnt lgkmcnt(1)
	v_mfma_f32_32x32x16_bf16 v[48:63], a[16:19], a[24:27], v[48:63]
	v_mfma_f32_32x32x16_bf16 v[32:47], a[20:23], a[24:27], v[32:47]
	s_and_b32 m0, s32, 7
	s_lshl_b32 m0, m0, 11
	s_add_i32 m0, m0, 0x20400
	s_nop 0
	global_load_lds_dwordx4 v[180:181], off
	s_waitcnt vmcnt(6)
	s_waitcnt lgkmcnt(0)
	s_barrier
	ds_read_b128 a[12:15], v82 offset:53248
	ds_read_b128 a[8:11], v82 offset:49152
	ds_read_b128 a[4:7], v90
	ds_read_b128 a[0:3], v92
	s_nop 0
	v_lshl_add_u64 v[160:161], v[68:69], 0, s[30:31]
	s_nop 0
	v_mfma_f32_32x32x16_bf16 v[16:31], a[16:19], a[28:31], v[16:31]
	s_nop 0
	v_lshl_add_u64 v[162:163], v[70:71], 0, s[30:31]
	s_nop 0
	s_nop 0
	s_nop 0
	v_lshl_add_u64 v[164:165], v[72:73], 0, s[30:31]
	s_nop 0
	v_mfma_f32_32x32x16_bf16 v[0:15], a[20:23], a[28:31], v[0:15]
	s_and_b32 m0, s32, 7
	s_lshl_b32 m0, m0, 12
	s_add_i32 m0, m0, 0x0
	s_nop 0
	global_load_lds_dwordx4 v[158:159], off
	s_nop 0
	v_lshl_add_u64 v[166:167], v[74:75], 0, s[30:31]
	s_nop 0
	s_nop 0
	s_nop 0
	v_lshl_add_u64 v[168:169], v[76:77], 0, s[30:31]
	s_nop 0
	s_nop 0
	s_nop 0
	s_nop 0
	s_nop 0
	s_nop 0
	s_nop 0
	ds_read_b128 a[16:19], v93
	ds_read_b128 a[20:23], v91
	ds_read_b128 a[24:27], v84 offset:49152
	ds_read_b128 a[28:31], v84 offset:53248
	s_waitcnt lgkmcnt(4)
	v_mfma_f32_32x32x16_bf16 v[48:63], a[0:3], a[8:11], v[48:63]
	v_mfma_f32_32x32x16_bf16 v[32:47], a[4:7], a[8:11], v[32:47]
	v_mfma_f32_32x32x16_bf16 v[16:31], a[0:3], a[12:15], v[16:31]
	s_and_b32 m0, s32, 7
	s_lshl_b32 m0, m0, 12
	s_add_i32 m0, m0, 0x400
	s_nop 0
	global_load_lds_dwordx4 v[160:161], off
	v_mfma_f32_32x32x16_bf16 v[0:15], a[4:7], a[12:15], v[0:15]
	s_nop 0
	s_nop 0
	s_nop 0
	s_nop 0
	ds_read_b128 a[0:3], v95
	ds_read_b128 a[4:7], v94
	ds_read_b128 a[8:11], v86 offset:49152
	ds_read_b128 a[12:15], v86 offset:53248
	s_waitcnt lgkmcnt(5)
	v_mfma_f32_32x32x16_bf16 v[48:63], a[16:19], a[24:27], v[48:63]
	v_mfma_f32_32x32x16_bf16 v[32:47], a[20:23], a[24:27], v[32:47]
	s_and_b32 m0, s32, 7
	s_lshl_b32 m0, m0, 12
	s_add_i32 m0, m0, 0x800
	s_nop 0
	global_load_lds_dwordx4 v[162:163], off
	s_waitcnt lgkmcnt(4)
	v_mfma_f32_32x32x16_bf16 v[16:31], a[16:19], a[28:31], v[16:31]
	v_mfma_f32_32x32x16_bf16 v[0:15], a[20:23], a[28:31], v[0:15]
	s_nop 0
	s_nop 0
	s_nop 0
	s_nop 0
	ds_read_b128 a[16:19], v97
	ds_read_b128 a[20:23], v96
	ds_read_b128 a[24:27], v88 offset:49152
	ds_read_b128 a[28:31], v88 offset:53248
	s_waitcnt lgkmcnt(5)
	v_mfma_f32_32x32x16_bf16 v[48:63], a[0:3], a[8:11], v[48:63]
	s_and_b32 m0, s32, 7
	s_lshl_b32 m0, m0, 12
	s_add_i32 m0, m0, 0xc00
	s_nop 0
	global_load_lds_dwordx4 v[164:165], off
	v_mfma_f32_32x32x16_bf16 v[32:47], a[4:7], a[8:11], v[32:47]
	s_waitcnt lgkmcnt(4)
	v_mfma_f32_32x32x16_bf16 v[16:31], a[0:3], a[12:15], v[16:31]
	v_mfma_f32_32x32x16_bf16 v[0:15], a[4:7], a[12:15], v[0:15]
	s_and_b32 m0, s32, 7
	s_lshl_b32 m0, m0, 11
	s_add_i32 m0, m0, 0x8000
	s_nop 0
	global_load_lds_dwordx4 v[166:167], off
	s_nop 0
	s_nop 0
	s_nop 0
	s_nop 0
	s_waitcnt lgkmcnt(1)
	v_mfma_f32_32x32x16_bf16 v[48:63], a[16:19], a[24:27], v[48:63]
	v_mfma_f32_32x32x16_bf16 v[32:47], a[20:23], a[24:27], v[32:47]
	s_and_b32 m0, s32, 7
	s_lshl_b32 m0, m0, 11
	s_add_i32 m0, m0, 0x8400
	s_nop 0
	global_load_lds_dwordx4 v[168:169], off
	s_waitcnt vmcnt(6)
	s_waitcnt lgkmcnt(0)
	s_barrier
	ds_read_b128 a[12:15], v101
	ds_read_b128 a[8:11], v100
	ds_read_b128 a[4:7], v99
	ds_read_b128 a[0:3], v98
	v_mfma_f32_32x32x16_bf16 v[16:31], a[16:19], a[28:31], v[16:31]
	v_mfma_f32_32x32x16_bf16 v[0:15], a[20:23], a[28:31], v[0:15]
	s_nop 0
	s_nop 0
	s_nop 0
	s_nop 0
	ds_read_b128 a[16:19], v102
	ds_read_b128 a[20:23], v103
	ds_read_b128 a[24:27], v104
	ds_read_b128 a[28:31], v105
	s_waitcnt lgkmcnt(4)
	v_mfma_f32_32x32x16_bf16 v[48:63], a[0:3], a[8:11], v[48:63]
	v_mfma_f32_32x32x16_bf16 v[32:47], a[4:7], a[8:11], v[32:47]
	v_mfma_f32_32x32x16_bf16 v[16:31], a[0:3], a[12:15], v[16:31]
	v_mfma_f32_32x32x16_bf16 v[0:15], a[4:7], a[12:15], v[0:15]
	s_nop 0
	s_nop 0
	s_nop 0
	s_nop 0
	ds_read_b128 a[0:3], v106
	ds_read_b128 a[4:7], v107
	ds_read_b128 a[8:11], v108
	ds_read_b128 a[12:15], v109
	s_waitcnt lgkmcnt(5)
	v_mfma_f32_32x32x16_bf16 v[48:63], a[16:19], a[24:27], v[48:63]
	v_mfma_f32_32x32x16_bf16 v[32:47], a[20:23], a[24:27], v[32:47]
	s_waitcnt lgkmcnt(4)
	v_mfma_f32_32x32x16_bf16 v[16:31], a[16:19], a[28:31], v[16:31]
	v_mfma_f32_32x32x16_bf16 v[0:15], a[20:23], a[28:31], v[0:15]
	s_nop 0
	s_nop 0
	s_nop 0
	s_nop 0
	ds_read_b128 a[16:19], v110
	ds_read_b128 a[20:23], v111
	ds_read_b128 a[24:27], v112
	ds_read_b128 a[28:31], v113
	s_waitcnt lgkmcnt(5)
	v_mfma_f32_32x32x16_bf16 v[48:63], a[0:3], a[8:11], v[48:63]
	v_mfma_f32_32x32x16_bf16 v[32:47], a[4:7], a[8:11], v[32:47]
	s_waitcnt lgkmcnt(4)
	v_mfma_f32_32x32x16_bf16 v[16:31], a[0:3], a[12:15], v[16:31]
	v_mfma_f32_32x32x16_bf16 v[0:15], a[4:7], a[12:15], v[0:15]
	s_nop 0
	s_nop 0
	s_nop 0
	s_nop 0
	s_waitcnt lgkmcnt(1)
	v_mfma_f32_32x32x16_bf16 v[48:63], a[16:19], a[24:27], v[48:63]
	v_mfma_f32_32x32x16_bf16 v[32:47], a[20:23], a[24:27], v[32:47]
	s_waitcnt vmcnt(0)
	s_waitcnt lgkmcnt(0)
	s_barrier
	ds_read_b128 a[12:15], v82 offset:4096
	ds_read_b128 a[8:11], v82
	ds_read_b128 a[4:7], v83 offset:36864
	ds_read_b128 a[0:3], v83 offset:32768
	v_mfma_f32_32x32x16_bf16 v[16:31], a[16:19], a[28:31], v[16:31]
	v_mfma_f32_32x32x16_bf16 v[0:15], a[20:23], a[28:31], v[0:15]
	s_nop 0
	s_nop 0
	s_nop 0
	s_nop 0
	ds_read_b128 a[16:19], v85 offset:32768
	ds_read_b128 a[20:23], v85 offset:36864
	ds_read_b128 a[24:27], v84
	ds_read_b128 a[28:31], v84 offset:4096
	s_waitcnt lgkmcnt(4)
	v_mfma_f32_32x32x16_bf16 v[48:63], a[0:3], a[8:11], v[48:63]
	v_mfma_f32_32x32x16_bf16 v[32:47], a[4:7], a[8:11], v[32:47]
	v_mfma_f32_32x32x16_bf16 v[16:31], a[0:3], a[12:15], v[16:31]
	v_mfma_f32_32x32x16_bf16 v[0:15], a[4:7], a[12:15], v[0:15]
	s_nop 0
	s_nop 0
	s_nop 0
	s_nop 0
	ds_read_b128 a[0:3], v87 offset:32768
	ds_read_b128 a[4:7], v87 offset:36864
	ds_read_b128 a[8:11], v86
	ds_read_b128 a[12:15], v86 offset:4096
	s_waitcnt lgkmcnt(5)
	v_mfma_f32_32x32x16_bf16 v[48:63], a[16:19], a[24:27], v[48:63]
	v_mfma_f32_32x32x16_bf16 v[32:47], a[20:23], a[24:27], v[32:47]
	s_waitcnt lgkmcnt(4)
	v_mfma_f32_32x32x16_bf16 v[16:31], a[16:19], a[28:31], v[16:31]
	v_mfma_f32_32x32x16_bf16 v[0:15], a[20:23], a[28:31], v[0:15]
	s_nop 0
	s_nop 0
	s_nop 0
	s_nop 0
	s_waitcnt lgkmcnt(1)
	v_mfma_f32_32x32x16_bf16 v[48:63], a[0:3], a[8:11], v[48:63]
	v_mfma_f32_32x32x16_bf16 v[32:47], a[4:7], a[8:11], v[32:47]
	s_waitcnt lgkmcnt(0)
	v_mfma_f32_32x32x16_bf16 v[16:31], a[0:3], a[12:15], v[16:31]
	v_mfma_f32_32x32x16_bf16 v[0:15], a[4:7], a[12:15], v[0:15]
	ds_read_b128 v[66:69], v89 offset:32768
	ds_read_b128 v[70:73], v88
	ds_read_b128 v[74:77], v89 offset:36864
	ds_read_b128 v[82:85], v88 offset:4096
	s_waitcnt lgkmcnt(0)
	s_barrier
	s_waitcnt lgkmcnt(0)
	v_mfma_f32_32x32x16_bf16 v[48:63], v[66:69], v[70:73], v[48:63]
	v_mfma_f32_32x32x16_bf16 v[32:47], v[74:77], v[70:73], v[32:47]
	v_mov_b32_e32 v70, 0
	v_mfma_f32_32x32x16_bf16 v[16:31], v[66:69], v[82:85], v[16:31]
	v_lshl_or_b32 v69, v80, 6, v81
	v_add_u32_e32 v66, s20, v69
	v_cmp_gt_i32_e32 vcc, s69, v66
	v_mov_b32_e32 v68, 0
	v_ashrrev_i32_e32 v67, 31, v66
	v_mfma_f32_32x32x16_bf16 v[0:15], v[74:77], v[82:85], v[0:15]
	s_and_saveexec_b64 s[0:1], vcc
	s_cbranch_execz .LBB0_588
	v_lshl_add_u64 v[70:71], v[66:67], 2, s[76:77]
	global_load_dword v70, v[70:71], off
	s_waitcnt vmcnt(0)
	v_fmamk_f32 v70, v70, 0x3a800000, v188
	v_mul_f32_e32 v71, 0x4b800000, v70
	v_cmp_gt_f32_e32 vcc, s82, v70
	s_nop 1
	v_cndmask_b32_e32 v70, v70, v71, vcc
	v_rsq_f32_e32 v70, v70
	s_nop 0
	v_mul_f32_e32 v71, 0x45800000, v70
	v_cndmask_b32_e32 v70, v70, v71, vcc

.LBB0_612:
	v_readlane_b32 s0, v212, 1
	s_cmp_ge_i32 s56, s0
	s_mov_b64 s[0:1], -1
	s_cbranch_scc0 .LBB0_742
	s_ashr_i32 s1, s52, 31
	s_lshr_b32 s0, s1, 27
	s_add_i32 s2, s52, s0
	s_ashr_i32 s0, s2, 5
	s_and_b32 s2, s2, 0xffe0
	s_sub_i32 s2, s52, s2
	s_lshr_b32 s1, s1, 30
	s_bfe_i32 s20, s2, 0x80000
	s_add_i32 s1, s52, s1
	s_bfe_u32 s20, s20, 0x2000d
	s_and_b32 s1, s1, 0x1fffffc
	s_add_i32 s2, s2, s20
	s_sub_i32 s23, s52, s1
	s_ashr_i32 s1, s0, 31
	s_bfe_i32 s2, s2, 0x80000
	s_lshl_b64 s[20:21], s[0:1], 20
	v_readlane_b32 s22, v215, 46
	s_sext_i32_i16 s2, s2
	s_add_u32 s20, s22, s20
	v_readlane_b32 s22, v215, 47
	v_mov_b32_e32 v12, v133
	s_addc_u32 s21, s22, s21
	s_lshl_b32 s2, s2, 6
	s_and_b32 s22, s2, 0xffffff00
	v_ashrrev_i32_e32 v6, 6, v12
	v_bfe_u32 v7, v12, 3, 3
	v_lshl_or_b32 v8, v6, 5, v7
	v_add_u32_e32 v0, s22, v8
	s_waitcnt lgkmcnt(0)
	v_ashrrev_i32_e32 v1, 31, v0
	v_lshlrev_b64 v[2:3], 11, v[0:1]
	v_bfe_u32 v1, v12, 4, 2
	v_readlane_b32 s28, v215, 50
	v_xor_b32_e32 v1, v1, v12
	v_readlane_b32 s29, v215, 51
	v_lshlrev_b32_e32 v1, 4, v1
	v_and_b32_e32 v64, 0x70, v1
	v_lshl_add_u64 v[2:3], s[28:29], 0, v[2:3]
	v_or_b32_e32 v1, 8, v8
	v_lshl_add_u64 v[66:67], v[2:3], 0, v[64:65]
	v_add_u32_e32 v2, s22, v1
	v_lshrrev_b32_e32 v1, 1, v1
	v_xor_b32_e32 v1, v1, v12
	v_ashrrev_i32_e32 v3, 31, v2
	v_lshlrev_b32_e32 v1, 4, v1
	v_or_b32_e32 v0, 16, v0
	v_lshlrev_b64 v[2:3], 11, v[2:3]
	v_and_b32_e32 v4, 0x70, v1
	v_ashrrev_i32_e32 v1, 31, v0
	v_lshl_add_u64 v[2:3], s[28:29], 0, v[2:3]
	v_mov_b32_e32 v5, v65
	v_lshlrev_b64 v[0:1], 11, v[0:1]
	v_lshl_add_u64 v[68:69], v[2:3], 0, v[4:5]
	v_lshl_add_u64 v[0:1], s[28:29], 0, v[0:1]
	v_or_b32_e32 v2, 24, v8
	v_lshl_add_u64 v[70:71], v[0:1], 0, v[64:65]
	v_add_u32_e32 v0, s22, v2
	v_lshrrev_b32_e32 v2, 1, v2
	v_ashrrev_i32_e32 v1, 31, v0
	v_xor_b32_e32 v2, v2, v12
	v_lshlrev_b64 v[0:1], 11, v[0:1]
	v_lshlrev_b32_e32 v2, 4, v2
	v_lshl_add_u64 v[0:1], s[28:29], 0, v[0:1]
	v_and_b32_e32 v2, 0x70, v2
	v_mov_b32_e32 v3, v65
	s_lshl_b32 s2, s23, 7
	v_lshl_add_u64 v[72:73], v[0:1], 0, v[2:3]
	v_lshl_or_b32 v2, v6, 4, v7
	v_add_u32_e32 v0, s2, v2
	v_lshlrev_b32_e32 v3, 12, v6
	v_ashrrev_i32_e32 v1, 31, v0
	v_add_u32_e32 v125, 0, v3
	v_lshlrev_b64 v[0:1], 11, v[0:1]
	s_waitcnt vmcnt(0)
	v_readfirstlane_b32 s42, v125
	v_add_u32_e32 v126, 0x400, v125
	v_lshl_add_u64 v[0:1], s[20:21], 0, v[0:1]
	v_or_b32_e32 v2, 8, v2
	s_waitcnt lgkmcnt(0)
	s_barrier
	s_mov_b32 m0, s42
	v_readfirstlane_b32 s43, v126
	v_add_u32_e32 v127, 0x800, v125
	v_lshlrev_b32_e32 v5, 11, v6
	v_and_b32_e32 v79, 1, v6
	v_lshl_add_u64 v[74:75], v[0:1], 0, v[64:65]
	v_add_u32_e32 v0, s2, v2
	v_lshrrev_b32_e32 v2, 1, v2
	global_load_lds_dwordx4 v[66:67], off
	s_mov_b32 m0, s43
	v_readfirstlane_b32 s44, v127
	v_add_u32_e32 v128, 0xc00, v125
	v_add_u32_e32 v6, 0, v5
	v_ashrrev_i32_e32 v1, 31, v0
	v_xor_b32_e32 v2, v2, v12
	global_load_lds_dwordx4 v[68:69], off
	s_mov_b32 m0, s44
	v_readfirstlane_b32 s45, v128
	v_add_u32_e32 v130, 0x8000, v6
	v_lshlrev_b64 v[0:1], 11, v[0:1]
	v_lshlrev_b32_e32 v2, 4, v2
	global_load_lds_dwordx4 v[70:71], off
	s_mov_b32 m0, s45
	v_readfirstlane_b32 s46, v130
	v_add_u32_e32 v129, 0x8400, v6
	v_lshl_add_u64 v[0:1], s[20:21], 0, v[0:1]
	v_and_b32_e32 v64, 0x70, v2
	global_load_lds_dwordx4 v[72:73], off
	s_mov_b32 m0, s46
	v_readfirstlane_b32 s47, v129
	v_add_u32_e32 v119, 0xc000, v125
	v_lshl_add_u64 v[76:77], v[0:1], 0, v[64:65]
	global_load_lds_dwordx4 v[74:75], off
	s_mov_b32 m0, s47
	s_mov_b64 s[20:21], 0x80
	v_readfirstlane_b32 s36, v119
	v_add_u32_e32 v120, 0xc400, v125
	global_load_lds_dwordx4 v[76:77], off
	v_lshl_add_u64 v[0:1], v[66:67], 0, s[20:21]
	s_mov_b32 m0, s36
	v_readfirstlane_b32 s37, v120
	v_add_u32_e32 v121, 0xc800, v125
	global_load_lds_dwordx4 v[0:1], off
	v_lshl_add_u64 v[0:1], v[68:69], 0, s[20:21]
	s_mov_b32 m0, s37
	v_readfirstlane_b32 s38, v121
	v_add_u32_e32 v122, 0xcc00, v125
	global_load_lds_dwordx4 v[0:1], off
	v_lshl_add_u64 v[0:1], v[70:71], 0, s[20:21]
	s_mov_b32 m0, s38
	v_readfirstlane_b32 s39, v122
	v_add_u32_e32 v123, s85, v5
	global_load_lds_dwordx4 v[0:1], off
	v_lshl_add_u64 v[0:1], v[72:73], 0, s[20:21]
	s_mov_b32 m0, s39
	v_readfirstlane_b32 s40, v123
	v_add_u32_e32 v124, 0x14400, v6
	global_load_lds_dwordx4 v[0:1], off
	v_lshl_add_u64 v[0:1], v[74:75], 0, s[20:21]
	s_mov_b32 m0, s40
	v_readfirstlane_b32 s41, v124
	global_load_lds_dwordx4 v[0:1], off
	v_lshl_add_u64 v[0:1], v[76:77], 0, s[20:21]
	s_mov_b32 m0, s41
	v_lshrrev_b32_e32 v2, 1, v12
	v_bfe_u32 v64, v12, 5, 1
	global_load_lds_dwordx4 v[0:1], off
	v_add_u32_e32 v113, s3, v3
	v_bitop3_b32 v0, v2, v64, 7 bitop3:0x6c
	s_waitcnt vmcnt(6)
	s_mov_b64 s[30:31], 0x100
	v_readfirstlane_b32 s20, v113
	v_add_u32_e32 v114, 0x400, v113
	v_lshlrev_b32_e32 v110, 4, v0
	s_waitcnt lgkmcnt(0)
	s_barrier
	v_lshl_add_u64 v[0:1], v[66:67], 0, s[30:31]
	s_mov_b32 m0, s20
	v_readfirstlane_b32 s21, v114
	v_add_u32_e32 v115, 0x800, v113
	global_load_lds_dwordx4 v[0:1], off
	v_lshl_add_u64 v[0:1], v[68:69], 0, s[30:31]
	s_mov_b32 m0, s21
	v_readfirstlane_b32 s23, v115
	v_add_u32_e32 v116, 0xc00, v113
	v_readlane_b32 s29, v212, 31
	v_and_b32_e32 v80, 31, v12
	global_load_lds_dwordx4 v[0:1], off
	v_lshl_add_u64 v[0:1], v[70:71], 0, s[30:31]
	s_mov_b32 m0, s23
	v_readfirstlane_b32 s28, v116
	v_add_u32_e32 v117, s29, v5
	v_add_u32_e32 v2, s3, v5
	v_lshlrev_b32_e32 v4, 7, v80
	global_load_lds_dwordx4 v[0:1], off
	v_lshl_add_u64 v[0:1], v[72:73], 0, s[30:31]
	s_mov_b32 m0, s28
	v_readfirstlane_b32 s29, v117
	v_add_u32_e32 v118, 0x8400, v2
	v_lshl_or_b32 v102, v79, 13, v4
	global_load_lds_dwordx4 v[0:1], off
	v_lshl_add_u64 v[0:1], v[74:75], 0, s[30:31]
	s_mov_b32 m0, s29
	v_readfirstlane_b32 s33, v118
	global_load_lds_dwordx4 v[0:1], off
	v_lshl_add_u64 v[0:1], v[76:77], 0, s[30:31]
	s_mov_b32 m0, s33
	v_add_u32_e32 v100, 0, v102
	global_load_lds_dwordx4 v[0:1], off
	v_add_u32_e32 v82, v100, v110
	v_ashrrev_i32_e32 v78, 7, v12
	ds_read_b128 a[0:3], v82 offset:32768
	ds_read_b128 a[4:7], v82 offset:36864
	v_lshl_or_b32 v111, v78, 13, v4
	v_add_u32_e32 v101, 0, v111
	v_add_u32_e32 v81, v101, v110
	ds_read_b128 a[8:11], v81
	ds_read_b128 a[12:15], v81 offset:4096
	v_lshrrev_b32_e32 v182, 6, v133
	s_nop 0
	v_readfirstlane_b32 s32, v182
	s_waitcnt lgkmcnt(1)
	v_mfma_f32_32x32x16_bf16 v[48:63], a[0:3], a[8:11], 0
	v_bfe_u32 v103, v12, 1, 3
	v_bitop3_b32 v85, v64, v103, 4 bitop3:0x36
	v_lshlrev_b32_e32 v131, 4, v85
	v_add_u32_e32 v85, v101, v131
	s_mov_b64 s[30:31], 0x180
	s_nop 0
	v_or_b32_e32 v146, 0x8000, v102
	s_waitcnt vmcnt(12)
	v_mfma_f32_32x32x16_bf16 v[32:47], a[4:7], a[8:11], 0
	v_or_b32_e32 v147, 0x9000, v102
	v_add_u32_e32 v138, s3, v110
	v_add_u32_e32 v148, s3, v111
	v_or_b32_e32 v149, 0x1000, v111
	s_mov_b64 s[60:61], 0x80
	s_mov_b64 s[80:81], 0x200
	s_waitcnt lgkmcnt(0)
	v_mfma_f32_32x32x16_bf16 v[16:31], a[0:3], a[12:15], 0
	v_bitop3_b32 v0, v64, v103, 2 bitop3:0x36
	v_lshlrev_b32_e32 v112, 4, v0
	v_add_u32_e32 v83, v101, v112
	ds_read_b128 a[28:31], v83 offset:4096
	s_nop 0
	s_nop 0
	ds_read_b128 a[24:27], v83
	s_nop 0
	v_add_u32_e32 v84, v100, v112
	ds_read_b128 a[20:23], v84 offset:36864
	s_nop 0
	s_nop 0
	ds_read_b128 a[16:19], v84 offset:32768
	s_nop 0
	s_nop 0
	s_nop 0
	s_nop 0
	s_nop 0
	s_nop 0
	v_mfma_f32_32x32x16_bf16 v[0:15], a[4:7], a[12:15], 0
	v_add_u32_e32 v142, s3, v112
	s_nop 0
	v_add_u32_e32 v86, v100, v131
	ds_read_b128 a[0:3], v86 offset:32768
	ds_read_b128 a[4:7], v86 offset:36864
	ds_read_b128 a[8:11], v85
	ds_read_b128 a[12:15], v85 offset:4096
	s_waitcnt lgkmcnt(4)
	v_mfma_f32_32x32x16_bf16 v[48:63], a[16:19], a[24:27], v[48:63]
	v_mfma_f32_32x32x16_bf16 v[32:47], a[20:23], a[24:27], v[32:47]
	v_mfma_f32_32x32x16_bf16 v[16:31], a[16:19], a[28:31], v[16:31]
	s_nop 0
	v_bitop3_b32 v87, v64, v103, 6 bitop3:0x36
	v_lshlrev_b32_e32 v132, 4, v87
	v_add_u32_e32 v87, v101, v132
	v_lshlrev_b32_e32 v64, 2, v64
	v_mfma_f32_32x32x16_bf16 v[0:15], a[20:23], a[28:31], v[0:15]
	s_nop 0
	s_nop 0
	s_nop 0
	v_add_u32_e32 v88, v100, v132
	ds_read_b128 a[16:19], v88 offset:32768
	ds_read_b128 a[20:23], v88 offset:36864
	ds_read_b128 a[24:27], v87
	ds_read_b128 a[28:31], v87 offset:4096
	s_waitcnt lgkmcnt(5)
	v_mfma_f32_32x32x16_bf16 v[48:63], a[0:3], a[8:11], v[48:63]
	v_mfma_f32_32x32x16_bf16 v[32:47], a[4:7], a[8:11], v[32:47]
	s_nop 0
	s_waitcnt lgkmcnt(4)
	v_mfma_f32_32x32x16_bf16 v[16:31], a[0:3], a[12:15], v[16:31]
	s_nop 0
	v_mfma_f32_32x32x16_bf16 v[0:15], a[4:7], a[12:15], v[0:15]
	s_nop 0
	s_nop 0
	s_nop 0
	s_waitcnt lgkmcnt(1)
	v_mfma_f32_32x32x16_bf16 v[48:63], a[16:19], a[24:27], v[48:63]
	v_mfma_f32_32x32x16_bf16 v[32:47], a[20:23], a[24:27], v[32:47]
	s_nop 0
	s_waitcnt vmcnt(6)
	s_waitcnt lgkmcnt(0)
	s_barrier
	ds_read_b128 a[12:15], v81 offset:53248
	ds_read_b128 a[8:11], v81 offset:49152
	v_mfma_f32_32x32x16_bf16 v[16:31], a[16:19], a[28:31], v[16:31]
	v_lshl_add_u64 v[158:159], v[66:67], 0, s[30:31]
	s_nop 0
	v_lshl_add_u64 v[160:161], v[68:69], 0, s[30:31]
	s_nop 0
	s_nop 0
	s_nop 0
	v_lshl_add_u64 v[162:163], v[70:71], 0, s[30:31]
	s_nop 0
	v_mfma_f32_32x32x16_bf16 v[0:15], a[20:23], a[28:31], v[0:15]
	s_and_b32 m0, s32, 7
	s_lshl_b32 m0, m0, 12
	s_add_i32 m0, m0, 0x0
	s_nop 0
	global_load_lds_dwordx4 v[158:159], off
	s_nop 0
	v_lshl_add_u64 v[164:165], v[72:73], 0, s[30:31]
	s_nop 0
	s_nop 0
	s_nop 0
	v_lshl_add_u64 v[166:167], v[74:75], 0, s[30:31]
	s_nop 0
	s_nop 0
	s_nop 0
	v_lshl_add_u64 v[168:169], v[76:77], 0, s[30:31]
	s_add_i32 s30, 0, 0xc000
	v_add_u32_e32 v89, s30, v110
	v_add_u32_e32 v91, v89, v146
	v_add_u32_e32 v89, v89, v147
	ds_read_b128 a[4:7], v89
	ds_read_b128 a[0:3], v91
	s_nop 0
	s_nop 0
	s_nop 0
	s_nop 0
	s_nop 0
	s_nop 0
	s_nop 0
	s_nop 0
	s_nop 0
	v_add_u32_e32 v90, s30, v112
	v_add_u32_e32 v92, v90, v146
	ds_read_b128 a[16:19], v92
	v_add_u32_e32 v90, v90, v147
	ds_read_b128 a[20:23], v90
	ds_read_b128 a[24:27], v83 offset:49152
	ds_read_b128 a[28:31], v83 offset:53248
	s_waitcnt lgkmcnt(4)
	v_mfma_f32_32x32x16_bf16 v[48:63], a[0:3], a[8:11], v[48:63]
	s_nop 0
	s_nop 0
	v_mfma_f32_32x32x16_bf16 v[32:47], a[4:7], a[8:11], v[32:47]
	v_mfma_f32_32x32x16_bf16 v[16:31], a[0:3], a[12:15], v[16:31]
	s_and_b32 m0, s32, 7
	s_lshl_b32 m0, m0, 12
	s_add_i32 m0, m0, 0x400
	s_nop 0
	global_load_lds_dwordx4 v[160:161], off
	s_nop 0
	s_nop 0
	v_add_u32_e32 v93, s30, v131
	v_mfma_f32_32x32x16_bf16 v[0:15], a[4:7], a[12:15], v[0:15]
	s_nop 0
	s_nop 0
	s_nop 0
	s_nop 0
	v_add_u32_e32 v94, v93, v146
	ds_read_b128 a[0:3], v94
	v_add_u32_e32 v93, v93, v147
	ds_read_b128 a[4:7], v93
	ds_read_b128 a[8:11], v85 offset:49152
	ds_read_b128 a[12:15], v85 offset:53248
	s_waitcnt lgkmcnt(5)
	v_mfma_f32_32x32x16_bf16 v[48:63], a[16:19], a[24:27], v[48:63]
	v_mfma_f32_32x32x16_bf16 v[32:47], a[20:23], a[24:27], v[32:47]
	s_and_b32 m0, s32, 7
	s_lshl_b32 m0, m0, 12
	s_add_i32 m0, m0, 0x800
	s_nop 0
	global_load_lds_dwordx4 v[162:163], off
	s_waitcnt lgkmcnt(4)
	v_mfma_f32_32x32x16_bf16 v[16:31], a[16:19], a[28:31], v[16:31]
	s_nop 0
	s_nop 0
	v_add_u32_e32 v95, s30, v132
	s_mov_b64 s[30:31], 0x200
	v_mfma_f32_32x32x16_bf16 v[0:15], a[20:23], a[28:31], v[0:15]
	s_nop 0
	s_nop 0
	s_nop 0
	s_nop 0
	v_add_u32_e32 v96, v95, v146
	ds_read_b128 a[16:19], v96
	v_add_u32_e32 v95, v95, v147
	ds_read_b128 a[20:23], v95
	ds_read_b128 a[24:27], v87 offset:49152
	ds_read_b128 a[28:31], v87 offset:53248
	s_waitcnt lgkmcnt(5)
	v_mfma_f32_32x32x16_bf16 v[48:63], a[0:3], a[8:11], v[48:63]
	s_and_b32 m0, s32, 7
	s_lshl_b32 m0, m0, 12
	s_add_i32 m0, m0, 0xc00
	s_nop 0
	global_load_lds_dwordx4 v[164:165], off
	v_mfma_f32_32x32x16_bf16 v[32:47], a[4:7], a[8:11], v[32:47]
	s_waitcnt lgkmcnt(4)
	v_mfma_f32_32x32x16_bf16 v[16:31], a[0:3], a[12:15], v[16:31]
	s_nop 0
	s_nop 0
	v_add_u32_e32 v97, v138, v146
	v_mfma_f32_32x32x16_bf16 v[0:15], a[4:7], a[12:15], v[0:15]
	s_and_b32 m0, s32, 7
	s_lshl_b32 m0, m0, 11
	s_add_i32 m0, m0, 0x8000
	s_nop 0
	global_load_lds_dwordx4 v[166:167], off
	s_nop 0
	s_nop 0
	s_nop 0
	s_nop 0
	s_waitcnt lgkmcnt(1)
	v_mfma_f32_32x32x16_bf16 v[48:63], a[16:19], a[24:27], v[48:63]
	v_mfma_f32_32x32x16_bf16 v[32:47], a[20:23], a[24:27], v[32:47]
	s_and_b32 m0, s32, 7
	s_lshl_b32 m0, m0, 11
	s_add_i32 m0, m0, 0x8400
	s_nop 0
	global_load_lds_dwordx4 v[168:169], off
	s_waitcnt vmcnt(6)
	s_waitcnt lgkmcnt(0)
	s_barrier
	v_add_u32_e32 v100, v138, v149
	ds_read_b128 a[12:15], v100
	v_add_u32_e32 v99, v148, v110
	ds_read_b128 a[8:11], v99
	v_add_u32_e32 v98, v138, v147
	ds_read_b128 a[4:7], v98
	ds_read_b128 a[0:3], v97
	v_mfma_f32_32x32x16_bf16 v[16:31], a[16:19], a[28:31], v[16:31]
	v_lshl_add_u64 v[170:171], v[66:67], 0, s[30:31]
	s_nop 0
	v_lshl_add_u64 v[172:173], v[68:69], 0, s[30:31]
	s_nop 0
	s_nop 0
	s_nop 0
	v_lshl_add_u64 v[174:175], v[70:71], 0, s[30:31]
	s_nop 0
	v_mfma_f32_32x32x16_bf16 v[0:15], a[20:23], a[28:31], v[0:15]
	s_and_b32 m0, s32, 7
	s_lshl_b32 m0, m0, 12
	s_add_i32 m0, m0, 0xc000
	s_nop 0
	global_load_lds_dwordx4 v[170:171], off
	s_nop 0
	v_lshl_add_u64 v[176:177], v[72:73], 0, s[30:31]
	s_nop 0
	s_nop 0
	s_nop 0
	v_lshl_add_u64 v[178:179], v[74:75], 0, s[30:31]
	s_nop 0
	s_nop 0
	s_nop 0
	v_lshl_add_u64 v[180:181], v[76:77], 0, s[30:31]
	s_nop 0
	s_mov_b64 s[30:31], 0x280
	s_nop 0
	s_nop 0
	s_nop 0
	s_nop 0
	s_nop 0
	s_nop 0
	v_add_u32_e32 v101, v142, v146
	ds_read_b128 a[16:19], v101
	v_add_u32_e32 v102, v142, v147
	ds_read_b128 a[20:23], v102
	v_add_u32_e32 v103, v148, v112
	ds_read_b128 a[24:27], v103
	v_add_u32_e32 v104, v142, v149
	ds_read_b128 a[28:31], v104
	s_waitcnt lgkmcnt(4)
	v_mfma_f32_32x32x16_bf16 v[48:63], a[0:3], a[8:11], v[48:63]
	s_nop 0
	v_mfma_f32_32x32x16_bf16 v[32:47], a[4:7], a[8:11], v[32:47]
	s_nop 0
	s_nop 0
	s_nop 0
	s_nop 0
	s_nop 0
	s_nop 0
	v_add_u32_e32 v112, s3, v131
	v_mfma_f32_32x32x16_bf16 v[16:31], a[0:3], a[12:15], v[16:31]
	s_and_b32 m0, s32, 7
	s_lshl_b32 m0, m0, 12
	s_add_i32 m0, m0, 0xc400
	s_nop 0
	global_load_lds_dwordx4 v[172:173], off
	s_nop 0
	v_mfma_f32_32x32x16_bf16 v[0:15], a[4:7], a[12:15], v[0:15]
	s_nop 0
	s_nop 0
	v_add_u32_e32 v105, v112, v146
	s_nop 0
	ds_read_b128 a[0:3], v105
	v_add_u32_e32 v106, v112, v147
	ds_read_b128 a[4:7], v106
	v_add_u32_e32 v107, v148, v131
	ds_read_b128 a[8:11], v107
	v_add_u32_e32 v108, v112, v149
	ds_read_b128 a[12:15], v108
	s_waitcnt lgkmcnt(5)
	v_mfma_f32_32x32x16_bf16 v[48:63], a[16:19], a[24:27], v[48:63]
	v_mfma_f32_32x32x16_bf16 v[32:47], a[20:23], a[24:27], v[32:47]
	s_and_b32 m0, s32, 7
	s_lshl_b32 m0, m0, 12
	s_add_i32 m0, m0, 0xc800
	s_nop 0
	global_load_lds_dwordx4 v[174:175], off
	s_waitcnt lgkmcnt(4)
	v_mfma_f32_32x32x16_bf16 v[16:31], a[16:19], a[28:31], v[16:31]
	s_nop 0
	s_nop 0
	s_nop 0
	v_mfma_f32_32x32x16_bf16 v[0:15], a[20:23], a[28:31], v[0:15]
	s_nop 0
	s_nop 0
	v_add_u32_e32 v112, s3, v132
	v_add_u32_e32 v109, v112, v146
	ds_read_b128 a[16:19], v109
	v_add_u32_e32 v110, v112, v147
	ds_read_b128 a[20:23], v110
	v_add_u32_e32 v111, v148, v132
	ds_read_b128 a[24:27], v111
	v_add_u32_e32 v112, v112, v149
	ds_read_b128 a[28:31], v112
	s_waitcnt lgkmcnt(5)
	v_mfma_f32_32x32x16_bf16 v[48:63], a[0:3], a[8:11], v[48:63]
	s_and_b32 m0, s32, 7
	s_lshl_b32 m0, m0, 12
	s_add_i32 m0, m0, 0xcc00
	s_nop 0
	global_load_lds_dwordx4 v[176:177], off
	v_mfma_f32_32x32x16_bf16 v[32:47], a[4:7], a[8:11], v[32:47]
	s_nop 0
	s_nop 0
	s_nop 0
	s_nop 0
	s_nop 0
	s_nop 0
	s_nop 0
	s_waitcnt lgkmcnt(4)
	v_mfma_f32_32x32x16_bf16 v[16:31], a[0:3], a[12:15], v[16:31]
	s_nop 0
	v_mfma_f32_32x32x16_bf16 v[0:15], a[4:7], a[12:15], v[0:15]
	s_and_b32 m0, s32, 7
	s_lshl_b32 m0, m0, 11
	s_add_i32 m0, m0, 0x14000
	s_nop 0
	global_load_lds_dwordx4 v[178:179], off
	s_nop 0
	s_nop 0
	s_nop 0
	s_waitcnt lgkmcnt(1)
	v_mfma_f32_32x32x16_bf16 v[48:63], a[16:19], a[24:27], v[48:63]
	v_mfma_f32_32x32x16_bf16 v[32:47], a[20:23], a[24:27], v[32:47]
	s_and_b32 m0, s32, 7
	s_lshl_b32 m0, m0, 11
	s_add_i32 m0, m0, 0x14400
	s_nop 0
	global_load_lds_dwordx4 v[180:181], off
	s_waitcnt vmcnt(6)
	s_waitcnt lgkmcnt(0)
	s_barrier
	ds_read_b128 a[12:15], v81 offset:4096
	ds_read_b128 a[8:11], v81
	ds_read_b128 a[4:7], v82 offset:36864
	ds_read_b128 a[0:3], v82 offset:32768
	v_mfma_f32_32x32x16_bf16 v[16:31], a[16:19], a[28:31], v[16:31]
	v_lshl_add_u64 v[158:159], v[66:67], 0, s[30:31]
	s_nop 0
	v_lshl_add_u64 v[160:161], v[68:69], 0, s[30:31]
	s_nop 0
	s_nop 0
	s_nop 0
	v_lshl_add_u64 v[162:163], v[70:71], 0, s[30:31]
	s_nop 0
	v_mfma_f32_32x32x16_bf16 v[0:15], a[20:23], a[28:31], v[0:15]
	s_and_b32 m0, s32, 7
	s_lshl_b32 m0, m0, 12
	s_add_i32 m0, m0, 0x18000
	s_nop 0
	global_load_lds_dwordx4 v[158:159], off
	s_nop 0
	v_lshl_add_u64 v[164:165], v[72:73], 0, s[30:31]
	s_nop 0
	s_nop 0
	s_nop 0
	v_lshl_add_u64 v[166:167], v[74:75], 0, s[30:31]
	s_nop 0
	s_nop 0
	s_nop 0
	v_lshl_add_u64 v[168:169], v[76:77], 0, s[30:31]
	s_nop 0
	s_mov_b64 s[30:31], 0x300
	s_nop 0
	s_nop 0
	s_nop 0
	s_nop 0
	s_nop 0
	ds_read_b128 a[16:19], v84 offset:32768
	ds_read_b128 a[20:23], v84 offset:36864
	ds_read_b128 a[24:27], v83
	ds_read_b128 a[28:31], v83 offset:4096
	s_waitcnt lgkmcnt(4)
	v_mfma_f32_32x32x16_bf16 v[48:63], a[0:3], a[8:11], v[48:63]
	s_nop 0
	v_readfirstlane_b32 s42, v113
	v_mfma_f32_32x32x16_bf16 v[32:47], a[4:7], a[8:11], v[32:47]
	v_mfma_f32_32x32x16_bf16 v[16:31], a[0:3], a[12:15], v[16:31]
	s_and_b32 m0, s32, 7
	s_lshl_b32 m0, m0, 12
	s_add_i32 m0, m0, 0x18400
	s_nop 0
	global_load_lds_dwordx4 v[160:161], off
	v_mfma_f32_32x32x16_bf16 v[0:15], a[4:7], a[12:15], v[0:15]
	s_nop 0
	s_nop 0
	s_nop 0
	s_nop 0
	ds_read_b128 a[0:3], v86 offset:32768
	ds_read_b128 a[4:7], v86 offset:36864
	ds_read_b128 a[8:11], v85
	ds_read_b128 a[12:15], v85 offset:4096
	s_waitcnt lgkmcnt(5)
	v_mfma_f32_32x32x16_bf16 v[48:63], a[16:19], a[24:27], v[48:63]
	v_mfma_f32_32x32x16_bf16 v[32:47], a[20:23], a[24:27], v[32:47]
	s_and_b32 m0, s32, 7
	s_lshl_b32 m0, m0, 12
	s_add_i32 m0, m0, 0x18800
	s_nop 0
	global_load_lds_dwordx4 v[162:163], off
	s_waitcnt lgkmcnt(4)
	v_mfma_f32_32x32x16_bf16 v[16:31], a[16:19], a[28:31], v[16:31]
	v_mfma_f32_32x32x16_bf16 v[0:15], a[20:23], a[28:31], v[0:15]
	s_nop 0
	s_nop 0
	s_nop 0
	s_nop 0
	ds_read_b128 a[16:19], v88 offset:32768
	ds_read_b128 a[20:23], v88 offset:36864
	ds_read_b128 a[24:27], v87
	ds_read_b128 a[28:31], v87 offset:4096
	s_waitcnt lgkmcnt(5)
	v_mfma_f32_32x32x16_bf16 v[48:63], a[0:3], a[8:11], v[48:63]
	s_and_b32 m0, s32, 7
	s_lshl_b32 m0, m0, 12
	s_add_i32 m0, m0, 0x18c00
	s_nop 0
	global_load_lds_dwordx4 v[164:165], off
	v_mfma_f32_32x32x16_bf16 v[32:47], a[4:7], a[8:11], v[32:47]
	s_waitcnt lgkmcnt(4)
	v_mfma_f32_32x32x16_bf16 v[16:31], a[0:3], a[12:15], v[16:31]
	v_mfma_f32_32x32x16_bf16 v[0:15], a[4:7], a[12:15], v[0:15]
	s_and_b32 m0, s32, 7
	s_lshl_b32 m0, m0, 11
	s_add_i32 m0, m0, 0x20000
	s_nop 0
	global_load_lds_dwordx4 v[166:167], off
	s_nop 0
	s_nop 0
	s_nop 0
	s_nop 0
	s_waitcnt lgkmcnt(1)
	v_mfma_f32_32x32x16_bf16 v[48:63], a[16:19], a[24:27], v[48:63]
	v_mfma_f32_32x32x16_bf16 v[32:47], a[20:23], a[24:27], v[32:47]
	s_and_b32 m0, s32, 7
	s_lshl_b32 m0, m0, 11
	s_add_i32 m0, m0, 0x20400
	s_nop 0
	global_load_lds_dwordx4 v[168:169], off
	s_waitcnt vmcnt(6)
	s_waitcnt lgkmcnt(0)
	s_barrier
	ds_read_b128 a[12:15], v81 offset:53248
	ds_read_b128 a[8:11], v81 offset:49152
	ds_read_b128 a[4:7], v89
	ds_read_b128 a[0:3], v91
	v_mfma_f32_32x32x16_bf16 v[16:31], a[16:19], a[28:31], v[16:31]
	v_lshl_add_u64 v[170:171], v[66:67], 0, s[30:31]
	s_nop 0
	v_lshl_add_u64 v[172:173], v[68:69], 0, s[30:31]
	s_nop 0
	v_readfirstlane_b32 s43, v114
	s_nop 0
	v_lshl_add_u64 v[174:175], v[70:71], 0, s[30:31]
	s_nop 0
	v_mfma_f32_32x32x16_bf16 v[0:15], a[20:23], a[28:31], v[0:15]
	s_and_b32 m0, s32, 7
	s_lshl_b32 m0, m0, 12
	s_add_i32 m0, m0, 0x0
	s_nop 0
	global_load_lds_dwordx4 v[170:171], off
	s_nop 0
	v_lshl_add_u64 v[176:177], v[72:73], 0, s[30:31]
	s_nop 0
	v_readfirstlane_b32 s44, v115
	s_nop 0
	v_lshl_add_u64 v[178:179], v[74:75], 0, s[30:31]
	s_nop 0
	v_readfirstlane_b32 s45, v116
	s_nop 0
	v_lshl_add_u64 v[180:181], v[76:77], 0, s[30:31]
	s_nop 0
	s_mov_b64 s[30:31], 0x380
	s_nop 0
	s_nop 0
	s_nop 0
	s_nop 0
	s_nop 0
	ds_read_b128 a[16:19], v92
	ds_read_b128 a[20:23], v90
	ds_read_b128 a[24:27], v83 offset:49152
	ds_read_b128 a[28:31], v83 offset:53248
	s_waitcnt lgkmcnt(4)
	v_mfma_f32_32x32x16_bf16 v[48:63], a[0:3], a[8:11], v[48:63]
	s_nop 0
	v_readfirstlane_b32 s36, v119
	v_readfirstlane_b32 s46, v117
	v_readfirstlane_b32 s47, v118
	v_mfma_f32_32x32x16_bf16 v[32:47], a[4:7], a[8:11], v[32:47]
	v_mfma_f32_32x32x16_bf16 v[16:31], a[0:3], a[12:15], v[16:31]
	s_and_b32 m0, s32, 7
	s_lshl_b32 m0, m0, 12
	s_add_i32 m0, m0, 0x400
	s_nop 0
	global_load_lds_dwordx4 v[172:173], off
	v_mfma_f32_32x32x16_bf16 v[0:15], a[4:7], a[12:15], v[0:15]
	s_nop 0
	s_nop 0
	s_nop 0
	s_nop 0
	ds_read_b128 a[0:3], v94
	ds_read_b128 a[4:7], v93
	ds_read_b128 a[8:11], v85 offset:49152
	ds_read_b128 a[12:15], v85 offset:53248
	s_waitcnt lgkmcnt(5)
	v_mfma_f32_32x32x16_bf16 v[48:63], a[16:19], a[24:27], v[48:63]
	v_mfma_f32_32x32x16_bf16 v[32:47], a[20:23], a[24:27], v[32:47]
	s_and_b32 m0, s32, 7
	s_lshl_b32 m0, m0, 12
	s_add_i32 m0, m0, 0x800
	s_nop 0
	global_load_lds_dwordx4 v[174:175], off
	s_waitcnt lgkmcnt(4)
	v_mfma_f32_32x32x16_bf16 v[16:31], a[16:19], a[28:31], v[16:31]
	v_mfma_f32_32x32x16_bf16 v[0:15], a[20:23], a[28:31], v[0:15]
	s_nop 0
	s_nop 0
	s_nop 0
	s_nop 0
	ds_read_b128 a[16:19], v96
	ds_read_b128 a[20:23], v95
	ds_read_b128 a[24:27], v87 offset:49152
	ds_read_b128 a[28:31], v87 offset:53248
	s_waitcnt lgkmcnt(5)
	v_mfma_f32_32x32x16_bf16 v[48:63], a[0:3], a[8:11], v[48:63]
	s_and_b32 m0, s32, 7
	s_lshl_b32 m0, m0, 12
	s_add_i32 m0, m0, 0xc00
	s_nop 0
	global_load_lds_dwordx4 v[176:177], off
	v_mfma_f32_32x32x16_bf16 v[32:47], a[4:7], a[8:11], v[32:47]
	s_waitcnt lgkmcnt(4)
	v_mfma_f32_32x32x16_bf16 v[16:31], a[0:3], a[12:15], v[16:31]
	v_mfma_f32_32x32x16_bf16 v[0:15], a[4:7], a[12:15], v[0:15]
	s_and_b32 m0, s32, 7
	s_lshl_b32 m0, m0, 11
	s_add_i32 m0, m0, 0x8000
	s_nop 0
	global_load_lds_dwordx4 v[178:179], off
	s_nop 0
	s_nop 0
	s_nop 0
	s_nop 0
	s_waitcnt lgkmcnt(1)
	v_mfma_f32_32x32x16_bf16 v[48:63], a[16:19], a[24:27], v[48:63]
	v_mfma_f32_32x32x16_bf16 v[32:47], a[20:23], a[24:27], v[32:47]
	s_and_b32 m0, s32, 7
	s_lshl_b32 m0, m0, 11
	s_add_i32 m0, m0, 0x8400
	s_nop 0
	global_load_lds_dwordx4 v[180:181], off
	s_waitcnt vmcnt(6)
	s_waitcnt lgkmcnt(0)
	s_barrier
	ds_read_b128 a[12:15], v100
	ds_read_b128 a[8:11], v99
	ds_read_b128 a[4:7], v98
	ds_read_b128 a[0:3], v97
	v_mfma_f32_32x32x16_bf16 v[16:31], a[16:19], a[28:31], v[16:31]
	v_lshl_add_u64 v[158:159], v[66:67], 0, s[30:31]
	s_nop 0
	v_lshl_add_u64 v[160:161], v[68:69], 0, s[30:31]
	s_nop 0
	v_readfirstlane_b32 s37, v120
	s_nop 0
	v_lshl_add_u64 v[162:163], v[70:71], 0, s[30:31]
	s_nop 0
	v_mfma_f32_32x32x16_bf16 v[0:15], a[20:23], a[28:31], v[0:15]
	s_and_b32 m0, s32, 7
	s_lshl_b32 m0, m0, 12
	s_add_i32 m0, m0, 0xc000
	s_nop 0
	global_load_lds_dwordx4 v[158:159], off
	s_nop 0
	v_lshl_add_u64 v[164:165], v[72:73], 0, s[30:31]
	s_nop 0
	v_readfirstlane_b32 s38, v121
	s_nop 0
	v_lshl_add_u64 v[166:167], v[74:75], 0, s[30:31]
	s_nop 0
	v_readfirstlane_b32 s39, v122
	s_nop 0
	v_lshl_add_u64 v[168:169], v[76:77], 0, s[30:31]
	s_nop 0
	s_mov_b64 s[30:31], 0x400
	s_nop 0
	s_nop 0
	s_nop 0
	s_nop 0
	s_nop 0
	ds_read_b128 a[16:19], v101
	ds_read_b128 a[20:23], v102
	ds_read_b128 a[24:27], v103
	ds_read_b128 a[28:31], v104
	s_waitcnt lgkmcnt(4)
	v_mfma_f32_32x32x16_bf16 v[48:63], a[0:3], a[8:11], v[48:63]
	s_nop 0
	v_readfirstlane_b32 s20, v125
	v_readfirstlane_b32 s40, v123
	v_readfirstlane_b32 s41, v124
	v_mfma_f32_32x32x16_bf16 v[32:47], a[4:7], a[8:11], v[32:47]
	v_mfma_f32_32x32x16_bf16 v[16:31], a[0:3], a[12:15], v[16:31]
	s_and_b32 m0, s32, 7
	s_lshl_b32 m0, m0, 12
	s_add_i32 m0, m0, 0xc400
	s_nop 0
	global_load_lds_dwordx4 v[160:161], off
	v_mfma_f32_32x32x16_bf16 v[0:15], a[4:7], a[12:15], v[0:15]
	s_nop 0
	s_nop 0
	s_nop 0
	s_nop 0
	ds_read_b128 a[0:3], v105
	ds_read_b128 a[4:7], v106
	ds_read_b128 a[8:11], v107
	ds_read_b128 a[12:15], v108
	s_waitcnt lgkmcnt(5)
	v_mfma_f32_32x32x16_bf16 v[48:63], a[16:19], a[24:27], v[48:63]
	v_mfma_f32_32x32x16_bf16 v[32:47], a[20:23], a[24:27], v[32:47]
	s_and_b32 m0, s32, 7
	s_lshl_b32 m0, m0, 12
	s_add_i32 m0, m0, 0xc800
	s_nop 0
	global_load_lds_dwordx4 v[162:163], off
	s_waitcnt lgkmcnt(4)
	v_mfma_f32_32x32x16_bf16 v[16:31], a[16:19], a[28:31], v[16:31]
	v_mfma_f32_32x32x16_bf16 v[0:15], a[20:23], a[28:31], v[0:15]
	s_nop 0
	s_nop 0
	s_nop 0
	s_nop 0
	ds_read_b128 a[16:19], v109
	ds_read_b128 a[20:23], v110
	ds_read_b128 a[24:27], v111
	ds_read_b128 a[28:31], v112
	s_waitcnt lgkmcnt(5)
	v_mfma_f32_32x32x16_bf16 v[48:63], a[0:3], a[8:11], v[48:63]
	s_and_b32 m0, s32, 7
	s_lshl_b32 m0, m0, 12
	s_add_i32 m0, m0, 0xcc00
	s_nop 0
	global_load_lds_dwordx4 v[164:165], off
	v_mfma_f32_32x32x16_bf16 v[32:47], a[4:7], a[8:11], v[32:47]
	s_waitcnt lgkmcnt(4)
	v_mfma_f32_32x32x16_bf16 v[16:31], a[0:3], a[12:15], v[16:31]
	v_mfma_f32_32x32x16_bf16 v[0:15], a[4:7], a[12:15], v[0:15]
	s_and_b32 m0, s32, 7
	s_lshl_b32 m0, m0, 11
	s_add_i32 m0, m0, 0x14000
	s_nop 0
	global_load_lds_dwordx4 v[166:167], off
	s_nop 0
	s_nop 0
	s_nop 0
	s_nop 0
	s_waitcnt lgkmcnt(1)
	v_mfma_f32_32x32x16_bf16 v[48:63], a[16:19], a[24:27], v[48:63]
	v_mfma_f32_32x32x16_bf16 v[32:47], a[20:23], a[24:27], v[32:47]
	s_and_b32 m0, s32, 7
	s_lshl_b32 m0, m0, 11
	s_add_i32 m0, m0, 0x14400
	s_nop 0
	global_load_lds_dwordx4 v[168:169], off
	s_waitcnt vmcnt(6)
	s_waitcnt lgkmcnt(0)
	s_barrier
	ds_read_b128 a[12:15], v81 offset:4096
	ds_read_b128 a[8:11], v81
	ds_read_b128 a[4:7], v82 offset:36864
	ds_read_b128 a[0:3], v82 offset:32768
	v_mfma_f32_32x32x16_bf16 v[16:31], a[16:19], a[28:31], v[16:31]
	v_lshl_add_u64 v[170:171], v[66:67], 0, s[30:31]
	s_nop 0
	v_lshl_add_u64 v[172:173], v[68:69], 0, s[30:31]
	s_nop 0
	v_readfirstlane_b32 s21, v126
	s_nop 0
	v_lshl_add_u64 v[174:175], v[70:71], 0, s[30:31]
	s_nop 0
	v_mfma_f32_32x32x16_bf16 v[0:15], a[20:23], a[28:31], v[0:15]
	s_and_b32 m0, s32, 7
	s_lshl_b32 m0, m0, 12
	s_add_i32 m0, m0, 0x18000
	s_nop 0
	global_load_lds_dwordx4 v[170:171], off
	s_nop 0
	v_lshl_add_u64 v[176:177], v[72:73], 0, s[30:31]
	s_nop 0
	v_readfirstlane_b32 s23, v127
	s_nop 0
	v_lshl_add_u64 v[178:179], v[74:75], 0, s[30:31]
	s_nop 0
	v_readfirstlane_b32 s28, v128
	s_nop 0
	v_lshl_add_u64 v[180:181], v[76:77], 0, s[30:31]
	s_nop 0
	s_mov_b64 s[30:31], 0x480
	s_nop 0
	s_nop 0
	s_nop 0
	s_nop 0
	s_nop 0
	ds_read_b128 a[16:19], v84 offset:32768
	ds_read_b128 a[20:23], v84 offset:36864
	ds_read_b128 a[24:27], v83
	ds_read_b128 a[28:31], v83 offset:4096
	s_waitcnt lgkmcnt(4)
	v_mfma_f32_32x32x16_bf16 v[48:63], a[0:3], a[8:11], v[48:63]
	s_nop 0
	v_lshl_add_u64 v[164:165], v[72:73], 0, s[30:31]
	v_readfirstlane_b32 s29, v130
	v_readfirstlane_b32 s33, v129
	v_mfma_f32_32x32x16_bf16 v[32:47], a[4:7], a[8:11], v[32:47]
	v_mfma_f32_32x32x16_bf16 v[16:31], a[0:3], a[12:15], v[16:31]
	s_and_b32 m0, s32, 7
	s_lshl_b32 m0, m0, 12
	s_add_i32 m0, m0, 0x18400
	s_nop 0
	global_load_lds_dwordx4 v[172:173], off
	v_mfma_f32_32x32x16_bf16 v[0:15], a[4:7], a[12:15], v[0:15]
	s_nop 0
	s_nop 0
	s_nop 0
	s_nop 0
	ds_read_b128 a[0:3], v86 offset:32768
	ds_read_b128 a[4:7], v86 offset:36864
	ds_read_b128 a[8:11], v85
	ds_read_b128 a[12:15], v85 offset:4096
	s_waitcnt lgkmcnt(5)
	v_mfma_f32_32x32x16_bf16 v[48:63], a[16:19], a[24:27], v[48:63]
	v_mfma_f32_32x32x16_bf16 v[32:47], a[20:23], a[24:27], v[32:47]
	s_and_b32 m0, s32, 7
	s_lshl_b32 m0, m0, 12
	s_add_i32 m0, m0, 0x18800
	s_nop 0
	global_load_lds_dwordx4 v[174:175], off
	s_waitcnt lgkmcnt(4)
	v_mfma_f32_32x32x16_bf16 v[16:31], a[16:19], a[28:31], v[16:31]
	v_mfma_f32_32x32x16_bf16 v[0:15], a[20:23], a[28:31], v[0:15]
	s_nop 0
	s_nop 0
	s_nop 0
	s_nop 0
	ds_read_b128 a[16:19], v88 offset:32768
	ds_read_b128 a[20:23], v88 offset:36864
	ds_read_b128 a[24:27], v87
	ds_read_b128 a[28:31], v87 offset:4096
	s_waitcnt lgkmcnt(5)
	v_mfma_f32_32x32x16_bf16 v[48:63], a[0:3], a[8:11], v[48:63]
	s_and_b32 m0, s32, 7
	s_lshl_b32 m0, m0, 12
	s_add_i32 m0, m0, 0x18c00
	s_nop 0
	global_load_lds_dwordx4 v[176:177], off
	v_mfma_f32_32x32x16_bf16 v[32:47], a[4:7], a[8:11], v[32:47]
	s_waitcnt lgkmcnt(4)
	v_mfma_f32_32x32x16_bf16 v[16:31], a[0:3], a[12:15], v[16:31]
	v_mfma_f32_32x32x16_bf16 v[0:15], a[4:7], a[12:15], v[0:15]
	s_and_b32 m0, s32, 7
	s_lshl_b32 m0, m0, 11
	s_add_i32 m0, m0, 0x20000
	s_nop 0
	global_load_lds_dwordx4 v[178:179], off
	s_nop 0
	s_nop 0
	s_nop 0
	s_nop 0
	s_waitcnt lgkmcnt(1)
	v_mfma_f32_32x32x16_bf16 v[48:63], a[16:19], a[24:27], v[48:63]
	v_mfma_f32_32x32x16_bf16 v[32:47], a[20:23], a[24:27], v[32:47]
	s_and_b32 m0, s32, 7
	s_lshl_b32 m0, m0, 11
	s_add_i32 m0, m0, 0x20400
	s_nop 0
	global_load_lds_dwordx4 v[180:181], off
	s_waitcnt vmcnt(6)
	s_waitcnt lgkmcnt(0)
	s_barrier
	ds_read_b128 a[12:15], v81 offset:53248
	ds_read_b128 a[8:11], v81 offset:49152
	ds_read_b128 a[4:7], v89
	ds_read_b128 a[0:3], v91
	v_mfma_f32_32x32x16_bf16 v[16:31], a[16:19], a[28:31], v[16:31]
	v_lshl_add_u64 v[158:159], v[66:67], 0, s[30:31]
	s_nop 0
	v_lshl_add_u64 v[160:161], v[68:69], 0, s[30:31]
	s_nop 0
	s_nop 0
	s_nop 0
	v_lshl_add_u64 v[162:163], v[70:71], 0, s[30:31]
	s_nop 0
	v_mfma_f32_32x32x16_bf16 v[0:15], a[20:23], a[28:31], v[0:15]
	s_and_b32 m0, s32, 7
	s_lshl_b32 m0, m0, 12
	s_add_i32 m0, m0, 0x0
	s_nop 0
	global_load_lds_dwordx4 v[158:159], off
	s_nop 0
	s_nop 0
	s_nop 0
	s_nop 0
	v_lshl_add_u64 v[166:167], v[74:75], 0, s[30:31]
	s_nop 0
	s_nop 0
	s_nop 0
	v_lshl_add_u64 v[168:169], v[76:77], 0, s[30:31]
	s_nop 0
	s_mov_b64 s[30:31], 0x500
	s_nop 0
	s_nop 0
	s_nop 0
	s_nop 0
	s_nop 0
	ds_read_b128 a[16:19], v92
	ds_read_b128 a[20:23], v90
	ds_read_b128 a[24:27], v83 offset:49152
	ds_read_b128 a[28:31], v83 offset:53248
	s_waitcnt lgkmcnt(4)
	v_mfma_f32_32x32x16_bf16 v[48:63], a[0:3], a[8:11], v[48:63]
	s_nop 0
	v_lshl_add_u64 v[176:177], v[72:73], 0, s[30:31]
	v_mfma_f32_32x32x16_bf16 v[32:47], a[4:7], a[8:11], v[32:47]
	v_mfma_f32_32x32x16_bf16 v[16:31], a[0:3], a[12:15], v[16:31]
	s_and_b32 m0, s32, 7
	s_lshl_b32 m0, m0, 12
	s_add_i32 m0, m0, 0x400
	s_nop 0
	global_load_lds_dwordx4 v[160:161], off
	v_mfma_f32_32x32x16_bf16 v[0:15], a[4:7], a[12:15], v[0:15]
	s_nop 0
	s_nop 0
	s_nop 0
	s_nop 0
	ds_read_b128 a[0:3], v94
	ds_read_b128 a[4:7], v93
	ds_read_b128 a[8:11], v85 offset:49152
	ds_read_b128 a[12:15], v85 offset:53248
	s_waitcnt lgkmcnt(5)
	v_mfma_f32_32x32x16_bf16 v[48:63], a[16:19], a[24:27], v[48:63]
	v_mfma_f32_32x32x16_bf16 v[32:47], a[20:23], a[24:27], v[32:47]
	s_and_b32 m0, s32, 7
	s_lshl_b32 m0, m0, 12
	s_add_i32 m0, m0, 0x800
	s_nop 0
	global_load_lds_dwordx4 v[162:163], off
	s_waitcnt lgkmcnt(4)
	v_mfma_f32_32x32x16_bf16 v[16:31], a[16:19], a[28:31], v[16:31]
	v_mfma_f32_32x32x16_bf16 v[0:15], a[20:23], a[28:31], v[0:15]
	s_nop 0
	s_nop 0
	s_nop 0
	s_nop 0
	ds_read_b128 a[16:19], v96
	ds_read_b128 a[20:23], v95
	ds_read_b128 a[24:27], v87 offset:49152
	ds_read_b128 a[28:31], v87 offset:53248
	s_waitcnt lgkmcnt(5)
	v_mfma_f32_32x32x16_bf16 v[48:63], a[0:3], a[8:11], v[48:63]
	s_and_b32 m0, s32, 7
	s_lshl_b32 m0, m0, 12
	s_add_i32 m0, m0, 0xc00
	s_nop 0
	global_load_lds_dwordx4 v[164:165], off
	v_mfma_f32_32x32x16_bf16 v[32:47], a[4:7], a[8:11], v[32:47]
	s_waitcnt lgkmcnt(4)
	v_mfma_f32_32x32x16_bf16 v[16:31], a[0:3], a[12:15], v[16:31]
	v_mfma_f32_32x32x16_bf16 v[0:15], a[4:7], a[12:15], v[0:15]
	s_and_b32 m0, s32, 7
	s_lshl_b32 m0, m0, 11
	s_add_i32 m0, m0, 0x8000
	s_nop 0
	global_load_lds_dwordx4 v[166:167], off
	s_nop 0
	s_nop 0
	s_nop 0
	s_nop 0
	s_waitcnt lgkmcnt(1)
	v_mfma_f32_32x32x16_bf16 v[48:63], a[16:19], a[24:27], v[48:63]
	v_mfma_f32_32x32x16_bf16 v[32:47], a[20:23], a[24:27], v[32:47]
	s_and_b32 m0, s32, 7
	s_lshl_b32 m0, m0, 11
	s_add_i32 m0, m0, 0x8400
	s_nop 0
	global_load_lds_dwordx4 v[168:169], off
	s_waitcnt vmcnt(6)
	s_waitcnt lgkmcnt(0)
	s_barrier
	ds_read_b128 a[12:15], v100
	ds_read_b128 a[8:11], v99
	ds_read_b128 a[4:7], v98
	ds_read_b128 a[0:3], v97
	v_mfma_f32_32x32x16_bf16 v[16:31], a[16:19], a[28:31], v[16:31]
	v_lshl_add_u64 v[170:171], v[66:67], 0, s[30:31]
	s_nop 0
	v_lshl_add_u64 v[172:173], v[68:69], 0, s[30:31]
	s_nop 0
	s_nop 0
	s_nop 0
	v_lshl_add_u64 v[174:175], v[70:71], 0, s[30:31]
	s_nop 0
	v_mfma_f32_32x32x16_bf16 v[0:15], a[20:23], a[28:31], v[0:15]
	s_and_b32 m0, s32, 7
	s_lshl_b32 m0, m0, 12
	s_add_i32 m0, m0, 0xc000
	s_nop 0
	global_load_lds_dwordx4 v[170:171], off
	s_nop 0
	s_nop 0
	s_nop 0
	s_nop 0
	v_lshl_add_u64 v[178:179], v[74:75], 0, s[30:31]
	s_nop 0
	s_nop 0
	s_nop 0
	v_lshl_add_u64 v[180:181], v[76:77], 0, s[30:31]
	s_nop 0
	s_mov_b64 s[30:31], 0x580
	s_nop 0
	s_nop 0
	s_nop 0
	s_nop 0
	s_nop 0
	ds_read_b128 a[16:19], v101
	ds_read_b128 a[20:23], v102
	ds_read_b128 a[24:27], v103
	ds_read_b128 a[28:31], v104
	s_waitcnt lgkmcnt(4)
	v_mfma_f32_32x32x16_bf16 v[48:63], a[0:3], a[8:11], v[48:63]
	s_nop 0
	v_lshl_add_u64 v[164:165], v[72:73], 0, s[30:31]
	v_mfma_f32_32x32x16_bf16 v[32:47], a[4:7], a[8:11], v[32:47]
	v_mfma_f32_32x32x16_bf16 v[16:31], a[0:3], a[12:15], v[16:31]
	s_and_b32 m0, s32, 7
	s_lshl_b32 m0, m0, 12
	s_add_i32 m0, m0, 0xc400
	s_nop 0
	global_load_lds_dwordx4 v[172:173], off
	v_mfma_f32_32x32x16_bf16 v[0:15], a[4:7], a[12:15], v[0:15]
	s_nop 0
	s_nop 0
	s_nop 0
	s_nop 0
	ds_read_b128 a[0:3], v105
	ds_read_b128 a[4:7], v106
	ds_read_b128 a[8:11], v107
	ds_read_b128 a[12:15], v108
	s_waitcnt lgkmcnt(5)
	v_mfma_f32_32x32x16_bf16 v[48:63], a[16:19], a[24:27], v[48:63]
	v_mfma_f32_32x32x16_bf16 v[32:47], a[20:23], a[24:27], v[32:47]
	s_and_b32 m0, s32, 7
	s_lshl_b32 m0, m0, 12
	s_add_i32 m0, m0, 0xc800
	s_nop 0
	global_load_lds_dwordx4 v[174:175], off
	s_waitcnt lgkmcnt(4)
	v_mfma_f32_32x32x16_bf16 v[16:31], a[16:19], a[28:31], v[16:31]
	v_mfma_f32_32x32x16_bf16 v[0:15], a[20:23], a[28:31], v[0:15]
	s_nop 0
	s_nop 0
	s_nop 0
	s_nop 0
	ds_read_b128 a[16:19], v109
	ds_read_b128 a[20:23], v110
	ds_read_b128 a[24:27], v111
	ds_read_b128 a[28:31], v112
	s_waitcnt lgkmcnt(5)
	v_mfma_f32_32x32x16_bf16 v[48:63], a[0:3], a[8:11], v[48:63]
	s_and_b32 m0, s32, 7
	s_lshl_b32 m0, m0, 12
	s_add_i32 m0, m0, 0xcc00
	s_nop 0
	global_load_lds_dwordx4 v[176:177], off
	v_mfma_f32_32x32x16_bf16 v[32:47], a[4:7], a[8:11], v[32:47]
	s_waitcnt lgkmcnt(4)
	v_mfma_f32_32x32x16_bf16 v[16:31], a[0:3], a[12:15], v[16:31]
	v_mfma_f32_32x32x16_bf16 v[0:15], a[4:7], a[12:15], v[0:15]
	s_and_b32 m0, s32, 7
	s_lshl_b32 m0, m0, 11
	s_add_i32 m0, m0, 0x14000
	s_nop 0
	global_load_lds_dwordx4 v[178:179], off
	s_nop 0
	s_nop 0
	s_nop 0
	s_nop 0
	s_waitcnt lgkmcnt(1)
	v_mfma_f32_32x32x16_bf16 v[48:63], a[16:19], a[24:27], v[48:63]
	v_mfma_f32_32x32x16_bf16 v[32:47], a[20:23], a[24:27], v[32:47]
	s_and_b32 m0, s32, 7
	s_lshl_b32 m0, m0, 11
	s_add_i32 m0, m0, 0x14400
	s_nop 0
	global_load_lds_dwordx4 v[180:181], off
	s_waitcnt vmcnt(6)
	s_waitcnt lgkmcnt(0)
	s_barrier
	ds_read_b128 a[12:15], v81 offset:4096
	ds_read_b128 a[8:11], v81
	ds_read_b128 a[4:7], v82 offset:36864
	ds_read_b128 a[0:3], v82 offset:32768
	v_mfma_f32_32x32x16_bf16 v[16:31], a[16:19], a[28:31], v[16:31]
	v_lshl_add_u64 v[158:159], v[66:67], 0, s[30:31]
	s_nop 0
	v_lshl_add_u64 v[160:161], v[68:69], 0, s[30:31]
	s_nop 0
	s_nop 0
	s_nop 0
	v_lshl_add_u64 v[162:163], v[70:71], 0, s[30:31]
	s_nop 0
	v_mfma_f32_32x32x16_bf16 v[0:15], a[20:23], a[28:31], v[0:15]
	s_and_b32 m0, s32, 7
	s_lshl_b32 m0, m0, 12
	s_add_i32 m0, m0, 0x18000
	s_nop 0
	global_load_lds_dwordx4 v[158:159], off
	s_nop 0
	s_nop 0
	s_nop 0
	s_nop 0
	v_lshl_add_u64 v[166:167], v[74:75], 0, s[30:31]
	s_nop 0
	s_nop 0
	s_nop 0
	v_lshl_add_u64 v[168:169], v[76:77], 0, s[30:31]
	s_nop 0
	s_mov_b64 s[30:31], 0x600
	s_nop 0
	s_nop 0
	s_nop 0
	s_nop 0
	s_nop 0
	ds_read_b128 a[16:19], v84 offset:32768
	ds_read_b128 a[20:23], v84 offset:36864
	ds_read_b128 a[24:27], v83
	ds_read_b128 a[28:31], v83 offset:4096
	s_waitcnt lgkmcnt(4)
	v_mfma_f32_32x32x16_bf16 v[48:63], a[0:3], a[8:11], v[48:63]
	s_nop 0
	v_mfma_f32_32x32x16_bf16 v[32:47], a[4:7], a[8:11], v[32:47]
	v_mfma_f32_32x32x16_bf16 v[16:31], a[0:3], a[12:15], v[16:31]
	s_and_b32 m0, s32, 7
	s_lshl_b32 m0, m0, 12
	s_add_i32 m0, m0, 0x18400
	s_nop 0
	global_load_lds_dwordx4 v[160:161], off
	v_mfma_f32_32x32x16_bf16 v[0:15], a[4:7], a[12:15], v[0:15]
	s_nop 0
	s_nop 0
	s_nop 0
	s_nop 0
	ds_read_b128 a[0:3], v86 offset:32768
	ds_read_b128 a[4:7], v86 offset:36864
	ds_read_b128 a[8:11], v85
	ds_read_b128 a[12:15], v85 offset:4096
	s_waitcnt lgkmcnt(5)
	v_mfma_f32_32x32x16_bf16 v[48:63], a[16:19], a[24:27], v[48:63]
	v_mfma_f32_32x32x16_bf16 v[32:47], a[20:23], a[24:27], v[32:47]
	s_and_b32 m0, s32, 7
	s_lshl_b32 m0, m0, 12
	s_add_i32 m0, m0, 0x18800
	s_nop 0
	global_load_lds_dwordx4 v[162:163], off
	s_waitcnt lgkmcnt(4)
	v_mfma_f32_32x32x16_bf16 v[16:31], a[16:19], a[28:31], v[16:31]
	v_mfma_f32_32x32x16_bf16 v[0:15], a[20:23], a[28:31], v[0:15]
	s_nop 0
	s_nop 0
	s_nop 0
	s_nop 0
	ds_read_b128 a[16:19], v88 offset:32768
	ds_read_b128 a[20:23], v88 offset:36864
	ds_read_b128 a[24:27], v87
	ds_read_b128 a[28:31], v87 offset:4096
	s_waitcnt lgkmcnt(5)
	v_mfma_f32_32x32x16_bf16 v[48:63], a[0:3], a[8:11], v[48:63]
	s_and_b32 m0, s32, 7
	s_lshl_b32 m0, m0, 12
	s_add_i32 m0, m0, 0x18c00
	s_nop 0
	global_load_lds_dwordx4 v[164:165], off
	v_mfma_f32_32x32x16_bf16 v[32:47], a[4:7], a[8:11], v[32:47]
	s_waitcnt lgkmcnt(4)
	v_mfma_f32_32x32x16_bf16 v[16:31], a[0:3], a[12:15], v[16:31]
	v_mfma_f32_32x32x16_bf16 v[0:15], a[4:7], a[12:15], v[0:15]
	s_and_b32 m0, s32, 7
	s_lshl_b32 m0, m0, 11
	s_add_i32 m0, m0, 0x20000
	s_nop 0
	global_load_lds_dwordx4 v[166:167], off
	s_nop 0
	s_nop 0
	s_nop 0
	s_nop 0
	s_waitcnt lgkmcnt(1)
	v_mfma_f32_32x32x16_bf16 v[48:63], a[16:19], a[24:27], v[48:63]
	v_mfma_f32_32x32x16_bf16 v[32:47], a[20:23], a[24:27], v[32:47]
	s_and_b32 m0, s32, 7
	s_lshl_b32 m0, m0, 11
	s_add_i32 m0, m0, 0x20400
	s_nop 0
	global_load_lds_dwordx4 v[168:169], off
	s_waitcnt vmcnt(6)
	s_waitcnt lgkmcnt(0)
	s_barrier
	ds_read_b128 a[12:15], v81 offset:53248
	ds_read_b128 a[8:11], v81 offset:49152
	ds_read_b128 a[4:7], v89
	ds_read_b128 a[0:3], v91
	v_mfma_f32_32x32x16_bf16 v[16:31], a[16:19], a[28:31], v[16:31]
	v_lshl_add_u64 v[170:171], v[66:67], 0, s[30:31]
	s_nop 0
	v_lshl_add_u64 v[172:173], v[68:69], 0, s[30:31]
	s_nop 0
	s_nop 0
	s_nop 0
	v_lshl_add_u64 v[174:175], v[70:71], 0, s[30:31]
	s_nop 0
	v_mfma_f32_32x32x16_bf16 v[0:15], a[20:23], a[28:31], v[0:15]
	s_and_b32 m0, s32, 7
	s_lshl_b32 m0, m0, 12
	s_add_i32 m0, m0, 0x0
	s_nop 0
	global_load_lds_dwordx4 v[170:171], off
	s_nop 0
	v_lshl_add_u64 v[176:177], v[72:73], 0, s[30:31]
	s_nop 0
	s_nop 0
	s_nop 0
	v_lshl_add_u64 v[178:179], v[74:75], 0, s[30:31]
	s_nop 0
	s_nop 0
	s_nop 0
	v_lshl_add_u64 v[180:181], v[76:77], 0, s[30:31]
	s_nop 0
	s_mov_b64 s[30:31], 0x680
	s_nop 0
	s_nop 0
	s_nop 0
	s_nop 0
	s_nop 0
	ds_read_b128 a[16:19], v92
	ds_read_b128 a[20:23], v90
	ds_read_b128 a[24:27], v83 offset:49152
	ds_read_b128 a[28:31], v83 offset:53248
	s_waitcnt lgkmcnt(4)
	v_mfma_f32_32x32x16_bf16 v[48:63], a[0:3], a[8:11], v[48:63]
	s_nop 0
	v_mfma_f32_32x32x16_bf16 v[32:47], a[4:7], a[8:11], v[32:47]
	v_mfma_f32_32x32x16_bf16 v[16:31], a[0:3], a[12:15], v[16:31]
	s_and_b32 m0, s32, 7
	s_lshl_b32 m0, m0, 12
	s_add_i32 m0, m0, 0x400
	s_nop 0
	global_load_lds_dwordx4 v[172:173], off
	v_mfma_f32_32x32x16_bf16 v[0:15], a[4:7], a[12:15], v[0:15]
	s_nop 0
	s_nop 0
	s_nop 0
	s_nop 0
	ds_read_b128 a[0:3], v94
	ds_read_b128 a[4:7], v93
	ds_read_b128 a[8:11], v85 offset:49152
	ds_read_b128 a[12:15], v85 offset:53248
	s_waitcnt lgkmcnt(5)
	v_mfma_f32_32x32x16_bf16 v[48:63], a[16:19], a[24:27], v[48:63]
	v_mfma_f32_32x32x16_bf16 v[32:47], a[20:23], a[24:27], v[32:47]
	s_and_b32 m0, s32, 7
	s_lshl_b32 m0, m0, 12
	s_add_i32 m0, m0, 0x800
	s_nop 0
	global_load_lds_dwordx4 v[174:175], off
	s_waitcnt lgkmcnt(4)
	v_mfma_f32_32x32x16_bf16 v[16:31], a[16:19], a[28:31], v[16:31]
	v_mfma_f32_32x32x16_bf16 v[0:15], a[20:23], a[28:31], v[0:15]
	s_nop 0
	s_nop 0
	s_nop 0
	s_nop 0
	ds_read_b128 a[16:19], v96
	ds_read_b128 a[20:23], v95
	ds_read_b128 a[24:27], v87 offset:49152
	ds_read_b128 a[28:31], v87 offset:53248
	s_waitcnt lgkmcnt(5)
	v_mfma_f32_32x32x16_bf16 v[48:63], a[0:3], a[8:11], v[48:63]
	s_and_b32 m0, s32, 7
	s_lshl_b32 m0, m0, 12
	s_add_i32 m0, m0, 0xc00
	s_nop 0
	global_load_lds_dwordx4 v[176:177], off
	v_mfma_f32_32x32x16_bf16 v[32:47], a[4:7], a[8:11], v[32:47]
	s_waitcnt lgkmcnt(4)
	v_mfma_f32_32x32x16_bf16 v[16:31], a[0:3], a[12:15], v[16:31]
	v_mfma_f32_32x32x16_bf16 v[0:15], a[4:7], a[12:15], v[0:15]
	s_and_b32 m0, s32, 7
	s_lshl_b32 m0, m0, 11
	s_add_i32 m0, m0, 0x8000
	s_nop 0
	global_load_lds_dwordx4 v[178:179], off
	s_nop 0
	s_nop 0
	s_nop 0
	s_nop 0
	s_waitcnt lgkmcnt(1)
	v_mfma_f32_32x32x16_bf16 v[48:63], a[16:19], a[24:27], v[48:63]
	v_mfma_f32_32x32x16_bf16 v[32:47], a[20:23], a[24:27], v[32:47]
	s_and_b32 m0, s32, 7
	s_lshl_b32 m0, m0, 11
	s_add_i32 m0, m0, 0x8400
	s_nop 0
	global_load_lds_dwordx4 v[180:181], off
	s_waitcnt vmcnt(6)
	s_waitcnt lgkmcnt(0)
	s_barrier
	ds_read_b128 a[12:15], v100
	ds_read_b128 a[8:11], v99
	ds_read_b128 a[4:7], v98
	ds_read_b128 a[0:3], v97
	v_mfma_f32_32x32x16_bf16 v[16:31], a[16:19], a[28:31], v[16:31]
	v_lshl_add_u64 v[158:159], v[66:67], 0, s[30:31]
	s_nop 0
	v_lshl_add_u64 v[160:161], v[68:69], 0, s[30:31]
	s_nop 0
	s_nop 0
	s_nop 0
	v_lshl_add_u64 v[162:163], v[70:71], 0, s[30:31]
	s_nop 0
	v_mfma_f32_32x32x16_bf16 v[0:15], a[20:23], a[28:31], v[0:15]
	s_and_b32 m0, s32, 7
	s_lshl_b32 m0, m0, 12
	s_add_i32 m0, m0, 0xc000
	s_nop 0
	global_load_lds_dwordx4 v[158:159], off
	s_nop 0
	v_lshl_add_u64 v[164:165], v[72:73], 0, s[30:31]
	s_nop 0
	s_nop 0
	s_nop 0
	v_lshl_add_u64 v[166:167], v[74:75], 0, s[30:31]
	s_nop 0
	s_nop 0
	s_nop 0
	v_lshl_add_u64 v[168:169], v[76:77], 0, s[30:31]
	s_nop 0
	s_mov_b64 s[30:31], 0x700
	s_nop 0
	s_nop 0
	s_nop 0
	s_nop 0
	s_nop 0
	ds_read_b128 a[16:19], v101
	ds_read_b128 a[20:23], v102
	ds_read_b128 a[24:27], v103
	ds_read_b128 a[28:31], v104
	s_waitcnt lgkmcnt(4)
	v_mfma_f32_32x32x16_bf16 v[48:63], a[0:3], a[8:11], v[48:63]
	s_nop 0
	v_mfma_f32_32x32x16_bf16 v[32:47], a[4:7], a[8:11], v[32:47]
	v_mfma_f32_32x32x16_bf16 v[16:31], a[0:3], a[12:15], v[16:31]
	s_and_b32 m0, s32, 7
	s_lshl_b32 m0, m0, 12
	s_add_i32 m0, m0, 0xc400
	s_nop 0
	global_load_lds_dwordx4 v[160:161], off
	v_mfma_f32_32x32x16_bf16 v[0:15], a[4:7], a[12:15], v[0:15]
	s_nop 0
	s_nop 0
	s_nop 0
	s_nop 0
	ds_read_b128 a[0:3], v105
	ds_read_b128 a[4:7], v106
	ds_read_b128 a[8:11], v107
	ds_read_b128 a[12:15], v108
	s_waitcnt lgkmcnt(5)
	v_mfma_f32_32x32x16_bf16 v[48:63], a[16:19], a[24:27], v[48:63]
	v_mfma_f32_32x32x16_bf16 v[32:47], a[20:23], a[24:27], v[32:47]
	s_and_b32 m0, s32, 7
	s_lshl_b32 m0, m0, 12
	s_add_i32 m0, m0, 0xc800
	s_nop 0
	global_load_lds_dwordx4 v[162:163], off
	s_waitcnt lgkmcnt(4)
	v_mfma_f32_32x32x16_bf16 v[16:31], a[16:19], a[28:31], v[16:31]
	v_mfma_f32_32x32x16_bf16 v[0:15], a[20:23], a[28:31], v[0:15]
	s_nop 0
	s_nop 0
	s_nop 0
	s_nop 0
	ds_read_b128 a[16:19], v109
	ds_read_b128 a[20:23], v110
	ds_read_b128 a[24:27], v111
	ds_read_b128 a[28:31], v112
	s_waitcnt lgkmcnt(5)
	v_mfma_f32_32x32x16_bf16 v[48:63], a[0:3], a[8:11], v[48:63]
	s_and_b32 m0, s32, 7
	s_lshl_b32 m0, m0, 12
	s_add_i32 m0, m0, 0xcc00
	s_nop 0
	global_load_lds_dwordx4 v[164:165], off
	v_mfma_f32_32x32x16_bf16 v[32:47], a[4:7], a[8:11], v[32:47]
	s_waitcnt lgkmcnt(4)
	v_mfma_f32_32x32x16_bf16 v[16:31], a[0:3], a[12:15], v[16:31]
	v_mfma_f32_32x32x16_bf16 v[0:15], a[4:7], a[12:15], v[0:15]
	s_and_b32 m0, s32, 7
	s_lshl_b32 m0, m0, 11
	s_add_i32 m0, m0, 0x14000
	s_nop 0
	global_load_lds_dwordx4 v[166:167], off
	s_nop 0
	s_nop 0
	s_nop 0
	s_nop 0
	s_waitcnt lgkmcnt(1)
	v_mfma_f32_32x32x16_bf16 v[48:63], a[16:19], a[24:27], v[48:63]
	v_mfma_f32_32x32x16_bf16 v[32:47], a[20:23], a[24:27], v[32:47]
	s_and_b32 m0, s32, 7
	s_lshl_b32 m0, m0, 11
	s_add_i32 m0, m0, 0x14400
	s_nop 0
	global_load_lds_dwordx4 v[168:169], off
	s_waitcnt vmcnt(6)
	s_waitcnt lgkmcnt(0)
	s_barrier
	ds_read_b128 a[12:15], v81 offset:4096
	ds_read_b128 a[8:11], v81
	ds_read_b128 a[4:7], v82 offset:36864
	ds_read_b128 a[0:3], v82 offset:32768
	v_mfma_f32_32x32x16_bf16 v[16:31], a[16:19], a[28:31], v[16:31]
	v_lshl_add_u64 v[170:171], v[66:67], 0, s[30:31]
	s_nop 0
	v_lshl_add_u64 v[172:173], v[68:69], 0, s[30:31]
	s_nop 0
	s_nop 0
	s_nop 0
	v_lshl_add_u64 v[174:175], v[70:71], 0, s[30:31]
	s_nop 0
	v_mfma_f32_32x32x16_bf16 v[0:15], a[20:23], a[28:31], v[0:15]
	s_and_b32 m0, s32, 7
	s_lshl_b32 m0, m0, 12
	s_add_i32 m0, m0, 0x18000
	s_nop 0
	global_load_lds_dwordx4 v[170:171], off
	s_nop 0
	v_lshl_add_u64 v[176:177], v[72:73], 0, s[30:31]
	s_nop 0
	s_nop 0
	s_nop 0
	v_lshl_add_u64 v[178:179], v[74:75], 0, s[30:31]
	s_nop 0
	s_nop 0
	s_nop 0
	v_lshl_add_u64 v[180:181], v[76:77], 0, s[30:31]
	s_nop 0
	s_mov_b64 s[30:31], 0x780
	s_nop 0
	s_nop 0
	s_nop 0
	s_nop 0
	s_nop 0
	ds_read_b128 a[16:19], v84 offset:32768
	ds_read_b128 a[20:23], v84 offset:36864
	ds_read_b128 a[24:27], v83
	ds_read_b128 a[28:31], v83 offset:4096
	s_waitcnt lgkmcnt(4)
	v_mfma_f32_32x32x16_bf16 v[48:63], a[0:3], a[8:11], v[48:63]
	v_lshl_add_u64 v[158:159], v[66:67], 0, s[30:31]
	s_nop 0
	v_readlane_b32 s20, v214, 43
	v_mfma_f32_32x32x16_bf16 v[32:47], a[4:7], a[8:11], v[32:47]
	v_mfma_f32_32x32x16_bf16 v[16:31], a[0:3], a[12:15], v[16:31]
	s_and_b32 m0, s32, 7
	s_lshl_b32 m0, m0, 12
	s_add_i32 m0, m0, 0x18400
	s_nop 0
	global_load_lds_dwordx4 v[172:173], off
	v_mfma_f32_32x32x16_bf16 v[0:15], a[4:7], a[12:15], v[0:15]
	s_nop 0
	s_nop 0
	s_nop 0
	s_nop 0
	ds_read_b128 a[0:3], v86 offset:32768
	ds_read_b128 a[4:7], v86 offset:36864
	ds_read_b128 a[8:11], v85
	ds_read_b128 a[12:15], v85 offset:4096
	s_waitcnt lgkmcnt(5)
	v_mfma_f32_32x32x16_bf16 v[48:63], a[16:19], a[24:27], v[48:63]
	v_mfma_f32_32x32x16_bf16 v[32:47], a[20:23], a[24:27], v[32:47]
	s_and_b32 m0, s32, 7
	s_lshl_b32 m0, m0, 12
	s_add_i32 m0, m0, 0x18800
	s_nop 0
	global_load_lds_dwordx4 v[174:175], off
	s_waitcnt lgkmcnt(4)
	v_mfma_f32_32x32x16_bf16 v[16:31], a[16:19], a[28:31], v[16:31]
	v_mfma_f32_32x32x16_bf16 v[0:15], a[20:23], a[28:31], v[0:15]
	s_nop 0
	s_nop 0
	s_nop 0
	s_nop 0
	ds_read_b128 a[16:19], v88 offset:32768
	ds_read_b128 a[20:23], v88 offset:36864
	ds_read_b128 a[24:27], v87
	ds_read_b128 a[28:31], v87 offset:4096
	s_waitcnt lgkmcnt(5)
	v_mfma_f32_32x32x16_bf16 v[48:63], a[0:3], a[8:11], v[48:63]
	s_and_b32 m0, s32, 7
	s_lshl_b32 m0, m0, 12
	s_add_i32 m0, m0, 0x18c00
	s_nop 0
	global_load_lds_dwordx4 v[176:177], off
	v_mfma_f32_32x32x16_bf16 v[32:47], a[4:7], a[8:11], v[32:47]
	s_waitcnt lgkmcnt(4)
	v_mfma_f32_32x32x16_bf16 v[16:31], a[0:3], a[12:15], v[16:31]
	v_mfma_f32_32x32x16_bf16 v[0:15], a[4:7], a[12:15], v[0:15]
	s_and_b32 m0, s32, 7
	s_lshl_b32 m0, m0, 11
	s_add_i32 m0, m0, 0x20000
	s_nop 0
	global_load_lds_dwordx4 v[178:179], off
	s_nop 0
	s_nop 0
	s_nop 0
	s_nop 0
	s_waitcnt lgkmcnt(1)
	v_mfma_f32_32x32x16_bf16 v[48:63], a[16:19], a[24:27], v[48:63]
	v_mfma_f32_32x32x16_bf16 v[32:47], a[20:23], a[24:27], v[32:47]
	s_and_b32 m0, s32, 7
	s_lshl_b32 m0, m0, 11
	s_add_i32 m0, m0, 0x20400
	s_nop 0
	global_load_lds_dwordx4 v[180:181], off
	s_waitcnt vmcnt(6)
	s_waitcnt lgkmcnt(0)
	s_barrier
	ds_read_b128 a[12:15], v81 offset:53248
	ds_read_b128 a[8:11], v81 offset:49152
	ds_read_b128 a[4:7], v89
	ds_read_b128 a[0:3], v91
	s_nop 0
	v_lshl_add_u64 v[160:161], v[68:69], 0, s[30:31]
	s_nop 0
	v_mfma_f32_32x32x16_bf16 v[16:31], a[16:19], a[28:31], v[16:31]
	s_nop 0
	v_lshl_add_u64 v[162:163], v[70:71], 0, s[30:31]
	s_nop 0
	v_readlane_b32 s21, v214, 44
	s_nop 0
	v_lshl_add_u64 v[164:165], v[72:73], 0, s[30:31]
	s_nop 0
	v_mfma_f32_32x32x16_bf16 v[0:15], a[20:23], a[28:31], v[0:15]
	s_and_b32 m0, s32, 7
	s_lshl_b32 m0, m0, 12
	s_add_i32 m0, m0, 0x0
	s_nop 0
	global_load_lds_dwordx4 v[158:159], off
	s_nop 0
	v_lshl_add_u64 v[166:167], v[74:75], 0, s[30:31]
	s_nop 0
	s_lshl_b64 s[28:29], s[0:1], 21
	s_nop 0
	v_lshl_add_u64 v[168:169], v[76:77], 0, s[30:31]
	s_nop 0
	s_add_u32 s20, s20, s28
	s_nop 0
	s_nop 0
	s_nop 0
	s_nop 0
	s_nop 0
	ds_read_b128 a[16:19], v92
	ds_read_b128 a[20:23], v90
	ds_read_b128 a[24:27], v83 offset:49152
	ds_read_b128 a[28:31], v83 offset:53248
	s_waitcnt lgkmcnt(4)
	v_mfma_f32_32x32x16_bf16 v[48:63], a[0:3], a[8:11], v[48:63]
	s_addc_u32 s21, s21, s29
	v_readlane_b32 s23, v214, 41
	s_add_u32 s36, s23, s28
	v_readlane_b32 s23, v214, 42
	s_addc_u32 s37, s23, s29
	v_mfma_f32_32x32x16_bf16 v[32:47], a[4:7], a[8:11], v[32:47]
	v_mfma_f32_32x32x16_bf16 v[16:31], a[0:3], a[12:15], v[16:31]
	s_and_b32 m0, s32, 7
	s_lshl_b32 m0, m0, 12
	s_add_i32 m0, m0, 0x400
	s_nop 0
	global_load_lds_dwordx4 v[160:161], off
	v_mfma_f32_32x32x16_bf16 v[0:15], a[4:7], a[12:15], v[0:15]
	s_nop 0
	s_nop 0
	s_nop 0
	s_nop 0
	ds_read_b128 a[0:3], v94
	ds_read_b128 a[4:7], v93
	ds_read_b128 a[8:11], v85 offset:49152
	ds_read_b128 a[12:15], v85 offset:53248
	s_waitcnt lgkmcnt(5)
	v_mfma_f32_32x32x16_bf16 v[48:63], a[16:19], a[24:27], v[48:63]
	v_mfma_f32_32x32x16_bf16 v[32:47], a[20:23], a[24:27], v[32:47]
	s_and_b32 m0, s32, 7
	s_lshl_b32 m0, m0, 12
	s_add_i32 m0, m0, 0x800
	s_nop 0
	global_load_lds_dwordx4 v[162:163], off
	s_waitcnt lgkmcnt(4)
	v_mfma_f32_32x32x16_bf16 v[16:31], a[16:19], a[28:31], v[16:31]
	v_mfma_f32_32x32x16_bf16 v[0:15], a[20:23], a[28:31], v[0:15]
	s_nop 0
	s_nop 0
	s_nop 0
	s_nop 0
	ds_read_b128 a[16:19], v96
	ds_read_b128 a[20:23], v95
	ds_read_b128 a[24:27], v87 offset:49152
	ds_read_b128 a[28:31], v87 offset:53248
	s_waitcnt lgkmcnt(5)
	v_mfma_f32_32x32x16_bf16 v[48:63], a[0:3], a[8:11], v[48:63]
	s_and_b32 m0, s32, 7
	s_lshl_b32 m0, m0, 12
	s_add_i32 m0, m0, 0xc00
	s_nop 0
	global_load_lds_dwordx4 v[164:165], off
	v_mfma_f32_32x32x16_bf16 v[32:47], a[4:7], a[8:11], v[32:47]
	s_waitcnt lgkmcnt(4)
	v_mfma_f32_32x32x16_bf16 v[16:31], a[0:3], a[12:15], v[16:31]
	v_mfma_f32_32x32x16_bf16 v[0:15], a[4:7], a[12:15], v[0:15]
	s_and_b32 m0, s32, 7
	s_lshl_b32 m0, m0, 11
	s_add_i32 m0, m0, 0x8000
	s_nop 0
	global_load_lds_dwordx4 v[166:167], off
	s_nop 0
	s_nop 0
	s_nop 0
	s_nop 0
	s_waitcnt lgkmcnt(1)
	v_mfma_f32_32x32x16_bf16 v[48:63], a[16:19], a[24:27], v[48:63]
	v_mfma_f32_32x32x16_bf16 v[32:47], a[20:23], a[24:27], v[32:47]
	s_and_b32 m0, s32, 7
	s_lshl_b32 m0, m0, 11
	s_add_i32 m0, m0, 0x8400
	s_nop 0
	global_load_lds_dwordx4 v[168:169], off
	s_waitcnt vmcnt(6)
	s_waitcnt lgkmcnt(0)
	s_barrier
	ds_read_b128 a[12:15], v100
	ds_read_b128 a[8:11], v99
	ds_read_b128 a[4:7], v98
	ds_read_b128 a[0:3], v97
	v_mfma_f32_32x32x16_bf16 v[16:31], a[16:19], a[28:31], v[16:31]
	v_mfma_f32_32x32x16_bf16 v[0:15], a[20:23], a[28:31], v[0:15]
	s_nop 0
	s_nop 0
	s_nop 0
	s_nop 0
	ds_read_b128 a[16:19], v101
	ds_read_b128 a[20:23], v102
	ds_read_b128 a[24:27], v103
	ds_read_b128 a[28:31], v104
	s_waitcnt lgkmcnt(4)
	v_mfma_f32_32x32x16_bf16 v[48:63], a[0:3], a[8:11], v[48:63]
	v_mfma_f32_32x32x16_bf16 v[32:47], a[4:7], a[8:11], v[32:47]
	v_mfma_f32_32x32x16_bf16 v[16:31], a[0:3], a[12:15], v[16:31]
	v_mfma_f32_32x32x16_bf16 v[0:15], a[4:7], a[12:15], v[0:15]
	s_nop 0
	s_nop 0
	s_nop 0
	s_nop 0
	ds_read_b128 a[0:3], v105
	ds_read_b128 a[4:7], v106
	ds_read_b128 a[8:11], v107
	ds_read_b128 a[12:15], v108
	s_waitcnt lgkmcnt(5)
	v_mfma_f32_32x32x16_bf16 v[48:63], a[16:19], a[24:27], v[48:63]
	v_mfma_f32_32x32x16_bf16 v[32:47], a[20:23], a[24:27], v[32:47]
	s_waitcnt lgkmcnt(4)
	v_mfma_f32_32x32x16_bf16 v[16:31], a[16:19], a[28:31], v[16:31]
	v_mfma_f32_32x32x16_bf16 v[0:15], a[20:23], a[28:31], v[0:15]
	s_nop 0
	s_nop 0
	s_nop 0
	s_nop 0
	ds_read_b128 a[16:19], v109
	ds_read_b128 a[20:23], v110
	ds_read_b128 a[24:27], v111
	ds_read_b128 a[28:31], v112
	s_waitcnt lgkmcnt(5)
	v_mfma_f32_32x32x16_bf16 v[48:63], a[0:3], a[8:11], v[48:63]
	v_mfma_f32_32x32x16_bf16 v[32:47], a[4:7], a[8:11], v[32:47]
	s_waitcnt lgkmcnt(4)
	v_mfma_f32_32x32x16_bf16 v[16:31], a[0:3], a[12:15], v[16:31]
	v_mfma_f32_32x32x16_bf16 v[0:15], a[4:7], a[12:15], v[0:15]
	s_nop 0
	s_nop 0
	s_nop 0
	s_nop 0
	s_waitcnt lgkmcnt(1)
	v_mfma_f32_32x32x16_bf16 v[48:63], a[16:19], a[24:27], v[48:63]
	v_mfma_f32_32x32x16_bf16 v[32:47], a[20:23], a[24:27], v[32:47]
	s_waitcnt vmcnt(0)
	s_waitcnt lgkmcnt(0)
	s_barrier
	ds_read_b128 a[12:15], v81 offset:4096
	ds_read_b128 a[8:11], v81
	ds_read_b128 a[4:7], v82 offset:36864
	ds_read_b128 a[0:3], v82 offset:32768
	v_mfma_f32_32x32x16_bf16 v[16:31], a[16:19], a[28:31], v[16:31]
	v_mfma_f32_32x32x16_bf16 v[0:15], a[20:23], a[28:31], v[0:15]
	s_nop 0
	s_nop 0
	s_nop 0
	s_nop 0
	ds_read_b128 a[16:19], v84 offset:32768
	ds_read_b128 a[20:23], v84 offset:36864
	ds_read_b128 a[24:27], v83
	ds_read_b128 a[28:31], v83 offset:4096
	s_waitcnt lgkmcnt(4)
	v_mfma_f32_32x32x16_bf16 v[48:63], a[0:3], a[8:11], v[48:63]
	v_mfma_f32_32x32x16_bf16 v[32:47], a[4:7], a[8:11], v[32:47]
	v_mfma_f32_32x32x16_bf16 v[16:31], a[0:3], a[12:15], v[16:31]
	v_mfma_f32_32x32x16_bf16 v[0:15], a[4:7], a[12:15], v[0:15]
	s_nop 0
	s_nop 0
	s_nop 0
	s_nop 0
	ds_read_b128 a[0:3], v86 offset:32768
	ds_read_b128 a[4:7], v86 offset:36864
	ds_read_b128 a[8:11], v85
	ds_read_b128 a[12:15], v85 offset:4096
	s_waitcnt lgkmcnt(5)
	v_mfma_f32_32x32x16_bf16 v[48:63], a[16:19], a[24:27], v[48:63]
	v_mfma_f32_32x32x16_bf16 v[32:47], a[20:23], a[24:27], v[32:47]
	s_waitcnt lgkmcnt(4)
	v_mfma_f32_32x32x16_bf16 v[16:31], a[16:19], a[28:31], v[16:31]
	v_mfma_f32_32x32x16_bf16 v[0:15], a[20:23], a[28:31], v[0:15]
	s_nop 0
	s_nop 0
	s_nop 0
	s_nop 0
	s_waitcnt lgkmcnt(1)
	v_mfma_f32_32x32x16_bf16 v[48:63], a[0:3], a[8:11], v[48:63]
	v_mfma_f32_32x32x16_bf16 v[32:47], a[4:7], a[8:11], v[32:47]
	s_waitcnt lgkmcnt(0)
	v_mfma_f32_32x32x16_bf16 v[16:31], a[0:3], a[12:15], v[16:31]
	v_mfma_f32_32x32x16_bf16 v[0:15], a[4:7], a[12:15], v[0:15]
	ds_read_b128 v[66:69], v88 offset:32768
	ds_read_b128 v[70:73], v87
	ds_read_b128 v[74:77], v88 offset:36864
	ds_read_b128 v[82:85], v87 offset:4096
	s_waitcnt lgkmcnt(0)
	v_mfma_f32_32x32x16_bf16 v[48:63], v[66:69], v[70:73], v[48:63]
	v_mfma_f32_32x32x16_bf16 v[32:47], v[74:77], v[70:73], v[32:47]
	v_or_b32_e32 v70, s22, v80
	v_lshl_add_u32 v70, v78, 6, v70
	v_ashrrev_i32_e32 v71, 31, v70
	v_lshlrev_b64 v[72:73], 10, v[70:71]
	v_lshl_add_u64 v[86:87], s[36:37], 0, v[72:73]
	v_mfma_f32_32x32x16_bf16 v[16:31], v[66:69], v[82:85], v[16:31]
	v_lshlrev_b32_e32 v66, 6, v79
	v_or3_b32 v66, v66, v64, s2
	s_movk_i32 s2, 0xff
	v_cmp_lt_i32_e32 vcc, s2, v66
	v_mfma_f32_32x32x16_bf16 v[0:15], v[74:77], v[82:85], v[0:15]
	s_and_saveexec_b64 s[22:23], vcc
	s_xor_b64 s[28:29], exec, s[22:23]
	v_mov_b32_e32 v67, v65
	s_movk_i32 s22, 0xfc00
	v_lshl_add_u64 v[68:69], v[66:67], 2, v[86:87]
	s_mov_b32 s23, -1
	v_lshl_add_u64 v[68:69], v[68:69], 0, s[22:23]
	s_or_saveexec_b64 s[28:29], s[28:29]
	v_lshl_add_u64 v[90:91], s[20:21], 0, v[72:73]
	v_ashrrev_i32_e32 v67, 31, v66
	s_xor_b64 exec, exec, s[28:29]
	v_lshl_add_u64 v[68:69], v[66:67], 2, v[90:91]
	s_or_b64 exec, exec, s[28:29]
	s_lshl_b64 s[0:1], s[0:1], 19
	s_lshl_b64 s[22:23], s[0:1], 1
	v_readlane_b32 s0, v214, 37
	v_readlane_b32 s1, v214, 38
	s_add_u32 s0, s0, s22
	s_addc_u32 s1, s1, s23
	v_readlane_b32 s28, v214, 39
	v_readlane_b32 s29, v214, 40
	s_add_u32 s54, s28, s22
	v_and_b32_e32 v74, 0xdf, v70
	v_ashrrev_i32_e32 v71, 6, v70
	global_store_dwordx4 v[68:69], v[48:51], off
	v_add_u32_e32 v68, 0xffffff00, v66
	v_lshlrev_b32_e32 v69, 9, v66
	s_addc_u32 s55, s29, s23
	v_and_b32_e32 v71, -4, v71
	v_lshrrev_b32_e32 v92, 6, v68
	v_and_b32_e32 v72, 0x7800, v69
	v_lshlrev_b32_e32 v88, 1, v74
	s_and_saveexec_b64 s[22:23], vcc
	s_xor_b64 s[28:29], exec, s[22:23]
	s_cbranch_execz .LBB0_619
	v_add_u32_e32 v68, v92, v71
	v_ashrrev_i32_e32 v69, 31, v68
	v_lshlrev_b64 v[68:69], 15, v[68:69]
	v_lshl_add_u64 v[68:69], s[54:55], 0, v[68:69]
	v_mov_b32_e32 v73, v65
	v_lshl_add_u64 v[68:69], v[68:69], 0, v[72:73]
	v_mov_b32_e32 v89, v65
	v_bfe_u32 v73, v48, 16, 1
	v_lshl_add_u64 v[68:69], v[68:69], 0, v[88:89]
	v_add3_u32 v73, v48, v73, s27
	global_store_short_d16_hi v[68:69], v73, off
	v_bfe_u32 v73, v49, 16, 1
	v_add3_u32 v73, v49, v73, s27
	global_store_short_d16_hi v[68:69], v73, off offset:512
	v_bfe_u32 v73, v50, 16, 1
	v_add3_u32 v73, v50, v73, s27
	global_store_short_d16_hi v[68:69], v73, off offset:1024
	v_bfe_u32 v73, v51, 16, 1
	v_add3_u32 v73, v51, v73, s27
	global_store_short_d16_hi v[68:69], v73, off offset:1536

.LBB0_747:
	v_mov_b32_e32 v78, v133
	s_lshl_b32 s2, s2, 8
	v_ashrrev_i32_e32 v6, 6, v78
	v_bfe_u32 v7, v78, 3, 3
	v_lshl_or_b32 v8, v6, 5, v7
	v_add_u32_e32 v0, s2, v8
	s_waitcnt lgkmcnt(0)
	v_ashrrev_i32_e32 v1, 31, v0
	v_lshlrev_b64 v[2:3], 11, v[0:1]
	v_bfe_u32 v1, v78, 4, 2
	v_readlane_b32 s0, v215, 52
	v_xor_b32_e32 v1, v1, v78
	v_readlane_b32 s1, v215, 53
	v_lshlrev_b32_e32 v1, 4, v1
	v_and_b32_e32 v64, 0x70, v1
	v_lshl_add_u64 v[2:3], s[0:1], 0, v[2:3]
	v_or_b32_e32 v1, 8, v8
	v_lshl_add_u64 v[66:67], v[2:3], 0, v[64:65]
	v_add_u32_e32 v2, s2, v1
	v_lshrrev_b32_e32 v1, 1, v1
	v_xor_b32_e32 v1, v1, v78
	v_ashrrev_i32_e32 v3, 31, v2
	v_lshlrev_b32_e32 v1, 4, v1
	v_or_b32_e32 v0, 16, v0
	v_lshlrev_b64 v[2:3], 11, v[2:3]
	v_and_b32_e32 v4, 0x70, v1
	v_ashrrev_i32_e32 v1, 31, v0
	v_lshl_add_u64 v[2:3], s[0:1], 0, v[2:3]
	v_mov_b32_e32 v5, v65
	v_lshlrev_b64 v[0:1], 11, v[0:1]
	v_lshl_add_u64 v[68:69], v[2:3], 0, v[4:5]
	v_lshl_add_u64 v[0:1], s[0:1], 0, v[0:1]
	v_or_b32_e32 v2, 24, v8
	v_lshl_add_u64 v[70:71], v[0:1], 0, v[64:65]
	v_add_u32_e32 v0, s2, v2
	v_lshrrev_b32_e32 v2, 1, v2
	v_ashrrev_i32_e32 v1, 31, v0
	v_xor_b32_e32 v2, v2, v78
	v_lshlrev_b64 v[0:1], 11, v[0:1]
	v_lshlrev_b32_e32 v2, 4, v2
	v_lshl_add_u64 v[0:1], s[0:1], 0, v[0:1]
	v_and_b32_e32 v2, 0x70, v2
	v_mov_b32_e32 v3, v65
	v_lshl_add_u64 v[72:73], v[0:1], 0, v[2:3]
	v_lshl_or_b32 v2, v6, 4, v7
	v_add_u32_e32 v0, s20, v2
	v_lshlrev_b32_e32 v3, 12, v6
	v_ashrrev_i32_e32 v1, 31, v0
	v_add_u32_e32 v131, 0, v3
	v_lshlrev_b64 v[0:1], 11, v[0:1]
	s_waitcnt vmcnt(0)
	v_readfirstlane_b32 s40, v131
	v_add_u32_e32 v130, 0x400, v131
	v_lshl_add_u64 v[0:1], s[96:97], 0, v[0:1]
	v_or_b32_e32 v2, 8, v2
	s_waitcnt lgkmcnt(0)
	s_barrier
	s_mov_b32 m0, s40
	v_readfirstlane_b32 s41, v130
	v_add_u32_e32 v128, 0x800, v131
	v_lshlrev_b32_e32 v5, 11, v6
	v_and_b32_e32 v79, 1, v6
	v_lshl_add_u64 v[74:75], v[0:1], 0, v[64:65]
	v_add_u32_e32 v0, s20, v2
	v_lshrrev_b32_e32 v2, 1, v2
	global_load_lds_dwordx4 v[66:67], off
	s_mov_b32 m0, s41
	v_readfirstlane_b32 s42, v128
	v_add_u32_e32 v126, 0xc00, v131
	v_add_u32_e32 v6, 0, v5
	v_ashrrev_i32_e32 v1, 31, v0
	v_xor_b32_e32 v2, v2, v78
	global_load_lds_dwordx4 v[68:69], off
	s_mov_b32 m0, s42
	v_readfirstlane_b32 s43, v126
	v_add_u32_e32 v129, 0x8000, v6
	v_lshlrev_b64 v[0:1], 11, v[0:1]
	v_lshlrev_b32_e32 v2, 4, v2
	global_load_lds_dwordx4 v[70:71], off
	s_mov_b32 m0, s43
	v_readfirstlane_b32 s44, v129
	v_add_u32_e32 v127, 0x8400, v6
	v_lshl_add_u64 v[0:1], s[96:97], 0, v[0:1]
	v_and_b32_e32 v64, 0x70, v2
	global_load_lds_dwordx4 v[72:73], off
	s_mov_b32 m0, s44
	v_readfirstlane_b32 s45, v127
	v_add_u32_e32 v125, 0xc000, v131
	v_lshl_add_u64 v[76:77], v[0:1], 0, v[64:65]
	global_load_lds_dwordx4 v[74:75], off
	s_mov_b32 m0, s45
	s_mov_b64 s[0:1], 0x80
	v_readfirstlane_b32 s29, v125
	v_add_u32_e32 v120, 0xc400, v131
	global_load_lds_dwordx4 v[76:77], off
	v_lshl_add_u64 v[0:1], v[66:67], 0, s[0:1]
	s_mov_b32 m0, s29
	v_readfirstlane_b32 s33, v120
	v_add_u32_e32 v121, 0xc800, v131
	global_load_lds_dwordx4 v[0:1], off
	v_lshl_add_u64 v[0:1], v[68:69], 0, s[0:1]
	s_mov_b32 m0, s33
	v_readfirstlane_b32 s36, v121
	v_add_u32_e32 v122, 0xcc00, v131
	global_load_lds_dwordx4 v[0:1], off
	v_lshl_add_u64 v[0:1], v[70:71], 0, s[0:1]
	s_mov_b32 m0, s36
	v_readfirstlane_b32 s37, v122
	v_add_u32_e32 v123, s85, v5
	global_load_lds_dwordx4 v[0:1], off
	v_lshl_add_u64 v[0:1], v[72:73], 0, s[0:1]
	s_mov_b32 m0, s37
	v_readfirstlane_b32 s38, v123
	v_add_u32_e32 v124, 0x14400, v6
	global_load_lds_dwordx4 v[0:1], off
	v_lshl_add_u64 v[0:1], v[74:75], 0, s[0:1]
	s_mov_b32 m0, s38
	v_readfirstlane_b32 s39, v124
	global_load_lds_dwordx4 v[0:1], off
	v_lshl_add_u64 v[0:1], v[76:77], 0, s[0:1]
	s_mov_b32 m0, s39
	v_lshrrev_b32_e32 v2, 1, v78
	v_bfe_u32 v64, v78, 5, 1
	global_load_lds_dwordx4 v[0:1], off
	v_add_u32_e32 v119, s3, v3
	v_bitop3_b32 v0, v2, v64, 7 bitop3:0x6c
	s_waitcnt vmcnt(6)
	s_mov_b64 s[30:31], 0x100
	v_readfirstlane_b32 s0, v119
	v_add_u32_e32 v114, 0x400, v119
	v_lshlrev_b32_e32 v132, 4, v0
	s_waitcnt lgkmcnt(0)
	s_barrier
	v_lshl_add_u64 v[0:1], v[66:67], 0, s[30:31]
	s_mov_b32 m0, s0
	v_readfirstlane_b32 s1, v114
	v_add_u32_e32 v115, 0x800, v119
	global_load_lds_dwordx4 v[0:1], off
	v_lshl_add_u64 v[0:1], v[68:69], 0, s[30:31]
	s_mov_b32 m0, s1
	v_readfirstlane_b32 s21, v115
	v_add_u32_e32 v116, 0xc00, v119
	v_readlane_b32 s23, v212, 31
	v_and_b32_e32 v81, 31, v78
	global_load_lds_dwordx4 v[0:1], off
	v_lshl_add_u64 v[0:1], v[70:71], 0, s[30:31]
	s_mov_b32 m0, s21
	v_readfirstlane_b32 s22, v116
	v_add_u32_e32 v117, s23, v5
	v_add_u32_e32 v2, s3, v5
	v_lshlrev_b32_e32 v4, 7, v81
	global_load_lds_dwordx4 v[0:1], off
	v_lshl_add_u64 v[0:1], v[72:73], 0, s[30:31]
	s_mov_b32 m0, s22
	v_readfirstlane_b32 s23, v117
	v_add_u32_e32 v118, 0x8400, v2
	v_lshl_or_b32 v102, v79, 13, v4
	global_load_lds_dwordx4 v[0:1], off
	v_lshl_add_u64 v[0:1], v[74:75], 0, s[30:31]
	s_mov_b32 m0, s23
	v_readfirstlane_b32 s28, v118
	global_load_lds_dwordx4 v[0:1], off
	v_lshl_add_u64 v[0:1], v[76:77], 0, s[30:31]
	s_mov_b32 m0, s28
	v_add_u32_e32 v100, 0, v102
	global_load_lds_dwordx4 v[0:1], off
	v_add_u32_e32 v85, v100, v132
	v_ashrrev_i32_e32 v80, 7, v78
	ds_read_b128 v[0:3], v85 offset:32768
	ds_read_b128 v[86:89], v85 offset:36864
	v_lshl_or_b32 v134, v80, 13, v4
	v_add_u32_e32 v101, 0, v134
	v_add_u32_e32 v84, v101, v132
	ds_read_b128 v[4:7], v84
	v_bfe_u32 v103, v78, 1, 3
	s_waitcnt lgkmcnt(0)
	v_lshrrev_b32_e32 v182, 6, v133
	s_nop 0
	v_readfirstlane_b32 s32, v182
	v_mfma_f32_32x32x16_bf16 v[48:63], v[0:3], v[4:7], 0
	v_bitop3_b32 v8, v64, v103, 2 bitop3:0x36
	v_lshlrev_b32_e32 v135, 4, v8
	v_add_u32_e32 v83, v100, v135
	ds_read_b128 v[8:11], v83 offset:32768
	ds_read_b128 v[90:93], v83 offset:36864
	v_add_u32_e32 v82, v101, v135
	ds_read_b128 v[12:15], v82
	ds_read_b128 v[94:97], v82 offset:4096
	s_waitcnt vmcnt(12)
	v_mfma_f32_32x32x16_bf16 v[32:47], v[86:89], v[4:7], 0
	ds_read_b128 v[4:7], v84 offset:4096
	s_mov_b64 s[30:31], 0x180
	s_nop 0
	v_or_b32_e32 v143, 0x8000, v102
	v_or_b32_e32 v144, 0x9000, v102
	v_add_u32_e32 v145, s3, v134
	s_mov_b64 s[80:81], 0x200
	s_waitcnt lgkmcnt(0)
	v_mfma_f32_32x32x16_bf16 v[16:31], v[0:3], v[4:7], 0
	v_mfma_f32_32x32x16_bf16 v[48:63], v[8:11], v[12:15], v[48:63]
	v_mfma_f32_32x32x16_bf16 v[32:47], v[90:93], v[12:15], v[32:47]
	v_mfma_f32_32x32x16_bf16 v[16:31], v[8:11], v[94:97], v[16:31]
	v_mfma_f32_32x32x16_bf16 v[0:15], v[86:89], v[4:7], 0
	v_bitop3_b32 v86, v64, v103, 4 bitop3:0x36
	v_lshlrev_b32_e32 v138, 4, v86
	v_add_u32_e32 v87, v100, v138
	v_add_u32_e32 v86, v101, v138
	v_mfma_f32_32x32x16_bf16 v[0:15], v[90:93], v[94:97], v[0:15]
	ds_read_b128 v[88:91], v87 offset:32768
	ds_read_b128 v[92:95], v86
	ds_read_b128 v[96:99], v87 offset:36864
	s_waitcnt lgkmcnt(1)
	v_mfma_f32_32x32x16_bf16 v[48:63], v[88:91], v[92:95], v[48:63]
	s_waitcnt lgkmcnt(0)
	v_mfma_f32_32x32x16_bf16 v[32:47], v[96:99], v[92:95], v[32:47]
	ds_read_b128 v[92:95], v86 offset:4096
	s_waitcnt lgkmcnt(0)
	v_mfma_f32_32x32x16_bf16 v[16:31], v[88:91], v[92:95], v[16:31]
	v_bitop3_b32 v88, v64, v103, 6 bitop3:0x36
	v_lshlrev_b32_e32 v142, 4, v88
	v_add_u32_e32 v89, v100, v142
	v_add_u32_e32 v88, v101, v142
	v_mfma_f32_32x32x16_bf16 v[0:15], v[96:99], v[92:95], v[0:15]
	ds_read_b128 v[90:93], v89 offset:32768
	ds_read_b128 v[94:97], v88
	ds_read_b128 v[98:101], v89 offset:36864
	s_waitcnt lgkmcnt(1)
	v_mfma_f32_32x32x16_bf16 v[48:63], v[90:93], v[94:97], v[48:63]
	s_waitcnt lgkmcnt(0)
	v_mfma_f32_32x32x16_bf16 v[32:47], v[98:101], v[94:97], v[32:47]
	ds_read_b128 v[94:97], v88 offset:4096
	s_waitcnt vmcnt(6)
	s_waitcnt lgkmcnt(0)
	s_barrier
	s_waitcnt lgkmcnt(0)
	v_mfma_f32_32x32x16_bf16 v[16:31], v[90:93], v[94:97], v[16:31]
	v_lshl_add_u64 v[158:159], v[66:67], 0, s[30:31]
	s_nop 0
	v_lshl_add_u64 v[160:161], v[68:69], 0, s[30:31]
	s_nop 0
	s_nop 0
	s_nop 0
	v_lshl_add_u64 v[162:163], v[70:71], 0, s[30:31]
	s_nop 0
	v_mfma_f32_32x32x16_bf16 v[0:15], v[98:101], v[94:97], v[0:15]
	s_and_b32 m0, s32, 7
	s_lshl_b32 m0, m0, 12
	s_add_i32 m0, m0, 0x0
	s_nop 0
	global_load_lds_dwordx4 v[158:159], off
	s_nop 0
	v_lshl_add_u64 v[164:165], v[72:73], 0, s[30:31]
	s_nop 0
	s_nop 0
	s_nop 0
	v_lshl_add_u64 v[166:167], v[74:75], 0, s[30:31]
	s_nop 0
	s_nop 0
	s_nop 0
	v_lshl_add_u64 v[168:169], v[76:77], 0, s[30:31]
	s_nop 0
	s_add_i32 s30, 0, 0xc000
	s_nop 0
	v_add_u32_e32 v90, s30, v132
	v_add_u32_e32 v91, v90, v143
	v_add_u32_e32 v90, v90, v144
	ds_read_b128 v[92:95], v91
	ds_read_b128 v[96:99], v84 offset:49152
	ds_read_b128 v[100:103], v90
	ds_read_b128 v[150:153], v84 offset:53248
	s_waitcnt lgkmcnt(1)
	v_mfma_f32_32x32x16_bf16 v[48:63], v[92:95], v[96:99], v[48:63]
	s_nop 0
	v_mfma_f32_32x32x16_bf16 v[32:47], v[100:103], v[96:99], v[32:47]
	s_waitcnt lgkmcnt(0)
	v_mfma_f32_32x32x16_bf16 v[16:31], v[92:95], v[150:153], v[16:31]
	s_and_b32 m0, s32, 7
	s_lshl_b32 m0, m0, 12
	s_add_i32 m0, m0, 0x400
	s_nop 0
	global_load_lds_dwordx4 v[160:161], off
	v_add_u32_e32 v92, s30, v135
	v_add_u32_e32 v94, v92, v143
	v_add_u32_e32 v92, v92, v144
	v_add_u32_e32 v93, s30, v138
	v_add_u32_e32 v95, v93, v143
	v_add_u32_e32 v93, v93, v144
	v_mfma_f32_32x32x16_bf16 v[0:15], v[100:103], v[150:153], v[0:15]
	ds_read_b128 v[96:99], v94
	ds_read_b128 v[100:103], v82 offset:49152
	ds_read_b128 v[104:107], v92
	ds_read_b128 v[154:157], v82 offset:53248
	s_waitcnt lgkmcnt(1)
	v_mfma_f32_32x32x16_bf16 v[48:63], v[96:99], v[100:103], v[48:63]
	v_mfma_f32_32x32x16_bf16 v[32:47], v[104:107], v[100:103], v[32:47]
	s_and_b32 m0, s32, 7
	s_lshl_b32 m0, m0, 12
	s_add_i32 m0, m0, 0x800
	s_nop 0
	global_load_lds_dwordx4 v[162:163], off
	s_waitcnt lgkmcnt(0)
	v_mfma_f32_32x32x16_bf16 v[16:31], v[96:99], v[154:157], v[16:31]
	v_mfma_f32_32x32x16_bf16 v[0:15], v[104:107], v[154:157], v[0:15]
	ds_read_b128 v[96:99], v95
	ds_read_b128 v[100:103], v86 offset:49152
	ds_read_b128 v[104:107], v93
	ds_read_b128 v[150:153], v86 offset:53248
	s_waitcnt lgkmcnt(1)
	v_mfma_f32_32x32x16_bf16 v[48:63], v[96:99], v[100:103], v[48:63]
	s_and_b32 m0, s32, 7
	s_lshl_b32 m0, m0, 12
	s_add_i32 m0, m0, 0xc00
	s_nop 0
	global_load_lds_dwordx4 v[164:165], off
	v_mfma_f32_32x32x16_bf16 v[32:47], v[104:107], v[100:103], v[32:47]
	s_waitcnt lgkmcnt(0)
	v_mfma_f32_32x32x16_bf16 v[16:31], v[96:99], v[150:153], v[16:31]
	v_add_u32_e32 v96, s30, v142
	v_add_u32_e32 v97, v96, v143
	v_add_u32_e32 v96, v96, v144
	s_mov_b64 s[30:31], 0x200
	v_mfma_f32_32x32x16_bf16 v[0:15], v[104:107], v[150:153], v[0:15]
	s_and_b32 m0, s32, 7
	s_lshl_b32 m0, m0, 11
	s_add_i32 m0, m0, 0x8000
	s_nop 0
	global_load_lds_dwordx4 v[166:167], off
	ds_read_b128 v[98:101], v97
	ds_read_b128 v[102:105], v88 offset:49152
	ds_read_b128 v[106:109], v96
	ds_read_b128 v[154:157], v88 offset:53248
	s_waitcnt lgkmcnt(1)
	v_mfma_f32_32x32x16_bf16 v[48:63], v[98:101], v[102:105], v[48:63]
	v_mfma_f32_32x32x16_bf16 v[32:47], v[106:109], v[102:105], v[32:47]
	s_and_b32 m0, s32, 7
	s_lshl_b32 m0, m0, 11
	s_add_i32 m0, m0, 0x8400
	s_nop 0
	global_load_lds_dwordx4 v[168:169], off
	s_waitcnt vmcnt(6)
	s_waitcnt lgkmcnt(0)
	s_barrier
	s_waitcnt lgkmcnt(0)
	v_mfma_f32_32x32x16_bf16 v[16:31], v[98:101], v[154:157], v[16:31]
	v_lshl_add_u64 v[170:171], v[66:67], 0, s[30:31]
	s_nop 0
	v_lshl_add_u64 v[172:173], v[68:69], 0, s[30:31]
	s_nop 0
	v_add_u32_e32 v101, s3, v132
	s_nop 0
	v_lshl_add_u64 v[174:175], v[70:71], 0, s[30:31]
	s_nop 0
	v_mfma_f32_32x32x16_bf16 v[0:15], v[106:109], v[154:157], v[0:15]
	s_and_b32 m0, s32, 7
	s_lshl_b32 m0, m0, 12
	s_add_i32 m0, m0, 0xc000
	s_nop 0
	global_load_lds_dwordx4 v[170:171], off
	s_nop 0
	v_lshl_add_u64 v[176:177], v[72:73], 0, s[30:31]
	s_nop 0
	v_add_u32_e32 v100, v145, v132
	s_nop 0
	v_lshl_add_u64 v[178:179], v[74:75], 0, s[30:31]
	s_nop 0
	v_or_b32_e32 v132, 0x1000, v134
	s_nop 0
	v_lshl_add_u64 v[180:181], v[76:77], 0, s[30:31]
	s_nop 0
	s_mov_b64 s[30:31], 0x280
	s_nop 0
	v_add_u32_e32 v98, v101, v143
	v_add_u32_e32 v99, v101, v144
	ds_read_b128 v[110:113], v98
	ds_read_b128 v[106:109], v99
	ds_read_b128 v[102:105], v100
	v_add_u32_e32 v101, v101, v132
	ds_read_b128 v[150:153], v101
	s_waitcnt lgkmcnt(1)
	v_mfma_f32_32x32x16_bf16 v[48:63], v[110:113], v[102:105], v[48:63]
	s_nop 0
	v_mfma_f32_32x32x16_bf16 v[32:47], v[106:109], v[102:105], v[32:47]
	s_waitcnt lgkmcnt(0)
	v_mfma_f32_32x32x16_bf16 v[16:31], v[110:113], v[150:153], v[16:31]
	s_and_b32 m0, s32, 7
	s_lshl_b32 m0, m0, 12
	s_add_i32 m0, m0, 0xc400
	s_nop 0
	global_load_lds_dwordx4 v[172:173], off
	v_mfma_f32_32x32x16_bf16 v[0:15], v[106:109], v[150:153], v[0:15]
	v_add_u32_e32 v105, s3, v135
	v_add_u32_e32 v103, v105, v143
	v_add_u32_e32 v102, v105, v144
	ds_read_b128 v[106:109], v103
	v_add_u32_e32 v104, v145, v135
	ds_read_b128 v[134:137], v102
	ds_read_b128 v[110:113], v104
	v_add_u32_e32 v105, v105, v132
	ds_read_b128 v[154:157], v105
	s_waitcnt lgkmcnt(1)
	v_mfma_f32_32x32x16_bf16 v[48:63], v[106:109], v[110:113], v[48:63]
	v_mfma_f32_32x32x16_bf16 v[32:47], v[134:137], v[110:113], v[32:47]
	s_and_b32 m0, s32, 7
	s_lshl_b32 m0, m0, 12
	s_add_i32 m0, m0, 0xc800
	s_nop 0
	global_load_lds_dwordx4 v[174:175], off
	s_waitcnt lgkmcnt(0)
	v_mfma_f32_32x32x16_bf16 v[16:31], v[106:109], v[154:157], v[16:31]
	v_add_u32_e32 v109, s3, v138
	v_add_u32_e32 v107, v109, v143
	v_add_u32_e32 v106, v109, v144
	v_add_u32_e32 v108, v145, v138
	ds_read_b128 v[138:141], v106
	v_add_u32_e32 v109, v109, v132
	v_mfma_f32_32x32x16_bf16 v[0:15], v[134:137], v[154:157], v[0:15]
	ds_read_b128 v[110:113], v107
	ds_read_b128 v[134:137], v108
	ds_read_b128 v[150:153], v109
	s_waitcnt lgkmcnt(1)
	v_mfma_f32_32x32x16_bf16 v[48:63], v[110:113], v[134:137], v[48:63]
	s_and_b32 m0, s32, 7
	s_lshl_b32 m0, m0, 12
	s_add_i32 m0, m0, 0xcc00
	s_nop 0
	global_load_lds_dwordx4 v[176:177], off
	v_mfma_f32_32x32x16_bf16 v[32:47], v[138:141], v[134:137], v[32:47]
	s_waitcnt lgkmcnt(0)
	v_mfma_f32_32x32x16_bf16 v[16:31], v[110:113], v[150:153], v[16:31]
	v_add_u32_e32 v113, s3, v142
	v_add_u32_e32 v111, v113, v143
	v_add_u32_e32 v110, v113, v144
	v_add_u32_e32 v112, v145, v142
	ds_read_b128 v[142:145], v110
	v_add_u32_e32 v113, v113, v132
	v_mfma_f32_32x32x16_bf16 v[0:15], v[138:141], v[150:153], v[0:15]
	s_and_b32 m0, s32, 7
	s_lshl_b32 m0, m0, 11
	s_add_i32 m0, m0, 0x14000
	s_nop 0
	global_load_lds_dwordx4 v[178:179], off
	ds_read_b128 v[134:137], v111
	ds_read_b128 v[138:141], v112
	ds_read_b128 v[154:157], v113
	s_waitcnt lgkmcnt(1)
	v_mfma_f32_32x32x16_bf16 v[48:63], v[134:137], v[138:141], v[48:63]
	v_mfma_f32_32x32x16_bf16 v[32:47], v[142:145], v[138:141], v[32:47]
	s_and_b32 m0, s32, 7
	s_lshl_b32 m0, m0, 11
	s_add_i32 m0, m0, 0x14400
	s_nop 0
	global_load_lds_dwordx4 v[180:181], off
	s_waitcnt vmcnt(6)
	s_waitcnt lgkmcnt(0)
	s_barrier
	s_waitcnt lgkmcnt(0)
	v_mfma_f32_32x32x16_bf16 v[16:31], v[134:137], v[154:157], v[16:31]
	v_lshl_add_u64 v[158:159], v[66:67], 0, s[30:31]
	s_nop 0
	v_lshl_add_u64 v[160:161], v[68:69], 0, s[30:31]
	s_nop 0
	s_nop 0
	s_nop 0
	v_lshl_add_u64 v[162:163], v[70:71], 0, s[30:31]
	s_nop 0
	v_mfma_f32_32x32x16_bf16 v[0:15], v[142:145], v[154:157], v[0:15]
	s_and_b32 m0, s32, 7
	s_lshl_b32 m0, m0, 12
	s_add_i32 m0, m0, 0x18000
	s_nop 0
	global_load_lds_dwordx4 v[158:159], off
	s_nop 0
	v_lshl_add_u64 v[164:165], v[72:73], 0, s[30:31]
	s_nop 0
	s_nop 0
	s_nop 0
	v_lshl_add_u64 v[166:167], v[74:75], 0, s[30:31]
	s_nop 0
	s_nop 0
	s_nop 0
	v_lshl_add_u64 v[168:169], v[76:77], 0, s[30:31]
	s_nop 0
	s_mov_b64 s[30:31], 0x300
	s_nop 0
	ds_read_b128 v[134:137], v85 offset:32768
	ds_read_b128 v[138:141], v84
	ds_read_b128 v[142:145], v85 offset:36864
	ds_read_b128 v[150:153], v84 offset:4096
	s_waitcnt lgkmcnt(1)
	v_mfma_f32_32x32x16_bf16 v[48:63], v[134:137], v[138:141], v[48:63]
	s_nop 0
	v_readfirstlane_b32 s40, v119
	v_mfma_f32_32x32x16_bf16 v[32:47], v[142:145], v[138:141], v[32:47]
	s_waitcnt lgkmcnt(0)
	v_mfma_f32_32x32x16_bf16 v[16:31], v[134:137], v[150:153], v[16:31]
	s_and_b32 m0, s32, 7
	s_lshl_b32 m0, m0, 12
	s_add_i32 m0, m0, 0x18400
	s_nop 0
	global_load_lds_dwordx4 v[160:161], off
	v_mfma_f32_32x32x16_bf16 v[0:15], v[142:145], v[150:153], v[0:15]
	ds_read_b128 v[134:137], v83 offset:32768
	ds_read_b128 v[138:141], v82
	ds_read_b128 v[142:145], v83 offset:36864
	ds_read_b128 v[154:157], v82 offset:4096
	s_waitcnt lgkmcnt(1)
	v_mfma_f32_32x32x16_bf16 v[48:63], v[134:137], v[138:141], v[48:63]
	v_mfma_f32_32x32x16_bf16 v[32:47], v[142:145], v[138:141], v[32:47]
	s_and_b32 m0, s32, 7
	s_lshl_b32 m0, m0, 12
	s_add_i32 m0, m0, 0x18800
	s_nop 0
	global_load_lds_dwordx4 v[162:163], off
	s_waitcnt lgkmcnt(0)
	v_mfma_f32_32x32x16_bf16 v[16:31], v[134:137], v[154:157], v[16:31]
	v_mfma_f32_32x32x16_bf16 v[0:15], v[142:145], v[154:157], v[0:15]
	ds_read_b128 v[134:137], v87 offset:32768
	ds_read_b128 v[138:141], v86
	ds_read_b128 v[142:145], v87 offset:36864
	ds_read_b128 v[150:153], v86 offset:4096
	s_waitcnt lgkmcnt(1)
	v_mfma_f32_32x32x16_bf16 v[48:63], v[134:137], v[138:141], v[48:63]
	s_and_b32 m0, s32, 7
	s_lshl_b32 m0, m0, 12
	s_add_i32 m0, m0, 0x18c00
	s_nop 0
	global_load_lds_dwordx4 v[164:165], off
	v_mfma_f32_32x32x16_bf16 v[32:47], v[142:145], v[138:141], v[32:47]
	s_waitcnt lgkmcnt(0)
	v_mfma_f32_32x32x16_bf16 v[16:31], v[134:137], v[150:153], v[16:31]
	v_mfma_f32_32x32x16_bf16 v[0:15], v[142:145], v[150:153], v[0:15]
	s_and_b32 m0, s32, 7
	s_lshl_b32 m0, m0, 11
	s_add_i32 m0, m0, 0x20000
	s_nop 0
	global_load_lds_dwordx4 v[166:167], off
	ds_read_b128 v[134:137], v89 offset:32768
	ds_read_b128 v[138:141], v88
	ds_read_b128 v[142:145], v89 offset:36864
	ds_read_b128 v[154:157], v88 offset:4096
	s_waitcnt lgkmcnt(1)
	v_mfma_f32_32x32x16_bf16 v[48:63], v[134:137], v[138:141], v[48:63]
	v_mfma_f32_32x32x16_bf16 v[32:47], v[142:145], v[138:141], v[32:47]
	s_and_b32 m0, s32, 7
	s_lshl_b32 m0, m0, 11
	s_add_i32 m0, m0, 0x20400
	s_nop 0
	global_load_lds_dwordx4 v[168:169], off
	s_waitcnt vmcnt(6)
	s_waitcnt lgkmcnt(0)
	s_barrier
	s_waitcnt lgkmcnt(0)
	v_mfma_f32_32x32x16_bf16 v[16:31], v[134:137], v[154:157], v[16:31]
	v_lshl_add_u64 v[170:171], v[66:67], 0, s[30:31]
	s_nop 0
	v_lshl_add_u64 v[172:173], v[68:69], 0, s[30:31]
	s_nop 0
	v_readfirstlane_b32 s41, v114
	s_nop 0
	v_lshl_add_u64 v[174:175], v[70:71], 0, s[30:31]
	s_nop 0
	v_mfma_f32_32x32x16_bf16 v[0:15], v[142:145], v[154:157], v[0:15]
	s_and_b32 m0, s32, 7
	s_lshl_b32 m0, m0, 12
	s_add_i32 m0, m0, 0x0
	s_nop 0
	global_load_lds_dwordx4 v[170:171], off
	s_nop 0
	v_lshl_add_u64 v[176:177], v[72:73], 0, s[30:31]
	s_nop 0
	v_readfirstlane_b32 s42, v115
	s_nop 0
	v_lshl_add_u64 v[178:179], v[74:75], 0, s[30:31]
	s_nop 0
	v_readfirstlane_b32 s43, v116
	s_nop 0
	v_lshl_add_u64 v[180:181], v[76:77], 0, s[30:31]
	s_nop 0
	s_mov_b64 s[30:31], 0x380
	s_nop 0
	ds_read_b128 v[134:137], v91
	ds_read_b128 v[138:141], v84 offset:49152
	ds_read_b128 v[142:145], v90
	ds_read_b128 v[150:153], v84 offset:53248
	s_waitcnt lgkmcnt(1)
	v_mfma_f32_32x32x16_bf16 v[48:63], v[134:137], v[138:141], v[48:63]
	s_nop 0
	v_readfirstlane_b32 s29, v125
	v_readfirstlane_b32 s44, v117
	v_readfirstlane_b32 s45, v118
	v_mfma_f32_32x32x16_bf16 v[32:47], v[142:145], v[138:141], v[32:47]
	s_waitcnt lgkmcnt(0)
	v_mfma_f32_32x32x16_bf16 v[16:31], v[134:137], v[150:153], v[16:31]
	s_and_b32 m0, s32, 7
	s_lshl_b32 m0, m0, 12
	s_add_i32 m0, m0, 0x400
	s_nop 0
	global_load_lds_dwordx4 v[172:173], off
	v_mfma_f32_32x32x16_bf16 v[0:15], v[142:145], v[150:153], v[0:15]
	ds_read_b128 v[134:137], v94
	ds_read_b128 v[138:141], v82 offset:49152
	ds_read_b128 v[142:145], v92
	ds_read_b128 v[154:157], v82 offset:53248
	s_waitcnt lgkmcnt(1)
	v_mfma_f32_32x32x16_bf16 v[48:63], v[134:137], v[138:141], v[48:63]
	v_mfma_f32_32x32x16_bf16 v[32:47], v[142:145], v[138:141], v[32:47]
	s_and_b32 m0, s32, 7
	s_lshl_b32 m0, m0, 12
	s_add_i32 m0, m0, 0x800
	s_nop 0
	global_load_lds_dwordx4 v[174:175], off
	s_waitcnt lgkmcnt(0)
	v_mfma_f32_32x32x16_bf16 v[16:31], v[134:137], v[154:157], v[16:31]
	v_mfma_f32_32x32x16_bf16 v[0:15], v[142:145], v[154:157], v[0:15]
	ds_read_b128 v[134:137], v95
	ds_read_b128 v[138:141], v86 offset:49152
	ds_read_b128 v[142:145], v93
	ds_read_b128 v[150:153], v86 offset:53248
	s_waitcnt lgkmcnt(1)
	v_mfma_f32_32x32x16_bf16 v[48:63], v[134:137], v[138:141], v[48:63]
	s_and_b32 m0, s32, 7
	s_lshl_b32 m0, m0, 12
	s_add_i32 m0, m0, 0xc00
	s_nop 0
	global_load_lds_dwordx4 v[176:177], off
	v_mfma_f32_32x32x16_bf16 v[32:47], v[142:145], v[138:141], v[32:47]
	s_waitcnt lgkmcnt(0)
	v_mfma_f32_32x32x16_bf16 v[16:31], v[134:137], v[150:153], v[16:31]
	v_mfma_f32_32x32x16_bf16 v[0:15], v[142:145], v[150:153], v[0:15]
	s_and_b32 m0, s32, 7
	s_lshl_b32 m0, m0, 11
	s_add_i32 m0, m0, 0x8000
	s_nop 0
	global_load_lds_dwordx4 v[178:179], off
	ds_read_b128 v[134:137], v97
	ds_read_b128 v[138:141], v88 offset:49152
	ds_read_b128 v[142:145], v96
	ds_read_b128 v[154:157], v88 offset:53248
	s_waitcnt lgkmcnt(1)
	v_mfma_f32_32x32x16_bf16 v[48:63], v[134:137], v[138:141], v[48:63]
	v_mfma_f32_32x32x16_bf16 v[32:47], v[142:145], v[138:141], v[32:47]
	s_and_b32 m0, s32, 7
	s_lshl_b32 m0, m0, 11
	s_add_i32 m0, m0, 0x8400
	s_nop 0
	global_load_lds_dwordx4 v[180:181], off
	s_waitcnt vmcnt(6)
	s_waitcnt lgkmcnt(0)
	s_barrier
	s_waitcnt lgkmcnt(0)
	v_mfma_f32_32x32x16_bf16 v[16:31], v[134:137], v[154:157], v[16:31]
	v_lshl_add_u64 v[158:159], v[66:67], 0, s[30:31]
	s_nop 0
	v_lshl_add_u64 v[160:161], v[68:69], 0, s[30:31]
	s_nop 0
	v_readfirstlane_b32 s33, v120
	s_nop 0
	v_lshl_add_u64 v[162:163], v[70:71], 0, s[30:31]
	s_nop 0
	v_mfma_f32_32x32x16_bf16 v[0:15], v[142:145], v[154:157], v[0:15]
	s_and_b32 m0, s32, 7
	s_lshl_b32 m0, m0, 12
	s_add_i32 m0, m0, 0xc000
	s_nop 0
	global_load_lds_dwordx4 v[158:159], off
	s_nop 0
	v_lshl_add_u64 v[164:165], v[72:73], 0, s[30:31]
	s_nop 0
	v_readfirstlane_b32 s36, v121
	s_nop 0
	v_lshl_add_u64 v[166:167], v[74:75], 0, s[30:31]
	s_nop 0
	v_readfirstlane_b32 s37, v122
	s_nop 0
	v_lshl_add_u64 v[168:169], v[76:77], 0, s[30:31]
	s_nop 0
	s_mov_b64 s[30:31], 0x400
	s_nop 0
	ds_read_b128 v[134:137], v98
	ds_read_b128 v[138:141], v100
	ds_read_b128 v[142:145], v99
	ds_read_b128 v[150:153], v101
	s_waitcnt lgkmcnt(1)
	v_mfma_f32_32x32x16_bf16 v[48:63], v[134:137], v[138:141], v[48:63]
	s_nop 0
	v_readfirstlane_b32 s0, v131
	v_readfirstlane_b32 s38, v123
	v_readfirstlane_b32 s39, v124
	v_mfma_f32_32x32x16_bf16 v[32:47], v[142:145], v[138:141], v[32:47]
	s_waitcnt lgkmcnt(0)
	v_mfma_f32_32x32x16_bf16 v[16:31], v[134:137], v[150:153], v[16:31]
	s_and_b32 m0, s32, 7
	s_lshl_b32 m0, m0, 12
	s_add_i32 m0, m0, 0xc400
	s_nop 0
	global_load_lds_dwordx4 v[160:161], off
	v_mfma_f32_32x32x16_bf16 v[0:15], v[142:145], v[150:153], v[0:15]
	ds_read_b128 v[134:137], v103
	ds_read_b128 v[138:141], v104
	ds_read_b128 v[142:145], v102
	ds_read_b128 v[154:157], v105
	s_waitcnt lgkmcnt(1)
	v_mfma_f32_32x32x16_bf16 v[48:63], v[134:137], v[138:141], v[48:63]
	v_mfma_f32_32x32x16_bf16 v[32:47], v[142:145], v[138:141], v[32:47]
	s_and_b32 m0, s32, 7
	s_lshl_b32 m0, m0, 12
	s_add_i32 m0, m0, 0xc800
	s_nop 0
	global_load_lds_dwordx4 v[162:163], off
	s_waitcnt lgkmcnt(0)
	v_mfma_f32_32x32x16_bf16 v[16:31], v[134:137], v[154:157], v[16:31]
	v_mfma_f32_32x32x16_bf16 v[0:15], v[142:145], v[154:157], v[0:15]
	ds_read_b128 v[134:137], v107
	ds_read_b128 v[138:141], v108
	ds_read_b128 v[142:145], v106
	ds_read_b128 v[150:153], v109
	s_waitcnt lgkmcnt(1)
	v_mfma_f32_32x32x16_bf16 v[48:63], v[134:137], v[138:141], v[48:63]
	s_and_b32 m0, s32, 7
	s_lshl_b32 m0, m0, 12
	s_add_i32 m0, m0, 0xcc00
	s_nop 0
	global_load_lds_dwordx4 v[164:165], off
	v_mfma_f32_32x32x16_bf16 v[32:47], v[142:145], v[138:141], v[32:47]
	s_waitcnt lgkmcnt(0)
	v_mfma_f32_32x32x16_bf16 v[16:31], v[134:137], v[150:153], v[16:31]
	v_mfma_f32_32x32x16_bf16 v[0:15], v[142:145], v[150:153], v[0:15]
	s_and_b32 m0, s32, 7
	s_lshl_b32 m0, m0, 11
	s_add_i32 m0, m0, 0x14000
	s_nop 0
	global_load_lds_dwordx4 v[166:167], off
	ds_read_b128 v[134:137], v111
	ds_read_b128 v[138:141], v112
	ds_read_b128 v[142:145], v110
	ds_read_b128 v[154:157], v113
	s_waitcnt lgkmcnt(1)
	v_mfma_f32_32x32x16_bf16 v[48:63], v[134:137], v[138:141], v[48:63]
	v_mfma_f32_32x32x16_bf16 v[32:47], v[142:145], v[138:141], v[32:47]
	s_and_b32 m0, s32, 7
	s_lshl_b32 m0, m0, 11
	s_add_i32 m0, m0, 0x14400
	s_nop 0
	global_load_lds_dwordx4 v[168:169], off
	s_waitcnt vmcnt(6)
	s_waitcnt lgkmcnt(0)
	s_barrier
	s_waitcnt lgkmcnt(0)
	v_mfma_f32_32x32x16_bf16 v[16:31], v[134:137], v[154:157], v[16:31]
	v_lshl_add_u64 v[170:171], v[66:67], 0, s[30:31]
	s_nop 0
	v_lshl_add_u64 v[172:173], v[68:69], 0, s[30:31]
	s_nop 0
	v_readfirstlane_b32 s1, v130
	s_nop 0
	v_lshl_add_u64 v[174:175], v[70:71], 0, s[30:31]
	s_nop 0
	v_mfma_f32_32x32x16_bf16 v[0:15], v[142:145], v[154:157], v[0:15]
	s_and_b32 m0, s32, 7
	s_lshl_b32 m0, m0, 12
	s_add_i32 m0, m0, 0x18000
	s_nop 0
	global_load_lds_dwordx4 v[170:171], off
	s_nop 0
	v_lshl_add_u64 v[176:177], v[72:73], 0, s[30:31]
	s_nop 0
	v_readfirstlane_b32 s21, v128
	s_nop 0
	v_lshl_add_u64 v[178:179], v[74:75], 0, s[30:31]
	s_nop 0
	v_readfirstlane_b32 s22, v126
	s_nop 0
	v_lshl_add_u64 v[180:181], v[76:77], 0, s[30:31]
	s_nop 0
	s_mov_b64 s[30:31], 0x480
	s_nop 0
	ds_read_b128 v[134:137], v85 offset:32768
	ds_read_b128 v[138:141], v84
	ds_read_b128 v[142:145], v85 offset:36864
	ds_read_b128 v[150:153], v84 offset:4096
	s_waitcnt lgkmcnt(1)
	v_mfma_f32_32x32x16_bf16 v[48:63], v[134:137], v[138:141], v[48:63]
	s_nop 0
	v_lshl_add_u64 v[160:161], v[68:69], 0, s[30:31]
	v_readfirstlane_b32 s23, v129
	v_lshl_add_u64 v[166:167], v[74:75], 0, s[30:31]
	v_readfirstlane_b32 s28, v127
	v_lshl_add_u64 v[168:169], v[76:77], 0, s[30:31]
	v_mfma_f32_32x32x16_bf16 v[32:47], v[142:145], v[138:141], v[32:47]
	s_waitcnt lgkmcnt(0)
	v_mfma_f32_32x32x16_bf16 v[16:31], v[134:137], v[150:153], v[16:31]
	s_and_b32 m0, s32, 7
	s_lshl_b32 m0, m0, 12
	s_add_i32 m0, m0, 0x18400
	s_nop 0
	global_load_lds_dwordx4 v[172:173], off
	v_mfma_f32_32x32x16_bf16 v[0:15], v[142:145], v[150:153], v[0:15]
	ds_read_b128 v[134:137], v83 offset:32768
	ds_read_b128 v[138:141], v82
	ds_read_b128 v[142:145], v83 offset:36864
	ds_read_b128 v[154:157], v82 offset:4096
	s_waitcnt lgkmcnt(1)
	v_mfma_f32_32x32x16_bf16 v[48:63], v[134:137], v[138:141], v[48:63]
	v_mfma_f32_32x32x16_bf16 v[32:47], v[142:145], v[138:141], v[32:47]
	s_and_b32 m0, s32, 7
	s_lshl_b32 m0, m0, 12
	s_add_i32 m0, m0, 0x18800
	s_nop 0
	global_load_lds_dwordx4 v[174:175], off
	s_waitcnt lgkmcnt(0)
	v_mfma_f32_32x32x16_bf16 v[16:31], v[134:137], v[154:157], v[16:31]
	v_mfma_f32_32x32x16_bf16 v[0:15], v[142:145], v[154:157], v[0:15]
	ds_read_b128 v[134:137], v87 offset:32768
	ds_read_b128 v[138:141], v86
	ds_read_b128 v[142:145], v87 offset:36864
	ds_read_b128 v[150:153], v86 offset:4096
	s_waitcnt lgkmcnt(1)
	v_mfma_f32_32x32x16_bf16 v[48:63], v[134:137], v[138:141], v[48:63]
	s_and_b32 m0, s32, 7
	s_lshl_b32 m0, m0, 12
	s_add_i32 m0, m0, 0x18c00
	s_nop 0
	global_load_lds_dwordx4 v[176:177], off
	v_mfma_f32_32x32x16_bf16 v[32:47], v[142:145], v[138:141], v[32:47]
	s_waitcnt lgkmcnt(0)
	v_mfma_f32_32x32x16_bf16 v[16:31], v[134:137], v[150:153], v[16:31]
	v_mfma_f32_32x32x16_bf16 v[0:15], v[142:145], v[150:153], v[0:15]
	s_and_b32 m0, s32, 7
	s_lshl_b32 m0, m0, 11
	s_add_i32 m0, m0, 0x20000
	s_nop 0
	global_load_lds_dwordx4 v[178:179], off
	ds_read_b128 v[134:137], v89 offset:32768
	ds_read_b128 v[138:141], v88
	ds_read_b128 v[142:145], v89 offset:36864
	ds_read_b128 v[154:157], v88 offset:4096
	s_waitcnt lgkmcnt(1)
	v_mfma_f32_32x32x16_bf16 v[48:63], v[134:137], v[138:141], v[48:63]
	v_mfma_f32_32x32x16_bf16 v[32:47], v[142:145], v[138:141], v[32:47]
	s_and_b32 m0, s32, 7
	s_lshl_b32 m0, m0, 11
	s_add_i32 m0, m0, 0x20400
	s_nop 0
	global_load_lds_dwordx4 v[180:181], off
	s_waitcnt vmcnt(6)
	s_waitcnt lgkmcnt(0)
	s_barrier
	s_waitcnt lgkmcnt(0)
	v_mfma_f32_32x32x16_bf16 v[16:31], v[134:137], v[154:157], v[16:31]
	v_lshl_add_u64 v[158:159], v[66:67], 0, s[30:31]
	s_nop 0
	s_nop 0
	s_nop 0
	s_nop 0
	v_lshl_add_u64 v[162:163], v[70:71], 0, s[30:31]
	s_nop 0
	v_mfma_f32_32x32x16_bf16 v[0:15], v[142:145], v[154:157], v[0:15]
	s_and_b32 m0, s32, 7
	s_lshl_b32 m0, m0, 12
	s_add_i32 m0, m0, 0x0
	s_nop 0
	global_load_lds_dwordx4 v[158:159], off
	s_nop 0
	v_lshl_add_u64 v[164:165], v[72:73], 0, s[30:31]
	s_nop 0
	s_mov_b64 s[30:31], 0x500
	s_nop 0
	s_nop 0
	v_lshl_add_u64 v[174:175], v[70:71], 0, s[30:31]
	s_nop 0
	s_nop 0
	s_nop 0
	s_nop 0
	ds_read_b128 v[126:129], v91
	ds_read_b128 v[134:137], v84 offset:49152
	ds_read_b128 v[138:141], v90
	ds_read_b128 v[150:153], v84 offset:53248
	s_waitcnt lgkmcnt(1)
	v_mfma_f32_32x32x16_bf16 v[48:63], v[126:129], v[134:137], v[48:63]
	s_nop 0
	v_mfma_f32_32x32x16_bf16 v[32:47], v[138:141], v[134:137], v[32:47]
	s_waitcnt lgkmcnt(0)
	v_mfma_f32_32x32x16_bf16 v[16:31], v[126:129], v[150:153], v[16:31]
	s_and_b32 m0, s32, 7
	s_lshl_b32 m0, m0, 12
	s_add_i32 m0, m0, 0x400
	s_nop 0
	global_load_lds_dwordx4 v[160:161], off
	v_mfma_f32_32x32x16_bf16 v[0:15], v[138:141], v[150:153], v[0:15]
	ds_read_b128 v[126:129], v94
	ds_read_b128 v[134:137], v82 offset:49152
	ds_read_b128 v[138:141], v92
	ds_read_b128 v[154:157], v82 offset:53248
	s_waitcnt lgkmcnt(1)
	v_mfma_f32_32x32x16_bf16 v[48:63], v[126:129], v[134:137], v[48:63]
	v_mfma_f32_32x32x16_bf16 v[32:47], v[138:141], v[134:137], v[32:47]
	s_and_b32 m0, s32, 7
	s_lshl_b32 m0, m0, 12
	s_add_i32 m0, m0, 0x800
	s_nop 0
	global_load_lds_dwordx4 v[162:163], off
	s_waitcnt lgkmcnt(0)
	v_mfma_f32_32x32x16_bf16 v[16:31], v[126:129], v[154:157], v[16:31]
	v_mfma_f32_32x32x16_bf16 v[0:15], v[138:141], v[154:157], v[0:15]
	ds_read_b128 v[126:129], v95
	ds_read_b128 v[134:137], v86 offset:49152
	ds_read_b128 v[138:141], v93
	ds_read_b128 v[150:153], v86 offset:53248
	s_waitcnt lgkmcnt(1)
	v_mfma_f32_32x32x16_bf16 v[48:63], v[126:129], v[134:137], v[48:63]
	s_and_b32 m0, s32, 7
	s_lshl_b32 m0, m0, 12
	s_add_i32 m0, m0, 0xc00
	s_nop 0
	global_load_lds_dwordx4 v[164:165], off
	v_mfma_f32_32x32x16_bf16 v[32:47], v[138:141], v[134:137], v[32:47]
	s_waitcnt lgkmcnt(0)
	v_mfma_f32_32x32x16_bf16 v[16:31], v[126:129], v[150:153], v[16:31]
	v_mfma_f32_32x32x16_bf16 v[0:15], v[138:141], v[150:153], v[0:15]
	s_and_b32 m0, s32, 7
	s_lshl_b32 m0, m0, 11
	s_add_i32 m0, m0, 0x8000
	s_nop 0
	global_load_lds_dwordx4 v[166:167], off
	ds_read_b128 v[126:129], v97
	ds_read_b128 v[134:137], v88 offset:49152
	ds_read_b128 v[138:141], v96
	ds_read_b128 v[154:157], v88 offset:53248
	s_waitcnt lgkmcnt(1)
	v_mfma_f32_32x32x16_bf16 v[48:63], v[126:129], v[134:137], v[48:63]
	v_mfma_f32_32x32x16_bf16 v[32:47], v[138:141], v[134:137], v[32:47]
	s_and_b32 m0, s32, 7
	s_lshl_b32 m0, m0, 11
	s_add_i32 m0, m0, 0x8400
	s_nop 0
	global_load_lds_dwordx4 v[168:169], off
	s_waitcnt vmcnt(6)
	s_waitcnt lgkmcnt(0)
	s_barrier
	s_waitcnt lgkmcnt(0)
	v_mfma_f32_32x32x16_bf16 v[16:31], v[126:129], v[154:157], v[16:31]
	v_lshl_add_u64 v[170:171], v[66:67], 0, s[30:31]
	s_nop 0
	v_lshl_add_u64 v[172:173], v[68:69], 0, s[30:31]
	s_nop 0
	s_nop 0
	s_nop 0
	s_nop 0
	v_mfma_f32_32x32x16_bf16 v[0:15], v[138:141], v[154:157], v[0:15]
	s_and_b32 m0, s32, 7
	s_lshl_b32 m0, m0, 12
	s_add_i32 m0, m0, 0xc000
	s_nop 0
	global_load_lds_dwordx4 v[170:171], off
	s_nop 0
	v_lshl_add_u64 v[176:177], v[72:73], 0, s[30:31]
	s_nop 0
	s_nop 0
	s_nop 0
	v_lshl_add_u64 v[178:179], v[74:75], 0, s[30:31]
	s_nop 0
	s_nop 0
	s_nop 0
	v_lshl_add_u64 v[180:181], v[76:77], 0, s[30:31]
	s_nop 0
	s_mov_b64 s[30:31], 0x580
	s_nop 0
	ds_read_b128 v[120:123], v98
	ds_read_b128 v[124:127], v100
	ds_read_b128 v[128:131], v99
	ds_read_b128 v[150:153], v101
	s_waitcnt lgkmcnt(1)
	v_mfma_f32_32x32x16_bf16 v[48:63], v[120:123], v[124:127], v[48:63]
	s_nop 0
	v_lshl_add_u64 v[162:163], v[70:71], 0, s[30:31]
	v_mfma_f32_32x32x16_bf16 v[32:47], v[128:131], v[124:127], v[32:47]
	s_waitcnt lgkmcnt(0)
	v_mfma_f32_32x32x16_bf16 v[16:31], v[120:123], v[150:153], v[16:31]
	s_and_b32 m0, s32, 7
	s_lshl_b32 m0, m0, 12
	s_add_i32 m0, m0, 0xc400
	s_nop 0
	global_load_lds_dwordx4 v[172:173], off
	v_mfma_f32_32x32x16_bf16 v[0:15], v[128:131], v[150:153], v[0:15]
	ds_read_b128 v[120:123], v103
	ds_read_b128 v[124:127], v104
	ds_read_b128 v[128:131], v102
	ds_read_b128 v[154:157], v105
	s_waitcnt lgkmcnt(1)
	v_mfma_f32_32x32x16_bf16 v[48:63], v[120:123], v[124:127], v[48:63]
	v_mfma_f32_32x32x16_bf16 v[32:47], v[128:131], v[124:127], v[32:47]
	s_and_b32 m0, s32, 7
	s_lshl_b32 m0, m0, 12
	s_add_i32 m0, m0, 0xc800
	s_nop 0
	global_load_lds_dwordx4 v[174:175], off
	s_waitcnt lgkmcnt(0)
	v_mfma_f32_32x32x16_bf16 v[16:31], v[120:123], v[154:157], v[16:31]
	v_mfma_f32_32x32x16_bf16 v[0:15], v[128:131], v[154:157], v[0:15]
	ds_read_b128 v[120:123], v107
	ds_read_b128 v[124:127], v108
	ds_read_b128 v[128:131], v106
	ds_read_b128 v[150:153], v109
	s_waitcnt lgkmcnt(1)
	v_mfma_f32_32x32x16_bf16 v[48:63], v[120:123], v[124:127], v[48:63]
	s_and_b32 m0, s32, 7
	s_lshl_b32 m0, m0, 12
	s_add_i32 m0, m0, 0xcc00
	s_nop 0
	global_load_lds_dwordx4 v[176:177], off
	v_mfma_f32_32x32x16_bf16 v[32:47], v[128:131], v[124:127], v[32:47]
	s_waitcnt lgkmcnt(0)
	v_mfma_f32_32x32x16_bf16 v[16:31], v[120:123], v[150:153], v[16:31]
	v_mfma_f32_32x32x16_bf16 v[0:15], v[128:131], v[150:153], v[0:15]
	s_and_b32 m0, s32, 7
	s_lshl_b32 m0, m0, 11
	s_add_i32 m0, m0, 0x14000
	s_nop 0
	global_load_lds_dwordx4 v[178:179], off
	ds_read_b128 v[120:123], v111
	ds_read_b128 v[124:127], v112
	ds_read_b128 v[128:131], v110
	ds_read_b128 v[154:157], v113
	s_waitcnt lgkmcnt(1)
	v_mfma_f32_32x32x16_bf16 v[48:63], v[120:123], v[124:127], v[48:63]
	v_mfma_f32_32x32x16_bf16 v[32:47], v[128:131], v[124:127], v[32:47]
	s_and_b32 m0, s32, 7
	s_lshl_b32 m0, m0, 11
	s_add_i32 m0, m0, 0x14400
	s_nop 0
	global_load_lds_dwordx4 v[180:181], off
	s_waitcnt vmcnt(6)
	s_waitcnt lgkmcnt(0)
	s_barrier
	s_waitcnt lgkmcnt(0)
	v_mfma_f32_32x32x16_bf16 v[16:31], v[120:123], v[154:157], v[16:31]
	v_lshl_add_u64 v[158:159], v[66:67], 0, s[30:31]
	s_nop 0
	v_lshl_add_u64 v[160:161], v[68:69], 0, s[30:31]
	s_nop 0
	s_nop 0
	s_nop 0
	s_nop 0
	v_mfma_f32_32x32x16_bf16 v[0:15], v[128:131], v[154:157], v[0:15]
	s_and_b32 m0, s32, 7
	s_lshl_b32 m0, m0, 12
	s_add_i32 m0, m0, 0x18000
	s_nop 0
	global_load_lds_dwordx4 v[158:159], off
	s_nop 0
	v_lshl_add_u64 v[164:165], v[72:73], 0, s[30:31]
	s_nop 0
	s_nop 0
	s_nop 0
	v_lshl_add_u64 v[166:167], v[74:75], 0, s[30:31]
	s_nop 0
	s_nop 0
	s_nop 0
	v_lshl_add_u64 v[168:169], v[76:77], 0, s[30:31]
	s_nop 0
	s_mov_b64 s[30:31], 0x600
	s_nop 0
	ds_read_b128 v[114:117], v85 offset:32768
	ds_read_b128 v[118:121], v84
	ds_read_b128 v[122:125], v85 offset:36864
	ds_read_b128 v[150:153], v84 offset:4096
	s_waitcnt lgkmcnt(1)
	v_mfma_f32_32x32x16_bf16 v[48:63], v[114:117], v[118:121], v[48:63]
	s_nop 0
	v_mfma_f32_32x32x16_bf16 v[32:47], v[122:125], v[118:121], v[32:47]
	s_waitcnt lgkmcnt(0)
	v_mfma_f32_32x32x16_bf16 v[16:31], v[114:117], v[150:153], v[16:31]
	s_and_b32 m0, s32, 7
	s_lshl_b32 m0, m0, 12
	s_add_i32 m0, m0, 0x18400
	s_nop 0
	global_load_lds_dwordx4 v[160:161], off
	v_mfma_f32_32x32x16_bf16 v[0:15], v[122:125], v[150:153], v[0:15]
	ds_read_b128 v[114:117], v83 offset:32768
	ds_read_b128 v[118:121], v82
	ds_read_b128 v[122:125], v83 offset:36864
	ds_read_b128 v[154:157], v82 offset:4096
	s_waitcnt lgkmcnt(1)
	v_mfma_f32_32x32x16_bf16 v[48:63], v[114:117], v[118:121], v[48:63]
	v_mfma_f32_32x32x16_bf16 v[32:47], v[122:125], v[118:121], v[32:47]
	s_and_b32 m0, s32, 7
	s_lshl_b32 m0, m0, 12
	s_add_i32 m0, m0, 0x18800
	s_nop 0
	global_load_lds_dwordx4 v[162:163], off
	s_waitcnt lgkmcnt(0)
	v_mfma_f32_32x32x16_bf16 v[16:31], v[114:117], v[154:157], v[16:31]
	v_mfma_f32_32x32x16_bf16 v[0:15], v[122:125], v[154:157], v[0:15]
	ds_read_b128 v[114:117], v87 offset:32768
	ds_read_b128 v[118:121], v86
	ds_read_b128 v[122:125], v87 offset:36864
	ds_read_b128 v[150:153], v86 offset:4096
	s_waitcnt lgkmcnt(1)
	v_mfma_f32_32x32x16_bf16 v[48:63], v[114:117], v[118:121], v[48:63]
	s_and_b32 m0, s32, 7
	s_lshl_b32 m0, m0, 12
	s_add_i32 m0, m0, 0x18c00
	s_nop 0
	global_load_lds_dwordx4 v[164:165], off
	v_mfma_f32_32x32x16_bf16 v[32:47], v[122:125], v[118:121], v[32:47]
	s_waitcnt lgkmcnt(0)
	v_mfma_f32_32x32x16_bf16 v[16:31], v[114:117], v[150:153], v[16:31]
	v_mfma_f32_32x32x16_bf16 v[0:15], v[122:125], v[150:153], v[0:15]
	s_and_b32 m0, s32, 7
	s_lshl_b32 m0, m0, 11
	s_add_i32 m0, m0, 0x20000
	s_nop 0
	global_load_lds_dwordx4 v[166:167], off
	ds_read_b128 v[114:117], v89 offset:32768
	ds_read_b128 v[118:121], v88
	ds_read_b128 v[122:125], v89 offset:36864
	ds_read_b128 v[154:157], v88 offset:4096
	s_waitcnt lgkmcnt(1)
	v_mfma_f32_32x32x16_bf16 v[48:63], v[114:117], v[118:121], v[48:63]
	v_mfma_f32_32x32x16_bf16 v[32:47], v[122:125], v[118:121], v[32:47]
	s_and_b32 m0, s32, 7
	s_lshl_b32 m0, m0, 11
	s_add_i32 m0, m0, 0x20400
	s_nop 0
	global_load_lds_dwordx4 v[168:169], off
	s_waitcnt vmcnt(6)
	s_waitcnt lgkmcnt(0)
	s_barrier
	s_waitcnt lgkmcnt(0)
	v_mfma_f32_32x32x16_bf16 v[16:31], v[114:117], v[154:157], v[16:31]
	v_lshl_add_u64 v[170:171], v[66:67], 0, s[30:31]
	s_nop 0
	v_lshl_add_u64 v[172:173], v[68:69], 0, s[30:31]
	s_nop 0
	s_nop 0
	s_nop 0
	v_lshl_add_u64 v[174:175], v[70:71], 0, s[30:31]
	s_nop 0
	v_mfma_f32_32x32x16_bf16 v[0:15], v[122:125], v[154:157], v[0:15]
	s_and_b32 m0, s32, 7
	s_lshl_b32 m0, m0, 12
	s_add_i32 m0, m0, 0x0
	s_nop 0
	global_load_lds_dwordx4 v[170:171], off
	s_nop 0
	v_lshl_add_u64 v[176:177], v[72:73], 0, s[30:31]
	s_nop 0
	s_nop 0
	s_nop 0
	v_lshl_add_u64 v[178:179], v[74:75], 0, s[30:31]
	s_nop 0
	s_nop 0
	s_nop 0
	v_lshl_add_u64 v[180:181], v[76:77], 0, s[30:31]
	s_nop 0
	s_mov_b64 s[30:31], 0x680
	s_nop 0
	ds_read_b128 v[114:117], v91
	ds_read_b128 v[118:121], v84 offset:49152
	ds_read_b128 v[122:125], v90
	ds_read_b128 v[150:153], v84 offset:53248
	s_waitcnt lgkmcnt(1)
	v_mfma_f32_32x32x16_bf16 v[48:63], v[114:117], v[118:121], v[48:63]
	s_nop 0
	v_mfma_f32_32x32x16_bf16 v[32:47], v[122:125], v[118:121], v[32:47]
	s_waitcnt lgkmcnt(0)
	v_mfma_f32_32x32x16_bf16 v[16:31], v[114:117], v[150:153], v[16:31]
	s_and_b32 m0, s32, 7
	s_lshl_b32 m0, m0, 12
	s_add_i32 m0, m0, 0x400
	s_nop 0
	global_load_lds_dwordx4 v[172:173], off
	v_mfma_f32_32x32x16_bf16 v[0:15], v[122:125], v[150:153], v[0:15]
	ds_read_b128 v[114:117], v94
	ds_read_b128 v[118:121], v82 offset:49152
	ds_read_b128 v[122:125], v92
	ds_read_b128 v[154:157], v82 offset:53248
	s_waitcnt lgkmcnt(1)
	v_mfma_f32_32x32x16_bf16 v[48:63], v[114:117], v[118:121], v[48:63]
	v_mfma_f32_32x32x16_bf16 v[32:47], v[122:125], v[118:121], v[32:47]
	s_and_b32 m0, s32, 7
	s_lshl_b32 m0, m0, 12
	s_add_i32 m0, m0, 0x800
	s_nop 0
	global_load_lds_dwordx4 v[174:175], off
	s_waitcnt lgkmcnt(0)
	v_mfma_f32_32x32x16_bf16 v[16:31], v[114:117], v[154:157], v[16:31]
	v_mfma_f32_32x32x16_bf16 v[0:15], v[122:125], v[154:157], v[0:15]
	ds_read_b128 v[114:117], v95
	ds_read_b128 v[118:121], v86 offset:49152
	ds_read_b128 v[122:125], v93
	ds_read_b128 v[150:153], v86 offset:53248
	s_waitcnt lgkmcnt(1)
	v_mfma_f32_32x32x16_bf16 v[48:63], v[114:117], v[118:121], v[48:63]
	s_and_b32 m0, s32, 7
	s_lshl_b32 m0, m0, 12
	s_add_i32 m0, m0, 0xc00
	s_nop 0
	global_load_lds_dwordx4 v[176:177], off
	v_mfma_f32_32x32x16_bf16 v[32:47], v[122:125], v[118:121], v[32:47]
	s_waitcnt lgkmcnt(0)
	v_mfma_f32_32x32x16_bf16 v[16:31], v[114:117], v[150:153], v[16:31]
	v_mfma_f32_32x32x16_bf16 v[0:15], v[122:125], v[150:153], v[0:15]
	s_and_b32 m0, s32, 7
	s_lshl_b32 m0, m0, 11
	s_add_i32 m0, m0, 0x8000
	s_nop 0
	global_load_lds_dwordx4 v[178:179], off
	ds_read_b128 v[114:117], v97
	ds_read_b128 v[118:121], v88 offset:49152
	ds_read_b128 v[122:125], v96
	ds_read_b128 v[154:157], v88 offset:53248
	s_waitcnt lgkmcnt(1)
	v_mfma_f32_32x32x16_bf16 v[48:63], v[114:117], v[118:121], v[48:63]
	v_mfma_f32_32x32x16_bf16 v[32:47], v[122:125], v[118:121], v[32:47]
	s_and_b32 m0, s32, 7
	s_lshl_b32 m0, m0, 11
	s_add_i32 m0, m0, 0x8400
	s_nop 0
	global_load_lds_dwordx4 v[180:181], off
	s_waitcnt vmcnt(6)
	s_waitcnt lgkmcnt(0)
	s_barrier
	s_waitcnt lgkmcnt(0)
	v_mfma_f32_32x32x16_bf16 v[16:31], v[114:117], v[154:157], v[16:31]
	v_lshl_add_u64 v[158:159], v[66:67], 0, s[30:31]
	s_nop 0
	v_lshl_add_u64 v[160:161], v[68:69], 0, s[30:31]
	s_nop 0
	s_nop 0
	s_nop 0
	v_lshl_add_u64 v[162:163], v[70:71], 0, s[30:31]
	s_nop 0
	v_mfma_f32_32x32x16_bf16 v[0:15], v[122:125], v[154:157], v[0:15]
	s_and_b32 m0, s32, 7
	s_lshl_b32 m0, m0, 12
	s_add_i32 m0, m0, 0xc000
	s_nop 0
	global_load_lds_dwordx4 v[158:159], off
	s_nop 0
	v_lshl_add_u64 v[164:165], v[72:73], 0, s[30:31]
	s_nop 0
	s_nop 0
	s_nop 0
	v_lshl_add_u64 v[166:167], v[74:75], 0, s[30:31]
	s_nop 0
	s_nop 0
	s_nop 0
	v_lshl_add_u64 v[168:169], v[76:77], 0, s[30:31]
	s_nop 0
	s_mov_b64 s[30:31], 0x700
	s_nop 0
	ds_read_b128 v[114:117], v98
	ds_read_b128 v[118:121], v100
	ds_read_b128 v[122:125], v99
	ds_read_b128 v[150:153], v101
	s_waitcnt lgkmcnt(1)
	v_mfma_f32_32x32x16_bf16 v[48:63], v[114:117], v[118:121], v[48:63]
	s_nop 0
	v_mfma_f32_32x32x16_bf16 v[32:47], v[122:125], v[118:121], v[32:47]
	s_waitcnt lgkmcnt(0)
	v_mfma_f32_32x32x16_bf16 v[16:31], v[114:117], v[150:153], v[16:31]
	s_and_b32 m0, s32, 7
	s_lshl_b32 m0, m0, 12
	s_add_i32 m0, m0, 0xc400
	s_nop 0
	global_load_lds_dwordx4 v[160:161], off
	v_mfma_f32_32x32x16_bf16 v[0:15], v[122:125], v[150:153], v[0:15]
	ds_read_b128 v[114:117], v103
	ds_read_b128 v[118:121], v104
	ds_read_b128 v[122:125], v102
	ds_read_b128 v[154:157], v105
	s_waitcnt lgkmcnt(1)
	v_mfma_f32_32x32x16_bf16 v[48:63], v[114:117], v[118:121], v[48:63]
	v_mfma_f32_32x32x16_bf16 v[32:47], v[122:125], v[118:121], v[32:47]
	s_and_b32 m0, s32, 7
	s_lshl_b32 m0, m0, 12
	s_add_i32 m0, m0, 0xc800
	s_nop 0
	global_load_lds_dwordx4 v[162:163], off
	s_waitcnt lgkmcnt(0)
	v_mfma_f32_32x32x16_bf16 v[16:31], v[114:117], v[154:157], v[16:31]
	v_mfma_f32_32x32x16_bf16 v[0:15], v[122:125], v[154:157], v[0:15]
	ds_read_b128 v[114:117], v107
	ds_read_b128 v[118:121], v108
	ds_read_b128 v[122:125], v106
	ds_read_b128 v[150:153], v109
	s_waitcnt lgkmcnt(1)
	v_mfma_f32_32x32x16_bf16 v[48:63], v[114:117], v[118:121], v[48:63]
	s_and_b32 m0, s32, 7
	s_lshl_b32 m0, m0, 12
	s_add_i32 m0, m0, 0xcc00
	s_nop 0
	global_load_lds_dwordx4 v[164:165], off
	v_mfma_f32_32x32x16_bf16 v[32:47], v[122:125], v[118:121], v[32:47]
	s_waitcnt lgkmcnt(0)
	v_mfma_f32_32x32x16_bf16 v[16:31], v[114:117], v[150:153], v[16:31]
	v_mfma_f32_32x32x16_bf16 v[0:15], v[122:125], v[150:153], v[0:15]
	s_and_b32 m0, s32, 7
	s_lshl_b32 m0, m0, 11
	s_add_i32 m0, m0, 0x14000
	s_nop 0
	global_load_lds_dwordx4 v[166:167], off
	ds_read_b128 v[114:117], v111
	ds_read_b128 v[118:121], v112
	ds_read_b128 v[122:125], v110
	ds_read_b128 v[154:157], v113
	s_waitcnt lgkmcnt(1)
	v_mfma_f32_32x32x16_bf16 v[48:63], v[114:117], v[118:121], v[48:63]
	v_mfma_f32_32x32x16_bf16 v[32:47], v[122:125], v[118:121], v[32:47]
	s_and_b32 m0, s32, 7
	s_lshl_b32 m0, m0, 11
	s_add_i32 m0, m0, 0x14400
	s_nop 0
	global_load_lds_dwordx4 v[168:169], off
	s_waitcnt vmcnt(6)
	s_waitcnt lgkmcnt(0)
	s_barrier
	s_waitcnt lgkmcnt(0)
	v_mfma_f32_32x32x16_bf16 v[16:31], v[114:117], v[154:157], v[16:31]
	v_lshl_add_u64 v[170:171], v[66:67], 0, s[30:31]
	s_nop 0
	v_lshl_add_u64 v[172:173], v[68:69], 0, s[30:31]
	s_nop 0
	s_nop 0
	s_nop 0
	v_lshl_add_u64 v[174:175], v[70:71], 0, s[30:31]
	s_nop 0
	v_mfma_f32_32x32x16_bf16 v[0:15], v[122:125], v[154:157], v[0:15]
	s_and_b32 m0, s32, 7
	s_lshl_b32 m0, m0, 12
	s_add_i32 m0, m0, 0x18000
	s_nop 0
	global_load_lds_dwordx4 v[170:171], off
	s_nop 0
	v_lshl_add_u64 v[176:177], v[72:73], 0, s[30:31]
	s_nop 0
	s_nop 0
	s_nop 0
	v_lshl_add_u64 v[178:179], v[74:75], 0, s[30:31]
	s_nop 0
	s_nop 0
	s_nop 0
	v_lshl_add_u64 v[180:181], v[76:77], 0, s[30:31]
	s_nop 0
	s_mov_b64 s[30:31], 0x780
	s_nop 0
	ds_read_b128 v[114:117], v85 offset:32768
	ds_read_b128 v[118:121], v84
	ds_read_b128 v[122:125], v85 offset:36864
	ds_read_b128 v[150:153], v84 offset:4096
	s_waitcnt lgkmcnt(1)
	v_mfma_f32_32x32x16_bf16 v[48:63], v[114:117], v[118:121], v[48:63]
	v_lshl_add_u64 v[158:159], v[66:67], 0, s[30:31]
	s_nop 0
	v_mfma_f32_32x32x16_bf16 v[32:47], v[122:125], v[118:121], v[32:47]
	s_waitcnt lgkmcnt(0)
	v_mfma_f32_32x32x16_bf16 v[16:31], v[114:117], v[150:153], v[16:31]
	s_and_b32 m0, s32, 7
	s_lshl_b32 m0, m0, 12
	s_add_i32 m0, m0, 0x18400
	s_nop 0
	global_load_lds_dwordx4 v[172:173], off
	v_mfma_f32_32x32x16_bf16 v[0:15], v[122:125], v[150:153], v[0:15]
	ds_read_b128 v[114:117], v83 offset:32768
	ds_read_b128 v[118:121], v82
	ds_read_b128 v[122:125], v83 offset:36864
	ds_read_b128 v[154:157], v82 offset:4096
	s_waitcnt lgkmcnt(1)
	v_mfma_f32_32x32x16_bf16 v[48:63], v[114:117], v[118:121], v[48:63]
	v_mfma_f32_32x32x16_bf16 v[32:47], v[122:125], v[118:121], v[32:47]
	s_and_b32 m0, s32, 7
	s_lshl_b32 m0, m0, 12
	s_add_i32 m0, m0, 0x18800
	s_nop 0
	global_load_lds_dwordx4 v[174:175], off
	s_waitcnt lgkmcnt(0)
	v_mfma_f32_32x32x16_bf16 v[16:31], v[114:117], v[154:157], v[16:31]
	v_mfma_f32_32x32x16_bf16 v[0:15], v[122:125], v[154:157], v[0:15]
	ds_read_b128 v[114:117], v87 offset:32768
	ds_read_b128 v[118:121], v86
	ds_read_b128 v[122:125], v87 offset:36864
	ds_read_b128 v[150:153], v86 offset:4096
	s_waitcnt lgkmcnt(1)
	v_mfma_f32_32x32x16_bf16 v[48:63], v[114:117], v[118:121], v[48:63]
	s_and_b32 m0, s32, 7
	s_lshl_b32 m0, m0, 12
	s_add_i32 m0, m0, 0x18c00
	s_nop 0
	global_load_lds_dwordx4 v[176:177], off
	v_mfma_f32_32x32x16_bf16 v[32:47], v[122:125], v[118:121], v[32:47]
	s_waitcnt lgkmcnt(0)
	v_mfma_f32_32x32x16_bf16 v[16:31], v[114:117], v[150:153], v[16:31]
	v_mfma_f32_32x32x16_bf16 v[0:15], v[122:125], v[150:153], v[0:15]
	s_and_b32 m0, s32, 7
	s_lshl_b32 m0, m0, 11
	s_add_i32 m0, m0, 0x20000
	s_nop 0
	global_load_lds_dwordx4 v[178:179], off
	ds_read_b128 v[114:117], v89 offset:32768
	ds_read_b128 v[118:121], v88
	ds_read_b128 v[122:125], v89 offset:36864
	ds_read_b128 v[154:157], v88 offset:4096
	s_waitcnt lgkmcnt(1)
	v_mfma_f32_32x32x16_bf16 v[48:63], v[114:117], v[118:121], v[48:63]
	v_mfma_f32_32x32x16_bf16 v[32:47], v[122:125], v[118:121], v[32:47]
	s_and_b32 m0, s32, 7
	s_lshl_b32 m0, m0, 11
	s_add_i32 m0, m0, 0x20400
	s_nop 0
	global_load_lds_dwordx4 v[180:181], off
	s_waitcnt vmcnt(6)
	s_waitcnt lgkmcnt(0)
	s_barrier
	s_nop 0
	v_lshl_add_u64 v[160:161], v[68:69], 0, s[30:31]
	s_nop 0
	s_waitcnt lgkmcnt(0)
	v_mfma_f32_32x32x16_bf16 v[16:31], v[114:117], v[154:157], v[16:31]
	s_nop 0
	v_lshl_add_u64 v[162:163], v[70:71], 0, s[30:31]
	s_nop 0
	s_nop 0
	s_nop 0
	v_lshl_add_u64 v[164:165], v[72:73], 0, s[30:31]
	s_nop 0
	v_mfma_f32_32x32x16_bf16 v[0:15], v[122:125], v[154:157], v[0:15]
	s_and_b32 m0, s32, 7
	s_lshl_b32 m0, m0, 12
	s_add_i32 m0, m0, 0x0
	s_nop 0
	global_load_lds_dwordx4 v[158:159], off
	s_nop 0
	v_lshl_add_u64 v[166:167], v[74:75], 0, s[30:31]
	s_nop 0
	s_nop 0
	s_nop 0
	v_lshl_add_u64 v[168:169], v[76:77], 0, s[30:31]
	s_nop 0
	s_nop 0
	s_nop 0
	ds_read_b128 v[66:69], v91
	ds_read_b128 v[70:73], v84 offset:49152
	ds_read_b128 v[74:77], v90
	ds_read_b128 v[150:153], v84 offset:53248
	s_waitcnt lgkmcnt(1)
	v_mfma_f32_32x32x16_bf16 v[48:63], v[66:69], v[70:73], v[48:63]
	v_mfma_f32_32x32x16_bf16 v[32:47], v[74:77], v[70:73], v[32:47]
	s_waitcnt lgkmcnt(0)
	v_mfma_f32_32x32x16_bf16 v[16:31], v[66:69], v[150:153], v[16:31]
	s_and_b32 m0, s32, 7
	s_lshl_b32 m0, m0, 12
	s_add_i32 m0, m0, 0x400
	s_nop 0
	global_load_lds_dwordx4 v[160:161], off
	v_mfma_f32_32x32x16_bf16 v[0:15], v[74:77], v[150:153], v[0:15]
	ds_read_b128 v[66:69], v94
	ds_read_b128 v[70:73], v82 offset:49152
	ds_read_b128 v[74:77], v92
	ds_read_b128 v[154:157], v82 offset:53248
	s_waitcnt lgkmcnt(1)
	v_mfma_f32_32x32x16_bf16 v[48:63], v[66:69], v[70:73], v[48:63]
	v_mfma_f32_32x32x16_bf16 v[32:47], v[74:77], v[70:73], v[32:47]
	s_and_b32 m0, s32, 7
	s_lshl_b32 m0, m0, 12
	s_add_i32 m0, m0, 0x800
	s_nop 0
	global_load_lds_dwordx4 v[162:163], off
	s_waitcnt lgkmcnt(0)
	v_mfma_f32_32x32x16_bf16 v[16:31], v[66:69], v[154:157], v[16:31]
	v_mfma_f32_32x32x16_bf16 v[0:15], v[74:77], v[154:157], v[0:15]
	ds_read_b128 v[66:69], v95
	ds_read_b128 v[70:73], v86 offset:49152
	ds_read_b128 v[74:77], v93
	ds_read_b128 v[150:153], v86 offset:53248
	s_waitcnt lgkmcnt(1)
	v_mfma_f32_32x32x16_bf16 v[48:63], v[66:69], v[70:73], v[48:63]
	s_and_b32 m0, s32, 7
	s_lshl_b32 m0, m0, 12
	s_add_i32 m0, m0, 0xc00
	s_nop 0
	global_load_lds_dwordx4 v[164:165], off
	v_mfma_f32_32x32x16_bf16 v[32:47], v[74:77], v[70:73], v[32:47]
	s_waitcnt lgkmcnt(0)
	v_mfma_f32_32x32x16_bf16 v[16:31], v[66:69], v[150:153], v[16:31]
	v_mfma_f32_32x32x16_bf16 v[0:15], v[74:77], v[150:153], v[0:15]
	s_and_b32 m0, s32, 7
	s_lshl_b32 m0, m0, 11
	s_add_i32 m0, m0, 0x8000
	s_nop 0
	global_load_lds_dwordx4 v[166:167], off
	ds_read_b128 v[66:69], v97
	ds_read_b128 v[70:73], v88 offset:49152
	ds_read_b128 v[74:77], v96
	ds_read_b128 v[154:157], v88 offset:53248
	s_waitcnt lgkmcnt(1)
	v_mfma_f32_32x32x16_bf16 v[48:63], v[66:69], v[70:73], v[48:63]
	v_mfma_f32_32x32x16_bf16 v[32:47], v[74:77], v[70:73], v[32:47]
	s_and_b32 m0, s32, 7
	s_lshl_b32 m0, m0, 11
	s_add_i32 m0, m0, 0x8400
	s_nop 0
	global_load_lds_dwordx4 v[168:169], off
	s_waitcnt vmcnt(6)
	s_waitcnt lgkmcnt(0)
	s_barrier
	s_waitcnt lgkmcnt(0)
	v_mfma_f32_32x32x16_bf16 v[16:31], v[66:69], v[154:157], v[16:31]
	v_lshrrev_b32_e32 v183, 7, v133
	v_and_b32_e32 v184, 31, v133
	v_lshl_or_b32 v183, v183, 6, v184
	v_add_u32_e32 v183, s2, v183
	v_lshlrev_b32_e32 v183, 2, v183
	global_load_dword v184, v183, s[76:77]
	global_load_dword v185, v183, s[76:77] offset:128
	v_mfma_f32_32x32x16_bf16 v[0:15], v[74:77], v[154:157], v[0:15]
	ds_read_b128 v[66:69], v98
	ds_read_b128 v[70:73], v100
	ds_read_b128 v[74:77], v99
	ds_read_b128 v[150:153], v101
	s_waitcnt lgkmcnt(1)
	v_mfma_f32_32x32x16_bf16 v[48:63], v[66:69], v[70:73], v[48:63]
	v_mfma_f32_32x32x16_bf16 v[32:47], v[74:77], v[70:73], v[32:47]
	s_waitcnt lgkmcnt(0)
	v_mfma_f32_32x32x16_bf16 v[16:31], v[66:69], v[150:153], v[16:31]
	v_mfma_f32_32x32x16_bf16 v[0:15], v[74:77], v[150:153], v[0:15]
	ds_read_b128 v[66:69], v103
	ds_read_b128 v[70:73], v104
	ds_read_b128 v[74:77], v102
	ds_read_b128 v[154:157], v105
	s_waitcnt lgkmcnt(1)
	v_mfma_f32_32x32x16_bf16 v[48:63], v[66:69], v[70:73], v[48:63]
	v_mfma_f32_32x32x16_bf16 v[32:47], v[74:77], v[70:73], v[32:47]
	s_waitcnt lgkmcnt(0)
	v_mfma_f32_32x32x16_bf16 v[16:31], v[66:69], v[154:157], v[16:31]
	v_mfma_f32_32x32x16_bf16 v[0:15], v[74:77], v[154:157], v[0:15]
	ds_read_b128 v[66:69], v107
	ds_read_b128 v[70:73], v108
	ds_read_b128 v[74:77], v106
	ds_read_b128 v[150:153], v109
	s_waitcnt lgkmcnt(1)
	v_mfma_f32_32x32x16_bf16 v[48:63], v[66:69], v[70:73], v[48:63]
	v_mfma_f32_32x32x16_bf16 v[32:47], v[74:77], v[70:73], v[32:47]
	s_waitcnt lgkmcnt(0)
	v_mfma_f32_32x32x16_bf16 v[16:31], v[66:69], v[150:153], v[16:31]
	v_mfma_f32_32x32x16_bf16 v[0:15], v[74:77], v[150:153], v[0:15]
	ds_read_b128 v[66:69], v111
	ds_read_b128 v[70:73], v112
	ds_read_b128 v[74:77], v110
	ds_read_b128 v[154:157], v113
	s_waitcnt lgkmcnt(1)
	v_mfma_f32_32x32x16_bf16 v[48:63], v[66:69], v[70:73], v[48:63]
	v_mfma_f32_32x32x16_bf16 v[32:47], v[74:77], v[70:73], v[32:47]
	s_waitcnt vmcnt(0)
	s_waitcnt lgkmcnt(0)
	s_barrier
	s_waitcnt lgkmcnt(0)
	v_mfma_f32_32x32x16_bf16 v[16:31], v[66:69], v[154:157], v[16:31]
	v_mfma_f32_32x32x16_bf16 v[0:15], v[74:77], v[154:157], v[0:15]
	ds_read_b128 v[66:69], v85 offset:32768
	ds_read_b128 v[70:73], v84
	ds_read_b128 v[74:77], v85 offset:36864
	ds_read_b128 v[150:153], v84 offset:4096
	s_waitcnt lgkmcnt(1)
	v_mfma_f32_32x32x16_bf16 v[48:63], v[66:69], v[70:73], v[48:63]
	v_mfma_f32_32x32x16_bf16 v[32:47], v[74:77], v[70:73], v[32:47]
	s_waitcnt lgkmcnt(0)
	v_mfma_f32_32x32x16_bf16 v[16:31], v[66:69], v[150:153], v[16:31]
	v_mfma_f32_32x32x16_bf16 v[0:15], v[74:77], v[150:153], v[0:15]
	ds_read_b128 v[66:69], v83 offset:32768
	ds_read_b128 v[70:73], v82
	ds_read_b128 v[74:77], v83 offset:36864
	ds_read_b128 v[154:157], v82 offset:4096
	s_waitcnt lgkmcnt(1)
	v_mfma_f32_32x32x16_bf16 v[48:63], v[66:69], v[70:73], v[48:63]
	v_mfma_f32_32x32x16_bf16 v[32:47], v[74:77], v[70:73], v[32:47]
	s_waitcnt lgkmcnt(0)
	v_mfma_f32_32x32x16_bf16 v[16:31], v[66:69], v[154:157], v[16:31]
	v_mfma_f32_32x32x16_bf16 v[0:15], v[74:77], v[154:157], v[0:15]
	ds_read_b128 v[66:69], v87 offset:32768
	ds_read_b128 v[70:73], v86
	ds_read_b128 v[74:77], v87 offset:36864
	ds_read_b128 v[150:153], v86 offset:4096
	s_waitcnt lgkmcnt(1)
	v_mfma_f32_32x32x16_bf16 v[48:63], v[66:69], v[70:73], v[48:63]
	v_mfma_f32_32x32x16_bf16 v[32:47], v[74:77], v[70:73], v[32:47]
	s_waitcnt lgkmcnt(0)
	v_mfma_f32_32x32x16_bf16 v[16:31], v[66:69], v[150:153], v[16:31]
	v_mfma_f32_32x32x16_bf16 v[0:15], v[74:77], v[150:153], v[0:15]
	ds_read_b128 v[70:73], v89 offset:32768
	ds_read_b128 v[66:69], v88
	ds_read_b128 v[74:77], v89 offset:36864
	ds_read_b128 v[82:85], v88 offset:4096
	s_waitcnt lgkmcnt(0)
	s_barrier
	s_waitcnt lgkmcnt(0)
	v_mfma_f32_32x32x16_bf16 v[48:63], v[70:73], v[66:69], v[48:63]
	v_mfma_f32_32x32x16_bf16 v[32:47], v[74:77], v[66:69], v[32:47]
	v_lshl_or_b32 v69, v80, 6, v81
	v_add_u32_e32 v66, s2, v69
	v_cmp_gt_i32_e32 vcc, s69, v66
	v_ashrrev_i32_e32 v67, 31, v66
	v_mov_b32_e32 v68, 0
	v_mfma_f32_32x32x16_bf16 v[16:31], v[70:73], v[82:85], v[16:31]
	v_mov_b32_e32 v70, 0
	v_mfma_f32_32x32x16_bf16 v[0:15], v[74:77], v[82:85], v[0:15]
	s_and_saveexec_b64 s[0:1], vcc
	s_cbranch_execz .LBB0_749
	v_lshl_add_u64 v[70:71], v[66:67], 2, s[76:77]
	v_mov_b32_e32 v70, v184
	v_fmamk_f32 v70, v70, 0x3a800000, v188
	v_mul_f32_e32 v71, 0x4b800000, v70
	v_cmp_gt_f32_e32 vcc, s82, v70
	s_nop 1
	v_cndmask_b32_e32 v70, v70, v71, vcc
	v_rsq_f32_e32 v70, v70
	s_nop 0
	v_mul_f32_e32 v71, 0x45800000, v70
	v_cndmask_b32_e32 v70, v70, v71, vcc
